# all flat memory ops converted to global on top of the attention k-loop rewrite
# speedup vs baseline: 1.0043x; 1.0041x over previous
_Z8mega_fwd4Args:
	s_load_dwordx8 s[4:11], s[0:1], 0x80
	s_load_dword s3, s[0:1], 0xc0
	s_load_dwordx4 s[92:95], s[0:1], 0xa0
	s_load_dwordx2 s[50:51], s[0:1], 0xb8
	v_and_b32_e32 v226, 0x3ff, v0
	v_cmp_gt_u32_e32 vcc, 2, v226
	v_readfirstlane_b32 s33, v226
	s_waitcnt lgkmcnt(0)
	v_writelane_b32 v252, s4, 0
	s_nop 1
	v_writelane_b32 v252, s5, 1
	v_writelane_b32 v252, s6, 2
	v_writelane_b32 v252, s7, 3
	v_writelane_b32 v252, s8, 4
	v_writelane_b32 v252, s9, 5
	v_writelane_b32 v252, s10, 6
	v_writelane_b32 v252, s11, 7
	s_add_u32 s10, s0, 0xb8
	s_addc_u32 s11, s1, 0
	s_and_saveexec_b64 s[4:5], vcc
	v_lshl_add_u32 v1, v226, 2, 0
	v_add_u32_e32 v1, 0x23fe0, v1
	v_mov_b32_e32 v2, 0
	ds_write_b32 v1, v2
	s_or_b64 exec, exec, s[4:5]
	s_mov_b64 s[22:23], s[94:95]
	s_waitcnt lgkmcnt(0)
	s_barrier
	s_add_u32 s25, s22, 0x1000
	s_getreg_b32 s4, hwreg(HW_REG_XCC_ID, 0, 4)
	s_addc_u32 s27, s23, 0
	s_and_b32 s29, s4, 15
	v_cmp_eq_u32_e64 s[6:7], 0, v226
	s_mov_b64 s[4:5], exec
	s_nop 0
	v_writelane_b32 v252, s6, 8
	s_nop 1
	v_writelane_b32 v252, s7, 9
	s_and_b64 s[6:7], s[4:5], s[6:7]
	s_mov_b64 exec, s[6:7]
	s_cbranch_execz .LBB0_4
	s_lshl_b32 s6, s29, 8
	s_add_u32 s6, s25, s6
	s_addc_u32 s7, s27, 0
	v_mov_b32_e32 v1, 1
	v_mov_b64_e32 v[2:3], s[6:7]
	global_atomic_add v[2:3], v1, off offset:1024

.LBB0_18:
	v_lshrrev_b32_e32 v2, 1, v4
	v_and_b32_e32 v11, 0xff8, v4
	v_and_b32_e32 v12, 0x7c0, v2
	v_ashrrev_i32_e32 v8, 9, v6
	v_and_b32_e32 v7, 0x400, v5
	v_lshlrev_b32_e32 v2, 1, v11
	v_and_or_b32 v11, v4, 56, v12
	v_ashrrev_i32_e32 v9, 31, v8
	v_mad_i32_i24 v7, v11, v8, v7
	v_lshlrev_b64 v[14:15], 13, v[8:9]
	v_and_b32_e32 v9, 0xff8, v7
	v_add_u32_e32 v7, v7, v8
	v_and_b32_e32 v11, 0xfff, v7
	v_add_u32_e32 v7, v7, v8
	v_and_b32_e32 v12, 0xffe, v7
	v_add_u32_e32 v7, v7, v8
	v_and_b32_e32 v13, 0xfff, v7
	v_add_u32_e32 v7, v7, v8
	v_lshl_add_u32 v9, v9, 2, 0
	v_lshl_add_u32 v11, v11, 2, 0
	v_lshl_add_u32 v12, v12, 2, 0
	v_lshl_add_u32 v13, v13, 2, 0
	v_and_b32_e32 v16, 0xffc, v7
	v_add_u32_e32 v7, v7, v8
	ds_read_b32 v9, v9
	ds_read_b32 v11, v11
	ds_read_b32 v17, v12
	ds_read_b32 v13, v13
	v_lshl_add_u32 v12, v16, 2, 0
	v_and_b32_e32 v16, 0xfff, v7
	v_add_u32_e32 v7, v7, v8
	v_and_b32_e32 v18, 0xffe, v7
	v_add_u32_e32 v7, v7, v8
	v_and_b32_e32 v7, 0xfff, v7
	v_lshl_add_u32 v16, v16, 2, 0
	v_lshl_add_u32 v8, v18, 2, 0
	v_lshl_add_u32 v7, v7, 2, 0
	ds_read_b32 v19, v12
	ds_read_b32 v16, v16
	ds_read_b32 v18, v8
	ds_read_b32 v7, v7
	s_mov_b64 s[14:15], s[94:95]
	v_add_u32_e32 v6, s8, v6
	s_waitcnt lgkmcnt(0)
	v_cvt_pk_bf16_f32 v12, v9, v11
	v_cmp_lt_i32_e32 vcc, s13, v6
	v_lshl_add_u64 v[8:9], s[14:15], 0, v[14:15]
	v_lshl_add_u64 v[8:9], v[8:9], 0, v[2:3]
	s_or_b64 s[6:7], vcc, s[6:7]
	v_add_co_u32_e32 v8, vcc, 0x2b00000, v8
	v_add_u32_e32 v5, s12, v5
	v_add_u32_e32 v4, s9, v4
	v_cvt_pk_bf16_f32 v13, v17, v13
	v_cvt_pk_bf16_f32 v14, v19, v16
	v_addc_co_u32_e32 v9, vcc, 0, v9, vcc
	v_cvt_pk_bf16_f32 v15, v18, v7
	global_store_dwordx4 v[8:9], v[12:15], off
	s_andn2_b64 exec, exec, s[6:7]
	s_cbranch_execnz .LBB0_18

.LBB0_29:
	global_load_dword v5, v[2:3], off
	v_ashrrev_i32_e32 v6, 6, v4
	v_add_u32_e32 v8, 0x200, v4
	v_lshl_add_u32 v20, v6, 8, v11
	v_cmp_lt_i32_e32 vcc, s61, v4
	v_mov_b32_e32 v4, v8
	v_add_u32_e32 v22, 0xc000, v20
	ds_read2st64_b32 v[8:9], v20 offset0:192 offset1:204
	ds_read2st64_b32 v[18:19], v20 offset0:216 offset1:228
	ds_read2st64_b32 v[20:21], v20 offset0:240 offset1:252
	s_mov_b64 s[70:71], s[94:95]
	v_ashrrev_i32_e32 v7, 31, v6
	v_lshl_add_u64 v[6:7], s[12:13], 0, v[6:7]
	ds_read2st64_b32 v[22:23], v22 offset0:72 offset1:84
	v_lshlrev_b32_e32 v14, 2, v12
	v_mov_b64_e32 v[24:25], s[70:71]
	v_mad_u64_u32 v[24:25], s[70:71], v6, s17, v[24:25]
	v_mov_b32_e32 v6, v25
	v_mad_u64_u32 v[6:7], s[70:71], v7, s17, v[6:7]
	v_mov_b32_e32 v25, v6
	v_lshl_add_u64 v[6:7], s[6:7], 2, v[24:25]
	v_lshl_add_u64 v[6:7], v[6:7], 0, v[14:15]
	s_or_b64 s[14:15], vcc, s[14:15]
	v_add_co_u32_e32 v6, vcc, 0x100000, v6
	s_waitcnt vmcnt(0) lgkmcnt(0)
	v_add_f32_e32 v5, v5, v8
	v_add_f32_e32 v5, v5, v9
	s_waitcnt lgkmcnt(2)
	v_add_f32_e32 v5, v5, v18
	v_add_f32_e32 v5, v5, v19
	s_waitcnt lgkmcnt(1)
	v_add_f32_e32 v5, v5, v20
	v_add_f32_e32 v5, v5, v21
	s_waitcnt lgkmcnt(0)
	v_add_f32_e32 v5, v5, v22
	v_addc_co_u32_e32 v7, vcc, 0, v7, vcc
	v_add_f32_e32 v5, v5, v23
	global_store_dword v[6:7], v5, off
	s_andn2_b64 exec, exec, s[14:15]
	s_cbranch_execnz .LBB0_29
	s_branch .LBB0_24

.LBB0_36:
	s_andn2_saveexec_b64 s[0:1], s[6:7]
	v_or_b32_e32 v3, v1, v4
	s_or_b64 exec, exec, s[0:1]
	v_lshlrev_b32_e32 v1, 3, v3
	v_or3_b32 v4, v1, v41, v6
	v_readlane_b32 s36, v252, 0
	v_ashrrev_i32_e32 v5, 31, v4
	v_readlane_b32 s42, v252, 6
	v_readlane_b32 s43, v252, 7
	s_mov_b32 s6, 0xf149f2ca
	v_mul_u32_u24_e32 v18, 0x208, v18
	v_lshl_add_u64 v[4:5], v[4:5], 2, s[42:43]
	global_load_dword v1, v[4:5], off
	v_max3_f32 v19, v19, s6, v24
	v_mul_f32_e32 v41, 0x41000000, v44
	v_lshlrev_b32_e32 v44, 2, v18
	v_max3_f32 v18, v19, v20, v25
	v_max3_f32 v18, v18, v26, v29
	v_max3_f32 v18, v18, v30, v35
	s_mov_b64 s[0:1], s[94:95]
	v_mul_hi_i32_i24_e32 v5, 0x2080, v42
	v_mul_i32_i24_e32 v4, 0x2080, v42
	v_max3_f32 v18, v18, v31, v36
	v_mul_u32_u24_e32 v6, 0x104, v6
	v_mov_b32_e32 v45, 0
	v_max3_f32 v18, v18, v32, v37
	v_lshl_add_u64 v[4:5], s[0:1], 0, v[4:5]
	v_lshl_add_u64 v[4:5], v[4:5], 0, v[44:45]
	v_lshlrev_b32_e32 v44, 2, v6
	v_max3_f32 v6, v18, v15, v21
	v_ashrrev_i32_e32 v3, 31, v2
	v_lshl_add_u64 v[4:5], v[4:5], 0, v[44:45]
	v_max3_f32 v6, v6, v7, v11
	v_lshl_add_u64 v[2:3], v[2:3], 2, v[4:5]
	v_max3_f32 v4, v6, v8, v12
	v_max3_f32 v4, v4, v9, v13
	v_max3_f32 v4, v4, v14, v16
	v_max3_f32 v4, v4, v17, v22
	v_max3_f32 v4, v4, v23, v27
	v_max3_f32 v4, v4, v28, v33
	v_max3_f32 v4, v4, v34, v38
	v_max3_f32 v4, v4, v39, v40
	v_fmac_f32_e32 v4, v43, v41
	v_add_co_u32_e32 v2, vcc, 0x20000, v2
	v_readlane_b32 s37, v252, 1
	s_nop 0
	v_addc_co_u32_e32 v3, vcc, 0, v3, vcc
	v_readlane_b32 s38, v252, 2
	v_readlane_b32 s39, v252, 3
	v_readlane_b32 s40, v252, 4
	v_readlane_b32 s41, v252, 5
	s_waitcnt vmcnt(0)
	v_sub_f32_e32 v1, v1, v4
	v_mul_f32_e32 v1, 0x3fb8aa3b, v1
	global_store_dword v[2:3], v1, off
.LBB0_39:
	s_or_b64 exec, exec, s[4:5]
	s_cmp_eq_u32 s2, 8
	s_movk_i32 s4, 0x1bf
	s_cselect_b64 s[0:1], -1, 0
	v_cmp_lt_i32_e32 vcc, s4, v10
	s_and_b64 s[0:1], s[0:1], vcc
	s_and_saveexec_b64 s[4:5], s[0:1]
	s_cbranch_execz .LBB0_44
	v_and_b32_e32 v13, 63, v10
	v_readlane_b32 s36, v252, 0
	v_lshlrev_b32_e32 v2, 2, v13
	v_readlane_b32 s38, v252, 2
	v_readlane_b32 s39, v252, 3
	s_nop 4
	global_load_dword v3, v2, s[38:39]
	global_load_dword v5, v2, s[38:39] offset:256
	global_load_dword v6, v2, s[38:39] offset:512
	global_load_dword v7, v2, s[38:39] offset:768
	v_xor_b32_e32 v1, 4, v2
	v_cmp_eq_u32_e64 s[0:1], 0, v13
	v_readlane_b32 s37, v252, 1
	v_readlane_b32 s40, v252, 4
	v_readlane_b32 s41, v252, 5
	v_readlane_b32 s42, v252, 6
	v_readlane_b32 s43, v252, 7
	s_waitcnt vmcnt(0)
	v_mul_f32_e32 v4, v3, v5
	ds_bpermute_b32 v9, v1, v4
	v_mul_f32_e32 v8, v6, v7
	ds_bpermute_b32 v8, v1, v8
	v_xor_b32_e32 v4, 8, v2
	s_waitcnt lgkmcnt(0)
	v_fmac_f32_e32 v9, v3, v5
	ds_bpermute_b32 v3, v4, v9
	v_fmac_f32_e32 v8, v6, v7
	ds_bpermute_b32 v6, v4, v8
	v_xor_b32_e32 v5, 16, v2
	s_waitcnt lgkmcnt(1)
	v_add_f32_e32 v3, v9, v3
	s_waitcnt lgkmcnt(0)
	v_add_f32_e32 v7, v8, v6
	ds_bpermute_b32 v8, v5, v3
	ds_bpermute_b32 v9, v5, v7
	v_xor_b32_e32 v6, 32, v2
	s_waitcnt lgkmcnt(1)
	v_add_f32_e32 v3, v3, v8
	s_waitcnt lgkmcnt(0)
	v_add_f32_e32 v8, v7, v9
	ds_bpermute_b32 v9, v6, v3
	ds_bpermute_b32 v10, v6, v8
	v_xor_b32_e32 v7, 64, v2
	s_waitcnt lgkmcnt(1)
	v_add_f32_e32 v3, v3, v9
	s_waitcnt lgkmcnt(0)
	v_add_f32_e32 v9, v8, v10
	ds_bpermute_b32 v10, v7, v3
	ds_bpermute_b32 v12, v7, v9
	v_xor_b32_e32 v8, 0x80, v2
	s_waitcnt lgkmcnt(1)
	v_add_f32_e32 v11, v3, v10
	s_waitcnt lgkmcnt(0)
	v_add_f32_e32 v9, v9, v12
	ds_bpermute_b32 v12, v8, v11
	ds_bpermute_b32 v10, v8, v9
	v_mov_b32_e32 v3, 0
	v_lshl_add_u64 v[2:3], s[38:39], 0, v[2:3]
	s_and_saveexec_b64 s[6:7], s[0:1]
	s_cbranch_execz .LBB0_42
	s_waitcnt lgkmcnt(1)
	v_add_f32_e32 v11, v11, v12
	s_mov_b32 s8, 0x3fb8aa3b
	v_mul_f32_e32 v12, 0x3fb8aa3b, v11
	v_fma_f32 v13, v11, s8, -v12
	v_rndne_f32_e32 v14, v12
	v_fmac_f32_e32 v13, 0x32a5705f, v11
	v_sub_f32_e32 v12, v12, v14
	v_add_f32_e32 v12, v12, v13
	v_exp_f32_e32 v12, v12
	v_cvt_i32_f32_e32 v13, v14
	s_waitcnt lgkmcnt(0)
	v_add_f32_e32 v9, v9, v10
	s_mov_b32 s9, 0xc2ce8ed0
	v_cmp_ngt_f32_e32 vcc, s9, v11
	v_ldexp_f32 v10, v12, v13
	v_mul_f32_e32 v12, 0x3fb8aa3b, v9
	v_fma_f32 v13, v9, s8, -v12
	v_rndne_f32_e32 v14, v12
	v_fmac_f32_e32 v13, 0x32a5705f, v9
	v_sub_f32_e32 v12, v12, v14
	v_add_f32_e32 v12, v12, v13
	v_exp_f32_e32 v12, v12
	v_cvt_i32_f32_e32 v13, v14
	s_mov_b32 s12, 0x42b17218
	v_cndmask_b32_e32 v10, 0, v10, vcc
	v_mov_b32_e32 v14, 0x7f800000
	v_cmp_nlt_f32_e32 vcc, s12, v11
	v_ldexp_f32 v11, v12, v13
	s_nop 0
	v_cndmask_b32_e32 v10, v14, v10, vcc
	v_cmp_ngt_f32_e32 vcc, s9, v9
	s_mov_b64 s[8:9], s[94:95]
	s_nop 0
	v_cndmask_b32_e32 v11, 0, v11, vcc
	v_cmp_nlt_f32_e32 vcc, s12, v9
	s_mov_b32 s12, 0x10000
	s_nop 0
	v_cndmask_b32_e32 v9, v14, v11, vcc
	v_sub_f32_e32 v9, v10, v9
	v_mov_b32_e32 v10, s8
	v_add_co_u32_e32 v10, vcc, s12, v10
	v_mov_b32_e32 v11, s9
	v_add_f32_e32 v9, 0x3e4ccccc, v9
	v_addc_co_u32_e32 v11, vcc, 0, v11, vcc
	s_mov_b64 s[8:9], s[94:95]
	global_store_dword v[10:11], v9, off
	s_nop 0
	v_mov_b32_e32 v9, s8
	v_add_co_u32_e32 v10, vcc, 0x10000, v9
	v_mov_b32_e32 v9, s9
	s_nop 0
	v_addc_co_u32_e32 v11, vcc, 0, v9, vcc
	v_mov_b32_e32 v9, 0x3f4ccccd
	global_store_dword v[10:11], v9, off offset:4
.LBB0_42:
	s_or_b64 exec, exec, s[6:7]
	global_load_dword v9, v[2:3], off offset:1024
	s_waitcnt lgkmcnt(0)
	global_load_dword v10, v[2:3], off offset:1280
	global_load_dword v11, v[2:3], off offset:1536
	s_nop 0
	global_load_dword v2, v[2:3], off offset:1792
	s_waitcnt vmcnt(0)
	v_mul_f32_e32 v3, v9, v10
	ds_bpermute_b32 v3, v1, v3
	v_mul_f32_e32 v12, v11, v2
	ds_bpermute_b32 v1, v1, v12
	s_waitcnt lgkmcnt(1)
	v_fmac_f32_e32 v3, v9, v10
	s_waitcnt lgkmcnt(0)
	v_fmac_f32_e32 v1, v11, v2
	ds_bpermute_b32 v2, v4, v3
	ds_bpermute_b32 v4, v4, v1
	s_waitcnt lgkmcnt(1)
	v_add_f32_e32 v2, v3, v2
	s_waitcnt lgkmcnt(0)
	v_add_f32_e32 v1, v1, v4
	ds_bpermute_b32 v3, v5, v2
	ds_bpermute_b32 v4, v5, v1
	s_waitcnt lgkmcnt(1)
	v_add_f32_e32 v2, v2, v3
	s_waitcnt lgkmcnt(0)
	v_add_f32_e32 v1, v1, v4
	ds_bpermute_b32 v3, v6, v2
	ds_bpermute_b32 v4, v6, v1
	s_waitcnt lgkmcnt(1)
	v_add_f32_e32 v2, v2, v3
	s_waitcnt lgkmcnt(0)
	v_add_f32_e32 v1, v1, v4
	ds_bpermute_b32 v3, v7, v2
	ds_bpermute_b32 v4, v7, v1
	s_waitcnt lgkmcnt(1)
	v_add_f32_e32 v3, v2, v3
	s_waitcnt lgkmcnt(0)
	v_add_f32_e32 v1, v1, v4
	ds_bpermute_b32 v4, v8, v3
	ds_bpermute_b32 v2, v8, v1
	s_and_b64 exec, exec, s[0:1]
	s_cbranch_execz .LBB0_44
	s_waitcnt lgkmcnt(1)
	v_add_f32_e32 v3, v3, v4
	s_mov_b32 s0, 0x3fb8aa3b
	v_mul_f32_e32 v4, 0x3fb8aa3b, v3
	v_fma_f32 v5, v3, s0, -v4
	v_rndne_f32_e32 v6, v4
	v_fmac_f32_e32 v5, 0x32a5705f, v3
	v_sub_f32_e32 v4, v4, v6
	v_add_f32_e32 v4, v4, v5
	v_exp_f32_e32 v4, v4
	v_cvt_i32_f32_e32 v5, v6
	s_waitcnt lgkmcnt(0)
	v_add_f32_e32 v1, v1, v2
	s_mov_b32 s1, 0xc2ce8ed0
	v_cmp_ngt_f32_e32 vcc, s1, v3
	v_ldexp_f32 v2, v4, v5
	v_mul_f32_e32 v4, 0x3fb8aa3b, v1
	v_fma_f32 v5, v1, s0, -v4
	v_rndne_f32_e32 v6, v4
	v_fmac_f32_e32 v5, 0x32a5705f, v1
	v_sub_f32_e32 v4, v4, v6
	v_add_f32_e32 v4, v4, v5
	v_exp_f32_e32 v4, v4
	v_cvt_i32_f32_e32 v5, v6
	s_mov_b32 s6, 0x42b17218
	v_cndmask_b32_e32 v2, 0, v2, vcc
	v_mov_b32_e32 v6, 0x7f800000
	v_cmp_nlt_f32_e32 vcc, s6, v3
	v_ldexp_f32 v3, v4, v5
	s_nop 0
	v_cndmask_b32_e32 v2, v6, v2, vcc
	v_cmp_ngt_f32_e32 vcc, s1, v1
	s_mov_b64 s[0:1], s[94:95]
	s_nop 0
	v_cndmask_b32_e32 v3, 0, v3, vcc
	v_cmp_nlt_f32_e32 vcc, s6, v1
	s_mov_b32 s6, 0x10000
	s_nop 0
	v_cndmask_b32_e32 v1, v6, v3, vcc
	v_sub_f32_e32 v1, v2, v1
	v_mov_b32_e32 v2, s0
	v_add_co_u32_e32 v2, vcc, s6, v2
	v_mov_b32_e32 v3, s1
	v_add_f32_e32 v1, 0x3eb60549, v1
	v_addc_co_u32_e32 v3, vcc, 0, v3, vcc
	s_mov_b64 s[0:1], s[94:95]
	global_store_dword v[2:3], v1, off offset:8
	s_nop 0
	v_mov_b32_e32 v1, s0
	v_add_co_u32_e32 v2, vcc, 0x10000, v1
	v_mov_b32_e32 v1, s1
	s_nop 0
	v_addc_co_u32_e32 v3, vcc, 0, v1, vcc
	v_mov_b32_e32 v1, 0x3f24fd5c
	global_store_dword v[2:3], v1, off offset:12

.LBB0_62:
	global_load_dword v47, v[0:1], off sc1
	global_load_dword v32, v[2:3], off sc1
	global_load_dword v33, v[4:5], off sc1
	global_load_dword v34, v[6:7], off sc1
	global_load_dword v35, v[8:9], off sc1
	global_load_dword v36, v[10:11], off sc1
	global_load_dword v37, v[12:13], off sc1
	global_load_dword v38, v[14:15], off sc1
	global_load_dword v39, v[16:17], off sc1
	global_load_dword v40, v[18:19], off sc1
	global_load_dword v41, v[20:21], off sc1
	global_load_dword v42, v[22:23], off sc1
	global_load_dword v43, v[24:25], off sc1
	global_load_dword v44, v[26:27], off sc1
	global_load_dword v45, v[28:29], off sc1
	global_load_dword v46, v[30:31], off sc1
	s_or_b64 s[28:29], s[28:29], exec
	s_or_b64 s[26:27], s[26:27], exec
	s_waitcnt vmcnt(0) lgkmcnt(0)
	v_add_u32_e32 v48, v32, v47
	v_add_u32_e32 v48, v48, v33
	v_add_u32_e32 v48, v48, v34
	v_add_u32_e32 v48, v48, v35
	v_add_u32_e32 v48, v48, v36
	v_add_u32_e32 v48, v48, v37
	v_add_u32_e32 v48, v48, v38
	v_add_u32_e32 v48, v48, v39
	v_add_u32_e32 v48, v48, v40
	v_add_u32_e32 v48, v48, v41
	v_add_u32_e32 v48, v48, v42
	v_add_u32_e32 v48, v48, v43
	v_add_u32_e32 v48, v48, v44
	v_add_u32_e32 v48, v48, v45
	v_add_u32_e32 v48, v48, v46
	v_cmp_ne_u32_e32 vcc, s6, v48
	s_and_saveexec_b64 s[30:31], vcc
	s_cbranch_execz .LBB0_61
	s_and_b32 s36, s3, 0xff
	s_mov_b64 s[34:35], -1
	s_cmp_eq_u32 s36, 0
	s_mov_b64 s[38:39], -1
	s_mov_b64 s[36:37], -1
	s_sleep 1
	s_cbranch_scc1 .LBB0_65
	s_and_saveexec_b64 s[40:41], s[38:39]
	s_cbranch_execz .LBB0_60
	s_branch .LBB0_68
.LBB0_65:
	v_readlane_b32 s8, v252, 42
	v_readlane_b32 s9, v252, 43
	s_mov_b64 s[38:39], 0
	s_nop 0
	v_mov_b64_e32 v[48:49], s[8:9]
	global_load_dword v48, v[48:49], off sc1
	s_waitcnt vmcnt(0) lgkmcnt(0)
	v_cmp_eq_u32_e32 vcc, 0, v48
	s_and_saveexec_b64 s[40:41], vcc
	s_cmp_lt_u32 s3, 0x400001
	s_cselect_b64 s[38:39], -1, 0
	s_xor_b64 s[36:37], exec, -1
	s_and_b64 s[38:39], s[38:39], exec
	s_or_b64 exec, exec, s[40:41]
	s_and_saveexec_b64 s[40:41], s[38:39]
	s_cbranch_execz .LBB0_60

.LBB0_69:
	s_or_b64 exec, exec, s[22:23]
	s_xor_b64 s[22:23], s[24:25], -1
	s_and_saveexec_b64 s[24:25], s[22:23]
	s_xor_b64 s[22:23], exec, s[24:25]
	s_cbranch_execz .LBB0_71
	v_readlane_b32 s8, v252, 42
	v_readlane_b32 s9, v252, 43
	v_mov_b32_e32 v2, 1
	s_nop 0
	v_mov_b64_e32 v[0:1], s[8:9]
	global_atomic_add v[0:1], v2, off

.LBB0_72:
	v_readlane_b32 s8, v253, 26
	v_readlane_b32 s9, v253, 27
	v_mov_b32_e32 v1, 1
	v_cvt_f32_u32_e32 v3, v2
	v_mov_b64_e32 v[4:5], s[8:9]
	global_atomic_add v1, v[4:5], v1, off sc0
	v_sub_u32_e32 v4, 0, v2
	v_rcp_iflag_f32_e32 v3, v3
	s_nop 0
	v_mul_f32_e32 v3, 0x4f7ffffe, v3
	v_cvt_u32_f32_e32 v3, v3
	v_mul_lo_u32 v4, v4, v3
	v_mul_hi_u32 v4, v3, v4
	v_add_u32_e32 v3, v3, v4
	s_waitcnt vmcnt(0) lgkmcnt(0)
	v_mul_hi_u32 v3, v1, v3
	v_mul_lo_u32 v5, v3, v2
	v_add_u32_e32 v4, 1, v1
	v_sub_u32_e32 v1, v1, v5
	v_add_u32_e32 v6, 1, v3
	v_cmp_ge_u32_e32 vcc, v1, v2
	v_sub_u32_e32 v5, v1, v2
	s_nop 0
	v_cndmask_b32_e32 v3, v3, v6, vcc
	v_cndmask_b32_e32 v1, v1, v5, vcc
	v_add_u32_e32 v5, 1, v3
	v_cmp_ge_u32_e32 vcc, v1, v2
	s_nop 1
	v_cndmask_b32_e32 v1, v3, v5, vcc
	v_mad_u64_u32 v[2:3], s[22:23], v2, v1, v[2:3]
	v_cmp_ne_u32_e32 vcc, v4, v2
	s_and_saveexec_b64 s[22:23], vcc
	s_xor_b64 s[22:23], exec, s[22:23]
	s_cbranch_execz .LBB0_85
	v_readlane_b32 s8, v253, 28
	v_readlane_b32 s9, v253, 29
	s_nop 1
	v_mov_b64_e32 v[2:3], s[8:9]
	global_load_dword v0, v[2:3], off sc1
	s_waitcnt vmcnt(0) lgkmcnt(0)
	v_cmp_eq_u32_e32 vcc, v0, v1
	s_and_saveexec_b64 s[24:25], vcc
	s_cbranch_execz .LBB0_84
	s_mov_b32 s3, 1
	s_mov_b64 s[26:27], 0
	s_branch .LBB0_76

.LBB0_76:
	s_and_b32 s36, s3, 0xff
	s_mov_b64 s[34:35], -1
	s_cmp_lg_u32 s36, 0
	s_mov_b64 s[36:37], -1
	s_sleep 1
	s_cbranch_scc1 .LBB0_80
	v_readlane_b32 s8, v252, 42
	v_readlane_b32 s9, v252, 43
	s_mov_b64 s[36:37], 0
	s_mov_b64 s[38:39], -1
	v_mov_b64_e32 v[2:3], s[8:9]
	global_load_dword v0, v[2:3], off sc1
	s_waitcnt vmcnt(0) lgkmcnt(0)
	v_cmp_eq_u32_e32 vcc, 0, v0
	s_and_saveexec_b64 s[40:41], vcc
	s_cmp_lt_u32 s3, 0x400001
	s_cselect_b64 s[36:37], -1, 0
	s_xor_b64 s[38:39], exec, -1
	s_and_b64 s[36:37], s[36:37], exec
	s_or_b64 exec, exec, s[40:41]
.LBB0_80:
	s_andn2_b64 s[30:31], s[30:31], exec
	s_and_b64 s[38:39], s[38:39], exec
	s_or_b64 s[30:31], s[30:31], s[38:39]
	s_and_saveexec_b64 s[38:39], s[36:37]
	s_cbranch_execz .LBB0_75
	v_readlane_b32 s8, v253, 28
	v_readlane_b32 s9, v253, 29
	s_add_i32 s3, s3, 1
	s_or_b64 s[30:31], s[30:31], exec
	v_mov_b64_e32 v[2:3], s[8:9]
	global_load_dword v0, v[2:3], off sc1
	s_waitcnt vmcnt(0) lgkmcnt(0)
	v_cmp_ne_u32_e32 vcc, v0, v1
	s_orn2_b64 s[34:35], vcc, exec
	s_branch .LBB0_75
.LBB0_82:
	s_or_b64 exec, exec, s[26:27]
	s_xor_b64 s[26:27], s[28:29], -1
	s_and_saveexec_b64 s[28:29], s[26:27]
	s_xor_b64 s[28:29], exec, s[28:29]
	s_cbranch_execz .LBB0_84
	v_readlane_b32 s8, v252, 42
	v_readlane_b32 s9, v252, 43
	v_mov_b32_e32 v2, 1
	s_nop 0
	v_mov_b64_e32 v[0:1], s[8:9]
	global_atomic_add v[0:1], v2, off

.LBB0_85:
	s_andn2_saveexec_b64 s[22:23], s[22:23]
	s_cbranch_execz .LBB0_101
	v_readlane_b32 s8, v253, 30
	v_readlane_b32 s9, v253, 31
	buffer_wbl2 sc1
	s_waitcnt vmcnt(0)
	v_mov_b32_e32 v1, 1
	v_mov_b64_e32 v[2:3], s[8:9]
	global_atomic_add v1, v[2:3], v1, off sc0
	v_cvt_f32_u32_e32 v2, v0
	v_sub_u32_e32 v3, 0, v0
	v_readlane_b32 s8, v253, 32
	v_readlane_b32 s9, v253, 33
	v_rcp_iflag_f32_e32 v2, v2
	s_mov_b64 s[24:25], -1
	v_mul_f32_e32 v2, 0x4f7ffffe, v2
	v_cvt_u32_f32_e32 v2, v2
	v_mul_lo_u32 v3, v3, v2
	v_mul_hi_u32 v3, v2, v3
	v_add_u32_e32 v2, v2, v3
	s_waitcnt vmcnt(0) lgkmcnt(0)
	v_mul_hi_u32 v2, v1, v2
	v_mul_lo_u32 v4, v2, v0
	v_add_u32_e32 v3, 1, v1
	v_sub_u32_e32 v1, v1, v4
	v_add_u32_e32 v5, 1, v2
	v_cmp_ge_u32_e32 vcc, v1, v0
	v_sub_u32_e32 v4, v1, v0
	s_nop 0
	v_cndmask_b32_e32 v2, v2, v5, vcc
	v_cndmask_b32_e32 v1, v1, v4, vcc
	v_add_u32_e32 v4, 1, v2
	v_cmp_ge_u32_e32 vcc, v1, v0
	s_nop 1
	v_cndmask_b32_e32 v2, v2, v4, vcc
	v_mad_u64_u32 v[0:1], s[22:23], v0, v2, v[0:1]
	v_cmp_ne_u32_e32 vcc, v3, v0
	v_mov_b64_e32 v[0:1], s[8:9]
	s_and_saveexec_b64 s[22:23], vcc
	s_cbranch_execz .LBB0_98
	v_readlane_b32 s8, v253, 32
	v_readlane_b32 s9, v253, 33
	s_mov_b64 s[26:27], 0
	s_nop 0
	v_mov_b64_e32 v[0:1], s[8:9]
	global_load_dword v0, v[0:1], off sc1
	s_waitcnt vmcnt(0) lgkmcnt(0)
	v_cmp_eq_u32_e32 vcc, v0, v2
	s_and_saveexec_b64 s[24:25], vcc
	s_cbranch_execz .LBB0_97
	s_mov_b32 s3, 1
	s_branch .LBB0_90

.LBB0_92:
	v_readlane_b32 s8, v252, 42
	v_readlane_b32 s9, v252, 43
	s_mov_b64 s[34:35], 0
	s_mov_b64 s[30:31], -1
	v_mov_b64_e32 v[0:1], s[8:9]
	global_load_dword v0, v[0:1], off sc1
	s_waitcnt vmcnt(0) lgkmcnt(0)
	v_cmp_eq_u32_e32 vcc, 0, v0
	s_and_saveexec_b64 s[36:37], vcc
	s_cmp_lt_u32 s3, 0x400001
	s_cselect_b64 s[34:35], -1, 0
	s_xor_b64 s[30:31], exec, -1
	s_and_b64 s[34:35], s[34:35], exec
	s_or_b64 exec, exec, s[36:37]
	s_mov_b64 s[36:37], -1
	s_and_saveexec_b64 s[38:39], s[34:35]
	s_cbranch_execz .LBB0_89
.LBB0_95:
	v_readlane_b32 s8, v253, 32
	v_readlane_b32 s9, v253, 33
	s_add_i32 s3, s3, 1
	s_or_b64 s[30:31], s[30:31], exec
	v_mov_b64_e32 v[0:1], s[8:9]
	global_load_dword v0, v[0:1], off sc1
	s_waitcnt vmcnt(0) lgkmcnt(0)
	v_cmp_ne_u32_e32 vcc, v0, v2
	s_orn2_b64 s[36:37], vcc, exec
	s_branch .LBB0_89

.LBB0_98:
	s_or_b64 exec, exec, s[22:23]
	s_and_saveexec_b64 s[22:23], s[24:25]
	s_cbranch_execz .LBB0_100
	v_mov_b32_e32 v2, 1
	global_atomic_add v[0:1], v2, off
.LBB0_100:
	s_or_b64 exec, exec, s[22:23]
	v_readlane_b32 s8, v253, 28
	v_readlane_b32 s9, v253, 29
	v_mov_b32_e32 v2, 1
	s_waitcnt vmcnt(0) lgkmcnt(0)
	buffer_inv sc1
	v_mov_b64_e32 v[0:1], s[8:9]
	global_atomic_add v[0:1], v2, off
	s_waitcnt vmcnt(0)

.LBB0_102:
	s_or_b64 exec, exec, s[34:35]
	v_readlane_b32 s8, v253, 28
	v_readlane_b32 s9, v253, 29
	s_waitcnt vmcnt(0) lgkmcnt(0)
	buffer_inv sc1
	v_mov_b64_e32 v[0:1], s[8:9]
	global_atomic_add v[0:1], v230, off
	s_waitcnt vmcnt(0)

.LBB0_112:
	v_lshl_add_u64 v[24:25], s[38:39], 0, v[176:177]
	v_add_co_u32_e32 v24, vcc, 0x4000000, v24
	s_mul_i32 s0, s22, 0x9000
	s_nop 0
	v_addc_co_u32_e32 v25, vcc, 0, v25, vcc
	global_load_dwordx2 v[36:37], v[24:25], off offset:1536
	global_load_dwordx2 v[38:39], v[24:25], off offset:1024
	global_load_dwordx2 v[40:41], v[24:25], off offset:512
	global_load_dwordx2 v[42:43], v[24:25], off
	v_readlane_b32 s7, v255, 34
	s_mul_hi_i32 s1, s22, 0x9000
	s_add_u32 s0, s7, s0
	v_readlane_b32 s7, v255, 35
	s_addc_u32 s1, s7, s1
	s_add_u32 s40, s0, 0x1000
	s_addc_u32 s41, s1, 0
	global_load_dwordx4 v[24:27], v[0:1], off
	v_lshl_add_u64 v[28:29], s[40:41], 0, v[8:9]
	v_lshl_add_u64 v[44:45], s[0:1], 0, v[8:9]
	global_load_dwordx4 v[28:31], v[28:29], off
	s_nop 0
	global_load_dwordx4 v[32:35], v[44:45], off
	s_mov_b32 s0, 0x4b00000
	s_waitcnt vmcnt(0)
	v_cvt_f32_f16_e32 v46, v37
	v_cvt_f32_f16_sdwa v47, v37 dst_sel:DWORD dst_unused:UNUSED_PAD src0_sel:WORD_1
	v_cvt_f32_f16_e32 v48, v36
	v_cvt_f32_f16_sdwa v49, v36 dst_sel:DWORD dst_unused:UNUSED_PAD src0_sel:WORD_1
	v_cvt_f32_f16_e32 v36, v39
	v_cvt_f32_f16_sdwa v37, v39 dst_sel:DWORD dst_unused:UNUSED_PAD src0_sel:WORD_1
	v_cvt_f32_f16_e32 v50, v38
	v_cvt_f32_f16_sdwa v51, v38 dst_sel:DWORD dst_unused:UNUSED_PAD src0_sel:WORD_1
	v_cvt_f32_f16_e32 v38, v41
	v_cvt_f32_f16_sdwa v39, v41 dst_sel:DWORD dst_unused:UNUSED_PAD src0_sel:WORD_1
	v_cvt_f32_f16_sdwa v53, v40 dst_sel:DWORD dst_unused:UNUSED_PAD src0_sel:WORD_1
	v_cvt_f32_f16_sdwa v41, v42 dst_sel:DWORD dst_unused:UNUSED_PAD src0_sel:WORD_1
	v_cvt_f32_f16_sdwa v55, v43 dst_sel:DWORD dst_unused:UNUSED_PAD src0_sel:WORD_1
	v_cvt_f32_f16_e32 v52, v40
	v_cvt_f32_f16_e32 v40, v42
	v_cvt_f32_f16_e32 v54, v43
	v_mov_b32_e32 v56, v41
	v_mov_b32_e32 v57, v55
	v_mov_b32_e32 v60, v53
	v_mov_b32_e32 v61, v39
	v_mov_b32_e32 v42, v40
	v_mov_b32_e32 v43, v54
	v_mov_b32_e32 v58, v52
	v_mov_b32_e32 v59, v38
	v_pk_mul_f32 v[56:57], v[56:57], v[56:57]
	v_pk_mul_f32 v[60:61], v[60:61], v[60:61]
	v_mul_f32_e32 v62, v51, v51
	v_mul_f32_e32 v64, v37, v37
	v_pk_fma_f32 v[42:43], v[42:43], v[42:43], v[56:57]
	v_pk_fma_f32 v[56:57], v[58:59], v[58:59], v[60:61]
	v_pk_mul_f32 v[66:67], v[48:49], v[48:49]
	v_pk_mul_f32 v[68:69], v[46:47], v[46:47]
	v_pk_fma_f32 v[62:63], v[50:51], v[50:51], v[62:63] op_sel_hi:[1,1,0]
	v_pk_fma_f32 v[64:65], v[36:37], v[36:37], v[64:65] op_sel_hi:[1,1,0]
	v_pk_add_f32 v[42:43], v[42:43], v[42:43] op_sel:[0,1] op_sel_hi:[1,0]
	v_pk_add_f32 v[56:57], v[56:57], v[56:57] op_sel:[0,1] op_sel_hi:[1,0]
	v_mov_b32_e32 v63, v68
	v_mov_b32_e32 v65, v69
	v_mov_b32_e32 v43, v66
	v_mov_b32_e32 v57, v67
	v_pk_add_f32 v[58:59], v[62:63], v[64:65]
	v_pk_add_f32 v[42:43], v[42:43], v[56:57]
	s_waitcnt lgkmcnt(0)
	v_pk_add_f32 v[30:31], v[30:31], 1.0 op_sel_hi:[1,0]
	v_pk_add_f32 v[42:43], v[42:43], v[58:59]
	v_pk_add_f32 v[28:29], v[28:29], 1.0 op_sel_hi:[1,0]
	v_add_f32_e32 v23, v42, v43
	ds_bpermute_b32 v42, v17, v23
	s_waitcnt lgkmcnt(0)
	v_add_f32_e32 v23, v23, v42
	ds_bpermute_b32 v42, v18, v23
	s_waitcnt lgkmcnt(0)
	v_add_f32_e32 v23, v23, v42
	ds_bpermute_b32 v42, v19, v23
	s_waitcnt lgkmcnt(0)
	v_add_f32_e32 v23, v23, v42
	ds_bpermute_b32 v42, v20, v23
	s_waitcnt lgkmcnt(0)
	v_add_f32_e32 v23, v23, v42
	ds_bpermute_b32 v42, v21, v23
	s_waitcnt lgkmcnt(0)
	v_add_f32_e32 v23, v23, v42
	ds_bpermute_b32 v56, v22, v23
	v_lshl_add_u64 v[42:43], s[36:37], 0, v[176:177]
	v_add_co_u32_e64 v42, s[0:1], s0, v42
	s_waitcnt lgkmcnt(0)
	v_add_f32_e32 v23, v23, v56
	v_fmamk_f32 v23, v23, 0x3a800000, v228
	v_mul_f32_e32 v56, 0x4f800000, v23
	v_cmp_gt_f32_e32 vcc, s89, v23
	v_addc_co_u32_e64 v43, s[0:1], 0, v43, s[0:1]
	s_nop 0
	v_cndmask_b32_e32 v23, v23, v56, vcc
	v_sqrt_f32_e32 v56, v23
	s_nop 0
	v_add_u32_e32 v57, -1, v56
	v_add_u32_e32 v58, 1, v56
	v_fma_f32 v59, -v57, v56, v23
	v_fma_f32 v60, -v58, v56, v23
	v_cmp_ge_f32_e64 s[0:1], 0, v59
	s_nop 1
	v_cndmask_b32_e64 v56, v56, v57, s[0:1]
	v_cmp_lt_f32_e64 s[0:1], 0, v60
	s_nop 1
	v_cndmask_b32_e64 v56, v56, v58, s[0:1]
	v_mul_f32_e32 v57, 0x37800000, v56
	v_cndmask_b32_e32 v56, v56, v57, vcc
	v_cmp_class_f32_e32 vcc, v23, v229
	s_nop 1
	v_cndmask_b32_e32 v23, v56, v23, vcc
	v_div_scale_f32 v56, s[0:1], v23, v23, 1.0
	v_rcp_f32_e32 v57, v56
	v_div_scale_f32 v58, vcc, 1.0, v23, 1.0
	v_readlane_b32 s0, v255, 1
	v_fma_f32 v59, -v56, v57, 1.0
	v_fmac_f32_e32 v57, v59, v57
	v_mul_f32_e32 v59, v58, v57
	v_fma_f32 v60, -v56, v59, v58
	v_fmac_f32_e32 v59, v60, v57
	v_fma_f32 v56, -v56, v59, v58
	v_div_fmas_f32 v56, v56, v57, v59
	v_div_fixup_f32 v56, v56, v23, 1.0
	v_pk_mul_f32 v[54:55], v[54:55], v[56:57] op_sel_hi:[1,0]
	v_pk_mul_f32 v[40:41], v[40:41], v[56:57] op_sel_hi:[1,0]
	v_pk_mul_f32 v[26:27], v[26:27], v[54:55]
	v_pk_mul_f32 v[24:25], v[24:25], v[40:41]
	v_pk_fma_f32 v[26:27], v[30:31], v[26:27], v[34:35]
	v_pk_fma_f32 v[24:25], v[28:29], v[24:25], v[32:33]
	v_lshl_add_u64 v[28:29], s[40:41], 0, v[10:11]
	v_cvt_pk_bf16_f32 v24, v24, v25
	v_cvt_pk_bf16_f32 v25, v26, v27
	global_store_dwordx2 v[42:43], v[24:25], off
	global_load_dwordx4 v[24:27], v[2:3], off
	s_nop 0
	global_load_dwordx4 v[28:31], v[28:29], off
	s_nop 0
	global_load_dwordx4 v[32:35], v[44:45], off offset:1024
	v_pk_mul_f32 v[38:39], v[38:39], v[56:57] op_sel_hi:[1,0]
	v_pk_mul_f32 v[40:41], v[52:53], v[56:57] op_sel_hi:[1,0]
	v_pk_mul_f32 v[36:37], v[36:37], v[56:57] op_sel_hi:[1,0]
	s_add_i32 s3, s3, s0
	s_add_u32 s38, s38, s12
	s_addc_u32 s39, s39, s13
	s_add_u32 s36, s36, s12
	s_addc_u32 s37, s37, s13
	s_cmpk_gt_i32 s3, 0x7fff
	v_readlane_b32 s1, v255, 2
	s_waitcnt vmcnt(0) lgkmcnt(0)
	v_pk_add_f32 v[30:31], v[30:31], 1.0 op_sel_hi:[1,0]
	v_pk_mul_f32 v[24:25], v[24:25], v[40:41]
	v_pk_mul_f32 v[26:27], v[26:27], v[38:39]
	v_pk_add_f32 v[28:29], v[28:29], 1.0 op_sel_hi:[1,0]
	v_pk_fma_f32 v[26:27], v[30:31], v[26:27], v[34:35]
	v_pk_fma_f32 v[24:25], v[28:29], v[24:25], v[32:33]
	v_lshl_add_u64 v[28:29], s[40:41], 0, v[12:13]
	v_cvt_pk_bf16_f32 v24, v24, v25
	v_cvt_pk_bf16_f32 v25, v26, v27
	global_store_dwordx2 v[42:43], v[24:25], off offset:512
	global_load_dwordx4 v[24:27], v[4:5], off
	s_nop 0
	global_load_dwordx4 v[28:31], v[28:29], off
	s_nop 0
	global_load_dwordx4 v[32:35], v[44:45], off offset:2048
	v_pk_mul_f32 v[38:39], v[50:51], v[56:57] op_sel_hi:[1,0]
	s_waitcnt vmcnt(0) lgkmcnt(0)
	v_pk_add_f32 v[30:31], v[30:31], 1.0 op_sel_hi:[1,0]
	v_pk_mul_f32 v[24:25], v[24:25], v[38:39]
	v_pk_mul_f32 v[26:27], v[26:27], v[36:37]
	v_pk_add_f32 v[28:29], v[28:29], 1.0 op_sel_hi:[1,0]
	v_pk_fma_f32 v[26:27], v[30:31], v[26:27], v[34:35]
	v_pk_fma_f32 v[24:25], v[28:29], v[24:25], v[32:33]
	v_lshl_add_u64 v[28:29], s[40:41], 0, v[14:15]
	v_cvt_pk_bf16_f32 v24, v24, v25
	v_cvt_pk_bf16_f32 v25, v26, v27
	global_store_dwordx2 v[42:43], v[24:25], off offset:1024
	global_load_dwordx4 v[24:27], v[6:7], off
	s_nop 0
	global_load_dwordx4 v[28:31], v[28:29], off
	s_nop 0
	global_load_dwordx4 v[32:35], v[44:45], off offset:3072
	v_pk_mul_f32 v[36:37], v[46:47], v[56:57] op_sel_hi:[1,0]
	v_pk_mul_f32 v[38:39], v[48:49], v[56:57] op_sel_hi:[1,0]
	s_waitcnt vmcnt(0) lgkmcnt(0)
	v_pk_add_f32 v[30:31], v[30:31], 1.0 op_sel_hi:[1,0]
	v_pk_mul_f32 v[24:25], v[24:25], v[38:39]
	v_pk_mul_f32 v[26:27], v[26:27], v[36:37]
	v_pk_add_f32 v[28:29], v[28:29], 1.0 op_sel_hi:[1,0]
	v_pk_fma_f32 v[26:27], v[30:31], v[26:27], v[34:35]
	v_pk_fma_f32 v[24:25], v[28:29], v[24:25], v[32:33]
	s_nop 0
	v_cvt_pk_bf16_f32 v24, v24, v25
	v_cvt_pk_bf16_f32 v25, v26, v27
	global_store_dwordx2 v[42:43], v[24:25], off offset:1536
	s_cbranch_scc1 .LBB0_117

.LBB0_120:
	v_readlane_b32 s8, v254, 38
	v_readlane_b32 s9, v254, 39
	s_andn2_b64 vcc, exec, s[8:9]
	s_mov_b32 s7, 0x4b00000
	s_cbranch_vccnz .LBB0_123
	s_mul_hi_i32 s1, s0, 0x9000
	s_mul_i32 s0, s0, 0x9000
	v_readlane_b32 s3, v255, 34
	s_add_u32 s0, s3, s0
	v_readlane_b32 s3, v255, 35
	s_addc_u32 s1, s3, s1
	s_add_u32 s36, s0, 0x1000
	s_addc_u32 s37, s1, 0
	v_lshlrev_b32_e32 v176, 4, v16
	v_lshl_add_u64 v[0:1], s[36:37], 0, v[176:177]
	global_load_dwordx4 v[20:23], v[0:1], off
	v_or_b32_e32 v0, 0x400, v176
	v_mov_b32_e32 v1, v177
	v_lshl_add_u64 v[2:3], s[36:37], 0, v[0:1]
	global_load_dwordx4 v[24:27], v[2:3], off
	v_or_b32_e32 v2, 0x800, v176
	v_mov_b32_e32 v3, v177
	v_readlane_b32 s8, v253, 46
	v_lshl_add_u64 v[4:5], s[36:37], 0, v[2:3]
	v_readlane_b32 s9, v253, 47
	global_load_dwordx4 v[28:31], v[4:5], off
	v_lshl_add_u64 v[12:13], s[0:1], 0, v[176:177]
	v_readlane_b32 s0, v255, 6
	v_readlane_b32 s1, v255, 7
	v_lshlrev_b32_e32 v17, 2, v16
	global_load_dwordx4 v[32:35], v176, s[8:9]
	global_load_dwordx4 v[36:39], v0, s[8:9]
	global_load_dwordx4 v[40:43], v2, s[8:9]
	v_or_b32_e32 v176, 0xc00, v176
	v_lshl_add_u64 v[0:1], s[36:37], 0, v[176:177]
	global_load_dwordx4 v[44:47], v[0:1], off
	s_nop 0
	global_load_dwordx4 v[0:3], v[12:13], off
	global_load_dwordx4 v[48:51], v176, s[8:9]
	global_load_dwordx4 v[4:7], v[12:13], off offset:1024
	global_load_dwordx4 v[8:11], v[12:13], off offset:2048
	s_nop 0
	global_load_dwordx4 v[12:15], v[12:13], off offset:3072
	s_add_u32 s36, s34, s0
	v_lshlrev_b32_e32 v176, 3, v16
	s_addc_u32 s37, s35, s1
	v_lshl_add_u64 v[18:19], s[34:35], 0, v[176:177]
	s_mov_b64 s[0:1], 0x4b00000
	v_readlane_b32 s40, v254, 58
	s_mov_b32 s22, 0
	v_xor_b32_e32 v101, 4, v17
	v_xor_b32_e32 v102, 8, v17
	v_xor_b32_e32 v103, 16, v17
	v_xor_b32_e32 v104, 32, v17
	v_xor_b32_e32 v105, 64, v17
	v_xor_b32_e32 v106, 0x80, v17
	v_lshl_add_u64 v[16:17], s[30:31], 0, v[176:177]
	v_lshl_add_u64 v[18:19], v[18:19], 0, s[0:1]
	v_readlane_b32 s41, v254, 59
	s_waitcnt vmcnt(0) lgkmcnt(0)
	v_pk_add_f32 v[22:23], v[22:23], 1.0 op_sel_hi:[1,0]
	v_pk_add_f32 v[52:53], v[20:21], 1.0 op_sel_hi:[1,0]
	v_pk_add_f32 v[26:27], v[26:27], 1.0 op_sel_hi:[1,0]
	v_pk_add_f32 v[54:55], v[24:25], 1.0 op_sel_hi:[1,0]
	v_pk_add_f32 v[30:31], v[30:31], 1.0 op_sel_hi:[1,0]
	v_pk_add_f32 v[56:57], v[28:29], 1.0 op_sel_hi:[1,0]
	v_pk_mul_f32 v[20:21], v[34:35], v[22:23]
	v_pk_mul_f32 v[22:23], v[32:33], v[52:53]
	v_pk_add_f32 v[32:33], v[46:47], 1.0 op_sel_hi:[1,0]
	v_pk_add_f32 v[34:35], v[44:45], 1.0 op_sel_hi:[1,0]
	v_pk_mul_f32 v[24:25], v[38:39], v[26:27]
	v_pk_mul_f32 v[26:27], v[36:37], v[54:55]
	v_pk_mul_f32 v[28:29], v[42:43], v[30:31]
	v_pk_mul_f32 v[30:31], v[40:41], v[56:57]
	v_pk_mul_f32 v[32:33], v[50:51], v[32:33]
	v_pk_mul_f32 v[34:35], v[48:49], v[34:35]
.LBB0_122:
	v_lshl_add_u64 v[36:37], s[40:41], 0, v[176:177]
	v_add_co_u32_e32 v36, vcc, 0x4000000, v36
	s_add_i32 s3, s72, s22
	s_nop 0
	v_addc_co_u32_e32 v37, vcc, 0, v37, vcc
	global_load_dwordx2 v[38:39], v[36:37], off
	s_add_i32 s0, s3, 1
	s_ashr_i32 s1, s0, 31
	s_lshl_b64 s[42:43], s[0:1], 11
	s_add_i32 s0, s3, 2
	s_ashr_i32 s1, s0, 31
	s_lshl_b64 s[38:39], s[0:1], 11
	s_add_i32 s0, s3, 3
	s_ashr_i32 s1, s0, 31
	s_lshl_b64 s[34:35], s[0:1], 11
	s_add_i32 s22, s22, 4
	s_add_u32 s40, s40, 0x2000
	s_addc_u32 s41, s41, 0
	s_waitcnt vmcnt(0)
	v_cvt_f32_f16_e32 v80, v38
	v_cvt_f32_f16_sdwa v81, v38 dst_sel:DWORD dst_unused:UNUSED_PAD src0_sel:WORD_1
	v_cvt_f32_f16_e32 v82, v39
	v_cvt_f32_f16_sdwa v83, v39 dst_sel:DWORD dst_unused:UNUSED_PAD src0_sel:WORD_1
	global_load_dwordx2 v[38:39], v[36:37], off offset:512
	v_mov_b32_e32 v110, v81
	v_mov_b32_e32 v108, v80
	v_mov_b32_e32 v111, v83
	v_mov_b32_e32 v109, v82
	v_pk_mul_f32 v[110:111], v[110:111], v[110:111]
	s_waitcnt vmcnt(0)
	v_cvt_f32_f16_e32 v76, v38
	v_cvt_f32_f16_sdwa v77, v38 dst_sel:DWORD dst_unused:UNUSED_PAD src0_sel:WORD_1
	v_cvt_f32_f16_e32 v78, v39
	v_cvt_f32_f16_sdwa v79, v39 dst_sel:DWORD dst_unused:UNUSED_PAD src0_sel:WORD_1
	global_load_dwordx2 v[38:39], v[36:37], off offset:1024
	v_mov_b32_e32 v112, v77
	global_load_dwordx2 v[36:37], v[36:37], off offset:1536
	v_mov_b32_e32 v113, v79
	v_pk_fma_f32 v[108:109], v[108:109], v[108:109], v[110:111]
	v_mov_b32_e32 v110, v76
	v_mov_b32_e32 v111, v78
	v_pk_mul_f32 v[112:113], v[112:113], v[112:113]
	v_pk_add_f32 v[108:109], v[108:109], v[108:109] op_sel:[0,1] op_sel_hi:[1,0]
	v_pk_fma_f32 v[110:111], v[110:111], v[110:111], v[112:113]
	s_waitcnt vmcnt(0)
	v_cvt_f32_f16_e32 v72, v38
	v_cvt_f32_f16_sdwa v73, v38 dst_sel:DWORD dst_unused:UNUSED_PAD src0_sel:WORD_1
	s_waitcnt vmcnt(0)
	v_cvt_f32_f16_e32 v68, v36
	v_cvt_f32_f16_sdwa v69, v36 dst_sel:DWORD dst_unused:UNUSED_PAD src0_sel:WORD_1
	v_cvt_f32_f16_e32 v70, v37
	v_cvt_f32_f16_sdwa v71, v37 dst_sel:DWORD dst_unused:UNUSED_PAD src0_sel:WORD_1
	v_lshl_add_u64 v[36:37], v[16:17], 0, s[42:43]
	v_cvt_f32_f16_e32 v74, v39
	v_cvt_f32_f16_sdwa v75, v39 dst_sel:DWORD dst_unused:UNUSED_PAD src0_sel:WORD_1
	global_load_dwordx2 v[38:39], v[36:37], off
	v_mul_f32_e32 v100, v73, v73
	v_pk_fma_f32 v[112:113], v[72:73], v[72:73], v[100:101] op_sel_hi:[1,1,0]
	v_mul_f32_e32 v100, v75, v75
	v_pk_add_f32 v[110:111], v[110:111], v[110:111] op_sel:[0,1] op_sel_hi:[1,0]
	v_pk_fma_f32 v[114:115], v[74:75], v[74:75], v[100:101] op_sel_hi:[1,1,0]
	v_pk_mul_f32 v[116:117], v[68:69], v[68:69]
	v_pk_mul_f32 v[118:119], v[70:71], v[70:71]
	v_mov_b32_e32 v109, v116
	v_mov_b32_e32 v111, v117
	v_mov_b32_e32 v113, v118
	v_mov_b32_e32 v115, v119
	v_pk_add_f32 v[108:109], v[108:109], v[110:111]
	v_pk_add_f32 v[110:111], v[112:113], v[114:115]
	s_waitcnt vmcnt(0)
	v_cvt_f32_f16_e32 v96, v38
	v_cvt_f32_f16_sdwa v97, v38 dst_sel:DWORD dst_unused:UNUSED_PAD src0_sel:WORD_1
	v_cvt_f32_f16_e32 v98, v39
	v_cvt_f32_f16_sdwa v99, v39 dst_sel:DWORD dst_unused:UNUSED_PAD src0_sel:WORD_1
	global_load_dwordx2 v[38:39], v[36:37], off offset:512
	v_pk_add_f32 v[108:109], v[108:109], v[110:111]
	s_waitcnt vmcnt(0)
	v_cvt_f32_f16_e32 v92, v38
	v_cvt_f32_f16_sdwa v93, v38 dst_sel:DWORD dst_unused:UNUSED_PAD src0_sel:WORD_1
	v_cvt_f32_f16_e32 v94, v39
	v_cvt_f32_f16_sdwa v95, v39 dst_sel:DWORD dst_unused:UNUSED_PAD src0_sel:WORD_1
	global_load_dwordx2 v[38:39], v[36:37], off offset:1024
	v_add_f32_e32 v100, v108, v109
	global_load_dwordx2 v[36:37], v[36:37], off offset:1536
	ds_bpermute_b32 v107, v101, v100
	s_waitcnt lgkmcnt(0)
	v_add_f32_e32 v100, v100, v107
	ds_bpermute_b32 v107, v102, v100
	s_waitcnt lgkmcnt(0)
	v_add_f32_e32 v100, v100, v107
	ds_bpermute_b32 v107, v103, v100
	s_waitcnt lgkmcnt(0)
	v_add_f32_e32 v100, v100, v107
	ds_bpermute_b32 v107, v104, v100
	s_waitcnt lgkmcnt(0)
	v_add_f32_e32 v100, v100, v107
	ds_bpermute_b32 v107, v105, v100
	s_waitcnt lgkmcnt(0)
	v_add_f32_e32 v100, v100, v107
	ds_bpermute_b32 v107, v106, v100
	s_waitcnt lgkmcnt(0)
	v_add_f32_e32 v100, v100, v107
	v_fmamk_f32 v100, v100, 0x3a800000, v228
	v_cmp_gt_f32_e32 vcc, s89, v100
	v_mul_f32_e32 v107, 0x4f800000, v100
	s_waitcnt vmcnt(1)
	v_cvt_f32_f16_e32 v88, v38
	v_cvt_f32_f16_sdwa v89, v38 dst_sel:DWORD dst_unused:UNUSED_PAD src0_sel:WORD_1
	s_waitcnt vmcnt(0)
	v_cvt_f32_f16_e32 v84, v36
	v_cvt_f32_f16_sdwa v85, v36 dst_sel:DWORD dst_unused:UNUSED_PAD src0_sel:WORD_1
	v_cvt_f32_f16_e32 v86, v37
	v_cvt_f32_f16_sdwa v87, v37 dst_sel:DWORD dst_unused:UNUSED_PAD src0_sel:WORD_1
	v_lshl_add_u64 v[36:37], v[16:17], 0, s[38:39]
	v_cvt_f32_f16_e32 v90, v39
	v_cvt_f32_f16_sdwa v91, v39 dst_sel:DWORD dst_unused:UNUSED_PAD src0_sel:WORD_1
	global_load_dwordx2 v[38:39], v[36:37], off
	v_cndmask_b32_e32 v100, v100, v107, vcc
	v_sqrt_f32_e32 v107, v100
	s_waitcnt vmcnt(0)
	v_cvt_f32_f16_e32 v64, v38
	v_cvt_f32_f16_sdwa v65, v38 dst_sel:DWORD dst_unused:UNUSED_PAD src0_sel:WORD_1
	v_cvt_f32_f16_e32 v66, v39
	v_cvt_f32_f16_sdwa v67, v39 dst_sel:DWORD dst_unused:UNUSED_PAD src0_sel:WORD_1
	global_load_dwordx2 v[38:39], v[36:37], off offset:512
	v_add_u32_e32 v108, -1, v107
	v_fma_f32 v109, -v108, v107, v100
	v_cmp_ge_f32_e64 s[0:1], 0, v109
	v_add_u32_e32 v109, 1, v107
	s_waitcnt vmcnt(0)
	v_cvt_f32_f16_e32 v60, v38
	v_cvt_f32_f16_sdwa v61, v38 dst_sel:DWORD dst_unused:UNUSED_PAD src0_sel:WORD_1
	v_cvt_f32_f16_e32 v62, v39
	v_cvt_f32_f16_sdwa v63, v39 dst_sel:DWORD dst_unused:UNUSED_PAD src0_sel:WORD_1
	global_load_dwordx2 v[38:39], v[36:37], off offset:1024
	v_cndmask_b32_e64 v108, v107, v108, s[0:1]
	global_load_dwordx2 v[36:37], v[36:37], off offset:1536
	v_fma_f32 v107, -v109, v107, v100
	v_cmp_lt_f32_e64 s[0:1], 0, v107
	s_waitcnt vmcnt(1)
	v_cvt_f32_f16_e32 v56, v38
	v_cvt_f32_f16_sdwa v57, v38 dst_sel:DWORD dst_unused:UNUSED_PAD src0_sel:WORD_1
	s_waitcnt vmcnt(0)
	v_cvt_f32_f16_e32 v52, v36
	v_cvt_f32_f16_sdwa v53, v36 dst_sel:DWORD dst_unused:UNUSED_PAD src0_sel:WORD_1
	v_cvt_f32_f16_e32 v54, v37
	v_cvt_f32_f16_sdwa v55, v37 dst_sel:DWORD dst_unused:UNUSED_PAD src0_sel:WORD_1
	v_lshl_add_u64 v[36:37], v[16:17], 0, s[34:35]
	v_cvt_f32_f16_e32 v58, v39
	v_cvt_f32_f16_sdwa v59, v39 dst_sel:DWORD dst_unused:UNUSED_PAD src0_sel:WORD_1
	global_load_dwordx2 v[38:39], v[36:37], off
	v_cndmask_b32_e64 v107, v108, v109, s[0:1]
	v_mul_f32_e32 v108, 0x37800000, v107
	v_cndmask_b32_e32 v107, v107, v108, vcc
	v_cmp_class_f32_e32 vcc, v100, v229
	s_waitcnt vmcnt(0)
	v_cvt_f32_f16_e32 v48, v38
	v_cvt_f32_f16_sdwa v49, v38 dst_sel:DWORD dst_unused:UNUSED_PAD src0_sel:WORD_1
	v_cvt_f32_f16_e32 v50, v39
	v_cvt_f32_f16_sdwa v51, v39 dst_sel:DWORD dst_unused:UNUSED_PAD src0_sel:WORD_1
	global_load_dwordx2 v[38:39], v[36:37], off offset:512
	v_cndmask_b32_e32 v100, v107, v100, vcc
	v_div_scale_f32 v107, s[0:1], v100, v100, 1.0
	v_rcp_f32_e32 v108, v107
	s_waitcnt vmcnt(0)
	v_cvt_f32_f16_e32 v44, v38
	v_cvt_f32_f16_sdwa v45, v38 dst_sel:DWORD dst_unused:UNUSED_PAD src0_sel:WORD_1
	v_cvt_f32_f16_e32 v46, v39
	v_cvt_f32_f16_sdwa v47, v39 dst_sel:DWORD dst_unused:UNUSED_PAD src0_sel:WORD_1
	global_load_dwordx2 v[38:39], v[36:37], off offset:1024
	v_fma_f32 v109, -v107, v108, 1.0
	v_fmac_f32_e32 v108, v109, v108
	v_div_scale_f32 v109, vcc, 1.0, v100, 1.0
	v_mul_f32_e32 v110, v109, v108
	v_fma_f32 v111, -v107, v110, v109
	v_fmac_f32_e32 v110, v111, v108
	v_fma_f32 v107, -v107, v110, v109
	v_div_fmas_f32 v107, v107, v108, v110
	v_div_fixup_f32 v100, v107, v100, 1.0
	v_pk_mul_f32 v[80:81], v[80:81], v[100:101] op_sel_hi:[1,0]
	v_pk_mul_f32 v[82:83], v[82:83], v[100:101] op_sel_hi:[1,0]
	v_lshl_add_u64 v[108:109], s[36:37], 0, v[176:177]
	v_pk_fma_f32 v[82:83], v[20:21], v[82:83], v[2:3]
	v_pk_fma_f32 v[80:81], v[22:23], v[80:81], v[0:1]
	v_pk_mul_f32 v[72:73], v[72:73], v[100:101] op_sel_hi:[1,0]
	v_pk_mul_f32 v[74:75], v[74:75], v[100:101] op_sel_hi:[1,0]
	v_pk_mul_f32 v[68:69], v[68:69], v[100:101] op_sel_hi:[1,0]
	v_pk_mul_f32 v[70:71], v[70:71], v[100:101] op_sel_hi:[1,0]
	v_cvt_pk_bf16_f32 v80, v80, v81
	v_cvt_pk_bf16_f32 v81, v82, v83
	v_add_co_u32_e32 v82, vcc, s7, v108
	v_pk_fma_f32 v[74:75], v[28:29], v[74:75], v[10:11]
	v_pk_fma_f32 v[72:73], v[30:31], v[72:73], v[8:9]
	v_pk_fma_f32 v[70:71], v[32:33], v[70:71], v[14:15]
	v_pk_fma_f32 v[68:69], v[34:35], v[68:69], v[12:13]
	v_addc_co_u32_e32 v83, vcc, 0, v109, vcc
	v_cvt_pk_bf16_f32 v72, v72, v73
	v_cvt_pk_bf16_f32 v73, v74, v75
	v_cvt_pk_bf16_f32 v68, v68, v69
	v_cvt_pk_bf16_f32 v69, v70, v71
	v_mov_b32_e32 v70, v97
	v_mov_b32_e32 v71, v99
	v_pk_mul_f32 v[76:77], v[76:77], v[100:101] op_sel_hi:[1,0]
	v_pk_mul_f32 v[78:79], v[78:79], v[100:101] op_sel_hi:[1,0]
	v_pk_mul_f32 v[70:71], v[70:71], v[70:71]
	v_pk_fma_f32 v[78:79], v[24:25], v[78:79], v[6:7]
	v_pk_fma_f32 v[76:77], v[26:27], v[76:77], v[4:5]
	v_mul_f32_e32 v74, v91, v91
	v_cvt_pk_bf16_f32 v76, v76, v77
	v_cvt_pk_bf16_f32 v77, v78, v79
	v_pk_fma_f32 v[74:75], v[90:91], v[90:91], v[74:75] op_sel_hi:[1,1,0]
	v_pk_mul_f32 v[78:79], v[86:87], v[86:87]
	s_add_u32 s36, s36, 0x2000
	v_mov_b32_e32 v75, v79
	s_addc_u32 s37, s37, 0
	s_cmp_ge_i32 s22, s10
	s_waitcnt vmcnt(0)
	v_cvt_f32_f16_e32 v40, v38
	v_cvt_f32_f16_sdwa v41, v38 dst_sel:DWORD dst_unused:UNUSED_PAD src0_sel:WORD_1
	v_cvt_f32_f16_e32 v42, v39
	v_cvt_f32_f16_sdwa v43, v39 dst_sel:DWORD dst_unused:UNUSED_PAD src0_sel:WORD_1
	global_load_dwordx2 v[38:39], v[36:37], off offset:1536
	s_waitcnt vmcnt(0)
	v_cvt_f32_f16_e32 v36, v38
	global_store_dwordx2 v[82:83], v[72:73], off offset:1024
	global_store_dwordx2 v[82:83], v[68:69], off offset:1536
	v_mov_b32_e32 v68, v96
	v_mov_b32_e32 v69, v98
	v_mov_b32_e32 v72, v93
	v_mov_b32_e32 v73, v95
	v_pk_fma_f32 v[68:69], v[68:69], v[68:69], v[70:71]
	v_mov_b32_e32 v70, v92
	v_mov_b32_e32 v71, v94
	v_pk_mul_f32 v[72:73], v[72:73], v[72:73]
	global_store_dwordx2 v[82:83], v[76:77], off offset:512
	v_pk_fma_f32 v[70:71], v[70:71], v[70:71], v[72:73]
	v_mul_f32_e32 v72, v89, v89
	v_pk_add_f32 v[68:69], v[68:69], v[68:69] op_sel:[0,1] op_sel_hi:[1,0]
	v_pk_add_f32 v[70:71], v[70:71], v[70:71] op_sel:[0,1] op_sel_hi:[1,0]
	v_pk_fma_f32 v[72:73], v[88:89], v[88:89], v[72:73] op_sel_hi:[1,1,0]
	v_pk_mul_f32 v[76:77], v[84:85], v[84:85]
	v_mov_b32_e32 v73, v78
	v_mov_b32_e32 v69, v76
	v_mov_b32_e32 v71, v77
	v_pk_add_f32 v[68:69], v[68:69], v[70:71]
	v_pk_add_f32 v[70:71], v[72:73], v[74:75]
	global_store_dwordx2 v[82:83], v[80:81], off
	v_pk_add_f32 v[68:69], v[68:69], v[70:71]
	v_pk_mul_f32 v[76:77], v[52:53], v[52:53]
	v_add_f32_e32 v68, v68, v69
	ds_bpermute_b32 v69, v101, v68
	v_pk_mul_f32 v[78:79], v[54:55], v[54:55]
	v_cvt_f32_f16_sdwa v37, v38 dst_sel:DWORD dst_unused:UNUSED_PAD src0_sel:WORD_1
	v_cvt_f32_f16_e32 v38, v39
	v_cvt_f32_f16_sdwa v39, v39 dst_sel:DWORD dst_unused:UNUSED_PAD src0_sel:WORD_1
	s_waitcnt lgkmcnt(0)
	v_add_f32_e32 v68, v68, v69
	ds_bpermute_b32 v69, v102, v68
	s_waitcnt lgkmcnt(0)
	v_add_f32_e32 v68, v68, v69
	ds_bpermute_b32 v69, v103, v68
	s_waitcnt lgkmcnt(0)
	v_add_f32_e32 v68, v68, v69
	ds_bpermute_b32 v69, v104, v68
	s_waitcnt lgkmcnt(0)
	v_add_f32_e32 v68, v68, v69
	ds_bpermute_b32 v69, v105, v68
	s_waitcnt lgkmcnt(0)
	v_add_f32_e32 v68, v68, v69
	ds_bpermute_b32 v69, v106, v68
	s_waitcnt lgkmcnt(0)
	v_add_f32_e32 v68, v68, v69
	v_fmamk_f32 v68, v68, 0x3a800000, v228
	v_cmp_gt_f32_e32 vcc, s89, v68
	v_mul_f32_e32 v69, 0x4f800000, v68
	s_nop 0
	v_cndmask_b32_e32 v68, v68, v69, vcc
	v_sqrt_f32_e32 v69, v68
	s_nop 0
	v_add_u32_e32 v70, -1, v69
	v_fma_f32 v71, -v70, v69, v68
	v_cmp_ge_f32_e64 s[0:1], 0, v71
	v_add_u32_e32 v71, 1, v69
	s_nop 0
	v_cndmask_b32_e64 v70, v69, v70, s[0:1]
	v_fma_f32 v69, -v71, v69, v68
	v_cmp_lt_f32_e64 s[0:1], 0, v69
	s_nop 1
	v_cndmask_b32_e64 v69, v70, v71, s[0:1]
	v_mul_f32_e32 v70, 0x37800000, v69
	v_cndmask_b32_e32 v69, v69, v70, vcc
	v_cmp_class_f32_e32 vcc, v68, v229
	s_nop 1
	v_cndmask_b32_e32 v68, v69, v68, vcc
	v_div_scale_f32 v69, s[0:1], v68, v68, 1.0
	v_rcp_f32_e32 v70, v69
	s_nop 0
	v_fma_f32 v71, -v69, v70, 1.0
	v_fmac_f32_e32 v70, v71, v70
	v_div_scale_f32 v71, vcc, 1.0, v68, 1.0
	v_mul_f32_e32 v72, v71, v70
	v_fma_f32 v73, -v69, v72, v71
	v_fmac_f32_e32 v72, v73, v70
	v_fma_f32 v69, -v69, v72, v71
	v_div_fmas_f32 v69, v69, v70, v72
	v_div_fixup_f32 v68, v69, v68, 1.0
	v_pk_mul_f32 v[72:73], v[96:97], v[68:69] op_sel_hi:[1,0]
	v_pk_mul_f32 v[74:75], v[98:99], v[68:69] op_sel_hi:[1,0]
	v_pk_fma_f32 v[72:73], v[22:23], v[72:73], v[0:1]
	v_pk_fma_f32 v[74:75], v[20:21], v[74:75], v[2:3]
	v_lshl_add_u64 v[70:71], v[18:19], 0, s[42:43]
	v_cvt_pk_bf16_f32 v72, v72, v73
	v_cvt_pk_bf16_f32 v73, v74, v75
	global_store_dwordx2 v[70:71], v[72:73], off
	v_pk_mul_f32 v[72:73], v[92:93], v[68:69] op_sel_hi:[1,0]
	v_pk_mul_f32 v[74:75], v[94:95], v[68:69] op_sel_hi:[1,0]
	v_pk_fma_f32 v[72:73], v[26:27], v[72:73], v[4:5]
	v_pk_fma_f32 v[74:75], v[24:25], v[74:75], v[6:7]
	v_cvt_pk_bf16_f32 v72, v72, v73
	v_cvt_pk_bf16_f32 v73, v74, v75
	global_store_dwordx2 v[70:71], v[72:73], off offset:512
	v_pk_mul_f32 v[72:73], v[88:89], v[68:69] op_sel_hi:[1,0]
	v_pk_mul_f32 v[74:75], v[90:91], v[68:69] op_sel_hi:[1,0]
	v_pk_fma_f32 v[72:73], v[30:31], v[72:73], v[8:9]
	v_pk_fma_f32 v[74:75], v[28:29], v[74:75], v[10:11]
	v_cvt_pk_bf16_f32 v72, v72, v73
	v_cvt_pk_bf16_f32 v73, v74, v75
	global_store_dwordx2 v[70:71], v[72:73], off offset:1024
	v_pk_mul_f32 v[72:73], v[84:85], v[68:69] op_sel_hi:[1,0]
	v_pk_mul_f32 v[68:69], v[86:87], v[68:69] op_sel_hi:[1,0]
	v_pk_fma_f32 v[72:73], v[34:35], v[72:73], v[12:13]
	v_pk_fma_f32 v[68:69], v[32:33], v[68:69], v[14:15]
	v_cvt_pk_bf16_f32 v72, v72, v73
	v_cvt_pk_bf16_f32 v73, v68, v69
	global_store_dwordx2 v[70:71], v[72:73], off offset:1536
	v_mov_b32_e32 v70, v65
	v_mov_b32_e32 v71, v67
	v_mov_b32_e32 v68, v64
	v_mov_b32_e32 v69, v66
	v_pk_mul_f32 v[70:71], v[70:71], v[70:71]
	v_mov_b32_e32 v72, v61
	v_mov_b32_e32 v73, v63
	v_pk_fma_f32 v[68:69], v[68:69], v[68:69], v[70:71]
	v_mov_b32_e32 v70, v60
	v_mov_b32_e32 v71, v62
	v_pk_mul_f32 v[72:73], v[72:73], v[72:73]
	v_mul_f32_e32 v74, v59, v59
	v_pk_fma_f32 v[70:71], v[70:71], v[70:71], v[72:73]
	v_mul_f32_e32 v72, v57, v57
	v_pk_add_f32 v[68:69], v[68:69], v[68:69] op_sel:[0,1] op_sel_hi:[1,0]
	v_pk_add_f32 v[70:71], v[70:71], v[70:71] op_sel:[0,1] op_sel_hi:[1,0]
	v_pk_fma_f32 v[72:73], v[56:57], v[56:57], v[72:73] op_sel_hi:[1,1,0]
	v_pk_fma_f32 v[74:75], v[58:59], v[58:59], v[74:75] op_sel_hi:[1,1,0]
	v_mov_b32_e32 v69, v76
	v_mov_b32_e32 v71, v77
	v_mov_b32_e32 v73, v78
	v_mov_b32_e32 v75, v79
	v_pk_add_f32 v[68:69], v[68:69], v[70:71]
	v_pk_add_f32 v[70:71], v[72:73], v[74:75]
	s_nop 0
	v_pk_add_f32 v[68:69], v[68:69], v[70:71]
	s_nop 0
	v_add_f32_e32 v68, v68, v69
	ds_bpermute_b32 v69, v101, v68
	s_waitcnt lgkmcnt(0)
	v_add_f32_e32 v68, v68, v69
	ds_bpermute_b32 v69, v102, v68
	s_waitcnt lgkmcnt(0)
	v_add_f32_e32 v68, v68, v69
	ds_bpermute_b32 v69, v103, v68
	s_waitcnt lgkmcnt(0)
	v_add_f32_e32 v68, v68, v69
	ds_bpermute_b32 v69, v104, v68
	s_waitcnt lgkmcnt(0)
	v_add_f32_e32 v68, v68, v69
	ds_bpermute_b32 v69, v105, v68
	s_waitcnt lgkmcnt(0)
	v_add_f32_e32 v68, v68, v69
	ds_bpermute_b32 v69, v106, v68
	s_waitcnt lgkmcnt(0)
	v_add_f32_e32 v68, v68, v69
	v_fmamk_f32 v68, v68, 0x3a800000, v228
	v_cmp_gt_f32_e32 vcc, s89, v68
	v_mul_f32_e32 v69, 0x4f800000, v68
	s_nop 0
	v_cndmask_b32_e32 v68, v68, v69, vcc
	v_sqrt_f32_e32 v69, v68
	s_nop 0
	v_add_u32_e32 v70, -1, v69
	v_fma_f32 v71, -v70, v69, v68
	v_cmp_ge_f32_e64 s[0:1], 0, v71
	v_add_u32_e32 v71, 1, v69
	s_nop 0
	v_cndmask_b32_e64 v70, v69, v70, s[0:1]
	v_fma_f32 v69, -v71, v69, v68
	v_cmp_lt_f32_e64 s[0:1], 0, v69
	s_nop 1
	v_cndmask_b32_e64 v69, v70, v71, s[0:1]
	v_mul_f32_e32 v70, 0x37800000, v69
	v_cndmask_b32_e32 v69, v69, v70, vcc
	v_cmp_class_f32_e32 vcc, v68, v229
	s_nop 1
	v_cndmask_b32_e32 v68, v69, v68, vcc
	v_div_scale_f32 v69, s[0:1], v68, v68, 1.0
	v_rcp_f32_e32 v70, v69
	s_nop 0
	v_fma_f32 v71, -v69, v70, 1.0
	v_fmac_f32_e32 v70, v71, v70
	v_div_scale_f32 v71, vcc, 1.0, v68, 1.0
	v_mul_f32_e32 v72, v71, v70
	v_fma_f32 v73, -v69, v72, v71
	v_fmac_f32_e32 v72, v73, v70
	v_fma_f32 v69, -v69, v72, v71
	v_div_fmas_f32 v69, v69, v70, v72
	v_div_fixup_f32 v68, v69, v68, 1.0
	v_pk_mul_f32 v[56:57], v[56:57], v[68:69] op_sel_hi:[1,0]
	v_pk_mul_f32 v[58:59], v[58:59], v[68:69] op_sel_hi:[1,0]
	v_pk_mul_f32 v[52:53], v[52:53], v[68:69] op_sel_hi:[1,0]
	v_pk_mul_f32 v[54:55], v[54:55], v[68:69] op_sel_hi:[1,0]
	v_pk_fma_f32 v[58:59], v[28:29], v[58:59], v[10:11]
	v_pk_fma_f32 v[56:57], v[30:31], v[56:57], v[8:9]
	v_pk_fma_f32 v[54:55], v[32:33], v[54:55], v[14:15]
	v_pk_fma_f32 v[52:53], v[34:35], v[52:53], v[12:13]
	v_lshl_add_u64 v[70:71], v[18:19], 0, s[38:39]
	v_cvt_pk_bf16_f32 v56, v56, v57
	v_cvt_pk_bf16_f32 v57, v58, v59
	v_cvt_pk_bf16_f32 v52, v52, v53
	v_cvt_pk_bf16_f32 v53, v54, v55
	v_mov_b32_e32 v54, v49
	v_mov_b32_e32 v55, v51
	v_pk_mul_f32 v[60:61], v[60:61], v[68:69] op_sel_hi:[1,0]
	v_pk_mul_f32 v[62:63], v[62:63], v[68:69] op_sel_hi:[1,0]
	global_store_dwordx2 v[70:71], v[56:57], off offset:1024
	global_store_dwordx2 v[70:71], v[52:53], off offset:1536
	v_mov_b32_e32 v52, v48
	v_mov_b32_e32 v53, v50
	v_pk_mul_f32 v[54:55], v[54:55], v[54:55]
	v_mov_b32_e32 v56, v45
	v_mov_b32_e32 v57, v47
	v_pk_fma_f32 v[62:63], v[24:25], v[62:63], v[6:7]
	v_pk_fma_f32 v[60:61], v[26:27], v[60:61], v[4:5]
	v_pk_fma_f32 v[52:53], v[52:53], v[52:53], v[54:55]
	v_mov_b32_e32 v54, v44
	v_mov_b32_e32 v55, v46
	v_pk_mul_f32 v[56:57], v[56:57], v[56:57]
	v_cvt_pk_bf16_f32 v60, v60, v61
	v_cvt_pk_bf16_f32 v61, v62, v63
	v_pk_fma_f32 v[54:55], v[54:55], v[54:55], v[56:57]
	v_mul_f32_e32 v56, v41, v41
	v_mul_f32_e32 v58, v43, v43
	global_store_dwordx2 v[70:71], v[60:61], off offset:512
	v_pk_add_f32 v[52:53], v[52:53], v[52:53] op_sel:[0,1] op_sel_hi:[1,0]
	v_pk_add_f32 v[54:55], v[54:55], v[54:55] op_sel:[0,1] op_sel_hi:[1,0]
	v_pk_fma_f32 v[56:57], v[40:41], v[40:41], v[56:57] op_sel_hi:[1,1,0]
	v_pk_fma_f32 v[58:59], v[42:43], v[42:43], v[58:59] op_sel_hi:[1,1,0]
	v_pk_mul_f32 v[60:61], v[36:37], v[36:37]
	v_pk_mul_f32 v[62:63], v[38:39], v[38:39]
	v_mov_b32_e32 v53, v60
	v_mov_b32_e32 v55, v61
	v_mov_b32_e32 v57, v62
	v_mov_b32_e32 v59, v63
	v_pk_add_f32 v[52:53], v[52:53], v[54:55]
	v_pk_add_f32 v[54:55], v[56:57], v[58:59]
	v_pk_mul_f32 v[64:65], v[64:65], v[68:69] op_sel_hi:[1,0]
	v_pk_add_f32 v[52:53], v[52:53], v[54:55]
	v_pk_mul_f32 v[66:67], v[66:67], v[68:69] op_sel_hi:[1,0]
	v_add_f32_e32 v52, v52, v53
	ds_bpermute_b32 v53, v101, v52
	v_pk_fma_f32 v[66:67], v[20:21], v[66:67], v[2:3]
	v_pk_fma_f32 v[64:65], v[22:23], v[64:65], v[0:1]
	s_waitcnt lgkmcnt(0)
	v_add_f32_e32 v52, v52, v53
	ds_bpermute_b32 v53, v102, v52
	v_cvt_pk_bf16_f32 v64, v64, v65
	v_cvt_pk_bf16_f32 v65, v66, v67
	global_store_dwordx2 v[70:71], v[64:65], off
	s_waitcnt lgkmcnt(0)
	v_add_f32_e32 v52, v52, v53
	ds_bpermute_b32 v53, v103, v52
	s_waitcnt lgkmcnt(0)
	v_add_f32_e32 v52, v52, v53
	ds_bpermute_b32 v53, v104, v52
	s_waitcnt lgkmcnt(0)
	v_add_f32_e32 v52, v52, v53
	ds_bpermute_b32 v53, v105, v52
	s_waitcnt lgkmcnt(0)
	v_add_f32_e32 v52, v52, v53
	ds_bpermute_b32 v53, v106, v52
	s_waitcnt lgkmcnt(0)
	v_add_f32_e32 v52, v52, v53
	v_fmamk_f32 v52, v52, 0x3a800000, v228
	v_cmp_gt_f32_e32 vcc, s89, v52
	v_mul_f32_e32 v53, 0x4f800000, v52
	s_nop 0
	v_cndmask_b32_e32 v52, v52, v53, vcc
	v_sqrt_f32_e32 v53, v52
	s_nop 0
	v_add_u32_e32 v54, -1, v53
	v_fma_f32 v55, -v54, v53, v52
	v_cmp_ge_f32_e64 s[0:1], 0, v55
	v_add_u32_e32 v55, 1, v53
	s_nop 0
	v_cndmask_b32_e64 v54, v53, v54, s[0:1]
	v_fma_f32 v53, -v55, v53, v52
	v_cmp_lt_f32_e64 s[0:1], 0, v53
	s_nop 1
	v_cndmask_b32_e64 v53, v54, v55, s[0:1]
	v_mul_f32_e32 v54, 0x37800000, v53
	v_cndmask_b32_e32 v53, v53, v54, vcc
	v_cmp_class_f32_e32 vcc, v52, v229
	s_nop 1
	v_cndmask_b32_e32 v52, v53, v52, vcc
	v_div_scale_f32 v53, s[0:1], v52, v52, 1.0
	v_rcp_f32_e32 v54, v53
	s_nop 0
	v_fma_f32 v55, -v53, v54, 1.0
	v_fmac_f32_e32 v54, v55, v54
	v_div_scale_f32 v55, vcc, 1.0, v52, 1.0
	v_mul_f32_e32 v56, v55, v54
	v_fma_f32 v57, -v53, v56, v55
	v_fmac_f32_e32 v56, v57, v54
	v_fma_f32 v53, -v53, v56, v55
	v_div_fmas_f32 v53, v53, v54, v56
	v_div_fixup_f32 v52, v53, v52, 1.0
	v_pk_mul_f32 v[48:49], v[48:49], v[52:53] op_sel_hi:[1,0]
	v_pk_mul_f32 v[50:51], v[50:51], v[52:53] op_sel_hi:[1,0]
	v_pk_mul_f32 v[44:45], v[44:45], v[52:53] op_sel_hi:[1,0]
	v_pk_mul_f32 v[46:47], v[46:47], v[52:53] op_sel_hi:[1,0]
	v_pk_mul_f32 v[40:41], v[40:41], v[52:53] op_sel_hi:[1,0]
	v_pk_mul_f32 v[42:43], v[42:43], v[52:53] op_sel_hi:[1,0]
	v_pk_mul_f32 v[36:37], v[36:37], v[52:53] op_sel_hi:[1,0]
	v_pk_mul_f32 v[38:39], v[38:39], v[52:53] op_sel_hi:[1,0]
	v_pk_fma_f32 v[50:51], v[20:21], v[50:51], v[2:3]
	v_pk_fma_f32 v[48:49], v[22:23], v[48:49], v[0:1]
	v_pk_fma_f32 v[46:47], v[24:25], v[46:47], v[6:7]
	v_pk_fma_f32 v[44:45], v[26:27], v[44:45], v[4:5]
	v_pk_fma_f32 v[42:43], v[28:29], v[42:43], v[10:11]
	v_pk_fma_f32 v[40:41], v[30:31], v[40:41], v[8:9]
	v_pk_fma_f32 v[38:39], v[32:33], v[38:39], v[14:15]
	v_pk_fma_f32 v[36:37], v[34:35], v[36:37], v[12:13]
	v_lshl_add_u64 v[54:55], v[18:19], 0, s[34:35]
	v_cvt_pk_bf16_f32 v48, v48, v49
	v_cvt_pk_bf16_f32 v49, v50, v51
	v_cvt_pk_bf16_f32 v44, v44, v45
	v_cvt_pk_bf16_f32 v45, v46, v47
	v_cvt_pk_bf16_f32 v40, v40, v41
	v_cvt_pk_bf16_f32 v41, v42, v43
	v_cvt_pk_bf16_f32 v36, v36, v37
	v_cvt_pk_bf16_f32 v37, v38, v39
	global_store_dwordx2 v[54:55], v[48:49], off
	global_store_dwordx2 v[54:55], v[44:45], off offset:512
	global_store_dwordx2 v[54:55], v[40:41], off offset:1024
	global_store_dwordx2 v[54:55], v[36:37], off offset:1536
	s_cbranch_scc0 .LBB0_122

.LBB0_131:
	global_load_dwordx4 v[28:31], v176, s[42:43]
	global_load_dwordx4 v[8:11], v176, s[42:43] offset:1024
	global_load_dwordx4 v[0:3], v176, s[42:43] offset:3072
	global_load_dwordx4 v[4:7], v176, s[42:43] offset:2048
	s_mul_hi_i32 s22, s3, 0x9000
	s_mul_i32 s3, s3, 0x9000
	v_readlane_b32 s7, v255, 34
	s_add_u32 s44, s7, s3
	v_readlane_b32 s3, v255, 35
	s_addc_u32 s45, s3, s22
	s_add_u32 s42, s44, 0x1000
	s_addc_u32 s43, s45, 0
	v_lshl_add_u64 v[32:33], s[42:43], 0, v[176:177]
	global_load_dwordx4 v[32:35], v[32:33], off
	s_nop 0
	global_load_dwordx4 v[36:39], v[14:15], off
	v_lshl_add_u64 v[44:45], s[44:45], 0, v[176:177]
	global_load_dwordx4 v[40:43], v[44:45], off
	s_lshl_b64 s[0:1], s[0:1], 11
	s_waitcnt vmcnt(0)
	v_pk_mul_f32 v[46:47], v[30:31], v[30:31]
	v_pk_mul_f32 v[48:49], v[28:29], v[28:29]
	v_pk_mul_f32 v[50:51], v[10:11], v[10:11]
	v_pk_mul_f32 v[52:53], v[8:9], v[8:9]
	v_pk_mov_b32 v[58:59], v[48:49], v[46:47] op_sel:[1,0]
	v_mov_b32_e32 v49, v47
	v_pk_mov_b32 v[46:47], v[52:53], v[50:51] op_sel:[1,0]
	v_mov_b32_e32 v53, v51
	v_mul_f32_e32 v57, v3, v3
	v_mul_f32_e32 v54, v5, v5
	v_mul_f32_e32 v56, v7, v7
	v_pk_add_f32 v[48:49], v[58:59], v[48:49]
	v_pk_add_f32 v[46:47], v[46:47], v[52:53]
	v_mul_f32_e32 v17, v0, v0
	v_mul_f32_e32 v19, v1, v1
	v_mul_f32_e32 v21, v2, v2
	v_pk_fma_f32 v[50:51], v[4:5], v[4:5], v[54:55] op_sel_hi:[1,1,0]
	v_pk_fma_f32 v[54:55], v[6:7], v[6:7], v[56:57] op_sel_hi:[1,1,0]
	v_pk_add_f32 v[48:49], v[48:49], v[48:49] op_sel:[0,1] op_sel_hi:[1,0]
	v_pk_add_f32 v[46:47], v[46:47], v[46:47] op_sel:[0,1] op_sel_hi:[1,0]
	v_mov_b32_e32 v51, v21
	v_mov_b32_e32 v55, v57
	v_mov_b32_e32 v49, v17
	v_mov_b32_e32 v47, v19
	v_pk_add_f32 v[50:51], v[50:51], v[54:55]
	v_pk_add_f32 v[46:47], v[48:49], v[46:47]
	s_waitcnt lgkmcnt(0)
	v_pk_add_f32 v[34:35], v[34:35], 1.0 op_sel_hi:[1,0]
	v_pk_add_f32 v[46:47], v[46:47], v[50:51]
	v_pk_add_f32 v[32:33], v[32:33], 1.0 op_sel_hi:[1,0]
	v_add_f32_e32 v17, v46, v47
	ds_bpermute_b32 v19, v22, v17
	v_lshl_add_u64 v[46:47], v[12:13], 0, s[0:1]
	s_waitcnt lgkmcnt(0)
	v_add_f32_e32 v17, v17, v19
	ds_bpermute_b32 v19, v23, v17
	s_waitcnt lgkmcnt(0)
	v_add_f32_e32 v17, v17, v19
	ds_bpermute_b32 v19, v24, v17
	s_waitcnt lgkmcnt(0)
	v_add_f32_e32 v17, v17, v19
	ds_bpermute_b32 v19, v25, v17
	s_waitcnt lgkmcnt(0)
	v_add_f32_e32 v17, v17, v19
	ds_bpermute_b32 v19, v26, v17
	s_waitcnt lgkmcnt(0)
	v_add_f32_e32 v19, v17, v19
	ds_bpermute_b32 v21, v27, v19
	v_mov_b32_e32 v17, v177
	s_waitcnt lgkmcnt(0)
	v_add_f32_e32 v19, v19, v21
	v_fmamk_f32 v19, v19, 0x3a800000, v228
	v_mul_f32_e32 v21, 0x4f800000, v19
	v_cmp_gt_f32_e32 vcc, s89, v19
	s_nop 1
	v_cndmask_b32_e32 v19, v19, v21, vcc
	v_sqrt_f32_e32 v21, v19
	s_nop 0
	v_add_u32_e32 v48, -1, v21
	v_add_u32_e32 v49, 1, v21
	v_fma_f32 v50, -v48, v21, v19
	v_fma_f32 v51, -v49, v21, v19
	v_cmp_ge_f32_e64 s[0:1], 0, v50
	s_nop 1
	v_cndmask_b32_e64 v21, v21, v48, s[0:1]
	v_cmp_lt_f32_e64 s[0:1], 0, v51
	s_nop 1
	v_cndmask_b32_e64 v21, v21, v49, s[0:1]
	v_mul_f32_e32 v48, 0x37800000, v21
	v_cndmask_b32_e32 v21, v21, v48, vcc
	v_cmp_class_f32_e32 vcc, v19, v229
	s_nop 1
	v_cndmask_b32_e32 v19, v21, v19, vcc
	v_div_scale_f32 v21, s[0:1], v19, v19, 1.0
	v_rcp_f32_e32 v48, v21
	v_div_scale_f32 v49, vcc, 1.0, v19, 1.0
	v_readlane_b32 s0, v255, 1
	v_fma_f32 v50, -v21, v48, 1.0
	v_fmac_f32_e32 v48, v50, v48
	v_mul_f32_e32 v50, v49, v48
	v_fma_f32 v51, -v21, v50, v49
	v_fmac_f32_e32 v50, v51, v48
	v_fma_f32 v21, -v21, v50, v49
	v_div_fmas_f32 v21, v21, v48, v50
	v_div_fixup_f32 v48, v21, v19, 1.0
	v_pk_mul_f32 v[30:31], v[30:31], v[48:49] op_sel_hi:[1,0]
	v_pk_mul_f32 v[28:29], v[28:29], v[48:49] op_sel_hi:[1,0]
	v_pk_mul_f32 v[30:31], v[38:39], v[30:31]
	v_pk_mul_f32 v[28:29], v[36:37], v[28:29]
	v_pk_fma_f32 v[30:31], v[34:35], v[30:31], v[42:43]
	v_pk_fma_f32 v[28:29], v[32:33], v[28:29], v[40:41]
	v_lshl_add_u64 v[32:33], s[42:43], 0, v[16:17]
	v_cvt_pk_bf16_f32 v28, v28, v29
	v_cvt_pk_bf16_f32 v29, v30, v31
	global_store_dwordx2 v[46:47], v[28:29], off
	global_load_dwordx4 v[28:31], v[14:15], off offset:1024
	s_nop 0
	global_load_dwordx4 v[32:35], v[32:33], off
	s_nop 0
	global_load_dwordx4 v[36:39], v[44:45], off offset:1024
	v_pk_mul_f32 v[10:11], v[10:11], v[48:49] op_sel_hi:[1,0]
	v_pk_mul_f32 v[8:9], v[8:9], v[48:49] op_sel_hi:[1,0]
	v_mov_b32_e32 v19, v177
	v_pk_mul_f32 v[6:7], v[6:7], v[48:49] op_sel_hi:[1,0]
	v_pk_mul_f32 v[4:5], v[4:5], v[48:49] op_sel_hi:[1,0]
	v_mov_b32_e32 v21, v177
	v_readlane_b32 s1, v255, 2
	s_add_u32 s40, s40, s0
	s_addc_u32 s41, s41, s1
	v_readlane_b32 s0, v255, 3
	v_pk_mul_f32 v[2:3], v[2:3], v[48:49] op_sel_hi:[1,0]
	v_pk_mul_f32 v[0:1], v[0:1], v[48:49] op_sel_hi:[1,0]
	v_readlane_b32 s1, v255, 4
	s_add_u32 s38, s38, s0
	s_addc_u32 s39, s39, s1
	s_cmpk_gt_i32 s40, 0x7fff
	s_waitcnt vmcnt(0)
	v_pk_mul_f32 v[8:9], v[28:29], v[8:9]
	v_pk_mul_f32 v[10:11], v[30:31], v[10:11]
	s_waitcnt lgkmcnt(0)
	v_pk_add_f32 v[28:29], v[34:35], 1.0 op_sel_hi:[1,0]
	v_pk_add_f32 v[30:31], v[32:33], 1.0 op_sel_hi:[1,0]
	v_pk_fma_f32 v[10:11], v[28:29], v[10:11], v[38:39]
	v_pk_fma_f32 v[8:9], v[30:31], v[8:9], v[36:37]
	v_lshl_add_u64 v[28:29], s[42:43], 0, v[18:19]
	v_cvt_pk_bf16_f32 v8, v8, v9
	v_cvt_pk_bf16_f32 v9, v10, v11
	global_store_dwordx2 v[46:47], v[8:9], off offset:512
	global_load_dwordx4 v[8:11], v[14:15], off offset:2048
	s_nop 0
	global_load_dwordx4 v[28:31], v[28:29], off
	s_nop 0
	global_load_dwordx4 v[32:35], v[44:45], off offset:2048
	s_waitcnt vmcnt(0)
	v_pk_mul_f32 v[4:5], v[8:9], v[4:5]
	v_pk_mul_f32 v[6:7], v[10:11], v[6:7]
	s_waitcnt lgkmcnt(0)
	v_pk_add_f32 v[8:9], v[30:31], 1.0 op_sel_hi:[1,0]
	v_pk_add_f32 v[10:11], v[28:29], 1.0 op_sel_hi:[1,0]
	v_pk_fma_f32 v[6:7], v[8:9], v[6:7], v[34:35]
	v_pk_fma_f32 v[4:5], v[10:11], v[4:5], v[32:33]
	v_lshl_add_u64 v[8:9], s[42:43], 0, v[20:21]
	v_cvt_pk_bf16_f32 v4, v4, v5
	v_cvt_pk_bf16_f32 v5, v6, v7
	global_store_dwordx2 v[46:47], v[4:5], off offset:1024
	global_load_dwordx4 v[4:7], v[14:15], off offset:3072
	s_nop 0
	global_load_dwordx4 v[8:11], v[8:9], off
	s_nop 0
	global_load_dwordx4 v[28:31], v[44:45], off offset:3072
	s_waitcnt vmcnt(0)
	v_pk_mul_f32 v[0:1], v[0:1], v[4:5]
	v_pk_mul_f32 v[2:3], v[2:3], v[6:7]
	s_waitcnt lgkmcnt(0)
	v_pk_add_f32 v[4:5], v[10:11], 1.0 op_sel_hi:[1,0]
	v_pk_add_f32 v[6:7], v[8:9], 1.0 op_sel_hi:[1,0]
	v_pk_fma_f32 v[2:3], v[2:3], v[4:5], v[30:31]
	v_pk_fma_f32 v[0:1], v[0:1], v[6:7], v[28:29]
	s_nop 0
	v_cvt_pk_bf16_f32 v0, v0, v1
	v_cvt_pk_bf16_f32 v1, v2, v3
	global_store_dwordx2 v[46:47], v[0:1], off offset:1536
	s_cbranch_scc1 .LBB0_138

.LBB0_141:
	v_readlane_b32 s8, v254, 38
	v_readlane_b32 s9, v254, 39
	s_andn2_b64 vcc, exec, s[8:9]
	s_cbranch_vccnz .LBB0_149
	s_mul_hi_i32 s1, s0, 0x9000
	s_mul_i32 s0, s0, 0x9000
	v_readlane_b32 s3, v255, 34
	s_add_u32 s0, s3, s0
	v_readlane_b32 s3, v255, 35
	s_addc_u32 s1, s3, s1
	s_add_u32 s38, s0, 0x1000
	s_addc_u32 s39, s1, 0
	v_lshlrev_b32_e32 v176, 4, v80
	v_lshl_add_u64 v[0:1], s[38:39], 0, v[176:177]
	global_load_dwordx4 v[16:19], v[0:1], off
	v_or_b32_e32 v0, 0x400, v176
	v_mov_b32_e32 v1, v177
	v_lshl_add_u64 v[0:1], s[38:39], 0, v[0:1]
	global_load_dwordx4 v[20:23], v[0:1], off
	v_or_b32_e32 v0, 0x800, v176
	v_mov_b32_e32 v1, v177
	v_lshl_add_u64 v[0:1], s[38:39], 0, v[0:1]
	v_readlane_b32 s8, v252, 10
	global_load_dwordx4 v[24:27], v[0:1], off
	v_readlane_b32 s20, v252, 22
	v_readlane_b32 s21, v252, 23
	s_nop 4
	global_load_dwordx4 v[28:31], v176, s[20:21]
	global_load_dwordx4 v[32:35], v176, s[20:21] offset:1024
	global_load_dwordx4 v[36:39], v176, s[20:21] offset:2048
	global_load_dwordx4 v[40:43], v176, s[20:21] offset:3072
	v_lshl_add_u64 v[12:13], s[0:1], 0, v[176:177]
	v_or_b32_e32 v176, 0xc00, v176
	v_lshl_add_u64 v[0:1], s[38:39], 0, v[176:177]
	global_load_dwordx4 v[44:47], v[0:1], off
	s_nop 0
	global_load_dwordx4 v[0:3], v[12:13], off
	global_load_dwordx4 v[4:7], v[12:13], off offset:1024
	global_load_dwordx4 v[8:11], v[12:13], off offset:2048
	s_nop 0
	global_load_dwordx4 v[12:15], v[12:13], off offset:3072
	v_readlane_b32 s0, v255, 5
	s_add_u32 s0, s34, s0
	v_readlane_b32 s1, v255, 8
	v_lshlrev_b32_e32 v48, 2, v80
	v_lshlrev_b32_e32 v176, 3, v80
	s_addc_u32 s1, s35, s1
	v_xor_b32_e32 v81, 4, v48
	v_xor_b32_e32 v102, 8, v48
	v_xor_b32_e32 v103, 16, v48
	v_xor_b32_e32 v104, 32, v48
	v_xor_b32_e32 v105, 64, v48
	v_xor_b32_e32 v106, 0x80, v48
	v_lshl_add_u64 v[82:83], s[36:37], 0, v[176:177]
	v_lshl_add_u64 v[84:85], s[0:1], 0, v[176:177]
	s_mov_b64 s[34:35], 0
	s_mov_b64 s[46:47], 0x2000
	v_readlane_b32 s9, v252, 11
	v_readlane_b32 s10, v252, 12
	v_readlane_b32 s11, v252, 13
	v_readlane_b32 s12, v252, 14
	v_readlane_b32 s13, v252, 15
	v_readlane_b32 s14, v252, 16
	v_readlane_b32 s15, v252, 17
	v_readlane_b32 s16, v252, 18
	v_readlane_b32 s17, v252, 19
	v_readlane_b32 s18, v252, 20
	v_readlane_b32 s19, v252, 21
	v_readlane_b32 s22, v252, 24
	v_readlane_b32 s23, v252, 25
	s_waitcnt vmcnt(0) lgkmcnt(0)
	v_pk_add_f32 v[18:19], v[18:19], 1.0 op_sel_hi:[1,0]
	v_pk_add_f32 v[16:17], v[16:17], 1.0 op_sel_hi:[1,0]
	v_pk_add_f32 v[22:23], v[22:23], 1.0 op_sel_hi:[1,0]
	v_pk_add_f32 v[20:21], v[20:21], 1.0 op_sel_hi:[1,0]
	v_pk_add_f32 v[26:27], v[26:27], 1.0 op_sel_hi:[1,0]
	v_pk_add_f32 v[24:25], v[24:25], 1.0 op_sel_hi:[1,0]
	v_pk_mul_f32 v[86:87], v[30:31], v[18:19]
	v_pk_mul_f32 v[88:89], v[28:29], v[16:17]
	v_pk_add_f32 v[16:17], v[46:47], 1.0 op_sel_hi:[1,0]
	v_pk_add_f32 v[18:19], v[44:45], 1.0 op_sel_hi:[1,0]
	v_pk_mul_f32 v[90:91], v[34:35], v[22:23]
	v_pk_mul_f32 v[92:93], v[32:33], v[20:21]
	v_pk_mul_f32 v[94:95], v[38:39], v[26:27]
	v_pk_mul_f32 v[96:97], v[36:37], v[24:25]
	v_pk_mul_f32 v[98:99], v[42:43], v[16:17]
	v_pk_mul_f32 v[100:101], v[40:41], v[18:19]
	s_branch .LBB0_144
.LBB0_143:
	s_waitcnt vmcnt(0)
	v_pk_mul_f32 v[38:39], v[78:79], v[78:79]
	v_pk_mul_f32 v[40:41], v[76:77], v[76:77]
	s_waitcnt vmcnt(8)
	v_mul_f32_e32 v37, v64, v64
	v_pk_mov_b32 v[42:43], v[40:41], v[38:39] op_sel:[1,0]
	v_mov_b32_e32 v41, v39
	v_pk_add_f32 v[38:39], v[42:43], v[40:41]
	v_pk_mul_f32 v[40:41], v[74:75], v[74:75]
	v_pk_mul_f32 v[42:43], v[72:73], v[72:73]
	v_pk_add_f32 v[38:39], v[38:39], v[38:39] op_sel:[0,1] op_sel_hi:[1,0]
	v_pk_mov_b32 v[44:45], v[42:43], v[40:41] op_sel:[1,0]
	v_mov_b32_e32 v43, v41
	v_pk_add_f32 v[40:41], v[44:45], v[42:43]
	v_mul_f32_e32 v42, v65, v65
	v_pk_add_f32 v[40:41], v[40:41], v[40:41] op_sel:[0,1] op_sel_hi:[1,0]
	v_mov_b32_e32 v39, v37
	v_mov_b32_e32 v41, v42
	v_pk_add_f32 v[38:39], v[38:39], v[40:41]
	v_mul_f32_e32 v40, v69, v69
	v_mul_f32_e32 v43, v66, v66
	v_pk_fma_f32 v[40:41], v[68:69], v[68:69], v[40:41] op_sel_hi:[1,1,0]
	v_mul_f32_e32 v42, v71, v71
	v_mul_f32_e32 v44, v67, v67
	v_mov_b32_e32 v41, v43
	v_pk_fma_f32 v[42:43], v[70:71], v[70:71], v[42:43] op_sel_hi:[1,1,0]
	v_readlane_b32 s72, v255, 26
	v_mov_b32_e32 v43, v44
	v_pk_add_f32 v[40:41], v[40:41], v[42:43]
	v_readlane_b32 s73, v255, 27
	v_pk_add_f32 v[38:39], v[38:39], v[40:41]
	s_nop 0
	v_add_f32_e32 v37, v38, v39
	ds_bpermute_b32 v38, v81, v37
	s_waitcnt lgkmcnt(0)
	v_add_f32_e32 v37, v37, v38
	ds_bpermute_b32 v38, v102, v37
	s_waitcnt lgkmcnt(0)
	v_add_f32_e32 v37, v37, v38
	ds_bpermute_b32 v38, v103, v37
	s_waitcnt lgkmcnt(0)
	v_add_f32_e32 v37, v37, v38
	ds_bpermute_b32 v38, v104, v37
	s_waitcnt lgkmcnt(0)
	v_add_f32_e32 v37, v37, v38
	ds_bpermute_b32 v38, v105, v37
	s_waitcnt lgkmcnt(0)
	v_add_f32_e32 v37, v37, v38
	ds_bpermute_b32 v38, v106, v37
	s_waitcnt lgkmcnt(0)
	v_add_f32_e32 v37, v37, v38
	v_fmamk_f32 v37, v37, 0x3a800000, v228
	v_mul_f32_e32 v38, 0x4f800000, v37
	v_cmp_gt_f32_e32 vcc, s89, v37
	s_nop 1
	v_cndmask_b32_e32 v37, v37, v38, vcc
	v_sqrt_f32_e32 v38, v37
	s_nop 0
	v_add_u32_e32 v39, -1, v38
	v_add_u32_e32 v40, 1, v38
	v_fma_f32 v41, -v39, v38, v37
	v_fma_f32 v42, -v40, v38, v37
	v_cmp_ge_f32_e64 s[0:1], 0, v41
	s_nop 1
	v_cndmask_b32_e64 v38, v38, v39, s[0:1]
	v_cmp_lt_f32_e64 s[0:1], 0, v42
	s_nop 1
	v_cndmask_b32_e64 v38, v38, v40, s[0:1]
	v_mul_f32_e32 v39, 0x37800000, v38
	v_cndmask_b32_e32 v38, v38, v39, vcc
	v_cmp_class_f32_e32 vcc, v37, v229
	s_nop 1
	v_cndmask_b32_e32 v107, v38, v37, vcc
	v_div_scale_f32 v108, s[0:1], v107, v107, 1.0
	v_rcp_f32_e32 v116, v108
	global_load_dwordx4 v[44:47], v36, s[42:43]
	global_load_dwordx4 v[52:55], v36, s[42:43] offset:1024
	global_load_dwordx4 v[40:43], v36, s[42:43] offset:2048
	s_nop 0
	global_load_dwordx4 v[36:39], v36, s[42:43] offset:3072
	v_fma_f32 v109, -v108, v116, 1.0
	v_fmac_f32_e32 v116, v109, v116
	v_div_scale_f32 v109, vcc, 1.0, v107, 1.0
	v_mul_f32_e32 v117, v109, v116
	v_fma_f32 v110, -v108, v117, v109
	v_fmac_f32_e32 v117, v110, v116
	v_fma_f32 v118, -v108, v117, v109
	s_waitcnt vmcnt(11)
	v_pk_mul_f32 v[108:109], v[62:63], v[62:63]
	v_pk_mul_f32 v[110:111], v[60:61], v[60:61]
	s_nop 0
	v_pk_mov_b32 v[112:113], v[110:111], v[108:109] op_sel:[1,0]
	v_mov_b32_e32 v111, v109
	v_pk_add_f32 v[108:109], v[112:113], v[110:111]
	s_waitcnt vmcnt(10)
	v_pk_mul_f32 v[110:111], v[58:59], v[58:59]
	v_pk_mul_f32 v[112:113], v[56:57], v[56:57]
	v_pk_add_f32 v[108:109], v[108:109], v[108:109] op_sel:[0,1] op_sel_hi:[1,0]
	v_pk_mov_b32 v[114:115], v[112:113], v[110:111] op_sel:[1,0]
	v_mov_b32_e32 v113, v111
	v_pk_add_f32 v[110:111], v[114:115], v[112:113]
	s_waitcnt vmcnt(8)
	v_mul_f32_e32 v112, v32, v32
	v_mul_f32_e32 v113, v33, v33
	v_pk_add_f32 v[110:111], v[110:111], v[110:111] op_sel:[0,1] op_sel_hi:[1,0]
	v_mov_b32_e32 v109, v112
	v_mov_b32_e32 v111, v113
	v_pk_add_f32 v[108:109], v[108:109], v[110:111]
	v_mul_f32_e32 v110, v49, v49
	v_mul_f32_e32 v112, v51, v51
	v_mul_f32_e32 v114, v34, v34
	v_mul_f32_e32 v115, v35, v35
	v_pk_fma_f32 v[110:111], v[48:49], v[48:49], v[110:111] op_sel_hi:[1,1,0]
	v_pk_fma_f32 v[112:113], v[50:51], v[50:51], v[112:113] op_sel_hi:[1,1,0]
	v_mov_b32_e32 v111, v114
	v_mov_b32_e32 v113, v115
	v_pk_add_f32 v[110:111], v[110:111], v[112:113]
	s_nop 0
	v_pk_add_f32 v[108:109], v[108:109], v[110:111]
	s_nop 0
	v_add_f32_e32 v109, v108, v109
	ds_bpermute_b32 v110, v81, v109
	v_div_fmas_f32 v108, v118, v116, v117
	v_div_fixup_f32 v108, v108, v107, 1.0
	v_pk_mul_f32 v[76:77], v[76:77], v[108:109] op_sel_hi:[1,0]
	v_pk_mul_f32 v[78:79], v[78:79], v[108:109] op_sel_hi:[1,0]
	s_waitcnt lgkmcnt(0)
	v_add_f32_e32 v107, v109, v110
	ds_bpermute_b32 v109, v102, v107
	v_pk_fma_f32 v[78:79], v[86:87], v[78:79], v[2:3]
	v_pk_fma_f32 v[76:77], v[88:89], v[76:77], v[0:1]
	s_waitcnt lgkmcnt(0)
	v_pk_mul_f32 v[72:73], v[72:73], v[108:109] op_sel_hi:[1,0]
	v_cvt_pk_bf16_f32 v76, v76, v77
	v_cvt_pk_bf16_f32 v77, v78, v79
	v_add_f32_e32 v78, v107, v109
	ds_bpermute_b32 v79, v103, v78
	global_store_dwordx2 v[84:85], v[76:77], off
	v_pk_mul_f32 v[74:75], v[74:75], v[108:109] op_sel_hi:[1,0]
	v_pk_fma_f32 v[72:73], v[92:93], v[72:73], v[4:5]
	v_pk_fma_f32 v[74:75], v[90:91], v[74:75], v[6:7]
	s_waitcnt lgkmcnt(0)
	v_add_f32_e32 v76, v78, v79
	ds_bpermute_b32 v77, v104, v76
	v_cvt_pk_bf16_f32 v72, v72, v73
	v_cvt_pk_bf16_f32 v73, v74, v75
	global_store_dwordx2 v[84:85], v[72:73], off offset:512
	v_pk_mul_f32 v[68:69], v[68:69], v[108:109] op_sel_hi:[1,0]
	s_waitcnt lgkmcnt(0)
	v_add_f32_e32 v72, v76, v77
	ds_bpermute_b32 v73, v105, v72
	v_pk_mul_f32 v[70:71], v[70:71], v[108:109] op_sel_hi:[1,0]
	v_pk_fma_f32 v[68:69], v[96:97], v[68:69], v[8:9]
	v_pk_fma_f32 v[70:71], v[94:95], v[70:71], v[10:11]
	v_cvt_pk_bf16_f32 v68, v68, v69
	s_waitcnt lgkmcnt(0)
	v_add_f32_e32 v72, v72, v73
	ds_bpermute_b32 v73, v106, v72
	v_cvt_pk_bf16_f32 v69, v70, v71
	global_store_dwordx2 v[84:85], v[68:69], off offset:1024
	v_pk_mul_f32 v[64:65], v[64:65], v[108:109] op_sel_hi:[1,0]
	v_pk_mul_f32 v[66:67], v[66:67], v[108:109] op_sel_hi:[1,0]
	s_waitcnt lgkmcnt(0)
	v_add_f32_e32 v68, v72, v73
	v_fmamk_f32 v68, v68, 0x3a800000, v228
	v_mul_f32_e32 v69, 0x4f800000, v68
	v_cmp_gt_f32_e32 vcc, s89, v68
	v_pk_fma_f32 v[66:67], v[98:99], v[66:67], v[14:15]
	v_pk_fma_f32 v[64:65], v[100:101], v[64:65], v[12:13]
	v_cndmask_b32_e32 v68, v68, v69, vcc
	v_sqrt_f32_e32 v69, v68
	v_cvt_pk_bf16_f32 v64, v64, v65
	v_cvt_pk_bf16_f32 v65, v66, v67
	global_store_dwordx2 v[84:85], v[64:65], off offset:1536
	v_add_u32_e32 v70, -1, v69
	v_fma_f32 v71, -v70, v69, v68
	v_cmp_ge_f32_e64 s[0:1], 0, v71
	v_add_u32_e32 v71, 1, v69
	v_lshl_add_u64 v[84:85], v[84:85], 0, s[46:47]
	v_cndmask_b32_e64 v70, v69, v70, s[0:1]
	v_fma_f32 v69, -v71, v69, v68
	v_cmp_lt_f32_e64 s[0:1], 0, v69
	s_nop 1
	v_cndmask_b32_e64 v69, v70, v71, s[0:1]
	v_mul_f32_e32 v70, 0x37800000, v69
	v_cndmask_b32_e32 v69, v69, v70, vcc
	v_cmp_class_f32_e32 vcc, v68, v229
	s_nop 1
	v_cndmask_b32_e32 v68, v69, v68, vcc
	v_div_scale_f32 v69, s[0:1], v68, v68, 1.0
	v_rcp_f32_e32 v70, v69
	s_lshl_b64 s[0:1], s[40:41], 11
	v_fma_f32 v64, -v69, v70, 1.0
	v_fmac_f32_e32 v70, v64, v70
	v_div_scale_f32 v64, vcc, 1.0, v68, 1.0
	v_mul_f32_e32 v65, v64, v70
	v_fma_f32 v66, -v69, v65, v64
	v_fmac_f32_e32 v65, v66, v70
	v_fma_f32 v64, -v69, v65, v64
	v_div_fmas_f32 v64, v64, v70, v65
	v_div_fixup_f32 v64, v64, v68, 1.0
	s_waitcnt vmcnt(0)
	v_pk_mul_f32 v[66:67], v[30:31], v[30:31]
	v_pk_mul_f32 v[68:69], v[28:29], v[28:29]
	v_mul_f32_e32 v65, v16, v16
	v_pk_mov_b32 v[70:71], v[68:69], v[66:67] op_sel:[1,0]
	v_mov_b32_e32 v69, v67
	v_pk_add_f32 v[66:67], v[70:71], v[68:69]
	v_pk_mul_f32 v[68:69], v[26:27], v[26:27]
	v_pk_mul_f32 v[70:71], v[24:25], v[24:25]
	v_pk_add_f32 v[66:67], v[66:67], v[66:67] op_sel:[0,1] op_sel_hi:[1,0]
	v_pk_mov_b32 v[72:73], v[70:71], v[68:69] op_sel:[1,0]
	v_mov_b32_e32 v71, v69
	v_pk_add_f32 v[68:69], v[72:73], v[70:71]
	v_mul_f32_e32 v70, v17, v17
	v_pk_add_f32 v[68:69], v[68:69], v[68:69] op_sel:[0,1] op_sel_hi:[1,0]
	v_mov_b32_e32 v67, v65
	v_mov_b32_e32 v69, v70
	v_pk_add_f32 v[66:67], v[66:67], v[68:69]
	v_mul_f32_e32 v68, v21, v21
	v_mul_f32_e32 v71, v18, v18
	v_pk_fma_f32 v[68:69], v[20:21], v[20:21], v[68:69] op_sel_hi:[1,1,0]
	v_mul_f32_e32 v70, v23, v23
	v_mul_f32_e32 v72, v19, v19
	v_mov_b32_e32 v69, v71
	v_pk_fma_f32 v[70:71], v[22:23], v[22:23], v[70:71] op_sel_hi:[1,1,0]
	s_nop 0
	v_mov_b32_e32 v71, v72
	v_pk_add_f32 v[68:69], v[68:69], v[70:71]
	s_nop 0
	v_pk_add_f32 v[66:67], v[66:67], v[68:69]
	s_nop 0
	v_add_f32_e32 v65, v66, v67
	ds_bpermute_b32 v68, v81, v65
	v_pk_mul_f32 v[60:61], v[60:61], v[64:65] op_sel_hi:[1,0]
	v_pk_mul_f32 v[62:63], v[62:63], v[64:65] op_sel_hi:[1,0]
	v_pk_fma_f32 v[60:61], v[88:89], v[60:61], v[0:1]
	v_pk_fma_f32 v[62:63], v[86:87], v[62:63], v[2:3]
	s_waitcnt lgkmcnt(0)
	v_add_f32_e32 v65, v65, v68
	ds_bpermute_b32 v68, v102, v65
	v_cvt_pk_bf16_f32 v60, v60, v61
	v_cvt_pk_bf16_f32 v61, v62, v63
	v_lshl_add_u64 v[66:67], v[82:83], 0, s[0:1]
	global_store_dwordx2 v[66:67], v[60:61], off
	s_waitcnt lgkmcnt(0)
	v_add_f32_e32 v62, v65, v68
	ds_bpermute_b32 v63, v103, v62
	v_pk_mul_f32 v[56:57], v[56:57], v[64:65] op_sel_hi:[1,0]
	v_pk_mul_f32 v[58:59], v[58:59], v[64:65] op_sel_hi:[1,0]
	v_pk_fma_f32 v[56:57], v[92:93], v[56:57], v[4:5]
	v_pk_fma_f32 v[58:59], v[90:91], v[58:59], v[6:7]
	s_waitcnt lgkmcnt(0)
	v_add_f32_e32 v60, v62, v63
	ds_bpermute_b32 v61, v104, v60
	v_cvt_pk_bf16_f32 v56, v56, v57
	v_cvt_pk_bf16_f32 v57, v58, v59
	global_store_dwordx2 v[66:67], v[56:57], off offset:512
	v_pk_mul_f32 v[48:49], v[48:49], v[64:65] op_sel_hi:[1,0]
	s_waitcnt lgkmcnt(0)
	v_add_f32_e32 v56, v60, v61
	ds_bpermute_b32 v57, v105, v56
	v_pk_mul_f32 v[50:51], v[50:51], v[64:65] op_sel_hi:[1,0]
	v_pk_fma_f32 v[48:49], v[96:97], v[48:49], v[8:9]
	v_pk_fma_f32 v[50:51], v[94:95], v[50:51], v[10:11]
	v_cvt_pk_bf16_f32 v48, v48, v49
	s_waitcnt lgkmcnt(0)
	v_add_f32_e32 v56, v56, v57
	ds_bpermute_b32 v57, v106, v56
	v_cvt_pk_bf16_f32 v49, v50, v51
	global_store_dwordx2 v[66:67], v[48:49], off offset:1024
	v_pk_mul_f32 v[32:33], v[32:33], v[64:65] op_sel_hi:[1,0]
	v_pk_mul_f32 v[34:35], v[34:35], v[64:65] op_sel_hi:[1,0]
	s_waitcnt lgkmcnt(0)
	v_add_f32_e32 v48, v56, v57
	v_fmamk_f32 v48, v48, 0x3a800000, v228
	v_mul_f32_e32 v49, 0x4f800000, v48
	v_cmp_gt_f32_e32 vcc, s89, v48
	v_pk_fma_f32 v[34:35], v[98:99], v[34:35], v[14:15]
	v_pk_fma_f32 v[32:33], v[100:101], v[32:33], v[12:13]
	v_cndmask_b32_e32 v48, v48, v49, vcc
	v_sqrt_f32_e32 v49, v48
	v_cvt_pk_bf16_f32 v32, v32, v33
	v_cvt_pk_bf16_f32 v33, v34, v35
	global_store_dwordx2 v[66:67], v[32:33], off offset:1536
	v_add_u32_e32 v50, -1, v49
	v_fma_f32 v51, -v50, v49, v48
	v_cmp_ge_f32_e64 s[0:1], 0, v51
	v_add_u32_e32 v51, 1, v49
	s_nop 0
	v_cndmask_b32_e64 v50, v49, v50, s[0:1]
	v_fma_f32 v49, -v51, v49, v48
	v_cmp_lt_f32_e64 s[0:1], 0, v49
	s_nop 1
	v_cndmask_b32_e64 v49, v50, v51, s[0:1]
	v_mul_f32_e32 v50, 0x37800000, v49
	v_cndmask_b32_e32 v49, v49, v50, vcc
	v_cmp_class_f32_e32 vcc, v48, v229
	s_nop 1
	v_cndmask_b32_e32 v48, v49, v48, vcc
	v_div_scale_f32 v49, s[0:1], v48, v48, 1.0
	v_rcp_f32_e32 v50, v49
	s_lshl_b64 s[0:1], s[38:39], 11
	v_fma_f32 v32, -v49, v50, 1.0
	v_fmac_f32_e32 v50, v32, v50
	v_div_scale_f32 v32, vcc, 1.0, v48, 1.0
	v_mul_f32_e32 v33, v32, v50
	v_fma_f32 v34, -v49, v33, v32
	v_fmac_f32_e32 v33, v34, v50
	v_fma_f32 v32, -v49, v33, v32
	v_div_fmas_f32 v32, v32, v50, v33
	v_div_fixup_f32 v32, v32, v48, 1.0
	v_pk_mul_f32 v[34:35], v[46:47], v[46:47]
	v_pk_mul_f32 v[48:49], v[44:45], v[44:45]
	v_mul_f32_e32 v33, v36, v36
	v_pk_mov_b32 v[50:51], v[48:49], v[34:35] op_sel:[1,0]
	v_mov_b32_e32 v49, v35
	v_pk_add_f32 v[34:35], v[50:51], v[48:49]
	v_pk_mul_f32 v[48:49], v[54:55], v[54:55]
	v_pk_mul_f32 v[50:51], v[52:53], v[52:53]
	v_pk_add_f32 v[34:35], v[34:35], v[34:35] op_sel:[0,1] op_sel_hi:[1,0]
	v_pk_mov_b32 v[56:57], v[50:51], v[48:49] op_sel:[1,0]
	v_mov_b32_e32 v51, v49
	v_pk_add_f32 v[48:49], v[56:57], v[50:51]
	v_mul_f32_e32 v50, v37, v37
	v_pk_add_f32 v[48:49], v[48:49], v[48:49] op_sel:[0,1] op_sel_hi:[1,0]
	v_mov_b32_e32 v35, v33
	v_mov_b32_e32 v49, v50
	v_pk_add_f32 v[34:35], v[34:35], v[48:49]
	v_mul_f32_e32 v48, v41, v41
	v_mul_f32_e32 v51, v38, v38
	v_pk_fma_f32 v[48:49], v[40:41], v[40:41], v[48:49] op_sel_hi:[1,1,0]
	v_mul_f32_e32 v50, v43, v43
	v_mul_f32_e32 v56, v39, v39
	v_mov_b32_e32 v49, v51
	v_pk_fma_f32 v[50:51], v[42:43], v[42:43], v[50:51] op_sel_hi:[1,1,0]
	s_nop 0
	v_mov_b32_e32 v51, v56
	v_pk_add_f32 v[48:49], v[48:49], v[50:51]
	s_nop 0
	v_pk_add_f32 v[34:35], v[34:35], v[48:49]
	s_nop 0
	v_add_f32_e32 v33, v34, v35
	ds_bpermute_b32 v48, v81, v33
	v_pk_mul_f32 v[28:29], v[28:29], v[32:33] op_sel_hi:[1,0]
	v_pk_mul_f32 v[30:31], v[30:31], v[32:33] op_sel_hi:[1,0]
	v_pk_fma_f32 v[28:29], v[88:89], v[28:29], v[0:1]
	v_pk_fma_f32 v[30:31], v[86:87], v[30:31], v[2:3]
	s_waitcnt lgkmcnt(0)
	v_add_f32_e32 v33, v33, v48
	ds_bpermute_b32 v48, v102, v33
	v_cvt_pk_bf16_f32 v28, v28, v29
	v_cvt_pk_bf16_f32 v29, v30, v31
	v_lshl_add_u64 v[34:35], v[82:83], 0, s[0:1]
	global_store_dwordx2 v[34:35], v[28:29], off
	s_waitcnt lgkmcnt(0)
	v_add_f32_e32 v30, v33, v48
	ds_bpermute_b32 v31, v103, v30
	v_pk_mul_f32 v[24:25], v[24:25], v[32:33] op_sel_hi:[1,0]
	v_pk_mul_f32 v[26:27], v[26:27], v[32:33] op_sel_hi:[1,0]
	v_pk_fma_f32 v[24:25], v[92:93], v[24:25], v[4:5]
	v_pk_fma_f32 v[26:27], v[90:91], v[26:27], v[6:7]
	s_waitcnt lgkmcnt(0)
	v_add_f32_e32 v28, v30, v31
	ds_bpermute_b32 v29, v104, v28
	v_cvt_pk_bf16_f32 v24, v24, v25
	v_cvt_pk_bf16_f32 v25, v26, v27
	global_store_dwordx2 v[34:35], v[24:25], off offset:512
	v_pk_mul_f32 v[20:21], v[20:21], v[32:33] op_sel_hi:[1,0]
	s_waitcnt lgkmcnt(0)
	v_add_f32_e32 v24, v28, v29
	ds_bpermute_b32 v25, v105, v24
	v_pk_mul_f32 v[22:23], v[22:23], v[32:33] op_sel_hi:[1,0]
	v_pk_fma_f32 v[20:21], v[96:97], v[20:21], v[8:9]
	v_pk_fma_f32 v[22:23], v[94:95], v[22:23], v[10:11]
	v_cvt_pk_bf16_f32 v20, v20, v21
	s_waitcnt lgkmcnt(0)
	v_add_f32_e32 v24, v24, v25
	ds_bpermute_b32 v25, v106, v24
	v_cvt_pk_bf16_f32 v21, v22, v23
	global_store_dwordx2 v[34:35], v[20:21], off offset:1024
	v_pk_mul_f32 v[16:17], v[16:17], v[32:33] op_sel_hi:[1,0]
	v_pk_mul_f32 v[18:19], v[18:19], v[32:33] op_sel_hi:[1,0]
	s_waitcnt lgkmcnt(0)
	v_add_f32_e32 v20, v24, v25
	v_fmamk_f32 v20, v20, 0x3a800000, v228
	v_mul_f32_e32 v21, 0x4f800000, v20
	v_cmp_gt_f32_e32 vcc, s89, v20
	v_pk_fma_f32 v[18:19], v[98:99], v[18:19], v[14:15]
	v_pk_fma_f32 v[16:17], v[100:101], v[16:17], v[12:13]
	v_cndmask_b32_e32 v20, v20, v21, vcc
	v_sqrt_f32_e32 v21, v20
	v_cvt_pk_bf16_f32 v16, v16, v17
	v_cvt_pk_bf16_f32 v17, v18, v19
	global_store_dwordx2 v[34:35], v[16:17], off offset:1536
	v_add_u32_e32 v22, -1, v21
	v_fma_f32 v23, -v22, v21, v20
	v_cmp_ge_f32_e64 s[0:1], 0, v23
	v_add_u32_e32 v23, 1, v21
	s_nop 0
	v_cndmask_b32_e64 v22, v21, v22, s[0:1]
	v_fma_f32 v21, -v23, v21, v20
	v_cmp_lt_f32_e64 s[0:1], 0, v21
	s_nop 1
	v_cndmask_b32_e64 v21, v22, v23, s[0:1]
	v_mul_f32_e32 v22, 0x37800000, v21
	v_cndmask_b32_e32 v21, v21, v22, vcc
	v_cmp_class_f32_e32 vcc, v20, v229
	s_nop 1
	v_cndmask_b32_e32 v20, v21, v20, vcc
	v_div_scale_f32 v21, s[0:1], v20, v20, 1.0
	v_rcp_f32_e32 v22, v21
	s_lshl_b64 s[0:1], s[36:37], 11
	s_add_u32 s34, s34, 4
	s_addc_u32 s35, 0, s35
	v_fma_f32 v16, -v21, v22, 1.0
	v_fmac_f32_e32 v22, v16, v22
	v_div_scale_f32 v16, vcc, 1.0, v20, 1.0
	v_mul_f32_e32 v17, v16, v22
	v_fma_f32 v18, -v21, v17, v16
	v_fmac_f32_e32 v17, v18, v22
	v_fma_f32 v16, -v21, v17, v16
	v_div_fmas_f32 v16, v16, v22, v17
	v_div_fixup_f32 v16, v16, v20, 1.0
	v_pk_mul_f32 v[20:21], v[44:45], v[16:17] op_sel_hi:[1,0]
	v_pk_mul_f32 v[22:23], v[46:47], v[16:17] op_sel_hi:[1,0]
	v_pk_fma_f32 v[20:21], v[88:89], v[20:21], v[0:1]
	v_pk_fma_f32 v[22:23], v[86:87], v[22:23], v[2:3]
	v_lshl_add_u64 v[18:19], v[82:83], 0, s[0:1]
	v_cvt_pk_bf16_f32 v20, v20, v21
	v_cvt_pk_bf16_f32 v21, v22, v23
	global_store_dwordx2 v[18:19], v[20:21], off
	v_pk_mul_f32 v[20:21], v[52:53], v[16:17] op_sel_hi:[1,0]
	v_pk_mul_f32 v[22:23], v[54:55], v[16:17] op_sel_hi:[1,0]
	v_pk_fma_f32 v[20:21], v[92:93], v[20:21], v[4:5]
	v_pk_fma_f32 v[22:23], v[90:91], v[22:23], v[6:7]
	v_cvt_pk_bf16_f32 v20, v20, v21
	v_cvt_pk_bf16_f32 v21, v22, v23
	global_store_dwordx2 v[18:19], v[20:21], off offset:512
	v_pk_mul_f32 v[20:21], v[40:41], v[16:17] op_sel_hi:[1,0]
	v_pk_mul_f32 v[22:23], v[42:43], v[16:17] op_sel_hi:[1,0]
	v_pk_fma_f32 v[20:21], v[96:97], v[20:21], v[8:9]
	v_pk_fma_f32 v[22:23], v[94:95], v[22:23], v[10:11]
	v_cvt_pk_bf16_f32 v20, v20, v21
	v_cvt_pk_bf16_f32 v21, v22, v23
	global_store_dwordx2 v[18:19], v[20:21], off offset:1024
	v_pk_mul_f32 v[20:21], v[36:37], v[16:17] op_sel_hi:[1,0]
	v_pk_mul_f32 v[16:17], v[38:39], v[16:17] op_sel_hi:[1,0]
	v_pk_fma_f32 v[20:21], v[100:101], v[20:21], v[12:13]
	v_pk_fma_f32 v[16:17], v[98:99], v[16:17], v[14:15]
	v_cvt_pk_bf16_f32 v20, v20, v21
	v_cvt_pk_bf16_f32 v21, v16, v17
	s_cmp_ge_i32 s34, s3
	global_store_dwordx2 v[18:19], v[20:21], off offset:1536
	s_cbranch_scc1 .LBB0_148

.LBB0_180:
	s_waitcnt lgkmcnt(0)
	v_mov_b64_e32 v[0:1], s[48:49]
	v_mov_b64_e32 v[2:3], s[60:61]
	global_load_dword v0, v[0:1], off sc1
	v_mov_b64_e32 v[4:5], s[76:77]
	global_load_dword v1, v[2:3], off sc1
	v_mov_b64_e32 v[2:3], s[62:63]
	v_readlane_b32 s8, v252, 44
	global_load_dword v2, v[2:3], off sc1
	v_mov_b64_e32 v[6:7], s[20:21]
	global_load_dword v3, v[4:5], off sc1
	v_mov_b64_e32 v[4:5], s[18:19]
	v_readlane_b32 s9, v252, 45
	global_load_dword v4, v[4:5], off sc1
	v_mov_b64_e32 v[12:13], s[54:55]
	global_load_dword v5, v[6:7], off sc1
	v_mov_b64_e32 v[6:7], s[8:9]
	v_readlane_b32 s8, v252, 46
	v_readlane_b32 s9, v252, 47
	global_load_dword v6, v[6:7], off sc1
	v_mov_b64_e32 v[14:15], s[66:67]
	v_mov_b64_e32 v[8:9], s[8:9]
	v_readlane_b32 s8, v252, 48
	v_readlane_b32 s9, v252, 49
	global_load_dword v7, v[8:9], off sc1
	s_or_b64 s[40:41], s[40:41], exec
	v_mov_b64_e32 v[8:9], s[8:9]
	v_readlane_b32 s8, v252, 50
	v_readlane_b32 s9, v252, 51
	global_load_dword v8, v[8:9], off sc1
	s_or_b64 s[38:39], s[38:39], exec
	v_mov_b64_e32 v[10:11], s[8:9]
	v_readlane_b32 s8, v252, 52
	v_readlane_b32 s9, v252, 53
	global_load_dword v9, v[10:11], off sc1
	s_nop 0
	v_mov_b64_e32 v[10:11], s[8:9]
	global_load_dword v10, v[10:11], off sc1
	v_readlane_b32 s8, v252, 54
	global_load_dword v11, v[12:13], off sc1
	v_mov_b64_e32 v[12:13], s[64:65]
	v_readlane_b32 s9, v252, 55
	global_load_dword v12, v[12:13], off sc1
	s_nop 0
	global_load_dword v13, v[14:15], off sc1
	v_mov_b64_e32 v[14:15], s[8:9]
	v_readlane_b32 s8, v252, 56
	v_readlane_b32 s9, v252, 57
	global_load_dword v14, v[14:15], off sc1
	s_nop 0
	v_mov_b64_e32 v[16:17], s[8:9]
	global_load_dword v15, v[16:17], off sc1
	s_waitcnt vmcnt(0) lgkmcnt(0)
	v_add_u32_e32 v16, v1, v0
	v_add_u32_e32 v16, v16, v2
	v_add_u32_e32 v16, v16, v3
	v_add_u32_e32 v16, v16, v4
	v_add_u32_e32 v16, v16, v5
	v_add_u32_e32 v16, v16, v6
	v_add_u32_e32 v16, v16, v7
	v_add_u32_e32 v16, v16, v8
	v_add_u32_e32 v16, v16, v9
	v_add_u32_e32 v16, v16, v10
	v_add_u32_e32 v16, v16, v11
	v_add_u32_e32 v16, v16, v12
	v_add_u32_e32 v16, v16, v13
	v_add_u32_e32 v16, v16, v14
	v_add_u32_e32 v16, v16, v15
	v_cmp_ne_u32_e32 vcc, s6, v16
	s_and_saveexec_b64 s[42:43], vcc
	s_cbranch_execz .LBB0_179
	s_and_b32 s22, s3, 0xff
	s_mov_b64 s[44:45], -1
	s_cmp_eq_u32 s22, 0
	s_mov_b64 s[68:69], -1
	s_mov_b64 s[46:47], -1
	s_sleep 1
	s_cbranch_scc1 .LBB0_183
	s_and_saveexec_b64 s[70:71], s[68:69]
	s_cbranch_execz .LBB0_178
	s_branch .LBB0_186
.LBB0_183:
	v_readlane_b32 s8, v252, 42
	v_readlane_b32 s9, v252, 43
	s_mov_b64 s[68:69], 0
	s_nop 0
	v_mov_b64_e32 v[16:17], s[8:9]
	global_load_dword v16, v[16:17], off sc1
	s_waitcnt vmcnt(0) lgkmcnt(0)
	v_cmp_eq_u32_e32 vcc, 0, v16
	s_and_saveexec_b64 s[70:71], vcc
	s_cmp_lt_u32 s3, 0x400001
	s_cselect_b64 s[58:59], -1, 0
	s_xor_b64 s[46:47], exec, -1
	s_and_b64 s[68:69], s[58:59], exec
	s_or_b64 exec, exec, s[70:71]
	s_and_saveexec_b64 s[70:71], s[68:69]
	s_cbranch_execz .LBB0_178

.LBB0_187:
	s_or_b64 exec, exec, s[34:35]
	s_xor_b64 s[34:35], s[36:37], -1
	s_and_saveexec_b64 s[36:37], s[34:35]
	s_xor_b64 s[34:35], exec, s[36:37]
	s_cbranch_execz .LBB0_189
	v_readlane_b32 s8, v252, 42
	v_readlane_b32 s9, v252, 43
	s_nop 1
	v_mov_b64_e32 v[16:17], s[8:9]
	global_atomic_add v[16:17], v230, off

.LBB0_190:
	v_readlane_b32 s8, v253, 26
	v_readlane_b32 s9, v253, 27
	v_cvt_f32_u32_e32 v3, v2
	v_rcp_iflag_f32_e32 v3, v3
	v_mov_b64_e32 v[4:5], s[8:9]
	global_atomic_add v1, v[4:5], v230, off sc0
	v_sub_u32_e32 v4, 0, v2
	v_mul_f32_e32 v3, 0x4f7ffffe, v3
	v_cvt_u32_f32_e32 v3, v3
	v_mul_lo_u32 v4, v4, v3
	v_mul_hi_u32 v4, v3, v4
	v_add_u32_e32 v3, v3, v4
	s_waitcnt vmcnt(0) lgkmcnt(0)
	v_mul_hi_u32 v3, v1, v3
	v_mul_lo_u32 v5, v3, v2
	v_add_u32_e32 v4, 1, v1
	v_sub_u32_e32 v1, v1, v5
	v_add_u32_e32 v6, 1, v3
	v_cmp_ge_u32_e32 vcc, v1, v2
	v_sub_u32_e32 v5, v1, v2
	s_nop 0
	v_cndmask_b32_e32 v3, v3, v6, vcc
	v_cndmask_b32_e32 v1, v1, v5, vcc
	v_add_u32_e32 v5, 1, v3
	v_cmp_ge_u32_e32 vcc, v1, v2
	s_nop 1
	v_cndmask_b32_e32 v1, v3, v5, vcc
	v_mad_u64_u32 v[2:3], s[34:35], v2, v1, v[2:3]
	v_cmp_ne_u32_e32 vcc, v4, v2
	s_and_saveexec_b64 s[34:35], vcc
	s_xor_b64 s[34:35], exec, s[34:35]
	s_cbranch_execz .LBB0_203
	v_readlane_b32 s8, v253, 28
	v_readlane_b32 s9, v253, 29
	s_nop 1
	v_mov_b64_e32 v[2:3], s[8:9]
	global_load_dword v0, v[2:3], off sc1
	s_waitcnt vmcnt(0) lgkmcnt(0)
	v_cmp_eq_u32_e32 vcc, v0, v1
	s_and_saveexec_b64 s[36:37], vcc
	s_cbranch_execz .LBB0_202
	s_mov_b32 s3, 1
	s_mov_b64 s[38:39], 0
	s_branch .LBB0_194

.LBB0_194:
	s_and_b32 s22, s3, 0xff
	s_mov_b64 s[44:45], -1
	s_cmp_lg_u32 s22, 0
	s_mov_b64 s[46:47], -1
	s_sleep 1
	s_cbranch_scc1 .LBB0_198
	v_readlane_b32 s8, v252, 42
	v_readlane_b32 s9, v252, 43
	s_mov_b64 s[46:47], 0
	s_mov_b64 s[68:69], -1
	v_mov_b64_e32 v[2:3], s[8:9]
	global_load_dword v0, v[2:3], off sc1
	s_waitcnt vmcnt(0) lgkmcnt(0)
	v_cmp_eq_u32_e32 vcc, 0, v0
	s_and_saveexec_b64 s[70:71], vcc
	s_cmp_lt_u32 s3, 0x400001
	s_cselect_b64 s[46:47], -1, 0
	s_xor_b64 s[68:69], exec, -1
	s_and_b64 s[46:47], s[46:47], exec
	s_or_b64 exec, exec, s[70:71]
.LBB0_198:
	s_andn2_b64 s[42:43], s[42:43], exec
	s_and_b64 s[58:59], s[68:69], exec
	s_or_b64 s[42:43], s[42:43], s[58:59]
	s_and_saveexec_b64 s[68:69], s[46:47]
	s_cbranch_execz .LBB0_193
	v_readlane_b32 s8, v253, 28
	v_readlane_b32 s9, v253, 29
	s_add_i32 s3, s3, 1
	s_or_b64 s[42:43], s[42:43], exec
	v_mov_b64_e32 v[2:3], s[8:9]
	global_load_dword v0, v[2:3], off sc1
	s_waitcnt vmcnt(0) lgkmcnt(0)
	v_cmp_ne_u32_e32 vcc, v0, v1
	s_orn2_b64 s[44:45], vcc, exec
	s_branch .LBB0_193
.LBB0_200:
	s_or_b64 exec, exec, s[38:39]
	s_xor_b64 s[38:39], s[40:41], -1
	s_and_saveexec_b64 s[40:41], s[38:39]
	s_xor_b64 s[40:41], exec, s[40:41]
	s_cbranch_execz .LBB0_202
	v_readlane_b32 s8, v252, 42
	v_readlane_b32 s9, v252, 43
	s_nop 1
	v_mov_b64_e32 v[0:1], s[8:9]
	global_atomic_add v[0:1], v230, off

.LBB0_203:
	s_andn2_saveexec_b64 s[34:35], s[34:35]
	s_cbranch_execz .LBB0_219
	v_readlane_b32 s8, v253, 30
	v_readlane_b32 s9, v253, 31
	buffer_wbl2 sc1
	s_waitcnt vmcnt(0)
	s_mov_b64 s[36:37], -1
	v_mov_b64_e32 v[2:3], s[8:9]
	global_atomic_add v1, v[2:3], v230, off sc0
	v_cvt_f32_u32_e32 v2, v0
	v_sub_u32_e32 v3, 0, v0
	v_readlane_b32 s8, v253, 32
	v_readlane_b32 s9, v253, 33
	v_rcp_iflag_f32_e32 v2, v2
	s_nop 0
	v_mul_f32_e32 v2, 0x4f7ffffe, v2
	v_cvt_u32_f32_e32 v2, v2
	v_mul_lo_u32 v3, v3, v2
	v_mul_hi_u32 v3, v2, v3
	v_add_u32_e32 v2, v2, v3
	s_waitcnt vmcnt(0) lgkmcnt(0)
	v_mul_hi_u32 v2, v1, v2
	v_mul_lo_u32 v4, v2, v0
	v_add_u32_e32 v3, 1, v1
	v_sub_u32_e32 v1, v1, v4
	v_add_u32_e32 v5, 1, v2
	v_cmp_ge_u32_e32 vcc, v1, v0
	v_sub_u32_e32 v4, v1, v0
	s_nop 0
	v_cndmask_b32_e32 v2, v2, v5, vcc
	v_cndmask_b32_e32 v1, v1, v4, vcc
	v_add_u32_e32 v4, 1, v2
	v_cmp_ge_u32_e32 vcc, v1, v0
	s_nop 1
	v_cndmask_b32_e32 v2, v2, v4, vcc
	v_mad_u64_u32 v[0:1], s[34:35], v0, v2, v[0:1]
	v_cmp_ne_u32_e32 vcc, v3, v0
	v_mov_b64_e32 v[0:1], s[8:9]
	s_and_saveexec_b64 s[34:35], vcc
	s_cbranch_execz .LBB0_216
	v_readlane_b32 s8, v253, 32
	v_readlane_b32 s9, v253, 33
	s_mov_b64 s[38:39], 0
	s_nop 0
	v_mov_b64_e32 v[0:1], s[8:9]
	global_load_dword v0, v[0:1], off sc1
	s_waitcnt vmcnt(0) lgkmcnt(0)
	v_cmp_eq_u32_e32 vcc, v0, v2
	s_and_saveexec_b64 s[36:37], vcc
	s_cbranch_execz .LBB0_215
	s_mov_b32 s3, 1
	s_branch .LBB0_208

.LBB0_210:
	v_readlane_b32 s8, v252, 42
	v_readlane_b32 s9, v252, 43
	s_mov_b64 s[46:47], 0
	s_mov_b64 s[44:45], -1
	v_mov_b64_e32 v[0:1], s[8:9]
	global_load_dword v0, v[0:1], off sc1
	s_waitcnt vmcnt(0) lgkmcnt(0)
	v_cmp_eq_u32_e32 vcc, 0, v0
	s_and_saveexec_b64 s[68:69], vcc
	s_cmp_lt_u32 s3, 0x400001
	s_cselect_b64 s[46:47], -1, 0
	s_xor_b64 s[44:45], exec, -1
	s_and_b64 s[46:47], s[46:47], exec
	s_or_b64 exec, exec, s[68:69]
	s_and_saveexec_b64 s[68:69], s[46:47]
	s_cbranch_execz .LBB0_207
.LBB0_213:
	v_readlane_b32 s8, v253, 32
	v_readlane_b32 s9, v253, 33
	s_add_i32 s3, s3, 1
	s_or_b64 s[44:45], s[44:45], exec
	v_mov_b64_e32 v[0:1], s[8:9]
	global_load_dword v0, v[0:1], off sc1
	s_waitcnt vmcnt(0) lgkmcnt(0)
	v_cmp_ne_u32_e32 vcc, v0, v2
	s_orn2_b64 s[42:43], vcc, exec
	s_branch .LBB0_207

.LBB0_216:
	s_or_b64 exec, exec, s[34:35]
	s_and_saveexec_b64 s[34:35], s[36:37]
	s_cbranch_execz .LBB0_218
	global_atomic_add v[0:1], v230, off

.LBB0_231:
	v_mul_f32_e32 v138, 0xbfb8aa3b, v124
	v_exp_f32_e32 v138, v138
	v_mul_f32_e32 v139, 0xbfb8aa3b, v125
	v_exp_f32_e32 v139, v139
	v_mul_f32_e32 v145, 0xbfb8aa3b, v126
	v_add_f32_e32 v138, 1.0, v138
	v_rcp_f32_e32 v148, v138
	v_add_f32_e32 v138, 1.0, v139
	v_rcp_f32_e32 v149, v138
	v_exp_f32_e32 v145, v145
	v_lshl_or_b32 v146, s78, 7, v142
	v_lshl_add_u32 v144, s79, 8, v140
	v_pk_mul_f32 v[124:125], v[124:125], v[148:149]
	v_mul_f32_e32 v148, 0xbfb8aa3b, v127
	v_exp_f32_e32 v148, v148
	v_pk_mul_f32 v[116:117], v[124:125], v[116:117]
	v_add_f32_e32 v124, 1.0, v145
	v_mul_f32_e32 v145, 0xbfb8aa3b, v120
	v_add_f32_e32 v125, 1.0, v148
	v_rcp_f32_e32 v124, v124
	v_rcp_f32_e32 v125, v125
	v_exp_f32_e32 v145, v145
	v_mul_f32_e32 v148, 0xbfb8aa3b, v121
	v_exp_f32_e32 v148, v148
	v_pk_mul_f32 v[124:125], v[126:127], v[124:125]
	v_add_f32_e32 v126, 1.0, v145
	v_mul_f32_e32 v145, 0xbfb8aa3b, v122
	v_add_f32_e32 v127, 1.0, v148
	v_exp_f32_e32 v145, v145
	v_mul_f32_e32 v148, 0xbfb8aa3b, v123
	v_exp_f32_e32 v149, v148
	v_rcp_f32_e32 v126, v126
	v_add_f32_e32 v145, 1.0, v145
	v_rcp_f32_e32 v127, v127
	v_rcp_f32_e32 v148, v145
	v_add_f32_e32 v145, 1.0, v149
	v_rcp_f32_e32 v149, v145
	v_pk_mul_f32 v[120:121], v[120:121], v[126:127]
	v_pk_mul_f32 v[118:119], v[124:125], v[118:119]
	v_pk_mul_f32 v[120:121], v[120:121], v[112:113]
	v_pk_mul_f32 v[112:113], v[122:123], v[148:149]
	v_ashrrev_i32_e32 v147, 31, v146
	v_pk_mul_f32 v[122:123], v[112:113], v[114:115]
	v_cvt_pk_bf16_f32 v115, v118, v119
	v_mul_f32_e32 v118, 0xbfb8aa3b, v108
	v_mul_f32_e32 v119, 0xbfb8aa3b, v109
	v_exp_f32_e32 v118, v118
	v_exp_f32_e32 v119, v119
	v_mov_b64_e32 v[138:139], s[34:35]
	v_mad_i64_i32 v[150:151], s[68:69], v144, s29, v[138:139]
	v_lshlrev_b64 v[112:113], 1, v[146:147]
	v_lshl_add_u64 v[124:125], v[150:151], 0, v[112:113]
	v_cvt_pk_bf16_f32 v114, v116, v117
	v_cvt_pk_bf16_f32 v116, v120, v121
	v_cvt_pk_bf16_f32 v117, v122, v123
	global_store_dwordx4 v[124:125], v[114:117], off
	s_andn2_b64 vcc, exec, s[36:37]
	s_mov_b64 s[36:37], -1
	v_add_f32_e32 v114, 1.0, v118
	v_add_f32_e32 v115, 1.0, v119
	v_rcp_f32_e32 v114, v114
	v_rcp_f32_e32 v115, v115
	v_or_b32_e32 v116, 16, v144
	v_mad_i64_i32 v[116:117], s[68:69], v116, s29, v[138:139]
	v_pk_mul_f32 v[108:109], v[108:109], v[114:115]
	v_mul_f32_e32 v114, 0xbfb8aa3b, v110
	v_mul_f32_e32 v115, 0xbfb8aa3b, v111
	v_exp_f32_e32 v114, v114
	v_exp_f32_e32 v115, v115
	v_pk_mul_f32 v[100:101], v[108:109], v[100:101]
	v_add_f32_e32 v108, 1.0, v114
	v_add_f32_e32 v109, 1.0, v115
	v_mul_f32_e32 v114, 0xbfb8aa3b, v104
	v_mul_f32_e32 v115, 0xbfb8aa3b, v105
	v_rcp_f32_e32 v108, v108
	v_rcp_f32_e32 v109, v109
	v_exp_f32_e32 v114, v114
	v_exp_f32_e32 v115, v115
	v_pk_mul_f32 v[108:109], v[110:111], v[108:109]
	v_add_f32_e32 v110, 1.0, v114
	v_add_f32_e32 v111, 1.0, v115
	v_mul_f32_e32 v114, 0xbfb8aa3b, v106
	v_mul_f32_e32 v115, 0xbfb8aa3b, v107
	v_exp_f32_e32 v114, v114
	v_exp_f32_e32 v115, v115
	v_rcp_f32_e32 v110, v110
	v_rcp_f32_e32 v111, v111
	v_add_f32_e32 v114, 1.0, v114
	v_add_f32_e32 v115, 1.0, v115
	v_rcp_f32_e32 v114, v114
	v_rcp_f32_e32 v115, v115
	v_pk_mul_f32 v[104:105], v[104:105], v[110:111]
	v_pk_mul_f32 v[102:103], v[108:109], v[102:103]
	v_pk_mul_f32 v[104:105], v[104:105], v[96:97]
	v_pk_mul_f32 v[96:97], v[106:107], v[114:115]
	v_lshl_add_u64 v[108:109], v[116:117], 0, v[112:113]
	v_pk_mul_f32 v[106:107], v[96:97], v[98:99]
	v_cvt_pk_bf16_f32 v96, v100, v101
	v_mul_f32_e32 v100, 0xbfb8aa3b, v92
	v_mul_f32_e32 v101, 0xbfb8aa3b, v93
	v_exp_f32_e32 v100, v100
	v_exp_f32_e32 v101, v101
	v_cvt_pk_bf16_f32 v97, v102, v103
	v_cvt_pk_bf16_f32 v98, v104, v105
	v_cvt_pk_bf16_f32 v99, v106, v107
	global_store_dwordx4 v[108:109], v[96:99], off
	s_nop 1
	v_add_f32_e32 v96, 1.0, v100
	v_add_f32_e32 v97, 1.0, v101
	v_rcp_f32_e32 v96, v96
	v_rcp_f32_e32 v97, v97
	v_or_b32_e32 v98, 32, v144
	v_mad_i64_i32 v[98:99], s[68:69], v98, s29, v[138:139]
	v_pk_mul_f32 v[92:93], v[92:93], v[96:97]
	v_mul_f32_e32 v96, 0xbfb8aa3b, v94
	v_mul_f32_e32 v97, 0xbfb8aa3b, v95
	v_exp_f32_e32 v96, v96
	v_exp_f32_e32 v97, v97
	v_pk_mul_f32 v[84:85], v[92:93], v[84:85]
	v_add_f32_e32 v92, 1.0, v96
	v_add_f32_e32 v93, 1.0, v97
	v_mul_f32_e32 v96, 0xbfb8aa3b, v88
	v_mul_f32_e32 v97, 0xbfb8aa3b, v89
	v_rcp_f32_e32 v92, v92
	v_rcp_f32_e32 v93, v93
	v_exp_f32_e32 v96, v96
	v_exp_f32_e32 v97, v97
	v_pk_mul_f32 v[92:93], v[94:95], v[92:93]
	v_add_f32_e32 v94, 1.0, v96
	v_add_f32_e32 v95, 1.0, v97
	v_mul_f32_e32 v96, 0xbfb8aa3b, v90
	v_mul_f32_e32 v97, 0xbfb8aa3b, v91
	v_exp_f32_e32 v96, v96
	v_exp_f32_e32 v97, v97
	v_rcp_f32_e32 v94, v94
	v_rcp_f32_e32 v95, v95
	v_add_f32_e32 v96, 1.0, v96
	v_add_f32_e32 v97, 1.0, v97
	v_rcp_f32_e32 v96, v96
	v_rcp_f32_e32 v97, v97
	v_pk_mul_f32 v[88:89], v[88:89], v[94:95]
	v_pk_mul_f32 v[86:87], v[92:93], v[86:87]
	v_pk_mul_f32 v[88:89], v[88:89], v[80:81]
	v_pk_mul_f32 v[80:81], v[90:91], v[96:97]
	v_lshl_add_u64 v[92:93], v[98:99], 0, v[112:113]
	v_pk_mul_f32 v[90:91], v[80:81], v[82:83]
	v_cvt_pk_bf16_f32 v80, v84, v85
	v_mul_f32_e32 v84, 0xbfb8aa3b, v76
	v_mul_f32_e32 v85, 0xbfb8aa3b, v77
	v_exp_f32_e32 v84, v84
	v_exp_f32_e32 v85, v85
	v_cvt_pk_bf16_f32 v81, v86, v87
	v_cvt_pk_bf16_f32 v82, v88, v89
	v_cvt_pk_bf16_f32 v83, v90, v91
	global_store_dwordx4 v[92:93], v[80:83], off
	s_nop 1
	v_add_f32_e32 v80, 1.0, v84
	v_add_f32_e32 v81, 1.0, v85
	v_rcp_f32_e32 v80, v80
	v_rcp_f32_e32 v81, v81
	v_or_b32_e32 v82, 48, v144
	v_mad_i64_i32 v[82:83], s[68:69], v82, s29, v[138:139]
	v_pk_mul_f32 v[76:77], v[76:77], v[80:81]
	v_mul_f32_e32 v80, 0xbfb8aa3b, v78
	v_mul_f32_e32 v81, 0xbfb8aa3b, v79
	v_exp_f32_e32 v80, v80
	v_exp_f32_e32 v81, v81
	v_pk_mul_f32 v[68:69], v[76:77], v[68:69]
	v_add_f32_e32 v76, 1.0, v80
	v_add_f32_e32 v77, 1.0, v81
	v_mul_f32_e32 v80, 0xbfb8aa3b, v72
	v_mul_f32_e32 v81, 0xbfb8aa3b, v73
	v_rcp_f32_e32 v76, v76
	v_rcp_f32_e32 v77, v77
	v_exp_f32_e32 v80, v80
	v_exp_f32_e32 v81, v81
	v_pk_mul_f32 v[76:77], v[78:79], v[76:77]
	v_add_f32_e32 v78, 1.0, v80
	v_add_f32_e32 v79, 1.0, v81
	v_mul_f32_e32 v80, 0xbfb8aa3b, v74
	v_mul_f32_e32 v81, 0xbfb8aa3b, v75
	v_exp_f32_e32 v80, v80
	v_exp_f32_e32 v81, v81
	v_rcp_f32_e32 v78, v78
	v_rcp_f32_e32 v79, v79
	v_add_f32_e32 v80, 1.0, v80
	v_add_f32_e32 v81, 1.0, v81
	v_rcp_f32_e32 v80, v80
	v_rcp_f32_e32 v81, v81
	v_pk_mul_f32 v[72:73], v[72:73], v[78:79]
	v_pk_mul_f32 v[70:71], v[76:77], v[70:71]
	v_pk_mul_f32 v[72:73], v[72:73], v[64:65]
	v_pk_mul_f32 v[64:65], v[74:75], v[80:81]
	v_lshl_add_u64 v[76:77], v[82:83], 0, v[112:113]
	v_pk_mul_f32 v[74:75], v[64:65], v[66:67]
	v_cvt_pk_bf16_f32 v64, v68, v69
	v_mul_f32_e32 v68, 0xbfb8aa3b, v60
	v_mul_f32_e32 v69, 0xbfb8aa3b, v61
	v_exp_f32_e32 v68, v68
	v_exp_f32_e32 v69, v69
	v_cvt_pk_bf16_f32 v65, v70, v71
	v_cvt_pk_bf16_f32 v66, v72, v73
	v_cvt_pk_bf16_f32 v67, v74, v75
	global_store_dwordx4 v[76:77], v[64:67], off
	s_nop 1
	v_add_f32_e32 v64, 1.0, v68
	v_add_f32_e32 v65, 1.0, v69
	v_rcp_f32_e32 v64, v64
	v_rcp_f32_e32 v65, v65
	v_add_u32_e32 v66, 0x80, v144
	v_mad_i64_i32 v[66:67], s[68:69], v66, s29, v[138:139]
	v_pk_mul_f32 v[60:61], v[60:61], v[64:65]
	v_mul_f32_e32 v64, 0xbfb8aa3b, v62
	v_mul_f32_e32 v65, 0xbfb8aa3b, v63
	v_exp_f32_e32 v64, v64
	v_exp_f32_e32 v65, v65
	v_pk_mul_f32 v[52:53], v[60:61], v[52:53]
	v_add_f32_e32 v60, 1.0, v64
	v_add_f32_e32 v61, 1.0, v65
	v_mul_f32_e32 v64, 0xbfb8aa3b, v56
	v_mul_f32_e32 v65, 0xbfb8aa3b, v57
	v_rcp_f32_e32 v60, v60
	v_rcp_f32_e32 v61, v61
	v_exp_f32_e32 v64, v64
	v_exp_f32_e32 v65, v65
	v_pk_mul_f32 v[60:61], v[62:63], v[60:61]
	v_add_f32_e32 v62, 1.0, v64
	v_add_f32_e32 v63, 1.0, v65
	v_mul_f32_e32 v64, 0xbfb8aa3b, v58
	v_mul_f32_e32 v65, 0xbfb8aa3b, v59
	v_exp_f32_e32 v64, v64
	v_exp_f32_e32 v65, v65
	v_rcp_f32_e32 v62, v62
	v_rcp_f32_e32 v63, v63
	v_add_f32_e32 v64, 1.0, v64
	v_add_f32_e32 v65, 1.0, v65
	v_rcp_f32_e32 v64, v64
	v_rcp_f32_e32 v65, v65
	v_pk_mul_f32 v[56:57], v[56:57], v[62:63]
	v_pk_mul_f32 v[54:55], v[60:61], v[54:55]
	v_pk_mul_f32 v[56:57], v[56:57], v[48:49]
	v_pk_mul_f32 v[48:49], v[58:59], v[64:65]
	v_lshl_add_u64 v[60:61], v[66:67], 0, v[112:113]
	v_pk_mul_f32 v[58:59], v[48:49], v[50:51]
	v_cvt_pk_bf16_f32 v48, v52, v53
	v_mul_f32_e32 v52, 0xbfb8aa3b, v44
	v_mul_f32_e32 v53, 0xbfb8aa3b, v45
	v_exp_f32_e32 v52, v52
	v_exp_f32_e32 v53, v53
	v_cvt_pk_bf16_f32 v49, v54, v55
	v_cvt_pk_bf16_f32 v50, v56, v57
	v_cvt_pk_bf16_f32 v51, v58, v59
	global_store_dwordx4 v[60:61], v[48:51], off
	s_nop 1
	v_add_f32_e32 v48, 1.0, v52
	v_add_f32_e32 v49, 1.0, v53
	v_rcp_f32_e32 v48, v48
	v_rcp_f32_e32 v49, v49
	v_add_u32_e32 v50, 0x90, v144
	v_mad_i64_i32 v[50:51], s[68:69], v50, s29, v[138:139]
	v_pk_mul_f32 v[44:45], v[44:45], v[48:49]
	v_mul_f32_e32 v48, 0xbfb8aa3b, v46
	v_mul_f32_e32 v49, 0xbfb8aa3b, v47
	v_exp_f32_e32 v48, v48
	v_exp_f32_e32 v49, v49
	v_pk_mul_f32 v[36:37], v[44:45], v[36:37]
	v_add_f32_e32 v44, 1.0, v48
	v_add_f32_e32 v45, 1.0, v49
	v_mul_f32_e32 v48, 0xbfb8aa3b, v40
	v_mul_f32_e32 v49, 0xbfb8aa3b, v41
	v_rcp_f32_e32 v44, v44
	v_rcp_f32_e32 v45, v45
	v_exp_f32_e32 v48, v48
	v_exp_f32_e32 v49, v49
	v_pk_mul_f32 v[44:45], v[46:47], v[44:45]
	v_add_f32_e32 v46, 1.0, v48
	v_add_f32_e32 v47, 1.0, v49
	v_mul_f32_e32 v48, 0xbfb8aa3b, v42
	v_mul_f32_e32 v49, 0xbfb8aa3b, v43
	v_exp_f32_e32 v48, v48
	v_exp_f32_e32 v49, v49
	v_rcp_f32_e32 v46, v46
	v_rcp_f32_e32 v47, v47
	v_add_f32_e32 v48, 1.0, v48
	v_add_f32_e32 v49, 1.0, v49
	v_rcp_f32_e32 v48, v48
	v_rcp_f32_e32 v49, v49
	v_pk_mul_f32 v[40:41], v[40:41], v[46:47]
	v_pk_mul_f32 v[38:39], v[44:45], v[38:39]
	v_pk_mul_f32 v[40:41], v[40:41], v[32:33]
	v_pk_mul_f32 v[32:33], v[42:43], v[48:49]
	v_lshl_add_u64 v[44:45], v[50:51], 0, v[112:113]
	v_pk_mul_f32 v[42:43], v[32:33], v[34:35]
	v_cvt_pk_bf16_f32 v32, v36, v37
	v_mul_f32_e32 v36, 0xbfb8aa3b, v28
	v_mul_f32_e32 v37, 0xbfb8aa3b, v29
	v_exp_f32_e32 v36, v36
	v_exp_f32_e32 v37, v37
	v_cvt_pk_bf16_f32 v33, v38, v39
	v_cvt_pk_bf16_f32 v34, v40, v41
	v_cvt_pk_bf16_f32 v35, v42, v43
	global_store_dwordx4 v[44:45], v[32:35], off
	s_nop 1
	v_add_f32_e32 v32, 1.0, v36
	v_add_f32_e32 v33, 1.0, v37
	v_rcp_f32_e32 v32, v32
	v_rcp_f32_e32 v33, v33
	v_add_u32_e32 v34, 0xa0, v144
	v_mad_i64_i32 v[34:35], s[68:69], v34, s29, v[138:139]
	v_pk_mul_f32 v[28:29], v[28:29], v[32:33]
	v_mul_f32_e32 v32, 0xbfb8aa3b, v30
	v_mul_f32_e32 v33, 0xbfb8aa3b, v31
	v_exp_f32_e32 v32, v32
	v_exp_f32_e32 v33, v33
	v_pk_mul_f32 v[20:21], v[28:29], v[20:21]
	v_add_f32_e32 v28, 1.0, v32
	v_add_f32_e32 v29, 1.0, v33
	v_mul_f32_e32 v32, 0xbfb8aa3b, v24
	v_mul_f32_e32 v33, 0xbfb8aa3b, v25
	v_rcp_f32_e32 v28, v28
	v_rcp_f32_e32 v29, v29
	v_exp_f32_e32 v32, v32
	v_exp_f32_e32 v33, v33
	v_pk_mul_f32 v[28:29], v[30:31], v[28:29]
	v_add_f32_e32 v30, 1.0, v32
	v_add_f32_e32 v31, 1.0, v33
	v_mul_f32_e32 v32, 0xbfb8aa3b, v26
	v_mul_f32_e32 v33, 0xbfb8aa3b, v27
	v_exp_f32_e32 v32, v32
	v_exp_f32_e32 v33, v33
	v_rcp_f32_e32 v30, v30
	v_rcp_f32_e32 v31, v31
	v_add_f32_e32 v32, 1.0, v32
	v_add_f32_e32 v33, 1.0, v33
	v_rcp_f32_e32 v32, v32
	v_rcp_f32_e32 v33, v33
	v_pk_mul_f32 v[24:25], v[24:25], v[30:31]
	v_pk_mul_f32 v[22:23], v[28:29], v[22:23]
	v_pk_mul_f32 v[24:25], v[24:25], v[16:17]
	v_pk_mul_f32 v[16:17], v[26:27], v[32:33]
	v_lshl_add_u64 v[28:29], v[34:35], 0, v[112:113]
	v_pk_mul_f32 v[26:27], v[16:17], v[18:19]
	v_cvt_pk_bf16_f32 v16, v20, v21
	v_mul_f32_e32 v20, 0xbfb8aa3b, v12
	v_mul_f32_e32 v21, 0xbfb8aa3b, v13
	v_exp_f32_e32 v20, v20
	v_exp_f32_e32 v21, v21
	v_cvt_pk_bf16_f32 v17, v22, v23
	v_cvt_pk_bf16_f32 v18, v24, v25
	v_cvt_pk_bf16_f32 v19, v26, v27
	global_store_dwordx4 v[28:29], v[16:19], off
	s_nop 1
	v_add_f32_e32 v16, 1.0, v20
	v_add_f32_e32 v17, 1.0, v21
	v_rcp_f32_e32 v16, v16
	v_rcp_f32_e32 v17, v17
	v_add_u32_e32 v18, 0xb0, v144
	v_mad_i64_i32 v[18:19], s[68:69], v18, s29, v[138:139]
	v_pk_mul_f32 v[12:13], v[12:13], v[16:17]
	v_mul_f32_e32 v16, 0xbfb8aa3b, v14
	v_mul_f32_e32 v17, 0xbfb8aa3b, v15
	v_exp_f32_e32 v16, v16
	v_exp_f32_e32 v17, v17
	v_pk_mul_f32 v[4:5], v[12:13], v[4:5]
	v_add_f32_e32 v12, 1.0, v16
	v_add_f32_e32 v13, 1.0, v17
	v_mul_f32_e32 v16, 0xbfb8aa3b, v8
	v_mul_f32_e32 v17, 0xbfb8aa3b, v9
	v_rcp_f32_e32 v12, v12
	v_rcp_f32_e32 v13, v13
	v_exp_f32_e32 v16, v16
	v_exp_f32_e32 v17, v17
	v_pk_mul_f32 v[12:13], v[14:15], v[12:13]
	v_add_f32_e32 v14, 1.0, v16
	v_add_f32_e32 v15, 1.0, v17
	v_mul_f32_e32 v16, 0xbfb8aa3b, v10
	v_mul_f32_e32 v17, 0xbfb8aa3b, v11
	v_exp_f32_e32 v16, v16
	v_exp_f32_e32 v17, v17
	v_rcp_f32_e32 v14, v14
	v_rcp_f32_e32 v15, v15
	v_add_f32_e32 v16, 1.0, v16
	v_add_f32_e32 v17, 1.0, v17
	v_rcp_f32_e32 v16, v16
	v_rcp_f32_e32 v17, v17
	v_pk_mul_f32 v[8:9], v[8:9], v[14:15]
	v_pk_mul_f32 v[6:7], v[12:13], v[6:7]
	v_pk_mul_f32 v[8:9], v[8:9], v[0:1]
	v_pk_mul_f32 v[0:1], v[10:11], v[16:17]
	v_lshl_add_u64 v[12:13], v[18:19], 0, v[112:113]
	v_pk_mul_f32 v[10:11], v[0:1], v[2:3]
	v_cvt_pk_bf16_f32 v0, v4, v5
	v_cvt_pk_bf16_f32 v1, v6, v7
	v_cvt_pk_bf16_f32 v2, v8, v9
	v_cvt_pk_bf16_f32 v3, v10, v11
	global_store_dwordx4 v[12:13], v[0:3], off
	s_cbranch_vccnz .LBB0_224
	s_andn2_b64 vcc, exec, s[0:1]
	s_cbranch_vccnz .LBB0_223
	s_barrier
	s_branch .LBB0_223

.LBB0_240:
	s_waitcnt lgkmcnt(0)
	v_mov_b64_e32 v[0:1], s[48:49]
	v_mov_b64_e32 v[2:3], s[60:61]
	global_load_dword v0, v[0:1], off sc1
	v_readlane_b32 s8, v252, 44
	global_load_dword v1, v[2:3], off sc1
	v_mov_b64_e32 v[2:3], s[62:63]
	global_load_dword v2, v[2:3], off sc1
	v_readlane_b32 s9, v252, 45
	s_or_b64 s[40:41], s[40:41], exec
	s_or_b64 s[38:39], s[38:39], exec
	s_waitcnt vmcnt(0) lgkmcnt(0)
	v_add_u32_e32 v4, v1, v0
	v_add_u32_e32 v6, v4, v2
	v_mov_b64_e32 v[4:5], s[76:77]
	global_load_dword v3, v[4:5], off sc1
	v_mov_b64_e32 v[4:5], s[18:19]
	global_load_dword v4, v[4:5], off sc1
	s_waitcnt vmcnt(0) lgkmcnt(0)
	v_add_u32_e32 v6, v6, v3
	v_add_u32_e32 v8, v6, v4
	v_mov_b64_e32 v[6:7], s[20:21]
	global_load_dword v5, v[6:7], off sc1
	v_mov_b64_e32 v[6:7], s[8:9]
	global_load_dword v6, v[6:7], off sc1
	v_readlane_b32 s8, v252, 46
	v_readlane_b32 s9, v252, 47
	s_waitcnt vmcnt(0) lgkmcnt(0)
	v_add_u32_e32 v8, v8, v5
	v_add_u32_e32 v10, v8, v6
	v_mov_b64_e32 v[8:9], s[8:9]
	v_readlane_b32 s8, v252, 48
	v_readlane_b32 s9, v252, 49
	global_load_dword v7, v[8:9], off sc1
	s_waitcnt vmcnt(0) lgkmcnt(0)
	v_add_u32_e32 v10, v10, v7
	v_mov_b64_e32 v[8:9], s[8:9]
	global_load_dword v8, v[8:9], off sc1
	v_readlane_b32 s8, v252, 50
	v_readlane_b32 s9, v252, 51
	s_waitcnt vmcnt(0) lgkmcnt(0)
	v_add_u32_e32 v12, v10, v8
	v_mov_b64_e32 v[10:11], s[8:9]
	v_readlane_b32 s8, v252, 52
	v_readlane_b32 s9, v252, 53
	global_load_dword v9, v[10:11], off sc1
	s_waitcnt vmcnt(0) lgkmcnt(0)
	v_add_u32_e32 v12, v12, v9
	v_mov_b64_e32 v[10:11], s[8:9]
	global_load_dword v10, v[10:11], off sc1
	v_readlane_b32 s8, v252, 54
	v_readlane_b32 s9, v252, 55
	s_waitcnt vmcnt(0) lgkmcnt(0)
	v_add_u32_e32 v14, v12, v10
	v_mov_b64_e32 v[12:13], s[54:55]
	global_load_dword v11, v[12:13], off sc1
	v_mov_b64_e32 v[12:13], s[64:65]
	global_load_dword v12, v[12:13], off sc1
	s_waitcnt vmcnt(0) lgkmcnt(0)
	v_add_u32_e32 v14, v14, v11
	v_add_u32_e32 v16, v14, v12
	v_mov_b64_e32 v[14:15], s[66:67]
	global_load_dword v13, v[14:15], off sc1
	v_mov_b64_e32 v[14:15], s[8:9]
	global_load_dword v14, v[14:15], off sc1
	v_readlane_b32 s8, v252, 56
	v_readlane_b32 s9, v252, 57
	s_waitcnt vmcnt(0) lgkmcnt(0)
	v_add_u32_e32 v16, v16, v13
	v_add_u32_e32 v18, v16, v14
	v_mov_b64_e32 v[16:17], s[8:9]
	global_load_dword v15, v[16:17], off sc1
	s_waitcnt vmcnt(0) lgkmcnt(0)
	v_add_u32_e32 v16, v18, v15
	v_cmp_ne_u32_e32 vcc, s6, v16
	s_and_saveexec_b64 s[42:43], vcc
	s_cbranch_execz .LBB0_239
	s_and_b32 s22, s3, 0xff
	s_mov_b64 s[44:45], -1
	s_cmp_eq_u32 s22, 0
	s_mov_b64 s[68:69], -1
	s_mov_b64 s[46:47], -1
	s_sleep 1
	s_cbranch_scc1 .LBB0_243
	s_and_saveexec_b64 s[70:71], s[68:69]
	s_cbranch_execz .LBB0_238
	s_branch .LBB0_246

.LBB0_250:
	v_readlane_b32 s8, v253, 26
	v_readlane_b32 s9, v253, 27
	v_cvt_f32_u32_e32 v1, v2
	v_rcp_iflag_f32_e32 v1, v1
	v_mov_b64_e32 v[4:5], s[8:9]
	global_atomic_add v3, v[4:5], v230, off sc0
	v_sub_u32_e32 v4, 0, v2
	v_mul_f32_e32 v1, 0x4f7ffffe, v1
	v_cvt_u32_f32_e32 v1, v1
	v_mul_lo_u32 v4, v4, v1
	v_mul_hi_u32 v4, v1, v4
	v_add_u32_e32 v1, v1, v4
	s_waitcnt vmcnt(0) lgkmcnt(0)
	v_mul_hi_u32 v1, v3, v1
	v_mul_lo_u32 v4, v1, v2
	v_sub_u32_e32 v4, v3, v4
	v_cmp_ge_u32_e32 vcc, v4, v2
	v_add_u32_e32 v5, 1, v1
	s_nop 0
	v_cndmask_b32_e32 v1, v1, v5, vcc
	v_sub_u32_e32 v5, v4, v2
	v_cndmask_b32_e32 v4, v4, v5, vcc
	v_cmp_ge_u32_e32 vcc, v4, v2
	v_add_u32_e32 v4, 1, v1
	s_nop 0
	v_cndmask_b32_e32 v1, v1, v4, vcc
	v_add_u32_e32 v4, 1, v3
	v_mad_u64_u32 v[2:3], s[34:35], v2, v1, v[2:3]
	v_cmp_ne_u32_e32 vcc, v4, v2
	s_and_saveexec_b64 s[34:35], vcc
	s_xor_b64 s[34:35], exec, s[34:35]
	s_cbranch_execz .LBB0_263
	v_readlane_b32 s8, v253, 28
	v_readlane_b32 s9, v253, 29
	s_nop 1
	v_mov_b64_e32 v[2:3], s[8:9]
	global_load_dword v0, v[2:3], off sc1
	s_waitcnt vmcnt(0) lgkmcnt(0)
	v_cmp_eq_u32_e32 vcc, v0, v1
	s_and_saveexec_b64 s[36:37], vcc
	s_cbranch_execz .LBB0_262
	s_mov_b32 s3, 1
	s_mov_b64 s[38:39], 0
	s_branch .LBB0_254

.LBB0_263:
	s_andn2_saveexec_b64 s[34:35], s[34:35]
	s_cbranch_execz .LBB0_279
	v_readlane_b32 s8, v253, 30
	v_readlane_b32 s9, v253, 31
	buffer_wbl2 sc1
	s_waitcnt vmcnt(0)
	s_mov_b64 s[36:37], -1
	v_mov_b64_e32 v[2:3], s[8:9]
	global_atomic_add v1, v[2:3], v230, off sc0
	v_cvt_f32_u32_e32 v2, v0
	v_sub_u32_e32 v3, 0, v0
	v_readlane_b32 s8, v253, 32
	v_readlane_b32 s9, v253, 33
	v_rcp_iflag_f32_e32 v2, v2
	s_nop 0
	v_mul_f32_e32 v2, 0x4f7ffffe, v2
	v_cvt_u32_f32_e32 v2, v2
	v_mul_lo_u32 v3, v3, v2
	v_mul_hi_u32 v3, v2, v3
	v_add_u32_e32 v2, v2, v3
	s_waitcnt vmcnt(0) lgkmcnt(0)
	v_mul_hi_u32 v2, v1, v2
	v_mul_lo_u32 v3, v2, v0
	v_sub_u32_e32 v3, v1, v3
	v_cmp_ge_u32_e32 vcc, v3, v0
	v_add_u32_e32 v4, 1, v2
	s_nop 0
	v_cndmask_b32_e32 v2, v2, v4, vcc
	v_sub_u32_e32 v4, v3, v0
	v_cndmask_b32_e32 v3, v3, v4, vcc
	v_cmp_ge_u32_e32 vcc, v3, v0
	v_add_u32_e32 v3, 1, v2
	s_nop 0
	v_cndmask_b32_e32 v2, v2, v3, vcc
	v_add_u32_e32 v3, 1, v1
	v_mad_u64_u32 v[0:1], s[34:35], v0, v2, v[0:1]
	v_cmp_ne_u32_e32 vcc, v3, v0
	v_mov_b64_e32 v[0:1], s[8:9]
	s_and_saveexec_b64 s[34:35], vcc
	s_cbranch_execz .LBB0_276
	v_readlane_b32 s8, v253, 32
	v_readlane_b32 s9, v253, 33
	s_mov_b64 s[38:39], 0
	s_nop 0
	v_mov_b64_e32 v[0:1], s[8:9]
	global_load_dword v0, v[0:1], off sc1
	s_waitcnt vmcnt(0) lgkmcnt(0)
	v_cmp_eq_u32_e32 vcc, v0, v2
	s_and_saveexec_b64 s[36:37], vcc
	s_cbranch_execz .LBB0_275
	s_mov_b32 s3, 1
	s_branch .LBB0_268

.LBB0_304:
	s_mul_hi_i32 s45, s43, 0x9000
	s_mul_i32 s43, s43, 0x9000
	s_add_u32 s44, s70, s43
	s_addc_u32 s45, s71, s45
	s_lshl_b32 s43, s80, 8
	s_or_b32 s43, s43, s76
	v_lshl_add_u32 v146, v129, 3, s43
	v_ashrrev_i32_e32 v147, 31, v146
	v_lshl_add_u64 v[142:143], v[146:147], 2, s[44:45]
	global_load_dwordx4 v[130:133], v[142:143], off
	global_load_dwordx4 v[134:137], v[142:143], off offset:16
	global_load_dwordx4 v[138:141], v[142:143], off offset:512
	s_nop 0
	global_load_dwordx4 v[142:145], v[142:143], off offset:528
	s_ashr_i32 s43, s42, 31
	s_lshl_b64 s[42:43], s[42:43], 11
	s_add_u32 s42, s30, s42
	v_add_u32_e32 v194, s61, v128
	s_addc_u32 s43, s31, s43
	v_ashrrev_i32_e32 v195, 31, v194
	v_lshl_add_u64 v[192:193], v[146:147], 1, s[42:43]
	v_lshlrev_b64 v[128:129], 11, v[194:195]
	v_lshl_add_u64 v[214:215], v[192:193], 0, v[128:129]
	global_load_dwordx4 v[206:209], v[214:215], off
	global_load_dwordx4 v[210:213], v[214:215], off offset:256
	v_add_u32_e32 v128, 16, v194
	v_ashrrev_i32_e32 v129, 31, v128
	v_lshlrev_b64 v[128:129], 11, v[128:129]
	v_lshl_add_u64 v[200:201], v[192:193], 0, v[128:129]
	v_add_u32_e32 v128, 32, v194
	v_ashrrev_i32_e32 v129, 31, v128
	v_lshlrev_b64 v[128:129], 11, v[128:129]
	v_lshl_add_u64 v[198:199], v[192:193], 0, v[128:129]
	v_add_u32_e32 v128, 48, v194
	v_ashrrev_i32_e32 v129, 31, v128
	v_lshlrev_b64 v[128:129], 11, v[128:129]
	v_lshl_add_u64 v[196:197], v[192:193], 0, v[128:129]
	s_mov_b64 s[42:43], -1
	s_and_b64 vcc, exec, s[40:41]
	s_waitcnt vmcnt(0) lgkmcnt(0)
	v_pk_mul_f32 v[174:175], v[132:133], 0.5 op_sel_hi:[1,0]
	v_pk_mul_f32 v[170:171], v[136:137], 0.5 op_sel_hi:[1,0]
	v_pk_mul_f32 v[166:167], v[140:141], 0.5 op_sel_hi:[1,0]
	v_pk_mul_f32 v[162:163], v[144:145], 0.5 op_sel_hi:[1,0]
	global_load_dwordx4 v[148:151], v[200:201], off
	global_load_dwordx4 v[144:147], v[200:201], off offset:256
	v_pk_mul_f32 v[168:169], v[138:139], 0.5 op_sel_hi:[1,0]
	v_pk_mul_f32 v[164:165], v[142:143], 0.5 op_sel_hi:[1,0]
	global_load_dwordx4 v[140:143], v[198:199], off
	global_load_dwordx4 v[136:139], v[198:199], off offset:256
	v_pk_mul_f32 v[190:191], v[130:131], 0.5 op_sel_hi:[1,0]
	v_pk_mul_f32 v[172:173], v[134:135], 0.5 op_sel_hi:[1,0]
	global_load_dwordx4 v[132:135], v[196:197], off
	global_load_dwordx4 v[128:131], v[196:197], off offset:256
	v_cvt_f32_f16_e32 v216, v206
	v_cvt_f32_f16_sdwa v217, v206 dst_sel:DWORD dst_unused:UNUSED_PAD src0_sel:WORD_1
	v_cvt_f32_f16_e32 v206, v207
	v_cvt_f32_f16_sdwa v207, v207 dst_sel:DWORD dst_unused:UNUSED_PAD src0_sel:WORD_1
	v_pk_fma_f32 v[124:125], v[124:125], v[190:191], v[216:217]
	v_pk_fma_f32 v[126:127], v[126:127], v[174:175], v[206:207]
	v_cvt_f32_f16_e32 v206, v208
	v_cvt_f32_f16_sdwa v207, v208 dst_sel:DWORD dst_unused:UNUSED_PAD src0_sel:WORD_1
	v_cvt_f32_f16_e32 v208, v209
	v_cvt_f32_f16_sdwa v209, v209 dst_sel:DWORD dst_unused:UNUSED_PAD src0_sel:WORD_1
	v_pk_fma_f32 v[208:209], v[122:123], v[170:171], v[208:209]
	v_pk_fma_f32 v[122:123], v[120:121], v[172:173], v[206:207]
	v_cvt_pk_f16_f32 v120, v124, v125
	v_cvt_pk_f16_f32 v121, v126, v127
	v_cvt_pk_f16_f32 v122, v122, v123
	v_cvt_pk_f16_f32 v123, v208, v209
	global_store_dwordx4 v[214:215], v[120:123], off
	s_nop 1
	v_cvt_f32_f16_e32 v120, v210
	v_cvt_f32_f16_sdwa v121, v210 dst_sel:DWORD dst_unused:UNUSED_PAD src0_sel:WORD_1
	v_cvt_f32_f16_e32 v122, v211
	v_cvt_f32_f16_sdwa v123, v211 dst_sel:DWORD dst_unused:UNUSED_PAD src0_sel:WORD_1
	v_pk_fma_f32 v[116:117], v[116:117], v[168:169], v[120:121]
	v_cvt_f32_f16_e32 v120, v212
	v_pk_fma_f32 v[118:119], v[118:119], v[166:167], v[122:123]
	v_cvt_f32_f16_sdwa v121, v212 dst_sel:DWORD dst_unused:UNUSED_PAD src0_sel:WORD_1
	v_cvt_f32_f16_e32 v122, v213
	v_cvt_f32_f16_sdwa v123, v213 dst_sel:DWORD dst_unused:UNUSED_PAD src0_sel:WORD_1
	v_pk_fma_f32 v[122:123], v[114:115], v[162:163], v[122:123]
	v_pk_fma_f32 v[114:115], v[112:113], v[164:165], v[120:121]
	v_cvt_pk_f16_f32 v112, v116, v117
	v_cvt_pk_f16_f32 v113, v118, v119
	v_cvt_pk_f16_f32 v114, v114, v115
	v_cvt_pk_f16_f32 v115, v122, v123
	global_store_dwordx4 v[214:215], v[112:115], off offset:256
	s_waitcnt vmcnt(7)
	s_nop 0
	v_cvt_f32_f16_e32 v112, v148
	v_cvt_f32_f16_sdwa v113, v148 dst_sel:DWORD dst_unused:UNUSED_PAD src0_sel:WORD_1
	v_cvt_f32_f16_e32 v114, v149
	v_cvt_f32_f16_sdwa v115, v149 dst_sel:DWORD dst_unused:UNUSED_PAD src0_sel:WORD_1
	v_pk_fma_f32 v[108:109], v[108:109], v[190:191], v[112:113]
	v_cvt_f32_f16_e32 v112, v150
	v_pk_fma_f32 v[110:111], v[110:111], v[174:175], v[114:115]
	v_cvt_f32_f16_sdwa v113, v150 dst_sel:DWORD dst_unused:UNUSED_PAD src0_sel:WORD_1
	v_cvt_f32_f16_e32 v114, v151
	v_cvt_f32_f16_sdwa v115, v151 dst_sel:DWORD dst_unused:UNUSED_PAD src0_sel:WORD_1
	v_pk_fma_f32 v[114:115], v[106:107], v[170:171], v[114:115]
	v_pk_fma_f32 v[106:107], v[104:105], v[172:173], v[112:113]
	v_cvt_pk_f16_f32 v104, v108, v109
	v_cvt_pk_f16_f32 v105, v110, v111
	v_cvt_pk_f16_f32 v106, v106, v107
	v_cvt_pk_f16_f32 v107, v114, v115
	global_store_dwordx4 v[200:201], v[104:107], off
	s_waitcnt vmcnt(7)
	s_nop 0
	v_cvt_f32_f16_e32 v104, v144
	v_cvt_f32_f16_sdwa v105, v144 dst_sel:DWORD dst_unused:UNUSED_PAD src0_sel:WORD_1
	v_cvt_f32_f16_e32 v106, v145
	v_cvt_f32_f16_sdwa v107, v145 dst_sel:DWORD dst_unused:UNUSED_PAD src0_sel:WORD_1
	v_pk_fma_f32 v[100:101], v[100:101], v[168:169], v[104:105]
	v_cvt_f32_f16_e32 v104, v146
	v_pk_fma_f32 v[102:103], v[102:103], v[166:167], v[106:107]
	v_cvt_f32_f16_sdwa v105, v146 dst_sel:DWORD dst_unused:UNUSED_PAD src0_sel:WORD_1
	v_cvt_f32_f16_e32 v106, v147
	v_cvt_f32_f16_sdwa v107, v147 dst_sel:DWORD dst_unused:UNUSED_PAD src0_sel:WORD_1
	v_pk_fma_f32 v[106:107], v[94:95], v[162:163], v[106:107]
	v_pk_fma_f32 v[94:95], v[92:93], v[164:165], v[104:105]
	v_cvt_pk_f16_f32 v92, v100, v101
	v_cvt_pk_f16_f32 v93, v102, v103
	v_cvt_pk_f16_f32 v94, v94, v95
	v_cvt_pk_f16_f32 v95, v106, v107
	global_store_dwordx4 v[200:201], v[92:95], off offset:256
	s_waitcnt vmcnt(7)
	s_nop 0
	v_cvt_f32_f16_e32 v92, v140
	v_cvt_f32_f16_sdwa v93, v140 dst_sel:DWORD dst_unused:UNUSED_PAD src0_sel:WORD_1
	v_cvt_f32_f16_e32 v94, v141
	v_cvt_f32_f16_sdwa v95, v141 dst_sel:DWORD dst_unused:UNUSED_PAD src0_sel:WORD_1
	v_pk_fma_f32 v[92:93], v[96:97], v[190:191], v[92:93]
	v_cvt_f32_f16_e32 v96, v142
	v_pk_fma_f32 v[94:95], v[98:99], v[174:175], v[94:95]
	v_cvt_f32_f16_sdwa v97, v142 dst_sel:DWORD dst_unused:UNUSED_PAD src0_sel:WORD_1
	v_cvt_f32_f16_e32 v98, v143
	v_cvt_f32_f16_sdwa v99, v143 dst_sel:DWORD dst_unused:UNUSED_PAD src0_sel:WORD_1
	v_pk_fma_f32 v[98:99], v[90:91], v[170:171], v[98:99]
	v_pk_fma_f32 v[90:91], v[88:89], v[172:173], v[96:97]
	v_cvt_pk_f16_f32 v88, v92, v93
	v_cvt_pk_f16_f32 v89, v94, v95
	v_cvt_pk_f16_f32 v90, v90, v91
	v_cvt_pk_f16_f32 v91, v98, v99
	global_store_dwordx4 v[198:199], v[88:91], off
	s_waitcnt vmcnt(7)
	s_nop 0
	v_cvt_f32_f16_e32 v88, v136
	v_cvt_f32_f16_sdwa v89, v136 dst_sel:DWORD dst_unused:UNUSED_PAD src0_sel:WORD_1
	v_cvt_f32_f16_e32 v90, v137
	v_cvt_f32_f16_sdwa v91, v137 dst_sel:DWORD dst_unused:UNUSED_PAD src0_sel:WORD_1
	v_pk_fma_f32 v[84:85], v[84:85], v[168:169], v[88:89]
	v_cvt_f32_f16_e32 v88, v138
	v_pk_fma_f32 v[86:87], v[86:87], v[166:167], v[90:91]
	v_cvt_f32_f16_sdwa v89, v138 dst_sel:DWORD dst_unused:UNUSED_PAD src0_sel:WORD_1
	v_cvt_f32_f16_e32 v90, v139
	v_cvt_f32_f16_sdwa v91, v139 dst_sel:DWORD dst_unused:UNUSED_PAD src0_sel:WORD_1
	v_pk_fma_f32 v[90:91], v[78:79], v[162:163], v[90:91]
	v_pk_fma_f32 v[78:79], v[76:77], v[164:165], v[88:89]
	v_cvt_pk_f16_f32 v76, v84, v85
	v_cvt_pk_f16_f32 v77, v86, v87
	v_cvt_pk_f16_f32 v78, v78, v79
	v_cvt_pk_f16_f32 v79, v90, v91
	global_store_dwordx4 v[198:199], v[76:79], off offset:256
	s_waitcnt vmcnt(7)
	s_nop 0
	v_cvt_f32_f16_e32 v76, v132
	v_cvt_f32_f16_sdwa v77, v132 dst_sel:DWORD dst_unused:UNUSED_PAD src0_sel:WORD_1
	v_cvt_f32_f16_e32 v78, v133
	v_cvt_f32_f16_sdwa v79, v133 dst_sel:DWORD dst_unused:UNUSED_PAD src0_sel:WORD_1
	v_pk_fma_f32 v[76:77], v[80:81], v[190:191], v[76:77]
	v_cvt_f32_f16_e32 v80, v134
	v_pk_fma_f32 v[78:79], v[82:83], v[174:175], v[78:79]
	v_cvt_f32_f16_sdwa v81, v134 dst_sel:DWORD dst_unused:UNUSED_PAD src0_sel:WORD_1
	v_cvt_f32_f16_e32 v82, v135
	v_cvt_f32_f16_sdwa v83, v135 dst_sel:DWORD dst_unused:UNUSED_PAD src0_sel:WORD_1
	v_pk_fma_f32 v[82:83], v[74:75], v[170:171], v[82:83]
	v_pk_fma_f32 v[74:75], v[72:73], v[172:173], v[80:81]
	v_cvt_pk_f16_f32 v72, v76, v77
	v_cvt_pk_f16_f32 v73, v78, v79
	v_cvt_pk_f16_f32 v74, v74, v75
	v_cvt_pk_f16_f32 v75, v82, v83
	global_store_dwordx4 v[196:197], v[72:75], off
	s_waitcnt vmcnt(7)
	s_nop 0
	v_cvt_f32_f16_e32 v72, v128
	v_cvt_f32_f16_sdwa v73, v128 dst_sel:DWORD dst_unused:UNUSED_PAD src0_sel:WORD_1
	v_cvt_f32_f16_e32 v74, v129
	v_cvt_f32_f16_sdwa v75, v129 dst_sel:DWORD dst_unused:UNUSED_PAD src0_sel:WORD_1
	v_pk_fma_f32 v[68:69], v[68:69], v[168:169], v[72:73]
	v_cvt_f32_f16_e32 v72, v130
	v_pk_fma_f32 v[70:71], v[70:71], v[166:167], v[74:75]
	v_cvt_f32_f16_sdwa v73, v130 dst_sel:DWORD dst_unused:UNUSED_PAD src0_sel:WORD_1
	v_cvt_f32_f16_e32 v74, v131
	v_cvt_f32_f16_sdwa v75, v131 dst_sel:DWORD dst_unused:UNUSED_PAD src0_sel:WORD_1
	v_pk_fma_f32 v[74:75], v[66:67], v[162:163], v[74:75]
	v_pk_fma_f32 v[66:67], v[64:65], v[164:165], v[72:73]
	v_cvt_pk_f16_f32 v64, v68, v69
	v_cvt_pk_f16_f32 v65, v70, v71
	v_cvt_pk_f16_f32 v66, v66, v67
	v_cvt_pk_f16_f32 v67, v74, v75
	global_store_dwordx4 v[196:197], v[64:67], off offset:256
	s_nop 1
	v_add_u32_e32 v64, 0x80, v194
	v_ashrrev_i32_e32 v65, 31, v64
	v_lshlrev_b64 v[64:65], 11, v[64:65]
	v_lshl_add_u64 v[100:101], v[192:193], 0, v[64:65]
	global_load_dwordx4 v[84:87], v[100:101], off
	global_load_dwordx4 v[88:91], v[100:101], off offset:256
	v_add_u32_e32 v64, 0x90, v194
	v_ashrrev_i32_e32 v65, 31, v64
	v_lshlrev_b64 v[64:65], 11, v[64:65]
	v_lshl_add_u64 v[102:103], v[192:193], 0, v[64:65]
	global_load_dwordx4 v[92:95], v[102:103], off
	global_load_dwordx4 v[96:99], v[102:103], off offset:256
	v_add_u32_e32 v64, 0xa0, v194
	v_ashrrev_i32_e32 v65, 31, v64
	v_lshlrev_b64 v[64:65], 11, v[64:65]
	v_lshl_add_u64 v[82:83], v[192:193], 0, v[64:65]
	global_load_dwordx4 v[76:79], v[82:83], off
	global_load_dwordx4 v[72:75], v[82:83], off offset:256
	v_add_u32_e32 v64, 0xb0, v194
	v_ashrrev_i32_e32 v65, 31, v64
	v_lshlrev_b64 v[64:65], 11, v[64:65]
	v_lshl_add_u64 v[80:81], v[192:193], 0, v[64:65]
	global_load_dwordx4 v[68:71], v[80:81], off
	global_load_dwordx4 v[64:67], v[80:81], off offset:256
	s_waitcnt vmcnt(7)
	v_cvt_f32_f16_e32 v104, v84
	v_cvt_f32_f16_sdwa v105, v84 dst_sel:DWORD dst_unused:UNUSED_PAD src0_sel:WORD_1
	v_cvt_f32_f16_e32 v84, v85
	v_cvt_f32_f16_sdwa v85, v85 dst_sel:DWORD dst_unused:UNUSED_PAD src0_sel:WORD_1
	v_pk_fma_f32 v[60:61], v[60:61], v[190:191], v[104:105]
	v_pk_fma_f32 v[62:63], v[62:63], v[174:175], v[84:85]
	v_cvt_f32_f16_e32 v84, v86
	v_cvt_f32_f16_sdwa v85, v86 dst_sel:DWORD dst_unused:UNUSED_PAD src0_sel:WORD_1
	v_cvt_f32_f16_e32 v86, v87
	v_cvt_f32_f16_sdwa v87, v87 dst_sel:DWORD dst_unused:UNUSED_PAD src0_sel:WORD_1
	v_pk_fma_f32 v[86:87], v[58:59], v[170:171], v[86:87]
	v_pk_fma_f32 v[58:59], v[56:57], v[172:173], v[84:85]
	v_cvt_pk_f16_f32 v56, v60, v61
	v_cvt_pk_f16_f32 v57, v62, v63
	v_cvt_pk_f16_f32 v58, v58, v59
	v_cvt_pk_f16_f32 v59, v86, v87
	global_store_dwordx4 v[100:101], v[56:59], off
	s_waitcnt vmcnt(7)
	s_nop 0
	v_cvt_f32_f16_e32 v56, v88
	v_cvt_f32_f16_sdwa v57, v88 dst_sel:DWORD dst_unused:UNUSED_PAD src0_sel:WORD_1
	v_cvt_f32_f16_e32 v58, v89
	v_cvt_f32_f16_sdwa v59, v89 dst_sel:DWORD dst_unused:UNUSED_PAD src0_sel:WORD_1
	v_pk_fma_f32 v[52:53], v[52:53], v[168:169], v[56:57]
	v_cvt_f32_f16_e32 v56, v90
	v_pk_fma_f32 v[54:55], v[54:55], v[166:167], v[58:59]
	v_cvt_f32_f16_sdwa v57, v90 dst_sel:DWORD dst_unused:UNUSED_PAD src0_sel:WORD_1
	v_cvt_f32_f16_e32 v58, v91
	v_cvt_f32_f16_sdwa v59, v91 dst_sel:DWORD dst_unused:UNUSED_PAD src0_sel:WORD_1
	v_pk_fma_f32 v[58:59], v[46:47], v[162:163], v[58:59]
	v_pk_fma_f32 v[46:47], v[44:45], v[164:165], v[56:57]
	v_cvt_pk_f16_f32 v44, v52, v53
	v_cvt_pk_f16_f32 v45, v54, v55
	v_cvt_pk_f16_f32 v46, v46, v47
	v_cvt_pk_f16_f32 v47, v58, v59
	global_store_dwordx4 v[100:101], v[44:47], off offset:256
	s_waitcnt vmcnt(7)
	s_nop 0
	v_cvt_f32_f16_e32 v44, v92
	v_cvt_f32_f16_sdwa v45, v92 dst_sel:DWORD dst_unused:UNUSED_PAD src0_sel:WORD_1
	v_cvt_f32_f16_e32 v46, v93
	v_cvt_f32_f16_sdwa v47, v93 dst_sel:DWORD dst_unused:UNUSED_PAD src0_sel:WORD_1
	v_pk_fma_f32 v[44:45], v[48:49], v[190:191], v[44:45]
	v_cvt_f32_f16_e32 v48, v94
	v_pk_fma_f32 v[46:47], v[50:51], v[174:175], v[46:47]
	v_cvt_f32_f16_sdwa v49, v94 dst_sel:DWORD dst_unused:UNUSED_PAD src0_sel:WORD_1
	v_cvt_f32_f16_e32 v50, v95
	v_cvt_f32_f16_sdwa v51, v95 dst_sel:DWORD dst_unused:UNUSED_PAD src0_sel:WORD_1
	v_pk_fma_f32 v[50:51], v[42:43], v[170:171], v[50:51]
	v_pk_fma_f32 v[42:43], v[40:41], v[172:173], v[48:49]
	v_cvt_pk_f16_f32 v40, v44, v45
	v_cvt_pk_f16_f32 v41, v46, v47
	v_cvt_pk_f16_f32 v42, v42, v43
	v_cvt_pk_f16_f32 v43, v50, v51
	global_store_dwordx4 v[102:103], v[40:43], off
	s_waitcnt vmcnt(7)
	s_nop 0
	v_cvt_f32_f16_e32 v40, v96
	v_cvt_f32_f16_sdwa v41, v96 dst_sel:DWORD dst_unused:UNUSED_PAD src0_sel:WORD_1
	v_cvt_f32_f16_e32 v42, v97
	v_cvt_f32_f16_sdwa v43, v97 dst_sel:DWORD dst_unused:UNUSED_PAD src0_sel:WORD_1
	v_pk_fma_f32 v[36:37], v[36:37], v[168:169], v[40:41]
	v_cvt_f32_f16_e32 v40, v98
	v_pk_fma_f32 v[38:39], v[38:39], v[166:167], v[42:43]
	v_cvt_f32_f16_sdwa v41, v98 dst_sel:DWORD dst_unused:UNUSED_PAD src0_sel:WORD_1
	v_cvt_f32_f16_e32 v42, v99
	v_cvt_f32_f16_sdwa v43, v99 dst_sel:DWORD dst_unused:UNUSED_PAD src0_sel:WORD_1
	v_pk_fma_f32 v[42:43], v[30:31], v[162:163], v[42:43]
	v_pk_fma_f32 v[30:31], v[28:29], v[164:165], v[40:41]
	v_cvt_pk_f16_f32 v28, v36, v37
	v_cvt_pk_f16_f32 v29, v38, v39
	v_cvt_pk_f16_f32 v30, v30, v31
	v_cvt_pk_f16_f32 v31, v42, v43
	global_store_dwordx4 v[102:103], v[28:31], off offset:256
	s_waitcnt vmcnt(7)
	s_nop 0
	v_cvt_f32_f16_e32 v28, v76
	v_cvt_f32_f16_sdwa v29, v76 dst_sel:DWORD dst_unused:UNUSED_PAD src0_sel:WORD_1
	v_cvt_f32_f16_e32 v30, v77
	v_cvt_f32_f16_sdwa v31, v77 dst_sel:DWORD dst_unused:UNUSED_PAD src0_sel:WORD_1
	v_pk_fma_f32 v[28:29], v[32:33], v[190:191], v[28:29]
	v_cvt_f32_f16_e32 v32, v78
	v_pk_fma_f32 v[30:31], v[34:35], v[174:175], v[30:31]
	v_cvt_f32_f16_sdwa v33, v78 dst_sel:DWORD dst_unused:UNUSED_PAD src0_sel:WORD_1
	v_cvt_f32_f16_e32 v34, v79
	v_cvt_f32_f16_sdwa v35, v79 dst_sel:DWORD dst_unused:UNUSED_PAD src0_sel:WORD_1
	v_pk_fma_f32 v[34:35], v[26:27], v[170:171], v[34:35]
	v_pk_fma_f32 v[26:27], v[24:25], v[172:173], v[32:33]
	v_cvt_pk_f16_f32 v24, v28, v29
	v_cvt_pk_f16_f32 v25, v30, v31
	v_cvt_pk_f16_f32 v26, v26, v27
	v_cvt_pk_f16_f32 v27, v34, v35
	global_store_dwordx4 v[82:83], v[24:27], off
	s_waitcnt vmcnt(7)
	s_nop 0
	v_cvt_f32_f16_e32 v24, v72
	v_cvt_f32_f16_sdwa v25, v72 dst_sel:DWORD dst_unused:UNUSED_PAD src0_sel:WORD_1
	v_cvt_f32_f16_e32 v26, v73
	v_cvt_f32_f16_sdwa v27, v73 dst_sel:DWORD dst_unused:UNUSED_PAD src0_sel:WORD_1
	v_pk_fma_f32 v[20:21], v[20:21], v[168:169], v[24:25]
	v_cvt_f32_f16_e32 v24, v74
	v_pk_fma_f32 v[22:23], v[22:23], v[166:167], v[26:27]
	v_cvt_f32_f16_sdwa v25, v74 dst_sel:DWORD dst_unused:UNUSED_PAD src0_sel:WORD_1
	v_cvt_f32_f16_e32 v26, v75
	v_cvt_f32_f16_sdwa v27, v75 dst_sel:DWORD dst_unused:UNUSED_PAD src0_sel:WORD_1
	v_pk_fma_f32 v[26:27], v[14:15], v[162:163], v[26:27]
	v_pk_fma_f32 v[14:15], v[12:13], v[164:165], v[24:25]
	v_cvt_pk_f16_f32 v12, v20, v21
	v_cvt_pk_f16_f32 v13, v22, v23
	v_cvt_pk_f16_f32 v14, v14, v15
	v_cvt_pk_f16_f32 v15, v26, v27
	global_store_dwordx4 v[82:83], v[12:15], off offset:256
	s_waitcnt vmcnt(7)
	s_nop 0
	v_cvt_f32_f16_e32 v12, v68
	v_cvt_f32_f16_sdwa v13, v68 dst_sel:DWORD dst_unused:UNUSED_PAD src0_sel:WORD_1
	v_cvt_f32_f16_e32 v14, v69
	v_cvt_f32_f16_sdwa v15, v69 dst_sel:DWORD dst_unused:UNUSED_PAD src0_sel:WORD_1
	v_pk_fma_f32 v[12:13], v[16:17], v[190:191], v[12:13]
	v_cvt_f32_f16_e32 v16, v70
	v_pk_fma_f32 v[14:15], v[18:19], v[174:175], v[14:15]
	v_cvt_f32_f16_sdwa v17, v70 dst_sel:DWORD dst_unused:UNUSED_PAD src0_sel:WORD_1
	v_cvt_f32_f16_e32 v18, v71
	v_cvt_f32_f16_sdwa v19, v71 dst_sel:DWORD dst_unused:UNUSED_PAD src0_sel:WORD_1
	v_pk_fma_f32 v[18:19], v[10:11], v[170:171], v[18:19]
	v_pk_fma_f32 v[10:11], v[8:9], v[172:173], v[16:17]
	v_cvt_pk_f16_f32 v8, v12, v13
	v_cvt_pk_f16_f32 v9, v14, v15
	v_cvt_pk_f16_f32 v10, v10, v11
	v_cvt_pk_f16_f32 v11, v18, v19
	global_store_dwordx4 v[80:81], v[8:11], off
	s_waitcnt vmcnt(7)
	s_nop 0
	v_cvt_f32_f16_e32 v8, v64
	v_cvt_f32_f16_sdwa v9, v64 dst_sel:DWORD dst_unused:UNUSED_PAD src0_sel:WORD_1
	v_cvt_f32_f16_e32 v10, v65
	v_cvt_f32_f16_sdwa v11, v65 dst_sel:DWORD dst_unused:UNUSED_PAD src0_sel:WORD_1
	v_pk_fma_f32 v[4:5], v[4:5], v[168:169], v[8:9]
	v_cvt_f32_f16_e32 v8, v66
	v_pk_fma_f32 v[6:7], v[6:7], v[166:167], v[10:11]
	v_cvt_f32_f16_sdwa v9, v66 dst_sel:DWORD dst_unused:UNUSED_PAD src0_sel:WORD_1
	v_cvt_f32_f16_e32 v10, v67
	v_cvt_f32_f16_sdwa v11, v67 dst_sel:DWORD dst_unused:UNUSED_PAD src0_sel:WORD_1
	v_pk_fma_f32 v[10:11], v[2:3], v[162:163], v[10:11]
	v_pk_fma_f32 v[2:3], v[0:1], v[164:165], v[8:9]
	v_cvt_pk_f16_f32 v0, v4, v5
	v_cvt_pk_f16_f32 v1, v6, v7
	v_cvt_pk_f16_f32 v2, v2, v3
	v_cvt_pk_f16_f32 v3, v10, v11
	global_store_dwordx4 v[80:81], v[0:3], off offset:256
	s_cbranch_vccnz .LBB0_285
	s_andn2_b64 vcc, exec, s[34:35]
	s_cbranch_vccnz .LBB0_284
	s_barrier
	s_branch .LBB0_284

.LBB0_335:
	s_lshl_b32 s22, s81, 8
	s_or_b32 s22, s22, s63
	v_lshl_add_u32 v150, v139, 3, s22
	s_mul_i32 s46, s68, 0x9000
	s_mul_hi_i32 s22, s68, 0x9000
	s_add_u32 s46, s70, s46
	v_ashrrev_i32_e32 v151, 31, v150
	s_addc_u32 s47, s71, s22
	v_lshlrev_b64 v[152:153], 2, v[150:151]
	v_lshl_add_u64 v[140:141], s[46:47], 0, v[152:153]
	global_load_dwordx4 v[142:145], v[140:141], off
	global_load_dwordx4 v[146:149], v[140:141], off offset:16
	global_load_dwordx4 v[164:167], v[140:141], off offset:512
	global_load_dwordx4 v[168:171], v[140:141], off offset:528
	v_add_u32_e32 v140, s62, v138
	v_ashrrev_i32_e32 v141, 31, v140
	v_lshl_add_u64 v[138:139], s[44:45], 0, v[152:153]
	v_lshlrev_b64 v[152:153], 12, v[140:141]
	v_lshl_add_u64 v[152:153], v[138:139], 0, v[152:153]
	global_load_dwordx4 v[172:175], v[152:153], off
	global_load_dwordx4 v[190:193], v[152:153], off offset:16
	global_load_dwordx4 v[194:197], v[152:153], off offset:528
	global_load_dwordx4 v[198:201], v[152:153], off offset:512
	v_add_u32_e32 v152, 16, v140
	v_ashrrev_i32_e32 v153, 31, v152
	v_lshlrev_b64 v[154:155], 12, v[152:153]
	v_lshl_add_u64 v[154:155], v[138:139], 0, v[154:155]
	global_load_dwordx4 v[202:205], v[154:155], off
	global_load_dwordx4 v[206:209], v[154:155], off offset:16
	global_load_dwordx4 v[210:213], v[154:155], off offset:512
	global_load_dwordx4 v[214:217], v[154:155], off offset:528
	s_lshl_b64 s[42:43], s[42:43], 11
	v_add_u32_e32 v218, 32, v140
	s_add_u32 s42, s30, s42
	v_ashrrev_i32_e32 v219, 31, v218
	s_addc_u32 s43, s31, s43
	v_lshlrev_b64 v[154:155], 11, v[140:141]
	v_lshlrev_b64 v[152:153], 11, v[152:153]
	v_lshlrev_b64 v[156:157], 12, v[218:219]
	v_lshl_add_u64 v[158:159], v[150:151], 1, s[42:43]
	v_lshl_add_u64 v[220:221], v[138:139], 0, v[156:157]
	v_lshl_add_u64 v[222:223], v[158:159], 0, v[154:155]
	v_lshl_add_u64 v[224:225], v[158:159], 0, v[152:153]
	s_and_b64 vcc, exec, s[40:41]
	s_mov_b64 s[40:41], -1
	s_waitcnt vmcnt(0) lgkmcnt(0)
	v_pk_mul_f32 v[154:155], v[144:145], 0.5 op_sel_hi:[1,0]
	v_pk_mul_f32 v[156:157], v[142:143], 0.5 op_sel_hi:[1,0]
	v_pk_mul_f32 v[150:151], v[148:149], 0.5 op_sel_hi:[1,0]
	v_pk_mul_f32 v[152:153], v[146:147], 0.5 op_sel_hi:[1,0]
	v_pk_mul_f32 v[146:147], v[166:167], 0.5 op_sel_hi:[1,0]
	v_pk_mul_f32 v[148:149], v[164:165], 0.5 op_sel_hi:[1,0]
	v_pk_mul_f32 v[142:143], v[170:171], 0.5 op_sel_hi:[1,0]
	v_pk_mul_f32 v[144:145], v[168:169], 0.5 op_sel_hi:[1,0]
	v_pk_fma_f32 v[126:127], v[126:127], v[154:155], v[174:175]
	v_pk_fma_f32 v[124:125], v[124:125], v[156:157], v[172:173]
	v_pk_fma_f32 v[122:123], v[122:123], v[150:151], v[192:193]
	v_pk_fma_f32 v[120:121], v[120:121], v[152:153], v[190:191]
	v_pk_fma_f32 v[108:109], v[108:109], v[148:149], v[198:199]
	v_pk_fma_f32 v[110:111], v[110:111], v[146:147], v[200:201]
	v_pk_fma_f32 v[164:165], v[102:103], v[146:147], v[212:213]
	v_pk_fma_f32 v[106:107], v[106:107], v[142:143], v[196:197]
	v_pk_fma_f32 v[104:105], v[104:105], v[144:145], v[194:195]
	v_pk_fma_f32 v[118:119], v[118:119], v[154:155], v[204:205]
	v_pk_fma_f32 v[116:117], v[116:117], v[156:157], v[202:203]
	v_pk_fma_f32 v[114:115], v[114:115], v[150:151], v[208:209]
	v_pk_fma_f32 v[112:113], v[112:113], v[152:153], v[206:207]
	v_pk_fma_f32 v[166:167], v[100:101], v[148:149], v[210:211]
	v_pk_fma_f32 v[168:169], v[98:99], v[142:143], v[216:217]
	v_pk_fma_f32 v[170:171], v[96:97], v[144:145], v[214:215]
	v_cvt_pk_f16_f32 v96, v124, v125
	v_cvt_pk_f16_f32 v97, v126, v127
	v_cvt_pk_f16_f32 v98, v120, v121
	v_cvt_pk_f16_f32 v99, v122, v123
	v_cvt_pk_f16_f32 v100, v108, v109
	v_cvt_pk_f16_f32 v109, v164, v165
	v_add_u32_e32 v164, 48, v140
	v_cvt_pk_f16_f32 v101, v110, v111
	v_cvt_pk_f16_f32 v102, v104, v105
	v_cvt_pk_f16_f32 v103, v106, v107
	v_cvt_pk_f16_f32 v104, v116, v117
	v_cvt_pk_f16_f32 v105, v118, v119
	v_cvt_pk_f16_f32 v106, v112, v113
	v_cvt_pk_f16_f32 v107, v114, v115
	v_cvt_pk_f16_f32 v108, v166, v167
	v_cvt_pk_f16_f32 v110, v170, v171
	v_cvt_pk_f16_f32 v111, v168, v169
	global_store_dwordx4 v[222:223], v[96:99], off
	global_store_dwordx4 v[222:223], v[100:103], off offset:256
	global_store_dwordx4 v[224:225], v[104:107], off
	global_store_dwordx4 v[224:225], v[108:111], off offset:256
	v_ashrrev_i32_e32 v165, 31, v164
	v_lshlrev_b64 v[112:113], 12, v[164:165]
	global_load_dwordx4 v[96:99], v[220:221], off
	global_load_dwordx4 v[100:103], v[220:221], off offset:16
	global_load_dwordx4 v[104:107], v[220:221], off offset:528
	global_load_dwordx4 v[108:111], v[220:221], off offset:512
	v_lshl_add_u64 v[124:125], v[138:139], 0, v[112:113]
	global_load_dwordx4 v[112:115], v[124:125], off
	global_load_dwordx4 v[116:119], v[124:125], off offset:16
	global_load_dwordx4 v[120:123], v[124:125], off offset:512
	s_nop 0
	global_load_dwordx4 v[124:127], v[124:125], off offset:528
	v_add_u32_e32 v166, 0x80, v140
	v_lshlrev_b64 v[168:169], 11, v[218:219]
	v_ashrrev_i32_e32 v167, 31, v166
	v_lshlrev_b64 v[164:165], 11, v[164:165]
	v_lshl_add_u64 v[168:169], v[158:159], 0, v[168:169]
	v_lshlrev_b64 v[170:171], 12, v[166:167]
	v_lshl_add_u64 v[164:165], v[158:159], 0, v[164:165]
	v_lshl_add_u64 v[170:171], v[138:139], 0, v[170:171]
	s_waitcnt vmcnt(6)
	v_pk_fma_f32 v[90:91], v[90:91], v[150:151], v[102:103]
	v_pk_fma_f32 v[94:95], v[94:95], v[154:155], v[98:99]
	v_pk_fma_f32 v[92:93], v[92:93], v[156:157], v[96:97]
	v_pk_fma_f32 v[88:89], v[88:89], v[152:153], v[100:101]
	s_waitcnt vmcnt(4)
	v_pk_fma_f32 v[76:77], v[76:77], v[148:149], v[108:109]
	s_waitcnt vmcnt(1)
	v_pk_fma_f32 v[96:97], v[70:71], v[146:147], v[122:123]
	v_pk_fma_f32 v[78:79], v[78:79], v[146:147], v[110:111]
	v_pk_fma_f32 v[74:75], v[74:75], v[142:143], v[106:107]
	v_pk_fma_f32 v[72:73], v[72:73], v[144:145], v[104:105]
	v_pk_fma_f32 v[86:87], v[86:87], v[154:155], v[114:115]
	v_pk_fma_f32 v[84:85], v[84:85], v[156:157], v[112:113]
	v_pk_fma_f32 v[82:83], v[82:83], v[150:151], v[118:119]
	v_pk_fma_f32 v[80:81], v[80:81], v[152:153], v[116:117]
	v_pk_fma_f32 v[98:99], v[68:69], v[148:149], v[120:121]
	s_waitcnt vmcnt(0)
	v_pk_fma_f32 v[100:101], v[66:67], v[142:143], v[126:127]
	v_pk_fma_f32 v[102:103], v[64:65], v[144:145], v[124:125]
	v_cvt_pk_f16_f32 v64, v92, v93
	v_cvt_pk_f16_f32 v65, v94, v95
	v_cvt_pk_f16_f32 v66, v88, v89
	v_cvt_pk_f16_f32 v67, v90, v91
	v_cvt_pk_f16_f32 v68, v76, v77
	v_cvt_pk_f16_f32 v77, v96, v97
	v_add_u32_e32 v96, 0x90, v140
	v_cvt_pk_f16_f32 v69, v78, v79
	v_cvt_pk_f16_f32 v70, v72, v73
	v_cvt_pk_f16_f32 v71, v74, v75
	v_cvt_pk_f16_f32 v72, v84, v85
	v_cvt_pk_f16_f32 v73, v86, v87
	v_cvt_pk_f16_f32 v74, v80, v81
	v_cvt_pk_f16_f32 v75, v82, v83
	v_cvt_pk_f16_f32 v76, v98, v99
	v_cvt_pk_f16_f32 v78, v102, v103
	v_cvt_pk_f16_f32 v79, v100, v101
	global_store_dwordx4 v[168:169], v[64:67], off
	global_store_dwordx4 v[168:169], v[68:71], off offset:256
	global_store_dwordx4 v[164:165], v[72:75], off
	global_store_dwordx4 v[164:165], v[76:79], off offset:256
	v_ashrrev_i32_e32 v97, 31, v96
	v_lshlrev_b64 v[80:81], 12, v[96:97]
	global_load_dwordx4 v[64:67], v[170:171], off
	global_load_dwordx4 v[68:71], v[170:171], off offset:16
	global_load_dwordx4 v[72:75], v[170:171], off offset:528
	global_load_dwordx4 v[76:79], v[170:171], off offset:512
	v_lshl_add_u64 v[92:93], v[138:139], 0, v[80:81]
	global_load_dwordx4 v[80:83], v[92:93], off
	global_load_dwordx4 v[84:87], v[92:93], off offset:16
	global_load_dwordx4 v[88:91], v[92:93], off offset:512
	s_nop 0
	global_load_dwordx4 v[92:95], v[92:93], off offset:528
	v_add_u32_e32 v98, 0xa0, v140
	v_lshlrev_b64 v[100:101], 11, v[166:167]
	v_ashrrev_i32_e32 v99, 31, v98
	v_lshlrev_b64 v[96:97], 11, v[96:97]
	v_lshl_add_u64 v[100:101], v[158:159], 0, v[100:101]
	v_lshlrev_b64 v[102:103], 12, v[98:99]
	v_lshl_add_u64 v[96:97], v[158:159], 0, v[96:97]
	v_lshl_add_u64 v[102:103], v[138:139], 0, v[102:103]
	s_waitcnt vmcnt(6)
	v_pk_fma_f32 v[58:59], v[58:59], v[150:151], v[70:71]
	v_pk_fma_f32 v[62:63], v[62:63], v[154:155], v[66:67]
	v_pk_fma_f32 v[60:61], v[60:61], v[156:157], v[64:65]
	v_pk_fma_f32 v[56:57], v[56:57], v[152:153], v[68:69]
	s_waitcnt vmcnt(4)
	v_pk_fma_f32 v[44:45], v[44:45], v[148:149], v[76:77]
	s_waitcnt vmcnt(1)
	v_pk_fma_f32 v[64:65], v[38:39], v[146:147], v[90:91]
	v_pk_fma_f32 v[46:47], v[46:47], v[146:147], v[78:79]
	v_pk_fma_f32 v[42:43], v[42:43], v[142:143], v[74:75]
	v_pk_fma_f32 v[40:41], v[40:41], v[144:145], v[72:73]
	v_pk_fma_f32 v[54:55], v[54:55], v[154:155], v[82:83]
	v_pk_fma_f32 v[52:53], v[52:53], v[156:157], v[80:81]
	v_pk_fma_f32 v[50:51], v[50:51], v[150:151], v[86:87]
	v_pk_fma_f32 v[48:49], v[48:49], v[152:153], v[84:85]
	v_pk_fma_f32 v[66:67], v[36:37], v[148:149], v[88:89]
	s_waitcnt vmcnt(0)
	v_pk_fma_f32 v[68:69], v[34:35], v[142:143], v[94:95]
	v_pk_fma_f32 v[70:71], v[32:33], v[144:145], v[92:93]
	v_cvt_pk_f16_f32 v32, v60, v61
	v_cvt_pk_f16_f32 v33, v62, v63
	v_cvt_pk_f16_f32 v34, v56, v57
	v_cvt_pk_f16_f32 v35, v58, v59
	v_cvt_pk_f16_f32 v36, v44, v45
	v_cvt_pk_f16_f32 v45, v64, v65
	v_add_u32_e32 v64, 0xb0, v140
	v_cvt_pk_f16_f32 v37, v46, v47
	v_cvt_pk_f16_f32 v38, v40, v41
	v_cvt_pk_f16_f32 v39, v42, v43
	v_cvt_pk_f16_f32 v40, v52, v53
	v_cvt_pk_f16_f32 v41, v54, v55
	v_cvt_pk_f16_f32 v42, v48, v49
	v_cvt_pk_f16_f32 v43, v50, v51
	v_cvt_pk_f16_f32 v44, v66, v67
	v_cvt_pk_f16_f32 v46, v70, v71
	v_cvt_pk_f16_f32 v47, v68, v69
	global_store_dwordx4 v[100:101], v[32:35], off
	global_store_dwordx4 v[100:101], v[36:39], off offset:256
	global_store_dwordx4 v[96:97], v[40:43], off
	global_store_dwordx4 v[96:97], v[44:47], off offset:256
	v_ashrrev_i32_e32 v65, 31, v64
	v_lshlrev_b64 v[48:49], 12, v[64:65]
	global_load_dwordx4 v[32:35], v[102:103], off
	v_lshl_add_u64 v[60:61], v[138:139], 0, v[48:49]
	global_load_dwordx4 v[36:39], v[102:103], off offset:16
	global_load_dwordx4 v[40:43], v[102:103], off offset:528
	global_load_dwordx4 v[44:47], v[102:103], off offset:512
	global_load_dwordx4 v[48:51], v[60:61], off
	global_load_dwordx4 v[52:55], v[60:61], off offset:16
	global_load_dwordx4 v[56:59], v[60:61], off offset:512
	s_nop 0
	global_load_dwordx4 v[60:63], v[60:61], off offset:528
	v_lshlrev_b64 v[66:67], 11, v[98:99]
	v_lshlrev_b64 v[64:65], 11, v[64:65]
	v_lshl_add_u64 v[66:67], v[158:159], 0, v[66:67]
	v_lshl_add_u64 v[64:65], v[158:159], 0, v[64:65]
	s_waitcnt vmcnt(7)
	v_pk_fma_f32 v[30:31], v[30:31], v[154:155], v[34:35]
	v_pk_fma_f32 v[28:29], v[28:29], v[156:157], v[32:33]
	s_waitcnt vmcnt(6)
	v_pk_fma_f32 v[26:27], v[26:27], v[150:151], v[38:39]
	v_pk_fma_f32 v[24:25], v[24:25], v[152:153], v[36:37]
	s_waitcnt vmcnt(4)
	v_pk_fma_f32 v[14:15], v[14:15], v[146:147], v[46:47]
	v_pk_fma_f32 v[12:13], v[12:13], v[148:149], v[44:45]
	v_pk_fma_f32 v[10:11], v[10:11], v[142:143], v[42:43]
	v_pk_fma_f32 v[8:9], v[8:9], v[144:145], v[40:41]
	s_waitcnt vmcnt(3)
	v_pk_fma_f32 v[22:23], v[22:23], v[154:155], v[50:51]
	v_pk_fma_f32 v[20:21], v[20:21], v[156:157], v[48:49]
	s_waitcnt vmcnt(2)
	v_pk_fma_f32 v[18:19], v[18:19], v[150:151], v[54:55]
	v_pk_fma_f32 v[16:17], v[16:17], v[152:153], v[52:53]
	s_waitcnt vmcnt(1)
	v_pk_fma_f32 v[32:33], v[6:7], v[146:147], v[58:59]
	v_pk_fma_f32 v[34:35], v[4:5], v[148:149], v[56:57]
	s_waitcnt vmcnt(0)
	v_pk_fma_f32 v[36:37], v[2:3], v[142:143], v[62:63]
	v_pk_fma_f32 v[38:39], v[0:1], v[144:145], v[60:61]
	v_cvt_pk_f16_f32 v0, v28, v29
	v_cvt_pk_f16_f32 v1, v30, v31
	v_cvt_pk_f16_f32 v2, v24, v25
	v_cvt_pk_f16_f32 v3, v26, v27
	v_cvt_pk_f16_f32 v4, v12, v13
	v_cvt_pk_f16_f32 v5, v14, v15
	v_cvt_pk_f16_f32 v6, v8, v9
	v_cvt_pk_f16_f32 v7, v10, v11
	v_cvt_pk_f16_f32 v8, v20, v21
	v_cvt_pk_f16_f32 v9, v22, v23
	v_cvt_pk_f16_f32 v10, v16, v17
	v_cvt_pk_f16_f32 v11, v18, v19
	v_cvt_pk_f16_f32 v12, v34, v35
	v_cvt_pk_f16_f32 v13, v32, v33
	v_cvt_pk_f16_f32 v14, v38, v39
	v_cvt_pk_f16_f32 v15, v36, v37
	global_store_dwordx4 v[66:67], v[0:3], off
	global_store_dwordx4 v[66:67], v[4:7], off offset:256
	global_store_dwordx4 v[64:65], v[8:11], off
	global_store_dwordx4 v[64:65], v[12:15], off offset:256
	s_cbranch_vccnz .LBB0_315
	s_andn2_b64 vcc, exec, s[34:35]
	s_cbranch_vccnz .LBB0_314
	s_barrier
	s_branch .LBB0_314

.LBB0_388:
	v_readlane_b32 s8, v255, 32
	v_readlane_b32 s9, v255, 33
	s_lshl_b32 s52, s8, 10
	v_readlane_b32 s8, v252, 10
	s_xor_b64 s[34:35], s[38:39], -1
	s_lshl_b64 s[36:37], s[52:53], 2
	v_readlane_b32 s22, v252, 24
	v_readlane_b32 s23, v252, 25
	s_add_u32 s44, s22, s36
	s_addc_u32 s45, s23, s37
	v_readlane_b32 s9, v252, 11
	s_and_b64 s[36:37], s[38:39], exec
	v_readlane_b32 s3, v255, 10
	v_and_b32_e32 v32, 63, v0
	s_cselect_b32 s3, s3, 1
	v_readlane_b32 s8, v254, 60
	s_mul_i32 s36, s3, s8
	s_and_b64 vcc, exec, s[34:35]
	v_lshlrev_b32_e32 v176, 4, v32
	v_readlane_b32 s10, v252, 12
	v_readlane_b32 s11, v252, 13
	v_readlane_b32 s12, v252, 14
	v_readlane_b32 s13, v252, 15
	v_readlane_b32 s14, v252, 16
	v_readlane_b32 s15, v252, 17
	v_readlane_b32 s16, v252, 18
	v_readlane_b32 s17, v252, 19
	v_readlane_b32 s18, v252, 20
	v_readlane_b32 s19, v252, 21
	v_readlane_b32 s20, v252, 22
	v_readlane_b32 s21, v252, 23
	v_readlane_b32 s9, v254, 61
	s_cbranch_vccnz .LBB0_390
	s_cmpk_lt_i32 s36, 0x4000
	s_cselect_b32 s3, s36, 0
	s_add_i32 s37, s3, 0xffffe000
	s_lshr_b32 s37, s37, 11
	s_ashr_i32 s22, s3, 10
	s_add_i32 s37, s37, 8
	s_cmpk_lt_i32 s3, 0x2000
	s_cselect_b32 s3, s22, s37
	s_mul_hi_i32 s22, s3, 0x9000
	s_mul_i32 s3, s3, 0x9000
	v_readlane_b32 s7, v255, 34
	s_add_u32 s3, s7, s3
	v_readlane_b32 s7, v255, 35
	s_addc_u32 s22, s7, s22
	s_add_u32 s46, s3, 0x3000
	s_addc_u32 s47, s22, 0
	s_add_u32 s68, s3, 0x4000
	s_addc_u32 s69, s22, 0
	v_lshl_add_u64 v[0:1], s[68:69], 0, v[176:177]
	global_load_dwordx4 v[8:11], v[0:1], off
	global_load_dwordx4 v[4:7], v176, s[44:45]
	global_load_dwordx4 v[12:15], v176, s[44:45] offset:1024
	global_load_dwordx4 v[20:23], v176, s[44:45] offset:2048
	global_load_dwordx4 v[28:31], v176, s[44:45] offset:3072
	v_lshl_add_u64 v[0:1], s[46:47], 0, v[176:177]
	global_load_dwordx4 v[0:3], v[0:1], off
	s_waitcnt vmcnt(0) lgkmcnt(0)
	v_pk_add_f32 v[8:9], v[8:9], 1.0 op_sel_hi:[1,0]
	v_pk_add_f32 v[10:11], v[10:11], 1.0 op_sel_hi:[1,0]
	v_pk_mul_f32 v[4:5], v[4:5], v[8:9]
	v_or_b32_e32 v8, 0x400, v176
	v_mov_b32_e32 v9, v177
	v_pk_mul_f32 v[6:7], v[6:7], v[10:11]
	v_lshl_add_u64 v[10:11], s[68:69], 0, v[8:9]
	global_load_dwordx4 v[16:19], v[10:11], off
	v_lshl_add_u64 v[8:9], s[46:47], 0, v[8:9]
	global_load_dwordx4 v[8:11], v[8:9], off
	s_waitcnt vmcnt(0) lgkmcnt(0)
	v_pk_add_f32 v[16:17], v[16:17], 1.0 op_sel_hi:[1,0]
	v_pk_add_f32 v[18:19], v[18:19], 1.0 op_sel_hi:[1,0]
	v_pk_mul_f32 v[12:13], v[12:13], v[16:17]
	v_or_b32_e32 v16, 0x800, v176
	v_mov_b32_e32 v17, v177
	v_pk_mul_f32 v[14:15], v[14:15], v[18:19]
	v_lshl_add_u64 v[18:19], s[68:69], 0, v[16:17]
	global_load_dwordx4 v[24:27], v[18:19], off
	v_lshl_add_u64 v[16:17], s[46:47], 0, v[16:17]
	global_load_dwordx4 v[16:19], v[16:17], off
	s_waitcnt vmcnt(0) lgkmcnt(0)
	v_pk_add_f32 v[24:25], v[24:25], 1.0 op_sel_hi:[1,0]
	v_pk_add_f32 v[26:27], v[26:27], 1.0 op_sel_hi:[1,0]
	v_pk_mul_f32 v[20:21], v[20:21], v[24:25]
	v_or_b32_e32 v24, 0xc00, v176
	v_mov_b32_e32 v25, v177
	v_pk_mul_f32 v[22:23], v[22:23], v[26:27]
	v_lshl_add_u64 v[26:27], s[68:69], 0, v[24:25]
	global_load_dwordx4 v[34:37], v[26:27], off
	v_lshl_add_u64 v[24:25], s[46:47], 0, v[24:25]
	global_load_dwordx4 v[24:27], v[24:25], off
	s_waitcnt vmcnt(0) lgkmcnt(0)
	v_pk_add_f32 v[36:37], v[36:37], 1.0 op_sel_hi:[1,0]
	v_pk_add_f32 v[34:35], v[34:35], 1.0 op_sel_hi:[1,0]
	v_pk_mul_f32 v[30:31], v[30:31], v[36:37]
	v_pk_mul_f32 v[28:29], v[28:29], v[34:35]

.LBB0_392:
	v_cvt_f32_f16_sdwa v81, v66 dst_sel:DWORD dst_unused:UNUSED_PAD src0_sel:WORD_1
	v_cvt_f32_f16_sdwa v85, v67 dst_sel:DWORD dst_unused:UNUSED_PAD src0_sel:WORD_1
	v_cvt_f32_f16_e32 v80, v66
	v_cvt_f32_f16_e32 v84, v67
	v_cvt_f32_f16_sdwa v79, v64 dst_sel:DWORD dst_unused:UNUSED_PAD src0_sel:WORD_1
	v_cvt_f32_f16_sdwa v83, v65 dst_sel:DWORD dst_unused:UNUSED_PAD src0_sel:WORD_1
	v_cvt_f32_f16_e32 v78, v64
	v_cvt_f32_f16_e32 v82, v65
	v_cvt_f32_f16_sdwa v73, v62 dst_sel:DWORD dst_unused:UNUSED_PAD src0_sel:WORD_1
	v_cvt_f32_f16_sdwa v77, v63 dst_sel:DWORD dst_unused:UNUSED_PAD src0_sel:WORD_1
	v_cvt_f32_f16_e32 v72, v62
	v_cvt_f32_f16_e32 v76, v63
	v_cvt_f32_f16_sdwa v71, v60 dst_sel:DWORD dst_unused:UNUSED_PAD src0_sel:WORD_1
	v_cvt_f32_f16_sdwa v75, v61 dst_sel:DWORD dst_unused:UNUSED_PAD src0_sel:WORD_1
	v_cvt_f32_f16_e32 v70, v60
	v_cvt_f32_f16_e32 v74, v61
	v_mov_b32_e32 v86, v81
	v_mov_b32_e32 v87, v85
	v_cvt_f32_f16_sdwa v65, v58 dst_sel:DWORD dst_unused:UNUSED_PAD src0_sel:WORD_1
	v_cvt_f32_f16_e32 v64, v58
	v_cvt_f32_f16_sdwa v69, v59 dst_sel:DWORD dst_unused:UNUSED_PAD src0_sel:WORD_1
	v_cvt_f32_f16_e32 v68, v59
	v_cvt_f32_f16_sdwa v63, v56 dst_sel:DWORD dst_unused:UNUSED_PAD src0_sel:WORD_1
	v_cvt_f32_f16_e32 v62, v56
	v_cvt_f32_f16_sdwa v67, v57 dst_sel:DWORD dst_unused:UNUSED_PAD src0_sel:WORD_1
	v_cvt_f32_f16_e32 v66, v57
	v_cvt_f32_f16_sdwa v57, v54 dst_sel:DWORD dst_unused:UNUSED_PAD src0_sel:WORD_1
	v_cvt_f32_f16_e32 v56, v54
	v_cvt_f32_f16_sdwa v61, v55 dst_sel:DWORD dst_unused:UNUSED_PAD src0_sel:WORD_1
	v_cvt_f32_f16_e32 v60, v55
	v_cvt_f32_f16_sdwa v55, v52 dst_sel:DWORD dst_unused:UNUSED_PAD src0_sel:WORD_1
	v_cvt_f32_f16_e32 v54, v52
	v_cvt_f32_f16_sdwa v59, v53 dst_sel:DWORD dst_unused:UNUSED_PAD src0_sel:WORD_1
	v_cvt_f32_f16_e32 v58, v53
	v_mov_b32_e32 v52, v80
	v_mov_b32_e32 v53, v84
	v_pk_mul_f32 v[86:87], v[86:87], v[86:87]
	v_mov_b32_e32 v88, v79
	v_mov_b32_e32 v89, v83
	v_pk_fma_f32 v[52:53], v[52:53], v[52:53], v[86:87]
	v_mov_b32_e32 v86, v78
	v_mov_b32_e32 v87, v82
	v_pk_mul_f32 v[88:89], v[88:89], v[88:89]
	v_mov_b32_e32 v90, v73
	v_mov_b32_e32 v91, v77
	v_pk_fma_f32 v[86:87], v[86:87], v[86:87], v[88:89]
	v_mov_b32_e32 v88, v72
	v_mov_b32_e32 v89, v76
	v_pk_mul_f32 v[90:91], v[90:91], v[90:91]
	v_mov_b32_e32 v92, v71
	v_mov_b32_e32 v93, v75
	v_pk_fma_f32 v[88:89], v[88:89], v[88:89], v[90:91]
	v_mov_b32_e32 v90, v70
	v_mov_b32_e32 v91, v74
	v_pk_mul_f32 v[92:93], v[92:93], v[92:93]
	v_mul_f32_e32 v94, v69, v69
	v_pk_fma_f32 v[90:91], v[90:91], v[90:91], v[92:93]
	v_mul_f32_e32 v92, v65, v65
	v_pk_add_f32 v[52:53], v[52:53], v[52:53] op_sel:[0,1] op_sel_hi:[1,0]
	v_pk_add_f32 v[88:89], v[88:89], v[88:89] op_sel:[0,1] op_sel_hi:[1,0]
	v_pk_fma_f32 v[92:93], v[64:65], v[64:65], v[92:93] op_sel_hi:[1,1,0]
	v_pk_fma_f32 v[94:95], v[68:69], v[68:69], v[94:95] op_sel_hi:[1,1,0]
	v_pk_mul_f32 v[100:101], v[56:57], v[56:57]
	v_pk_mul_f32 v[102:103], v[60:61], v[60:61]
	v_mov_b32_e32 v53, v100
	v_mov_b32_e32 v89, v101
	v_mov_b32_e32 v93, v102
	v_mov_b32_e32 v95, v103
	v_pk_add_f32 v[52:53], v[52:53], v[88:89]
	v_pk_add_f32 v[88:89], v[92:93], v[94:95]
	v_mul_f32_e32 v96, v63, v63
	v_mul_f32_e32 v98, v67, v67
	v_pk_add_f32 v[52:53], v[52:53], v[88:89]
	v_pk_add_f32 v[86:87], v[86:87], v[86:87] op_sel:[0,1] op_sel_hi:[1,0]
	v_pk_add_f32 v[90:91], v[90:91], v[90:91] op_sel:[0,1] op_sel_hi:[1,0]
	v_pk_fma_f32 v[96:97], v[62:63], v[62:63], v[96:97] op_sel_hi:[1,1,0]
	v_pk_fma_f32 v[98:99], v[66:67], v[66:67], v[98:99] op_sel_hi:[1,1,0]
	v_add_f32_e32 v92, v52, v53
	v_pk_mul_f32 v[52:53], v[54:55], v[54:55]
	v_pk_mul_f32 v[88:89], v[58:59], v[58:59]
	v_mov_b32_e32 v87, v52
	v_mov_b32_e32 v91, v53
	v_mov_b32_e32 v97, v88
	v_mov_b32_e32 v99, v89
	v_pk_add_f32 v[52:53], v[86:87], v[90:91]
	v_pk_add_f32 v[86:87], v[96:97], v[98:99]
	s_ashr_i32 s73, s72, 31
	v_pk_add_f32 v[52:53], v[52:53], v[86:87]
	s_add_i32 s36, s36, s38
	v_add_f32_e32 v53, v52, v53
	ds_bpermute_b32 v52, v33, v92
	v_readlane_b32 s48, v253, 44
	v_readlane_b32 s60, v253, 42
	v_readlane_b32 s62, v253, 40
	v_readlane_b32 s49, v253, 45
	s_waitcnt lgkmcnt(0)
	v_add_f32_e32 v52, v92, v52
	ds_bpermute_b32 v86, v47, v52
	v_readlane_b32 s61, v253, 43
	v_readlane_b32 s63, v253, 41
	s_waitcnt lgkmcnt(0)
	v_add_f32_e32 v52, v52, v86
	ds_bpermute_b32 v86, v49, v52
	s_waitcnt lgkmcnt(0)
	v_add_f32_e32 v52, v52, v86
	ds_bpermute_b32 v86, v51, v52
	s_waitcnt lgkmcnt(0)
	v_add_f32_e32 v52, v52, v86
	ds_bpermute_b32 v86, v108, v52
	s_waitcnt lgkmcnt(0)
	v_add_f32_e32 v52, v52, v86
	ds_bpermute_b32 v86, v109, v52
	s_waitcnt lgkmcnt(0)
	v_add_f32_e32 v52, v52, v86
	v_fmamk_f32 v52, v52, 0x3a800000, v228
	v_cmp_gt_f32_e32 vcc, s89, v52
	v_mul_f32_e32 v86, 0x4f800000, v52
	s_nop 0
	v_cndmask_b32_e32 v52, v52, v86, vcc
	v_sqrt_f32_e32 v86, v52
	s_nop 0
	v_add_u32_e32 v87, -1, v86
	v_fma_f32 v88, -v87, v86, v52
	v_cmp_ge_f32_e64 s[0:1], 0, v88
	v_add_u32_e32 v88, 1, v86
	s_nop 0
	v_cndmask_b32_e64 v87, v86, v87, s[0:1]
	v_fma_f32 v86, -v88, v86, v52
	v_cmp_lt_f32_e64 s[0:1], 0, v86
	s_nop 1
	v_cndmask_b32_e64 v86, v87, v88, s[0:1]
	v_mul_f32_e32 v87, 0x37800000, v86
	v_cndmask_b32_e32 v86, v86, v87, vcc
	v_cmp_class_f32_e32 vcc, v52, v229
	s_nop 1
	v_cndmask_b32_e32 v52, v86, v52, vcc
	v_div_scale_f32 v86, s[0:1], v52, v52, 1.0
	v_rcp_f32_e32 v87, v86
	s_nop 0
	v_fma_f32 v88, -v86, v87, 1.0
	v_fmac_f32_e32 v87, v88, v87
	v_div_scale_f32 v88, vcc, 1.0, v52, 1.0
	v_mul_f32_e32 v89, v88, v87
	v_fma_f32 v90, -v86, v89, v88
	v_fmac_f32_e32 v89, v90, v87
	v_fma_f32 v86, -v86, v89, v88
	v_div_fmas_f32 v86, v86, v87, v89
	v_div_fixup_f32 v52, v86, v52, 1.0
	ds_bpermute_b32 v86, v33, v53
	s_waitcnt lgkmcnt(0)
	v_add_f32_e32 v53, v53, v86
	ds_bpermute_b32 v86, v47, v53
	s_waitcnt lgkmcnt(0)
	v_add_f32_e32 v53, v53, v86
	ds_bpermute_b32 v86, v49, v53
	s_waitcnt lgkmcnt(0)
	v_add_f32_e32 v53, v53, v86
	ds_bpermute_b32 v86, v51, v53
	s_waitcnt lgkmcnt(0)
	v_add_f32_e32 v53, v53, v86
	ds_bpermute_b32 v86, v108, v53
	s_waitcnt lgkmcnt(0)
	v_add_f32_e32 v53, v53, v86
	ds_bpermute_b32 v86, v109, v53
	s_waitcnt lgkmcnt(0)
	v_add_f32_e32 v53, v53, v86
	v_fmamk_f32 v53, v53, 0x3a800000, v228
	v_cmp_gt_f32_e32 vcc, s89, v53
	v_mul_f32_e32 v86, 0x4f800000, v53
	s_nop 0
	v_cndmask_b32_e32 v53, v53, v86, vcc
	v_sqrt_f32_e32 v86, v53
	s_nop 0
	v_add_u32_e32 v87, -1, v86
	v_fma_f32 v88, -v87, v86, v53
	v_cmp_ge_f32_e64 s[0:1], 0, v88
	v_add_u32_e32 v88, 1, v86
	s_nop 0
	v_cndmask_b32_e64 v87, v86, v87, s[0:1]
	v_fma_f32 v86, -v88, v86, v53
	v_cmp_lt_f32_e64 s[0:1], 0, v86
	s_nop 1
	v_cndmask_b32_e64 v86, v87, v88, s[0:1]
	v_mul_f32_e32 v87, 0x37800000, v86
	v_cndmask_b32_e32 v86, v86, v87, vcc
	v_cmp_class_f32_e32 vcc, v53, v229
	s_nop 1
	v_cndmask_b32_e32 v53, v86, v53, vcc
	v_div_scale_f32 v86, s[0:1], v53, v53, 1.0
	v_rcp_f32_e32 v87, v86
	v_pk_mul_f32 v[80:81], v[80:81], v[52:53] op_sel_hi:[1,0]
	v_pk_mul_f32 v[84:85], v[84:85], v[52:53] op_sel_hi:[1,0]
	v_pk_fma_f32 v[80:81], v[4:5], v[80:81], v[0:1]
	v_fma_f32 v88, -v86, v87, 1.0
	v_fmac_f32_e32 v87, v88, v87
	v_div_scale_f32 v88, vcc, 1.0, v53, 1.0
	v_mul_f32_e32 v89, v88, v87
	v_fma_f32 v90, -v86, v89, v88
	v_fmac_f32_e32 v89, v90, v87
	v_fma_f32 v86, -v86, v89, v88
	v_div_fmas_f32 v86, v86, v87, v89
	v_div_fixup_f32 v86, v86, v53, 1.0
	v_pk_mul_f32 v[78:79], v[78:79], v[86:87] op_sel_hi:[1,0]
	v_pk_mul_f32 v[82:83], v[82:83], v[86:87] op_sel_hi:[1,0]
	v_pk_fma_f32 v[84:85], v[6:7], v[84:85], v[2:3]
	v_pk_fma_f32 v[82:83], v[6:7], v[82:83], v[2:3]
	v_pk_fma_f32 v[78:79], v[4:5], v[78:79], v[0:1]
	v_pk_add_f32 v[98:99], v[84:85], v[82:83]
	v_pk_add_f32 v[96:97], v[80:81], v[78:79]
	v_lshl_add_u64 v[88:89], v[38:39], 0, s[74:75]
	v_lshl_add_u64 v[90:91], v[38:39], 0, s[76:77]
	s_lshl_b64 s[0:1], s[72:73], 11
	v_cndmask_b32_e64 v53, v99, v85, s[40:41]
	v_cndmask_b32_e64 v87, v98, v84, s[40:41]
	v_cndmask_b32_e64 v97, v97, v81, s[40:41]
	v_cndmask_b32_e64 v96, v96, v80, s[40:41]
	v_sub_f32_e32 v98, v80, v78
	v_sub_f32_e32 v99, v81, v79
	v_sub_f32_e32 v100, v84, v82
	v_sub_f32_e32 v101, v85, v83
	v_cvt_pk_bf16_f32 v80, v80, v81
	v_cvt_pk_bf16_f32 v81, v84, v85
	v_cvt_pk_bf16_f32 v78, v78, v79
	v_cvt_pk_bf16_f32 v79, v82, v83
	v_lshl_add_u64 v[92:93], v[40:41], 0, s[0:1]
	v_cndmask_b32_e64 v101, v101, 0, s[40:41]
	v_cndmask_b32_e64 v100, v100, 0, s[40:41]
	v_cndmask_b32_e64 v99, v99, 0, s[40:41]
	v_cndmask_b32_e64 v98, v98, 0, s[40:41]
	global_store_dwordx2 v[88:89], v[80:81], off
	global_store_dwordx2 v[90:91], v[78:79], off
	v_cvt_pk_bf16_f32 v78, v96, v97
	v_cvt_pk_bf16_f32 v79, v87, v53
	v_pk_mul_f32 v[72:73], v[72:73], v[52:53] op_sel_hi:[1,0]
	v_pk_mul_f32 v[76:77], v[76:77], v[52:53] op_sel_hi:[1,0]
	v_pk_mul_f32 v[70:71], v[70:71], v[86:87] op_sel_hi:[1,0]
	v_pk_mul_f32 v[74:75], v[74:75], v[86:87] op_sel_hi:[1,0]
	v_lshl_add_u64 v[94:95], v[42:43], 0, s[0:1]
	global_store_dwordx2 v[92:93], v[78:79], off
	v_cvt_pk_bf16_f32 v78, v98, v99
	v_cvt_pk_bf16_f32 v79, v100, v101
	v_pk_fma_f32 v[76:77], v[14:15], v[76:77], v[10:11]
	v_pk_fma_f32 v[72:73], v[12:13], v[72:73], v[8:9]
	v_pk_fma_f32 v[74:75], v[14:15], v[74:75], v[10:11]
	v_pk_fma_f32 v[70:71], v[12:13], v[70:71], v[8:9]
	global_store_dwordx2 v[94:95], v[78:79], off
	v_pk_add_f32 v[78:79], v[72:73], v[70:71]
	v_pk_add_f32 v[80:81], v[76:77], v[74:75]
	v_cndmask_b32_e64 v79, v79, v73, s[40:41]
	v_cndmask_b32_e64 v53, v81, v77, s[40:41]
	v_cndmask_b32_e64 v80, v80, v76, s[40:41]
	v_cndmask_b32_e64 v78, v78, v72, s[40:41]
	v_sub_f32_e32 v81, v72, v70
	v_sub_f32_e32 v82, v73, v71
	v_sub_f32_e32 v83, v76, v74
	v_sub_f32_e32 v84, v77, v75
	v_cvt_pk_bf16_f32 v72, v72, v73
	v_cvt_pk_bf16_f32 v73, v76, v77
	v_cvt_pk_bf16_f32 v70, v70, v71
	v_cvt_pk_bf16_f32 v71, v74, v75
	v_cndmask_b32_e64 v84, v84, 0, s[40:41]
	v_cndmask_b32_e64 v83, v83, 0, s[40:41]
	v_cndmask_b32_e64 v82, v82, 0, s[40:41]
	v_cndmask_b32_e64 v81, v81, 0, s[40:41]
	global_store_dwordx2 v[88:89], v[72:73], off offset:512
	global_store_dwordx2 v[90:91], v[70:71], off offset:512
	v_cvt_pk_bf16_f32 v70, v78, v79
	v_cvt_pk_bf16_f32 v71, v80, v53
	v_pk_mul_f32 v[64:65], v[64:65], v[52:53] op_sel_hi:[1,0]
	v_pk_mul_f32 v[68:69], v[68:69], v[52:53] op_sel_hi:[1,0]
	v_pk_mul_f32 v[62:63], v[62:63], v[86:87] op_sel_hi:[1,0]
	v_pk_mul_f32 v[66:67], v[66:67], v[86:87] op_sel_hi:[1,0]
	global_store_dwordx2 v[92:93], v[70:71], off offset:512
	v_cvt_pk_bf16_f32 v70, v81, v82
	v_cvt_pk_bf16_f32 v71, v83, v84
	v_pk_fma_f32 v[68:69], v[22:23], v[68:69], v[18:19]
	v_pk_fma_f32 v[64:65], v[20:21], v[64:65], v[16:17]
	v_pk_fma_f32 v[66:67], v[22:23], v[66:67], v[18:19]
	v_pk_fma_f32 v[62:63], v[20:21], v[62:63], v[16:17]
	global_store_dwordx2 v[94:95], v[70:71], off offset:512
	v_pk_add_f32 v[70:71], v[64:65], v[62:63]
	v_pk_add_f32 v[72:73], v[68:69], v[66:67]
	v_cndmask_b32_e64 v71, v71, v65, s[40:41]
	v_cndmask_b32_e64 v53, v73, v69, s[40:41]
	v_cndmask_b32_e64 v72, v72, v68, s[40:41]
	v_cndmask_b32_e64 v70, v70, v64, s[40:41]
	v_sub_f32_e32 v73, v64, v62
	v_sub_f32_e32 v74, v65, v63
	v_sub_f32_e32 v75, v68, v66
	v_sub_f32_e32 v76, v69, v67
	v_cvt_pk_bf16_f32 v64, v64, v65
	v_cvt_pk_bf16_f32 v65, v68, v69
	v_cvt_pk_bf16_f32 v62, v62, v63
	v_cvt_pk_bf16_f32 v63, v66, v67
	v_cndmask_b32_e64 v76, v76, 0, s[40:41]
	v_cndmask_b32_e64 v75, v75, 0, s[40:41]
	v_cndmask_b32_e64 v74, v74, 0, s[40:41]
	v_cndmask_b32_e64 v73, v73, 0, s[40:41]
	global_store_dwordx2 v[88:89], v[64:65], off offset:1024
	global_store_dwordx2 v[90:91], v[62:63], off offset:1024
	v_cvt_pk_bf16_f32 v62, v70, v71
	v_cvt_pk_bf16_f32 v63, v72, v53
	v_pk_mul_f32 v[56:57], v[56:57], v[52:53] op_sel_hi:[1,0]
	v_pk_mul_f32 v[52:53], v[60:61], v[52:53] op_sel_hi:[1,0]
	v_pk_mul_f32 v[54:55], v[54:55], v[86:87] op_sel_hi:[1,0]
	v_pk_mul_f32 v[58:59], v[58:59], v[86:87] op_sel_hi:[1,0]
	global_store_dwordx2 v[92:93], v[62:63], off offset:1024
	v_cvt_pk_bf16_f32 v62, v73, v74
	v_cvt_pk_bf16_f32 v63, v75, v76
	v_pk_fma_f32 v[52:53], v[30:31], v[52:53], v[26:27]
	v_pk_fma_f32 v[56:57], v[28:29], v[56:57], v[24:25]
	v_pk_fma_f32 v[58:59], v[30:31], v[58:59], v[26:27]
	v_pk_fma_f32 v[54:55], v[28:29], v[54:55], v[24:25]
	s_add_u32 s46, s46, s68
	global_store_dwordx2 v[94:95], v[62:63], off offset:1024
	v_pk_add_f32 v[60:61], v[56:57], v[54:55]
	v_pk_add_f32 v[62:63], v[52:53], v[58:59]
	s_addc_u32 s47, s47, s69
	v_cndmask_b32_e64 v63, v63, v53, s[40:41]
	v_cndmask_b32_e64 v62, v62, v52, s[40:41]
	v_cndmask_b32_e64 v61, v61, v57, s[40:41]
	v_cndmask_b32_e64 v60, v60, v56, s[40:41]
	v_sub_f32_e32 v64, v56, v54
	v_sub_f32_e32 v65, v57, v55
	v_sub_f32_e32 v66, v52, v58
	v_sub_f32_e32 v67, v53, v59
	v_cvt_pk_bf16_f32 v56, v56, v57
	v_cvt_pk_bf16_f32 v57, v52, v53
	v_cvt_pk_bf16_f32 v52, v54, v55
	v_cvt_pk_bf16_f32 v53, v58, v59
	s_add_u32 s70, s70, s68
	v_cndmask_b32_e64 v67, v67, 0, s[40:41]
	v_cndmask_b32_e64 v66, v66, 0, s[40:41]
	v_cndmask_b32_e64 v65, v65, 0, s[40:41]
	v_cndmask_b32_e64 v64, v64, 0, s[40:41]
	global_store_dwordx2 v[88:89], v[56:57], off offset:1536
	global_store_dwordx2 v[90:91], v[52:53], off offset:1536
	v_cvt_pk_bf16_f32 v52, v60, v61
	v_cvt_pk_bf16_f32 v53, v62, v63
	s_addc_u32 s71, s71, s69
	v_readlane_b32 s76, v253, 38
	global_store_dwordx2 v[92:93], v[52:53], off offset:1536
	v_cvt_pk_bf16_f32 v52, v64, v65
	v_cvt_pk_bf16_f32 v53, v66, v67
	s_cmp_lt_i32 s36, s3
	v_readlane_b32 s77, v253, 39
	global_store_dwordx2 v[94:95], v[52:53], off offset:1536
	s_cbranch_scc0 .LBB0_405

.LBB0_401:
	s_add_i32 s58, s44, s40
	s_lshr_b32 s45, s0, 1
	s_sub_i32 s59, s0, s40
	s_cmp_eq_u32 s40, 0
	s_cselect_b64 s[40:41], -1, 0
	s_and_b64 s[0:1], s[40:41], exec
	s_cselect_b32 s0, s45, s59
	s_add_i32 s0, s0, s44
	s_ashr_i32 s59, s58, 31
	s_lshl_b64 s[74:75], s[58:59], 11
	s_ashr_i32 s1, s0, 31
	v_lshl_add_u64 v[52:53], v[36:37], 0, s[74:75]
	s_lshl_b64 s[76:77], s[0:1], 11
	v_lshl_add_u64 v[68:69], v[36:37], 0, s[76:77]
	global_load_dwordx2 v[66:67], v[52:53], off
	global_load_dwordx2 v[62:63], v[52:53], off offset:512
	global_load_dwordx2 v[58:59], v[52:53], off offset:1024
	global_load_dwordx2 v[54:55], v[52:53], off offset:1536
	global_load_dwordx2 v[64:65], v[68:69], off
	global_load_dwordx2 v[60:61], v[68:69], off offset:512
	global_load_dwordx2 v[56:57], v[68:69], off offset:1024
	s_nop 0
	global_load_dwordx2 v[52:53], v[68:69], off offset:1536
	v_cndmask_b32_e64 v68, 0, 1, s[34:35]
	v_cmp_ne_u32_e64 s[44:45], 1, v68
	s_andn2_b64 vcc, exec, s[34:35]
	v_lshlrev_b32_e32 v176, 4, v32
	v_lshlrev_b32_e32 v72, 4, v46
	v_lshlrev_b32_e32 v70, 4, v48
	v_lshlrev_b32_e32 v68, 4, v50
	s_cbranch_vccnz .LBB0_403
	s_mul_i32 s1, s39, 0x9000
	v_readlane_b32 s7, v255, 34
	s_mul_hi_i32 s0, s39, 0x9000
	s_add_u32 s39, s7, s1
	v_readlane_b32 s1, v255, 35
	s_addc_u32 s58, s1, s0
	s_add_u32 s0, s39, 0x3000
	s_addc_u32 s1, s58, 0
	s_add_u32 s82, s39, 0x4000
	s_addc_u32 s83, s58, 0
	v_lshl_add_u64 v[0:1], s[82:83], 0, v[176:177]
	global_load_dwordx4 v[8:11], v[0:1], off
	global_load_dwordx4 v[4:7], v[44:45], off
	global_load_dwordx4 v[12:15], v[44:45], off offset:1024
	v_mov_b32_e32 v73, v177
	v_lshl_add_u64 v[0:1], s[0:1], 0, v[176:177]
	global_load_dwordx4 v[0:3], v[0:1], off
	v_mov_b32_e32 v71, v177
	global_load_dwordx4 v[20:23], v[44:45], off offset:2048
	global_load_dwordx4 v[28:31], v[44:45], off offset:3072
	v_mov_b32_e32 v69, v177
	s_waitcnt vmcnt(0) lgkmcnt(0)
	v_pk_add_f32 v[8:9], v[8:9], 1.0 op_sel_hi:[1,0]
	s_nop 0
	v_pk_mul_f32 v[4:5], v[4:5], v[8:9]
	v_lshl_add_u64 v[8:9], s[82:83], 0, v[72:73]
	global_load_dwordx4 v[16:19], v[8:9], off
	v_pk_add_f32 v[10:11], v[10:11], 1.0 op_sel_hi:[1,0]
	v_lshl_add_u64 v[8:9], s[0:1], 0, v[72:73]
	v_pk_mul_f32 v[6:7], v[6:7], v[10:11]
	global_load_dwordx4 v[8:11], v[8:9], off
	s_waitcnt vmcnt(0) lgkmcnt(0)
	v_pk_add_f32 v[16:17], v[16:17], 1.0 op_sel_hi:[1,0]
	s_nop 0
	v_pk_mul_f32 v[12:13], v[12:13], v[16:17]
	v_lshl_add_u64 v[16:17], s[82:83], 0, v[70:71]
	global_load_dwordx4 v[24:27], v[16:17], off
	v_pk_add_f32 v[18:19], v[18:19], 1.0 op_sel_hi:[1,0]
	v_lshl_add_u64 v[16:17], s[0:1], 0, v[70:71]
	v_pk_mul_f32 v[14:15], v[14:15], v[18:19]
	global_load_dwordx4 v[16:19], v[16:17], off
	s_waitcnt vmcnt(0) lgkmcnt(0)
	v_pk_add_f32 v[24:25], v[24:25], 1.0 op_sel_hi:[1,0]
	s_nop 0
	v_pk_mul_f32 v[20:21], v[20:21], v[24:25]
	v_lshl_add_u64 v[24:25], s[82:83], 0, v[68:69]
	global_load_dwordx4 v[88:91], v[24:25], off
	v_pk_add_f32 v[26:27], v[26:27], 1.0 op_sel_hi:[1,0]
	v_lshl_add_u64 v[24:25], s[0:1], 0, v[68:69]
	v_pk_mul_f32 v[22:23], v[22:23], v[26:27]
	global_load_dwordx4 v[24:27], v[24:25], off
	s_waitcnt vmcnt(0) lgkmcnt(0)
	v_pk_add_f32 v[90:91], v[90:91], 1.0 op_sel_hi:[1,0]
	v_pk_add_f32 v[88:89], v[88:89], 1.0 op_sel_hi:[1,0]
	v_pk_mul_f32 v[30:31], v[30:31], v[90:91]
	v_pk_mul_f32 v[28:29], v[28:29], v[88:89]
.LBB0_403:
	s_waitcnt vmcnt(0)
	v_cvt_f32_f16_sdwa v101, v86 dst_sel:DWORD dst_unused:UNUSED_PAD src0_sel:WORD_1
	v_cvt_f32_f16_sdwa v105, v87 dst_sel:DWORD dst_unused:UNUSED_PAD src0_sel:WORD_1
	v_cvt_f32_f16_e32 v100, v86
	v_cvt_f32_f16_e32 v104, v87
	v_cvt_f32_f16_sdwa v99, v84 dst_sel:DWORD dst_unused:UNUSED_PAD src0_sel:WORD_1
	v_cvt_f32_f16_sdwa v103, v85 dst_sel:DWORD dst_unused:UNUSED_PAD src0_sel:WORD_1
	v_cvt_f32_f16_e32 v98, v84
	v_cvt_f32_f16_e32 v102, v85
	v_cvt_f32_f16_sdwa v93, v82 dst_sel:DWORD dst_unused:UNUSED_PAD src0_sel:WORD_1
	v_cvt_f32_f16_sdwa v97, v83 dst_sel:DWORD dst_unused:UNUSED_PAD src0_sel:WORD_1
	v_cvt_f32_f16_e32 v92, v82
	v_cvt_f32_f16_e32 v96, v83
	v_cvt_f32_f16_sdwa v91, v80 dst_sel:DWORD dst_unused:UNUSED_PAD src0_sel:WORD_1
	v_cvt_f32_f16_sdwa v95, v81 dst_sel:DWORD dst_unused:UNUSED_PAD src0_sel:WORD_1
	v_cvt_f32_f16_e32 v90, v80
	v_cvt_f32_f16_e32 v94, v81
	v_mov_b32_e32 v110, v101
	v_mov_b32_e32 v111, v105
	v_cvt_f32_f16_sdwa v85, v78 dst_sel:DWORD dst_unused:UNUSED_PAD src0_sel:WORD_1
	v_cvt_f32_f16_e32 v84, v78
	v_cvt_f32_f16_sdwa v89, v79 dst_sel:DWORD dst_unused:UNUSED_PAD src0_sel:WORD_1
	v_cvt_f32_f16_e32 v88, v79
	v_cvt_f32_f16_sdwa v83, v76 dst_sel:DWORD dst_unused:UNUSED_PAD src0_sel:WORD_1
	v_cvt_f32_f16_e32 v82, v76
	v_cvt_f32_f16_sdwa v87, v77 dst_sel:DWORD dst_unused:UNUSED_PAD src0_sel:WORD_1
	v_cvt_f32_f16_e32 v86, v77
	v_cvt_f32_f16_sdwa v77, v74 dst_sel:DWORD dst_unused:UNUSED_PAD src0_sel:WORD_1
	v_cvt_f32_f16_e32 v76, v74
	v_cvt_f32_f16_sdwa v81, v75 dst_sel:DWORD dst_unused:UNUSED_PAD src0_sel:WORD_1
	v_cvt_f32_f16_e32 v80, v75
	v_cvt_f32_f16_sdwa v75, v106 dst_sel:DWORD dst_unused:UNUSED_PAD src0_sel:WORD_1
	v_cvt_f32_f16_e32 v74, v106
	v_cvt_f32_f16_sdwa v79, v107 dst_sel:DWORD dst_unused:UNUSED_PAD src0_sel:WORD_1
	v_cvt_f32_f16_e32 v78, v107
	v_mov_b32_e32 v106, v100
	v_mov_b32_e32 v107, v104
	v_pk_mul_f32 v[110:111], v[110:111], v[110:111]
	v_mov_b32_e32 v112, v99
	v_mov_b32_e32 v113, v103
	v_pk_fma_f32 v[106:107], v[106:107], v[106:107], v[110:111]
	v_mov_b32_e32 v110, v98
	v_mov_b32_e32 v111, v102
	v_pk_mul_f32 v[112:113], v[112:113], v[112:113]
	v_mov_b32_e32 v114, v93
	v_mov_b32_e32 v115, v97
	v_pk_fma_f32 v[110:111], v[110:111], v[110:111], v[112:113]
	v_mov_b32_e32 v112, v92
	v_mov_b32_e32 v113, v96
	v_pk_mul_f32 v[114:115], v[114:115], v[114:115]
	v_mov_b32_e32 v116, v91
	v_mov_b32_e32 v117, v95
	v_pk_fma_f32 v[112:113], v[112:113], v[112:113], v[114:115]
	v_mov_b32_e32 v114, v90
	v_mov_b32_e32 v115, v94
	v_pk_mul_f32 v[116:117], v[116:117], v[116:117]
	v_mul_f32_e32 v118, v89, v89
	v_pk_fma_f32 v[114:115], v[114:115], v[114:115], v[116:117]
	v_mul_f32_e32 v116, v85, v85
	v_pk_add_f32 v[106:107], v[106:107], v[106:107] op_sel:[0,1] op_sel_hi:[1,0]
	v_pk_add_f32 v[112:113], v[112:113], v[112:113] op_sel:[0,1] op_sel_hi:[1,0]
	v_pk_fma_f32 v[116:117], v[84:85], v[84:85], v[116:117] op_sel_hi:[1,1,0]
	v_pk_fma_f32 v[118:119], v[88:89], v[88:89], v[118:119] op_sel_hi:[1,1,0]
	v_pk_mul_f32 v[124:125], v[76:77], v[76:77]
	v_pk_mul_f32 v[126:127], v[80:81], v[80:81]
	v_mov_b32_e32 v107, v124
	v_mov_b32_e32 v113, v125
	v_mov_b32_e32 v117, v126
	v_mov_b32_e32 v119, v127
	v_pk_add_f32 v[106:107], v[106:107], v[112:113]
	v_pk_add_f32 v[112:113], v[116:117], v[118:119]
	v_mul_f32_e32 v120, v83, v83
	v_pk_add_f32 v[106:107], v[106:107], v[112:113]
	v_mul_f32_e32 v122, v87, v87
	v_add_f32_e32 v69, v106, v107
	ds_bpermute_b32 v73, v33, v69
	v_pk_add_f32 v[110:111], v[110:111], v[110:111] op_sel:[0,1] op_sel_hi:[1,0]
	v_pk_add_f32 v[114:115], v[114:115], v[114:115] op_sel:[0,1] op_sel_hi:[1,0]
	v_pk_fma_f32 v[120:121], v[82:83], v[82:83], v[120:121] op_sel_hi:[1,1,0]
	v_pk_fma_f32 v[122:123], v[86:87], v[86:87], v[122:123] op_sel_hi:[1,1,0]
	s_waitcnt lgkmcnt(0)
	v_add_f32_e32 v69, v69, v73
	ds_bpermute_b32 v73, v47, v69
	v_pk_mul_f32 v[106:107], v[74:75], v[74:75]
	v_pk_mul_f32 v[112:113], v[78:79], v[78:79]
	v_mov_b32_e32 v111, v106
	v_mov_b32_e32 v115, v107
	s_waitcnt lgkmcnt(0)
	v_add_f32_e32 v69, v69, v73
	ds_bpermute_b32 v73, v49, v69
	v_mov_b32_e32 v121, v112
	v_mov_b32_e32 v123, v113
	v_pk_add_f32 v[106:107], v[110:111], v[114:115]
	v_pk_add_f32 v[110:111], v[120:121], v[122:123]
	s_waitcnt lgkmcnt(0)
	v_add_f32_e32 v69, v69, v73
	ds_bpermute_b32 v73, v51, v69
	v_pk_add_f32 v[106:107], v[106:107], v[110:111]
	v_lshl_add_u64 v[112:113], v[38:39], 0, s[78:79]
	v_add_f32_e32 v71, v106, v107
	v_lshl_add_u64 v[116:117], s[70:71], 0, v[34:35]
	s_waitcnt lgkmcnt(0)
	v_add_f32_e32 v69, v69, v73
	ds_bpermute_b32 v73, v108, v69
	v_lshl_add_u64 v[114:115], v[38:39], 0, s[80:81]
	v_lshl_add_u64 v[118:119], s[46:47], 0, v[34:35]
	s_waitcnt lgkmcnt(0)
	v_add_f32_e32 v69, v69, v73
	ds_bpermute_b32 v73, v109, v69
	s_waitcnt lgkmcnt(0)
	v_add_f32_e32 v69, v69, v73
	v_fmamk_f32 v69, v69, 0x3a800000, v228
	v_cmp_gt_f32_e32 vcc, s89, v69
	v_mul_f32_e32 v73, 0x4f800000, v69
	s_nop 0
	v_cndmask_b32_e32 v69, v69, v73, vcc
	v_sqrt_f32_e32 v73, v69
	s_nop 0
	v_add_u32_e32 v106, -1, v73
	v_fma_f32 v107, -v106, v73, v69
	v_cmp_ge_f32_e64 s[0:1], 0, v107
	v_add_u32_e32 v107, 1, v73
	s_nop 0
	v_cndmask_b32_e64 v106, v73, v106, s[0:1]
	v_fma_f32 v73, -v107, v73, v69
	v_cmp_lt_f32_e64 s[0:1], 0, v73
	s_nop 1
	v_cndmask_b32_e64 v73, v106, v107, s[0:1]
	v_mul_f32_e32 v106, 0x37800000, v73
	v_cndmask_b32_e32 v73, v73, v106, vcc
	v_cmp_class_f32_e32 vcc, v69, v229
	s_nop 1
	v_cndmask_b32_e32 v69, v73, v69, vcc
	v_div_scale_f32 v73, s[0:1], v69, v69, 1.0
	v_rcp_f32_e32 v106, v73
	s_nop 0
	v_fma_f32 v107, -v73, v106, 1.0
	v_fmac_f32_e32 v106, v107, v106
	v_div_scale_f32 v107, vcc, 1.0, v69, 1.0
	v_mul_f32_e32 v110, v107, v106
	v_fma_f32 v111, -v73, v110, v107
	v_fmac_f32_e32 v110, v111, v106
	v_fma_f32 v73, -v73, v110, v107
	v_div_fmas_f32 v73, v73, v106, v110
	v_div_fixup_f32 v106, v73, v69, 1.0
	ds_bpermute_b32 v69, v33, v71
	s_waitcnt lgkmcnt(0)
	v_add_f32_e32 v69, v71, v69
	ds_bpermute_b32 v71, v47, v69
	s_waitcnt lgkmcnt(0)
	v_add_f32_e32 v69, v69, v71
	ds_bpermute_b32 v71, v49, v69
	s_waitcnt lgkmcnt(0)
	v_add_f32_e32 v69, v69, v71
	ds_bpermute_b32 v71, v51, v69
	s_waitcnt lgkmcnt(0)
	v_add_f32_e32 v69, v69, v71
	ds_bpermute_b32 v71, v108, v69
	s_waitcnt lgkmcnt(0)
	v_add_f32_e32 v69, v69, v71
	ds_bpermute_b32 v71, v109, v69
	s_waitcnt lgkmcnt(0)
	v_add_f32_e32 v69, v69, v71
	v_fmamk_f32 v69, v69, 0x3a800000, v228
	v_cmp_gt_f32_e32 vcc, s89, v69
	v_mul_f32_e32 v71, 0x4f800000, v69
	s_nop 0
	v_cndmask_b32_e32 v69, v69, v71, vcc
	v_sqrt_f32_e32 v71, v69
	s_nop 0
	v_add_u32_e32 v73, -1, v71
	v_fma_f32 v107, -v73, v71, v69
	v_cmp_ge_f32_e64 s[0:1], 0, v107
	v_add_u32_e32 v107, 1, v71
	s_nop 0
	v_cndmask_b32_e64 v73, v71, v73, s[0:1]
	v_fma_f32 v71, -v107, v71, v69
	v_cmp_lt_f32_e64 s[0:1], 0, v71
	s_nop 1
	v_cndmask_b32_e64 v71, v73, v107, s[0:1]
	v_mul_f32_e32 v73, 0x37800000, v71
	v_cndmask_b32_e32 v71, v71, v73, vcc
	v_cmp_class_f32_e32 vcc, v69, v229
	s_nop 1
	v_cndmask_b32_e32 v69, v71, v69, vcc
	v_div_scale_f32 v71, s[0:1], v69, v69, 1.0
	v_rcp_f32_e32 v73, v71
	s_mov_b32 s0, 0x11b00000
	v_fma_f32 v107, -v71, v73, 1.0
	v_fmac_f32_e32 v73, v107, v73
	v_div_scale_f32 v107, vcc, 1.0, v69, 1.0
	v_mul_f32_e32 v110, v107, v73
	v_fma_f32 v111, -v71, v110, v107
	v_fmac_f32_e32 v110, v111, v73
	v_fma_f32 v71, -v71, v110, v107
	v_div_fmas_f32 v71, v71, v73, v110
	v_div_fixup_f32 v110, v71, v69, 1.0
	v_pk_mul_f32 v[100:101], v[100:101], v[106:107] op_sel_hi:[1,0]
	v_pk_mul_f32 v[98:99], v[98:99], v[110:111] op_sel_hi:[1,0]
	v_pk_mul_f32 v[104:105], v[104:105], v[106:107] op_sel_hi:[1,0]
	v_pk_fma_f32 v[100:101], v[4:5], v[100:101], v[0:1]
	v_pk_fma_f32 v[98:99], v[4:5], v[98:99], v[0:1]
	v_pk_fma_f32 v[104:105], v[6:7], v[104:105], v[2:3]
	v_pk_mul_f32 v[102:103], v[102:103], v[110:111] op_sel_hi:[1,0]
	v_pk_add_f32 v[120:121], v[100:101], v[98:99]
	v_pk_fma_f32 v[102:103], v[6:7], v[102:103], v[2:3]
	v_cndmask_b32_e64 v73, v121, v101, s[42:43]
	v_cndmask_b32_e64 v107, v120, v100, s[42:43]
	v_sub_f32_e32 v111, v100, v98
	v_sub_f32_e32 v120, v101, v99
	v_cvt_pk_bf16_f32 v100, v100, v101
	v_cvt_pk_bf16_f32 v101, v104, v105
	v_pk_add_f32 v[122:123], v[104:105], v[102:103]
	global_store_dwordx2 v[112:113], v[100:101], off
	v_add_co_u32_e32 v100, vcc, s0, v116
	v_cndmask_b32_e64 v69, v123, v105, s[42:43]
	v_cndmask_b32_e64 v71, v122, v104, s[42:43]
	v_sub_f32_e32 v121, v104, v102
	v_sub_f32_e32 v122, v105, v103
	v_cndmask_b32_e64 v111, v111, 0, s[42:43]
	v_cvt_pk_bf16_f32 v98, v98, v99
	v_cvt_pk_bf16_f32 v99, v102, v103
	v_addc_co_u32_e32 v101, vcc, 0, v117, vcc
	s_mov_b32 s0, 0x13b00000
	v_cndmask_b32_e64 v122, v122, 0, s[42:43]
	v_cndmask_b32_e64 v121, v121, 0, s[42:43]
	v_cndmask_b32_e64 v120, v120, 0, s[42:43]
	global_store_dwordx2 v[114:115], v[98:99], off
	v_cvt_pk_bf16_f32 v98, v107, v73
	v_cvt_pk_bf16_f32 v99, v71, v69
	v_add_co_u32_e32 v102, vcc, s0, v118
	v_pk_mul_f32 v[92:93], v[92:93], v[106:107] op_sel_hi:[1,0]
	v_pk_mul_f32 v[96:97], v[96:97], v[106:107] op_sel_hi:[1,0]
	v_pk_mul_f32 v[90:91], v[90:91], v[110:111] op_sel_hi:[1,0]
	v_pk_mul_f32 v[94:95], v[94:95], v[110:111] op_sel_hi:[1,0]
	global_store_dwordx2 v[100:101], v[98:99], off
	v_cvt_pk_bf16_f32 v98, v111, v120
	v_cvt_pk_bf16_f32 v99, v121, v122
	v_addc_co_u32_e32 v103, vcc, 0, v119, vcc
	v_pk_fma_f32 v[96:97], v[14:15], v[96:97], v[10:11]
	v_pk_fma_f32 v[92:93], v[12:13], v[92:93], v[8:9]
	v_pk_fma_f32 v[94:95], v[14:15], v[94:95], v[10:11]
	v_pk_fma_f32 v[90:91], v[12:13], v[90:91], v[8:9]
	global_store_dwordx2 v[102:103], v[98:99], off
	v_pk_add_f32 v[98:99], v[92:93], v[90:91]
	v_pk_add_f32 v[104:105], v[96:97], v[94:95]
	v_sub_f32_e32 v107, v97, v95
	v_cndmask_b32_e64 v69, v105, v97, s[42:43]
	v_cndmask_b32_e64 v71, v104, v96, s[42:43]
	v_cndmask_b32_e64 v73, v99, v93, s[42:43]
	v_cndmask_b32_e64 v98, v98, v92, s[42:43]
	v_sub_f32_e32 v99, v92, v90
	v_sub_f32_e32 v104, v93, v91
	v_sub_f32_e32 v105, v96, v94
	v_cndmask_b32_e64 v107, v107, 0, s[42:43]
	v_cvt_pk_bf16_f32 v92, v92, v93
	v_cvt_pk_bf16_f32 v93, v96, v97
	v_cvt_pk_bf16_f32 v90, v90, v91
	v_cvt_pk_bf16_f32 v91, v94, v95
	v_cndmask_b32_e64 v105, v105, 0, s[42:43]
	v_cndmask_b32_e64 v104, v104, 0, s[42:43]
	v_cndmask_b32_e64 v99, v99, 0, s[42:43]
	global_store_dwordx2 v[112:113], v[92:93], off offset:512
	global_store_dwordx2 v[114:115], v[90:91], off offset:512
	v_cvt_pk_bf16_f32 v90, v98, v73
	v_cvt_pk_bf16_f32 v91, v71, v69
	v_pk_mul_f32 v[84:85], v[84:85], v[106:107] op_sel_hi:[1,0]
	v_pk_mul_f32 v[88:89], v[88:89], v[106:107] op_sel_hi:[1,0]
	v_pk_mul_f32 v[82:83], v[82:83], v[110:111] op_sel_hi:[1,0]
	v_pk_mul_f32 v[86:87], v[86:87], v[110:111] op_sel_hi:[1,0]
	global_store_dwordx2 v[100:101], v[90:91], off offset:512
	v_cvt_pk_bf16_f32 v90, v99, v104
	v_cvt_pk_bf16_f32 v91, v105, v107
	v_pk_fma_f32 v[88:89], v[22:23], v[88:89], v[18:19]
	v_pk_fma_f32 v[84:85], v[20:21], v[84:85], v[16:17]
	v_pk_fma_f32 v[86:87], v[22:23], v[86:87], v[18:19]
	v_pk_fma_f32 v[82:83], v[20:21], v[82:83], v[16:17]
	global_store_dwordx2 v[102:103], v[90:91], off offset:512
	v_pk_add_f32 v[90:91], v[84:85], v[82:83]
	v_pk_add_f32 v[92:93], v[88:89], v[86:87]
	v_cndmask_b32_e64 v73, v91, v85, s[42:43]
	v_cndmask_b32_e64 v69, v93, v89, s[42:43]
	v_cndmask_b32_e64 v71, v92, v88, s[42:43]
	v_cndmask_b32_e64 v90, v90, v84, s[42:43]
	v_sub_f32_e32 v91, v84, v82
	v_sub_f32_e32 v92, v85, v83
	v_sub_f32_e32 v93, v88, v86
	v_sub_f32_e32 v94, v89, v87
	v_cvt_pk_bf16_f32 v84, v84, v85
	v_cvt_pk_bf16_f32 v85, v88, v89
	v_cvt_pk_bf16_f32 v82, v82, v83
	v_cvt_pk_bf16_f32 v83, v86, v87
	v_cndmask_b32_e64 v94, v94, 0, s[42:43]
	v_cndmask_b32_e64 v93, v93, 0, s[42:43]
	v_cndmask_b32_e64 v92, v92, 0, s[42:43]
	v_cndmask_b32_e64 v91, v91, 0, s[42:43]
	global_store_dwordx2 v[112:113], v[84:85], off offset:1024
	global_store_dwordx2 v[114:115], v[82:83], off offset:1024
	v_cvt_pk_bf16_f32 v82, v90, v73
	v_cvt_pk_bf16_f32 v83, v71, v69
	v_pk_mul_f32 v[76:77], v[76:77], v[106:107] op_sel_hi:[1,0]
	v_pk_mul_f32 v[80:81], v[80:81], v[106:107] op_sel_hi:[1,0]
	v_pk_mul_f32 v[74:75], v[74:75], v[110:111] op_sel_hi:[1,0]
	v_pk_mul_f32 v[78:79], v[78:79], v[110:111] op_sel_hi:[1,0]
	global_store_dwordx2 v[100:101], v[82:83], off offset:1024
	v_cvt_pk_bf16_f32 v82, v91, v92
	v_cvt_pk_bf16_f32 v83, v93, v94
	v_pk_fma_f32 v[80:81], v[30:31], v[80:81], v[26:27]
	v_pk_fma_f32 v[76:77], v[28:29], v[76:77], v[24:25]
	v_pk_fma_f32 v[78:79], v[30:31], v[78:79], v[26:27]
	v_pk_fma_f32 v[74:75], v[28:29], v[74:75], v[24:25]
	global_store_dwordx2 v[102:103], v[82:83], off offset:1024
	v_pk_add_f32 v[82:83], v[76:77], v[74:75]
	v_pk_add_f32 v[84:85], v[80:81], v[78:79]
	v_cndmask_b32_e64 v73, v83, v77, s[42:43]
	v_cndmask_b32_e64 v69, v85, v81, s[42:43]
	v_cndmask_b32_e64 v71, v84, v80, s[42:43]
	v_cndmask_b32_e64 v82, v82, v76, s[42:43]
	v_sub_f32_e32 v83, v76, v74
	v_sub_f32_e32 v84, v77, v75
	v_sub_f32_e32 v85, v80, v78
	v_sub_f32_e32 v86, v81, v79
	v_cvt_pk_bf16_f32 v76, v76, v77
	v_cvt_pk_bf16_f32 v77, v80, v81
	v_cvt_pk_bf16_f32 v74, v74, v75
	v_cvt_pk_bf16_f32 v75, v78, v79
	v_cndmask_b32_e64 v86, v86, 0, s[42:43]
	v_cndmask_b32_e64 v85, v85, 0, s[42:43]
	v_cndmask_b32_e64 v84, v84, 0, s[42:43]
	v_cndmask_b32_e64 v83, v83, 0, s[42:43]
	global_store_dwordx2 v[112:113], v[76:77], off offset:1536
	global_store_dwordx2 v[114:115], v[74:75], off offset:1536
	v_cvt_pk_bf16_f32 v74, v82, v73
	v_cvt_pk_bf16_f32 v75, v71, v69
	global_store_dwordx2 v[100:101], v[74:75], off offset:1536
	v_cvt_pk_bf16_f32 v74, v83, v84
	v_cvt_pk_bf16_f32 v75, v85, v86
	s_and_b64 vcc, exec, s[44:45]
	global_store_dwordx2 v[102:103], v[74:75], off offset:1536
	s_cbranch_vccnz .LBB0_392
	s_mul_i32 s1, s37, 0x9000
	v_readlane_b32 s7, v255, 34
	s_mul_hi_i32 s0, s37, 0x9000
	s_add_u32 s37, s7, s1
	v_readlane_b32 s1, v255, 35
	s_addc_u32 s39, s1, s0
	s_add_u32 s0, s37, 0x3000
	s_addc_u32 s1, s39, 0
	s_add_u32 s42, s37, 0x4000
	s_addc_u32 s43, s39, 0
	v_lshl_add_u64 v[0:1], s[42:43], 0, v[176:177]
	global_load_dwordx4 v[8:11], v[0:1], off
	global_load_dwordx4 v[4:7], v[44:45], off
	global_load_dwordx4 v[12:15], v[44:45], off offset:1024
	v_mov_b32_e32 v73, v177
	v_lshl_add_u64 v[0:1], s[0:1], 0, v[176:177]
	global_load_dwordx4 v[0:3], v[0:1], off
	v_mov_b32_e32 v71, v177
	global_load_dwordx4 v[20:23], v[44:45], off offset:2048
	global_load_dwordx4 v[28:31], v[44:45], off offset:3072
	v_mov_b32_e32 v69, v177
	s_waitcnt vmcnt(0) lgkmcnt(0)
	v_pk_add_f32 v[8:9], v[8:9], 1.0 op_sel_hi:[1,0]
	s_nop 0
	v_pk_mul_f32 v[4:5], v[4:5], v[8:9]
	v_lshl_add_u64 v[8:9], s[42:43], 0, v[72:73]
	global_load_dwordx4 v[16:19], v[8:9], off
	v_pk_add_f32 v[10:11], v[10:11], 1.0 op_sel_hi:[1,0]
	v_lshl_add_u64 v[8:9], s[0:1], 0, v[72:73]
	v_pk_mul_f32 v[6:7], v[6:7], v[10:11]
	global_load_dwordx4 v[8:11], v[8:9], off
	s_waitcnt vmcnt(0) lgkmcnt(0)
	v_pk_add_f32 v[16:17], v[16:17], 1.0 op_sel_hi:[1,0]
	s_nop 0
	v_pk_mul_f32 v[12:13], v[12:13], v[16:17]
	v_lshl_add_u64 v[16:17], s[42:43], 0, v[70:71]
	global_load_dwordx4 v[24:27], v[16:17], off
	v_pk_add_f32 v[18:19], v[18:19], 1.0 op_sel_hi:[1,0]
	v_lshl_add_u64 v[16:17], s[0:1], 0, v[70:71]
	v_pk_mul_f32 v[14:15], v[14:15], v[18:19]
	global_load_dwordx4 v[16:19], v[16:17], off
	s_waitcnt vmcnt(0) lgkmcnt(0)
	v_pk_add_f32 v[24:25], v[24:25], 1.0 op_sel_hi:[1,0]
	s_nop 0
	v_pk_mul_f32 v[20:21], v[20:21], v[24:25]
	v_lshl_add_u64 v[24:25], s[42:43], 0, v[68:69]
	global_load_dwordx4 v[70:73], v[24:25], off
	v_pk_add_f32 v[26:27], v[26:27], 1.0 op_sel_hi:[1,0]
	v_lshl_add_u64 v[24:25], s[0:1], 0, v[68:69]
	v_pk_mul_f32 v[22:23], v[22:23], v[26:27]
	global_load_dwordx4 v[24:27], v[24:25], off
	s_waitcnt vmcnt(0) lgkmcnt(0)
	v_pk_add_f32 v[68:69], v[72:73], 1.0 op_sel_hi:[1,0]
	v_pk_add_f32 v[70:71], v[70:71], 1.0 op_sel_hi:[1,0]
	v_pk_mul_f32 v[30:31], v[30:31], v[68:69]
	v_pk_mul_f32 v[28:29], v[28:29], v[70:71]
	s_branch .LBB0_392

.LBB0_465:
	v_readlane_b32 s4, v252, 0
	s_cmp_lt_i32 s63, 2
	v_readlane_b32 s8, v252, 4
	v_readlane_b32 s9, v252, 5
	v_readlane_b32 s10, v252, 6
	v_readlane_b32 s11, v252, 7
	s_cselect_b64 vcc, -1, 0
	v_readlane_b32 s8, v252, 26
	s_and_b64 s[68:69], vcc, exec
	v_readlane_b32 s5, v252, 1
	v_readlane_b32 s22, v252, 40
	v_readlane_b32 s23, v252, 41
	s_cselect_b32 s69, s83, s58
	s_cselect_b32 s68, s82, s3
	s_cselect_b32 s35, s23, s5
	s_cselect_b32 s37, s22, s4
	s_lshl_b64 s[70:71], s[44:45], 2
	s_add_u32 s70, s37, s70
	v_mov_b32_e32 v140, 0x3e38aa3b
	s_addc_u32 s71, s35, s71
	v_cndmask_b32_e32 v160, 1.0, v140, vcc
	global_load_dwordx4 v[148:151], v168, s[70:71] offset:16
	global_load_dwordx4 v[140:143], v168, s[70:71]
	s_lshl_b32 s35, s63, 8
	s_and_b32 s35, s35, 0x100
	v_pk_mul_f32 v[170:171], v[124:125], v[124:125]
	v_mul_f32_e32 v169, v113, v113
	s_mov_b32 s4, 0x20000
	v_readlane_b32 s6, v252, 2
	v_readlane_b32 s7, v252, 3
	v_readlane_b32 s9, v252, 27
	v_readlane_b32 s10, v252, 28
	v_readlane_b32 s11, v252, 29
	v_readlane_b32 s12, v252, 30
	v_readlane_b32 s13, v252, 31
	v_readlane_b32 s14, v252, 32
	v_readlane_b32 s15, v252, 33
	v_readlane_b32 s16, v252, 34
	v_readlane_b32 s17, v252, 35
	v_readlane_b32 s18, v252, 36
	v_readlane_b32 s19, v252, 37
	v_readlane_b32 s20, v252, 38
	v_readlane_b32 s21, v252, 39
	s_waitcnt vmcnt(0)
	v_pk_mul_f32 v[144:145], v[160:161], v[142:143] op_sel_hi:[0,1]
	v_pk_mul_f32 v[146:147], v[160:161], v[140:141] op_sel_hi:[0,1]
	v_pk_mul_f32 v[140:141], v[160:161], v[150:151] op_sel_hi:[0,1]
	v_pk_mul_f32 v[142:143], v[160:161], v[148:149] op_sel_hi:[0,1]
	global_load_dwordx4 v[156:159], v168, s[70:71] offset:144
	global_load_dwordx4 v[148:151], v168, s[70:71] offset:128
	s_waitcnt vmcnt(0)
	v_pk_mul_f32 v[152:153], v[160:161], v[150:151] op_sel_hi:[0,1]
	v_pk_mul_f32 v[150:151], v[160:161], v[156:157] op_sel_hi:[0,1]
	v_or_b32_e32 v156, s35, v166
	v_lshlrev_b32_e32 v176, 1, v156
	v_pk_mul_f32 v[156:157], v[126:127], v[126:127]
	v_pk_mul_f32 v[154:155], v[160:161], v[148:149] op_sel_hi:[0,1]
	v_pk_mov_b32 v[172:173], v[170:171], v[156:157] op_sel:[1,0]
	v_mov_b32_e32 v171, v157
	v_pk_add_f32 v[156:157], v[172:173], v[170:171]
	v_pk_mul_f32 v[170:171], v[122:123], v[122:123]
	v_pk_mul_f32 v[172:173], v[120:121], v[120:121]
	v_pk_mul_f32 v[148:149], v[160:161], v[158:159] op_sel_hi:[0,1]
	v_pk_mov_b32 v[174:175], v[172:173], v[170:171] op_sel:[1,0]
	v_mov_b32_e32 v173, v171
	v_pk_add_f32 v[170:171], v[174:175], v[172:173]
	v_mul_f32_e32 v161, v112, v112
	v_pk_add_f32 v[156:157], v[156:157], v[156:157] op_sel:[0,1] op_sel_hi:[1,0]
	v_pk_add_f32 v[170:171], v[170:171], v[170:171] op_sel:[0,1] op_sel_hi:[1,0]
	v_mov_b32_e32 v157, v161
	v_mov_b32_e32 v171, v169
	v_pk_add_f32 v[156:157], v[156:157], v[170:171]
	v_mul_f32_e32 v170, v117, v117
	v_mul_f32_e32 v172, v114, v114
	v_pk_fma_f32 v[170:171], v[116:117], v[116:117], v[170:171] op_sel_hi:[1,1,0]
	v_mul_f32_e32 v174, v115, v115
	v_mov_b32_e32 v171, v172
	v_mul_f32_e32 v172, v119, v119
	v_pk_fma_f32 v[172:173], v[118:119], v[118:119], v[172:173] op_sel_hi:[1,1,0]
	v_lshl_add_u32 v160, s62, 8, v162
	v_mov_b32_e32 v173, v174
	v_pk_add_f32 v[170:171], v[170:171], v[172:173]
	v_ashrrev_i32_e32 v161, 31, v160
	v_pk_add_f32 v[156:157], v[156:157], v[170:171]
	v_lshl_add_u64 v[158:159], s[68:69], 0, v[176:177]
	v_add_f32_e32 v156, v156, v157
	ds_bpermute_b32 v157, v164, v156
	s_mov_b64 s[62:63], 0x24000
	s_mov_b64 s[68:69], -1
	s_waitcnt lgkmcnt(0)
	v_add_f32_e32 v156, v156, v157
	ds_bpermute_b32 v157, v165, v156
	s_waitcnt lgkmcnt(0)
	v_add_f32_e32 v156, v156, v157
	v_fmamk_f32 v156, v156, 0x3c800000, v228
	v_rsq_f32_e32 v170, v156
	v_lshlrev_b64 v[156:157], 10, v[160:161]
	v_lshl_add_u64 v[156:157], v[158:159], 0, v[156:157]
	v_pk_mul_f32 v[124:125], v[124:125], v[170:171] op_sel_hi:[1,0]
	v_pk_mul_f32 v[126:127], v[126:127], v[170:171] op_sel_hi:[1,0]
	v_pk_mul_f32 v[120:121], v[120:121], v[170:171] op_sel_hi:[1,0]
	v_pk_mul_f32 v[122:123], v[122:123], v[170:171] op_sel_hi:[1,0]
	v_pk_mul_f32 v[126:127], v[144:145], v[126:127]
	v_pk_mul_f32 v[124:125], v[146:147], v[124:125]
	v_pk_mul_f32 v[172:173], v[140:141], v[122:123]
	v_pk_mul_f32 v[122:123], v[142:143], v[120:121]
	v_cvt_pk_bf16_f32 v120, v124, v125
	v_cvt_pk_bf16_f32 v121, v126, v127
	v_cvt_pk_bf16_f32 v122, v122, v123
	v_cvt_pk_bf16_f32 v123, v172, v173
	v_pk_mul_f32 v[116:117], v[116:117], v[170:171] op_sel_hi:[1,0]
	v_pk_mul_f32 v[118:119], v[118:119], v[170:171] op_sel_hi:[1,0]
	v_pk_mul_f32 v[112:113], v[112:113], v[170:171] op_sel_hi:[1,0]
	v_pk_mul_f32 v[114:115], v[114:115], v[170:171] op_sel_hi:[1,0]
	global_store_dwordx4 v[156:157], v[120:123], off
	v_pk_mul_f32 v[118:119], v[152:153], v[118:119]
	v_pk_mul_f32 v[116:117], v[154:155], v[116:117]
	v_pk_mul_f32 v[120:121], v[148:149], v[114:115]
	v_pk_mul_f32 v[114:115], v[150:151], v[112:113]
	v_cvt_pk_bf16_f32 v112, v116, v117
	v_cvt_pk_bf16_f32 v113, v118, v119
	v_cvt_pk_bf16_f32 v114, v114, v115
	v_cvt_pk_bf16_f32 v115, v120, v121
	global_store_dwordx4 v[156:157], v[112:115], off offset:64
	s_nop 1
	v_pk_mul_f32 v[112:113], v[110:111], v[110:111]
	v_pk_mul_f32 v[114:115], v[108:109], v[108:109]
	s_nop 0
	v_pk_mov_b32 v[116:117], v[114:115], v[112:113] op_sel:[1,0]
	v_mov_b32_e32 v115, v113
	v_pk_add_f32 v[112:113], v[116:117], v[114:115]
	v_pk_mul_f32 v[114:115], v[106:107], v[106:107]
	v_pk_mul_f32 v[116:117], v[104:105], v[104:105]
	v_pk_add_f32 v[112:113], v[112:113], v[112:113] op_sel:[0,1] op_sel_hi:[1,0]
	v_pk_mov_b32 v[118:119], v[116:117], v[114:115] op_sel:[1,0]
	v_mov_b32_e32 v117, v115
	v_pk_add_f32 v[114:115], v[118:119], v[116:117]
	v_mul_f32_e32 v116, v96, v96
	v_mul_f32_e32 v117, v97, v97
	v_pk_add_f32 v[114:115], v[114:115], v[114:115] op_sel:[0,1] op_sel_hi:[1,0]
	v_mov_b32_e32 v113, v116
	v_mov_b32_e32 v115, v117
	v_pk_add_f32 v[112:113], v[112:113], v[114:115]
	v_mul_f32_e32 v114, v101, v101
	v_mul_f32_e32 v116, v103, v103
	v_mul_f32_e32 v118, v98, v98
	v_mul_f32_e32 v119, v99, v99
	v_pk_fma_f32 v[114:115], v[100:101], v[100:101], v[114:115] op_sel_hi:[1,1,0]
	v_pk_fma_f32 v[116:117], v[102:103], v[102:103], v[116:117] op_sel_hi:[1,1,0]
	v_mov_b32_e32 v115, v118
	v_mov_b32_e32 v117, v119
	v_pk_add_f32 v[114:115], v[114:115], v[116:117]
	s_nop 0
	v_pk_add_f32 v[112:113], v[112:113], v[114:115]
	v_or_b32_e32 v114, 16, v160
	v_add_f32_e32 v112, v112, v113
	ds_bpermute_b32 v113, v164, v112
	v_ashrrev_i32_e32 v115, 31, v114
	v_lshlrev_b64 v[114:115], 10, v[114:115]
	v_lshl_add_u64 v[114:115], v[158:159], 0, v[114:115]
	s_waitcnt lgkmcnt(0)
	v_add_f32_e32 v112, v112, v113
	ds_bpermute_b32 v113, v165, v112
	s_waitcnt lgkmcnt(0)
	v_add_f32_e32 v112, v112, v113
	v_fmamk_f32 v112, v112, 0x3c800000, v228
	v_rsq_f32_e32 v112, v112
	s_nop 0
	v_pk_mul_f32 v[108:109], v[108:109], v[112:113] op_sel_hi:[1,0]
	v_pk_mul_f32 v[110:111], v[110:111], v[112:113] op_sel_hi:[1,0]
	v_pk_mul_f32 v[104:105], v[104:105], v[112:113] op_sel_hi:[1,0]
	v_pk_mul_f32 v[106:107], v[106:107], v[112:113] op_sel_hi:[1,0]
	v_pk_mul_f32 v[110:111], v[144:145], v[110:111]
	v_pk_mul_f32 v[108:109], v[146:147], v[108:109]
	v_pk_mul_f32 v[116:117], v[140:141], v[106:107]
	v_pk_mul_f32 v[106:107], v[142:143], v[104:105]
	v_cvt_pk_bf16_f32 v104, v108, v109
	v_cvt_pk_bf16_f32 v105, v110, v111
	v_cvt_pk_bf16_f32 v106, v106, v107
	v_cvt_pk_bf16_f32 v107, v116, v117
	v_pk_mul_f32 v[100:101], v[100:101], v[112:113] op_sel_hi:[1,0]
	v_pk_mul_f32 v[102:103], v[102:103], v[112:113] op_sel_hi:[1,0]
	v_pk_mul_f32 v[96:97], v[96:97], v[112:113] op_sel_hi:[1,0]
	v_pk_mul_f32 v[98:99], v[98:99], v[112:113] op_sel_hi:[1,0]
	global_store_dwordx4 v[114:115], v[104:107], off
	v_pk_mul_f32 v[102:103], v[152:153], v[102:103]
	v_pk_mul_f32 v[100:101], v[154:155], v[100:101]
	v_pk_mul_f32 v[104:105], v[148:149], v[98:99]
	v_pk_mul_f32 v[98:99], v[150:151], v[96:97]
	v_cvt_pk_bf16_f32 v96, v100, v101
	v_cvt_pk_bf16_f32 v97, v102, v103
	v_cvt_pk_bf16_f32 v98, v98, v99
	v_cvt_pk_bf16_f32 v99, v104, v105
	global_store_dwordx4 v[114:115], v[96:99], off offset:64
	s_nop 1
	v_pk_mul_f32 v[96:97], v[94:95], v[94:95]
	v_pk_mul_f32 v[98:99], v[92:93], v[92:93]
	s_nop 0
	v_pk_mov_b32 v[100:101], v[98:99], v[96:97] op_sel:[1,0]
	v_mov_b32_e32 v99, v97
	v_pk_add_f32 v[96:97], v[100:101], v[98:99]
	v_pk_mul_f32 v[98:99], v[90:91], v[90:91]
	v_pk_mul_f32 v[100:101], v[88:89], v[88:89]
	v_pk_add_f32 v[96:97], v[96:97], v[96:97] op_sel:[0,1] op_sel_hi:[1,0]
	v_pk_mov_b32 v[102:103], v[100:101], v[98:99] op_sel:[1,0]
	v_mov_b32_e32 v101, v99
	v_pk_add_f32 v[98:99], v[102:103], v[100:101]
	v_mul_f32_e32 v100, v80, v80
	v_mul_f32_e32 v101, v81, v81
	v_pk_add_f32 v[98:99], v[98:99], v[98:99] op_sel:[0,1] op_sel_hi:[1,0]
	v_mov_b32_e32 v97, v100
	v_mov_b32_e32 v99, v101
	v_pk_add_f32 v[96:97], v[96:97], v[98:99]
	v_mul_f32_e32 v98, v85, v85
	v_mul_f32_e32 v100, v87, v87
	v_mul_f32_e32 v102, v82, v82
	v_mul_f32_e32 v103, v83, v83
	v_pk_fma_f32 v[98:99], v[84:85], v[84:85], v[98:99] op_sel_hi:[1,1,0]
	v_pk_fma_f32 v[100:101], v[86:87], v[86:87], v[100:101] op_sel_hi:[1,1,0]
	v_mov_b32_e32 v99, v102
	v_mov_b32_e32 v101, v103
	v_pk_add_f32 v[98:99], v[98:99], v[100:101]
	s_nop 0
	v_pk_add_f32 v[96:97], v[96:97], v[98:99]
	v_or_b32_e32 v98, 32, v160
	v_add_f32_e32 v96, v96, v97
	ds_bpermute_b32 v97, v164, v96
	v_ashrrev_i32_e32 v99, 31, v98
	v_lshlrev_b64 v[98:99], 10, v[98:99]
	v_lshl_add_u64 v[98:99], v[158:159], 0, v[98:99]
	s_waitcnt lgkmcnt(0)
	v_add_f32_e32 v96, v96, v97
	ds_bpermute_b32 v97, v165, v96
	s_waitcnt lgkmcnt(0)
	v_add_f32_e32 v96, v96, v97
	v_fmamk_f32 v96, v96, 0x3c800000, v228
	v_rsq_f32_e32 v96, v96
	s_nop 0
	v_pk_mul_f32 v[92:93], v[92:93], v[96:97] op_sel_hi:[1,0]
	v_pk_mul_f32 v[94:95], v[94:95], v[96:97] op_sel_hi:[1,0]
	v_pk_mul_f32 v[88:89], v[88:89], v[96:97] op_sel_hi:[1,0]
	v_pk_mul_f32 v[90:91], v[90:91], v[96:97] op_sel_hi:[1,0]
	v_pk_mul_f32 v[94:95], v[144:145], v[94:95]
	v_pk_mul_f32 v[92:93], v[146:147], v[92:93]
	v_pk_mul_f32 v[100:101], v[140:141], v[90:91]
	v_pk_mul_f32 v[90:91], v[142:143], v[88:89]
	v_cvt_pk_bf16_f32 v88, v92, v93
	v_cvt_pk_bf16_f32 v89, v94, v95
	v_cvt_pk_bf16_f32 v90, v90, v91
	v_cvt_pk_bf16_f32 v91, v100, v101
	v_pk_mul_f32 v[84:85], v[84:85], v[96:97] op_sel_hi:[1,0]
	v_pk_mul_f32 v[86:87], v[86:87], v[96:97] op_sel_hi:[1,0]
	v_pk_mul_f32 v[80:81], v[80:81], v[96:97] op_sel_hi:[1,0]
	v_pk_mul_f32 v[82:83], v[82:83], v[96:97] op_sel_hi:[1,0]
	global_store_dwordx4 v[98:99], v[88:91], off
	v_pk_mul_f32 v[86:87], v[152:153], v[86:87]
	v_pk_mul_f32 v[84:85], v[154:155], v[84:85]
	v_pk_mul_f32 v[88:89], v[148:149], v[82:83]
	v_pk_mul_f32 v[82:83], v[150:151], v[80:81]
	v_cvt_pk_bf16_f32 v80, v84, v85
	v_cvt_pk_bf16_f32 v81, v86, v87
	v_cvt_pk_bf16_f32 v82, v82, v83
	v_cvt_pk_bf16_f32 v83, v88, v89
	global_store_dwordx4 v[98:99], v[80:83], off offset:64
	s_nop 1
	v_pk_mul_f32 v[80:81], v[78:79], v[78:79]
	v_pk_mul_f32 v[82:83], v[76:77], v[76:77]
	s_nop 0
	v_pk_mov_b32 v[84:85], v[82:83], v[80:81] op_sel:[1,0]
	v_mov_b32_e32 v83, v81
	v_pk_add_f32 v[80:81], v[84:85], v[82:83]
	v_pk_mul_f32 v[82:83], v[74:75], v[74:75]
	v_pk_mul_f32 v[84:85], v[72:73], v[72:73]
	v_pk_add_f32 v[80:81], v[80:81], v[80:81] op_sel:[0,1] op_sel_hi:[1,0]
	v_pk_mov_b32 v[86:87], v[84:85], v[82:83] op_sel:[1,0]
	v_mov_b32_e32 v85, v83
	v_pk_add_f32 v[82:83], v[86:87], v[84:85]
	v_mul_f32_e32 v84, v64, v64
	v_mul_f32_e32 v85, v65, v65
	v_pk_add_f32 v[82:83], v[82:83], v[82:83] op_sel:[0,1] op_sel_hi:[1,0]
	v_mov_b32_e32 v81, v84
	v_mov_b32_e32 v83, v85
	v_pk_add_f32 v[80:81], v[80:81], v[82:83]
	v_mul_f32_e32 v82, v69, v69
	v_mul_f32_e32 v84, v71, v71
	v_mul_f32_e32 v86, v66, v66
	v_mul_f32_e32 v87, v67, v67
	v_pk_fma_f32 v[82:83], v[68:69], v[68:69], v[82:83] op_sel_hi:[1,1,0]
	v_pk_fma_f32 v[84:85], v[70:71], v[70:71], v[84:85] op_sel_hi:[1,1,0]
	v_mov_b32_e32 v83, v86
	v_mov_b32_e32 v85, v87
	v_pk_add_f32 v[82:83], v[82:83], v[84:85]
	s_nop 0
	v_pk_add_f32 v[80:81], v[80:81], v[82:83]
	v_or_b32_e32 v82, 48, v160
	v_add_f32_e32 v80, v80, v81
	ds_bpermute_b32 v81, v164, v80
	v_ashrrev_i32_e32 v83, 31, v82
	v_lshlrev_b64 v[82:83], 10, v[82:83]
	v_lshl_add_u64 v[82:83], v[158:159], 0, v[82:83]
	s_waitcnt lgkmcnt(0)
	v_add_f32_e32 v80, v80, v81
	ds_bpermute_b32 v81, v165, v80
	s_waitcnt lgkmcnt(0)
	v_add_f32_e32 v80, v80, v81
	v_fmamk_f32 v80, v80, 0x3c800000, v228
	v_rsq_f32_e32 v80, v80
	s_nop 0
	v_pk_mul_f32 v[76:77], v[76:77], v[80:81] op_sel_hi:[1,0]
	v_pk_mul_f32 v[78:79], v[78:79], v[80:81] op_sel_hi:[1,0]
	v_pk_mul_f32 v[72:73], v[72:73], v[80:81] op_sel_hi:[1,0]
	v_pk_mul_f32 v[74:75], v[74:75], v[80:81] op_sel_hi:[1,0]
	v_pk_mul_f32 v[78:79], v[144:145], v[78:79]
	v_pk_mul_f32 v[76:77], v[146:147], v[76:77]
	v_pk_mul_f32 v[84:85], v[140:141], v[74:75]
	v_pk_mul_f32 v[74:75], v[142:143], v[72:73]
	v_cvt_pk_bf16_f32 v72, v76, v77
	v_cvt_pk_bf16_f32 v73, v78, v79
	v_cvt_pk_bf16_f32 v74, v74, v75
	v_cvt_pk_bf16_f32 v75, v84, v85
	v_pk_mul_f32 v[68:69], v[68:69], v[80:81] op_sel_hi:[1,0]
	v_pk_mul_f32 v[70:71], v[70:71], v[80:81] op_sel_hi:[1,0]
	v_pk_mul_f32 v[64:65], v[64:65], v[80:81] op_sel_hi:[1,0]
	v_pk_mul_f32 v[66:67], v[66:67], v[80:81] op_sel_hi:[1,0]
	global_store_dwordx4 v[82:83], v[72:75], off
	v_pk_mul_f32 v[70:71], v[152:153], v[70:71]
	v_pk_mul_f32 v[68:69], v[154:155], v[68:69]
	v_pk_mul_f32 v[72:73], v[148:149], v[66:67]
	v_pk_mul_f32 v[66:67], v[150:151], v[64:65]
	v_cvt_pk_bf16_f32 v64, v68, v69
	v_cvt_pk_bf16_f32 v65, v70, v71
	v_cvt_pk_bf16_f32 v66, v66, v67
	v_cvt_pk_bf16_f32 v67, v72, v73
	global_store_dwordx4 v[82:83], v[64:67], off offset:64
	s_nop 1
	v_pk_mul_f32 v[64:65], v[62:63], v[62:63]
	v_pk_mul_f32 v[66:67], v[60:61], v[60:61]
	s_nop 0
	v_pk_mov_b32 v[68:69], v[66:67], v[64:65] op_sel:[1,0]
	v_mov_b32_e32 v67, v65
	v_pk_add_f32 v[64:65], v[68:69], v[66:67]
	v_pk_mul_f32 v[66:67], v[58:59], v[58:59]
	v_pk_mul_f32 v[68:69], v[56:57], v[56:57]
	v_pk_add_f32 v[64:65], v[64:65], v[64:65] op_sel:[0,1] op_sel_hi:[1,0]
	v_pk_mov_b32 v[70:71], v[68:69], v[66:67] op_sel:[1,0]
	v_mov_b32_e32 v69, v67
	v_pk_add_f32 v[66:67], v[70:71], v[68:69]
	v_mul_f32_e32 v68, v48, v48
	v_mul_f32_e32 v69, v49, v49
	v_pk_add_f32 v[66:67], v[66:67], v[66:67] op_sel:[0,1] op_sel_hi:[1,0]
	v_mov_b32_e32 v65, v68
	v_mov_b32_e32 v67, v69
	v_pk_add_f32 v[64:65], v[64:65], v[66:67]
	v_mul_f32_e32 v66, v53, v53
	v_mul_f32_e32 v68, v55, v55
	v_mul_f32_e32 v70, v50, v50
	v_mul_f32_e32 v71, v51, v51
	v_pk_fma_f32 v[66:67], v[52:53], v[52:53], v[66:67] op_sel_hi:[1,1,0]
	v_pk_fma_f32 v[68:69], v[54:55], v[54:55], v[68:69] op_sel_hi:[1,1,0]
	v_mov_b32_e32 v67, v70
	v_mov_b32_e32 v69, v71
	v_pk_add_f32 v[66:67], v[66:67], v[68:69]
	s_nop 0
	v_pk_add_f32 v[64:65], v[64:65], v[66:67]
	v_lshl_add_u64 v[66:67], v[156:157], 0, s[84:85]
	v_add_f32_e32 v64, v64, v65
	ds_bpermute_b32 v65, v164, v64
	s_waitcnt lgkmcnt(0)
	v_add_f32_e32 v64, v64, v65
	ds_bpermute_b32 v65, v165, v64
	s_waitcnt lgkmcnt(0)
	v_add_f32_e32 v64, v64, v65
	v_fmamk_f32 v64, v64, 0x3c800000, v228
	v_rsq_f32_e32 v64, v64
	s_nop 0
	v_pk_mul_f32 v[60:61], v[60:61], v[64:65] op_sel_hi:[1,0]
	v_pk_mul_f32 v[62:63], v[62:63], v[64:65] op_sel_hi:[1,0]
	v_pk_mul_f32 v[60:61], v[146:147], v[60:61]
	v_pk_mul_f32 v[56:57], v[56:57], v[64:65] op_sel_hi:[1,0]
	v_pk_mul_f32 v[58:59], v[58:59], v[64:65] op_sel_hi:[1,0]
	v_pk_mul_f32 v[62:63], v[144:145], v[62:63]
	v_pk_mul_f32 v[68:69], v[140:141], v[58:59]
	v_pk_mul_f32 v[58:59], v[142:143], v[56:57]
	v_cvt_pk_bf16_f32 v56, v60, v61
	v_add_co_u32_e32 v60, vcc, s4, v156
	v_cvt_pk_bf16_f32 v57, v62, v63
	v_cvt_pk_bf16_f32 v58, v58, v59
	v_cvt_pk_bf16_f32 v59, v68, v69
	v_addc_co_u32_e32 v61, vcc, 0, v157, vcc
	v_pk_mul_f32 v[52:53], v[52:53], v[64:65] op_sel_hi:[1,0]
	v_pk_mul_f32 v[54:55], v[54:55], v[64:65] op_sel_hi:[1,0]
	v_pk_mul_f32 v[48:49], v[48:49], v[64:65] op_sel_hi:[1,0]
	v_pk_mul_f32 v[50:51], v[50:51], v[64:65] op_sel_hi:[1,0]
	global_store_dwordx4 v[60:61], v[56:59], off
	v_pk_mul_f32 v[54:55], v[152:153], v[54:55]
	v_pk_mul_f32 v[52:53], v[154:155], v[52:53]
	v_pk_mul_f32 v[56:57], v[148:149], v[50:51]
	v_pk_mul_f32 v[50:51], v[150:151], v[48:49]
	v_cvt_pk_bf16_f32 v48, v52, v53
	v_cvt_pk_bf16_f32 v49, v54, v55
	v_cvt_pk_bf16_f32 v50, v50, v51
	v_cvt_pk_bf16_f32 v51, v56, v57
	global_store_dwordx4 v[66:67], v[48:51], off offset:64
	s_mov_b32 s4, 0x24000
	s_nop 0
	v_pk_mul_f32 v[48:49], v[46:47], v[46:47]
	v_pk_mul_f32 v[50:51], v[44:45], v[44:45]
	s_nop 0
	v_pk_mov_b32 v[52:53], v[50:51], v[48:49] op_sel:[1,0]
	v_mov_b32_e32 v51, v49
	v_pk_add_f32 v[48:49], v[52:53], v[50:51]
	v_pk_mul_f32 v[50:51], v[42:43], v[42:43]
	v_pk_mul_f32 v[52:53], v[40:41], v[40:41]
	v_pk_add_f32 v[48:49], v[48:49], v[48:49] op_sel:[0,1] op_sel_hi:[1,0]
	v_pk_mov_b32 v[54:55], v[52:53], v[50:51] op_sel:[1,0]
	v_mov_b32_e32 v53, v51
	v_pk_add_f32 v[50:51], v[54:55], v[52:53]
	v_mul_f32_e32 v52, v32, v32
	v_mul_f32_e32 v53, v33, v33
	v_pk_add_f32 v[50:51], v[50:51], v[50:51] op_sel:[0,1] op_sel_hi:[1,0]
	v_mov_b32_e32 v49, v52
	v_mov_b32_e32 v51, v53
	v_pk_add_f32 v[48:49], v[48:49], v[50:51]
	v_mul_f32_e32 v50, v37, v37
	v_mul_f32_e32 v52, v39, v39
	v_mul_f32_e32 v54, v34, v34
	v_mul_f32_e32 v55, v35, v35
	v_pk_fma_f32 v[50:51], v[36:37], v[36:37], v[50:51] op_sel_hi:[1,1,0]
	v_pk_fma_f32 v[52:53], v[38:39], v[38:39], v[52:53] op_sel_hi:[1,1,0]
	v_mov_b32_e32 v51, v54
	v_mov_b32_e32 v53, v55
	v_pk_add_f32 v[50:51], v[50:51], v[52:53]
	s_nop 0
	v_pk_add_f32 v[48:49], v[48:49], v[50:51]
	v_lshl_add_u64 v[50:51], v[156:157], 0, s[62:63]
	v_add_f32_e32 v48, v48, v49
	ds_bpermute_b32 v49, v164, v48
	s_mov_b64 s[62:63], 0x28000
	s_waitcnt lgkmcnt(0)
	v_add_f32_e32 v48, v48, v49
	ds_bpermute_b32 v49, v165, v48
	s_waitcnt lgkmcnt(0)
	v_add_f32_e32 v48, v48, v49
	v_fmamk_f32 v48, v48, 0x3c800000, v228
	v_rsq_f32_e32 v48, v48
	s_nop 0
	v_pk_mul_f32 v[44:45], v[44:45], v[48:49] op_sel_hi:[1,0]
	v_pk_mul_f32 v[46:47], v[46:47], v[48:49] op_sel_hi:[1,0]
	v_pk_mul_f32 v[44:45], v[146:147], v[44:45]
	v_pk_mul_f32 v[40:41], v[40:41], v[48:49] op_sel_hi:[1,0]
	v_pk_mul_f32 v[42:43], v[42:43], v[48:49] op_sel_hi:[1,0]
	v_pk_mul_f32 v[46:47], v[144:145], v[46:47]
	v_pk_mul_f32 v[52:53], v[140:141], v[42:43]
	v_pk_mul_f32 v[42:43], v[142:143], v[40:41]
	v_cvt_pk_bf16_f32 v40, v44, v45
	v_add_co_u32_e32 v44, vcc, s4, v156
	v_cvt_pk_bf16_f32 v41, v46, v47
	v_cvt_pk_bf16_f32 v42, v42, v43
	v_cvt_pk_bf16_f32 v43, v52, v53
	v_addc_co_u32_e32 v45, vcc, 0, v157, vcc
	v_pk_mul_f32 v[36:37], v[36:37], v[48:49] op_sel_hi:[1,0]
	v_pk_mul_f32 v[38:39], v[38:39], v[48:49] op_sel_hi:[1,0]
	v_pk_mul_f32 v[32:33], v[32:33], v[48:49] op_sel_hi:[1,0]
	v_pk_mul_f32 v[34:35], v[34:35], v[48:49] op_sel_hi:[1,0]
	global_store_dwordx4 v[44:45], v[40:43], off
	v_pk_mul_f32 v[38:39], v[152:153], v[38:39]
	v_pk_mul_f32 v[36:37], v[154:155], v[36:37]
	v_pk_mul_f32 v[40:41], v[148:149], v[34:35]
	v_pk_mul_f32 v[34:35], v[150:151], v[32:33]
	v_cvt_pk_bf16_f32 v32, v36, v37
	v_cvt_pk_bf16_f32 v33, v38, v39
	v_cvt_pk_bf16_f32 v34, v34, v35
	v_cvt_pk_bf16_f32 v35, v40, v41
	global_store_dwordx4 v[50:51], v[32:35], off offset:64
	s_mov_b32 s4, 0x28000
	s_nop 0
	v_pk_mul_f32 v[32:33], v[30:31], v[30:31]
	v_pk_mul_f32 v[34:35], v[28:29], v[28:29]
	s_nop 0
	v_pk_mov_b32 v[36:37], v[34:35], v[32:33] op_sel:[1,0]
	v_mov_b32_e32 v35, v33
	v_pk_add_f32 v[32:33], v[36:37], v[34:35]
	v_pk_mul_f32 v[34:35], v[26:27], v[26:27]
	v_pk_mul_f32 v[36:37], v[24:25], v[24:25]
	v_pk_add_f32 v[32:33], v[32:33], v[32:33] op_sel:[0,1] op_sel_hi:[1,0]
	v_pk_mov_b32 v[38:39], v[36:37], v[34:35] op_sel:[1,0]
	v_mov_b32_e32 v37, v35
	v_pk_add_f32 v[34:35], v[38:39], v[36:37]
	v_mul_f32_e32 v36, v16, v16
	v_mul_f32_e32 v37, v17, v17
	v_pk_add_f32 v[34:35], v[34:35], v[34:35] op_sel:[0,1] op_sel_hi:[1,0]
	v_mov_b32_e32 v33, v36
	v_mov_b32_e32 v35, v37
	v_pk_add_f32 v[32:33], v[32:33], v[34:35]
	v_mul_f32_e32 v34, v21, v21
	v_mul_f32_e32 v36, v23, v23
	v_mul_f32_e32 v38, v18, v18
	v_mul_f32_e32 v39, v19, v19
	v_pk_fma_f32 v[34:35], v[20:21], v[20:21], v[34:35] op_sel_hi:[1,1,0]
	v_pk_fma_f32 v[36:37], v[22:23], v[22:23], v[36:37] op_sel_hi:[1,1,0]
	v_mov_b32_e32 v35, v38
	v_mov_b32_e32 v37, v39
	v_pk_add_f32 v[34:35], v[34:35], v[36:37]
	s_nop 0
	v_pk_add_f32 v[32:33], v[32:33], v[34:35]
	v_lshl_add_u64 v[34:35], v[156:157], 0, s[62:63]
	v_add_f32_e32 v32, v32, v33
	ds_bpermute_b32 v33, v164, v32
	s_mov_b64 s[62:63], 0x2c000
	s_waitcnt lgkmcnt(0)
	v_add_f32_e32 v32, v32, v33
	ds_bpermute_b32 v33, v165, v32
	s_waitcnt lgkmcnt(0)
	v_add_f32_e32 v32, v32, v33
	v_fmamk_f32 v32, v32, 0x3c800000, v228
	v_rsq_f32_e32 v32, v32
	s_nop 0
	v_pk_mul_f32 v[28:29], v[28:29], v[32:33] op_sel_hi:[1,0]
	v_pk_mul_f32 v[30:31], v[30:31], v[32:33] op_sel_hi:[1,0]
	v_pk_mul_f32 v[28:29], v[146:147], v[28:29]
	v_pk_mul_f32 v[24:25], v[24:25], v[32:33] op_sel_hi:[1,0]
	v_pk_mul_f32 v[26:27], v[26:27], v[32:33] op_sel_hi:[1,0]
	v_pk_mul_f32 v[30:31], v[144:145], v[30:31]
	v_pk_mul_f32 v[36:37], v[140:141], v[26:27]
	v_pk_mul_f32 v[26:27], v[142:143], v[24:25]
	v_cvt_pk_bf16_f32 v24, v28, v29
	v_add_co_u32_e32 v28, vcc, s4, v156
	v_cvt_pk_bf16_f32 v25, v30, v31
	v_cvt_pk_bf16_f32 v26, v26, v27
	v_cvt_pk_bf16_f32 v27, v36, v37
	v_addc_co_u32_e32 v29, vcc, 0, v157, vcc
	v_pk_mul_f32 v[20:21], v[20:21], v[32:33] op_sel_hi:[1,0]
	v_pk_mul_f32 v[22:23], v[22:23], v[32:33] op_sel_hi:[1,0]
	v_pk_mul_f32 v[16:17], v[16:17], v[32:33] op_sel_hi:[1,0]
	v_pk_mul_f32 v[18:19], v[18:19], v[32:33] op_sel_hi:[1,0]
	global_store_dwordx4 v[28:29], v[24:27], off
	v_pk_mul_f32 v[22:23], v[152:153], v[22:23]
	v_pk_mul_f32 v[20:21], v[154:155], v[20:21]
	v_pk_mul_f32 v[24:25], v[148:149], v[18:19]
	v_pk_mul_f32 v[18:19], v[150:151], v[16:17]
	v_cvt_pk_bf16_f32 v16, v20, v21
	v_cvt_pk_bf16_f32 v17, v22, v23
	v_cvt_pk_bf16_f32 v18, v18, v19
	v_cvt_pk_bf16_f32 v19, v24, v25
	global_store_dwordx4 v[34:35], v[16:19], off offset:64
	s_mov_b32 s4, 0x2c000
	s_nop 0
	v_pk_mul_f32 v[16:17], v[14:15], v[14:15]
	v_pk_mul_f32 v[18:19], v[12:13], v[12:13]
	s_nop 0
	v_pk_mov_b32 v[20:21], v[18:19], v[16:17] op_sel:[1,0]
	v_mov_b32_e32 v19, v17
	v_pk_add_f32 v[16:17], v[20:21], v[18:19]
	v_pk_mul_f32 v[18:19], v[10:11], v[10:11]
	v_pk_mul_f32 v[20:21], v[8:9], v[8:9]
	v_pk_add_f32 v[16:17], v[16:17], v[16:17] op_sel:[0,1] op_sel_hi:[1,0]
	v_pk_mov_b32 v[22:23], v[20:21], v[18:19] op_sel:[1,0]
	v_mov_b32_e32 v21, v19
	v_pk_add_f32 v[18:19], v[22:23], v[20:21]
	v_mul_f32_e32 v20, v0, v0
	v_mul_f32_e32 v21, v1, v1
	v_pk_add_f32 v[18:19], v[18:19], v[18:19] op_sel:[0,1] op_sel_hi:[1,0]
	v_mov_b32_e32 v17, v20
	v_mov_b32_e32 v19, v21
	v_pk_add_f32 v[16:17], v[16:17], v[18:19]
	v_mul_f32_e32 v18, v5, v5
	v_mul_f32_e32 v20, v7, v7
	v_mul_f32_e32 v22, v2, v2
	v_mul_f32_e32 v23, v3, v3
	v_pk_fma_f32 v[18:19], v[4:5], v[4:5], v[18:19] op_sel_hi:[1,1,0]
	v_pk_fma_f32 v[20:21], v[6:7], v[6:7], v[20:21] op_sel_hi:[1,1,0]
	v_mov_b32_e32 v19, v22
	v_mov_b32_e32 v21, v23
	v_pk_add_f32 v[18:19], v[18:19], v[20:21]
	s_nop 0
	v_pk_add_f32 v[16:17], v[16:17], v[18:19]
	v_lshl_add_u64 v[18:19], v[156:157], 0, s[62:63]
	v_add_f32_e32 v16, v16, v17
	ds_bpermute_b32 v17, v164, v16
	s_waitcnt lgkmcnt(0)
	v_add_f32_e32 v16, v16, v17
	ds_bpermute_b32 v17, v165, v16
	s_waitcnt lgkmcnt(0)
	v_add_f32_e32 v16, v16, v17
	v_fmamk_f32 v16, v16, 0x3c800000, v228
	v_rsq_f32_e32 v16, v16
	s_nop 0
	v_pk_mul_f32 v[12:13], v[12:13], v[16:17] op_sel_hi:[1,0]
	v_pk_mul_f32 v[14:15], v[14:15], v[16:17] op_sel_hi:[1,0]
	v_pk_mul_f32 v[12:13], v[146:147], v[12:13]
	v_pk_mul_f32 v[8:9], v[8:9], v[16:17] op_sel_hi:[1,0]
	v_pk_mul_f32 v[10:11], v[10:11], v[16:17] op_sel_hi:[1,0]
	v_pk_mul_f32 v[14:15], v[144:145], v[14:15]
	v_pk_mul_f32 v[20:21], v[140:141], v[10:11]
	v_pk_mul_f32 v[10:11], v[142:143], v[8:9]
	v_cvt_pk_bf16_f32 v8, v12, v13
	v_add_co_u32_e32 v12, vcc, s4, v156
	v_cvt_pk_bf16_f32 v9, v14, v15
	v_cvt_pk_bf16_f32 v10, v10, v11
	v_cvt_pk_bf16_f32 v11, v20, v21
	v_addc_co_u32_e32 v13, vcc, 0, v157, vcc
	v_pk_mul_f32 v[4:5], v[4:5], v[16:17] op_sel_hi:[1,0]
	v_pk_mul_f32 v[6:7], v[6:7], v[16:17] op_sel_hi:[1,0]
	v_pk_mul_f32 v[0:1], v[0:1], v[16:17] op_sel_hi:[1,0]
	v_pk_mul_f32 v[2:3], v[2:3], v[16:17] op_sel_hi:[1,0]
	global_store_dwordx4 v[12:13], v[8:11], off
	v_pk_mul_f32 v[6:7], v[152:153], v[6:7]
	v_pk_mul_f32 v[4:5], v[154:155], v[4:5]
	v_pk_mul_f32 v[8:9], v[148:149], v[2:3]
	v_pk_mul_f32 v[2:3], v[150:151], v[0:1]
	v_cvt_pk_bf16_f32 v0, v4, v5
	v_cvt_pk_bf16_f32 v1, v6, v7
	v_cvt_pk_bf16_f32 v2, v2, v3
	v_cvt_pk_bf16_f32 v3, v8, v9
	s_andn2_b64 vcc, exec, s[40:41]
	global_store_dwordx4 v[18:19], v[0:3], off offset:64
	s_cbranch_vccnz .LBB0_454
	s_andn2_b64 vcc, exec, s[0:1]
	s_cbranch_vccnz .LBB0_453
	s_barrier
	s_branch .LBB0_453

.LBB0_485:
	s_lshl_b32 s70, s86, 8
	s_ashr_i32 s71, s70, 31
	s_lshl_b64 s[70:71], s[70:71], 16
	s_add_u32 s37, s77, s70
	s_addc_u32 s39, s78, s71
	s_lshl_b32 s70, s83, 8
	s_ashr_i32 s71, s70, 31
	s_lshl_b64 s[70:71], s[70:71], 1
	s_add_u32 s37, s37, s70
	s_addc_u32 s39, s39, s71
	s_add_u32 s70, s37, s82
	s_addc_u32 s71, s39, 0
	v_lshl_add_u64 v[158:159], s[70:71], 0, v[176:177]
	v_lshl_add_u64 v[160:161], v[158:159], 0, v[136:137]
	v_cvt_pk_bf16_f32 v108, v108, v109
	v_cvt_pk_bf16_f32 v109, v110, v111
	v_cvt_pk_bf16_f32 v110, v104, v105
	v_cvt_pk_bf16_f32 v111, v106, v107
	v_cvt_pk_bf16_f32 v68, v68, v69
	v_cvt_pk_bf16_f32 v69, v70, v71
	v_cvt_pk_bf16_f32 v70, v64, v65
	v_lshl_add_u64 v[64:65], v[158:159], 0, v[144:145]
	v_cvt_pk_bf16_f32 v44, v44, v45
	v_cvt_pk_bf16_f32 v45, v46, v47
	v_cvt_pk_bf16_f32 v46, v40, v41
	v_cvt_pk_bf16_f32 v47, v42, v43
	global_store_dwordx4 v[160:161], v[108:111], off offset:256
	v_cvt_pk_bf16_f32 v92, v92, v93
	v_cvt_pk_bf16_f32 v93, v94, v95
	v_lshl_add_u64 v[108:109], v[158:159], 0, v[138:139]
	v_cvt_pk_bf16_f32 v94, v88, v89
	v_cvt_pk_bf16_f32 v95, v90, v91
	global_store_dwordx4 v[64:65], v[44:47], off offset:256
	v_cvt_pk_bf16_f32 v28, v28, v29
	v_cvt_pk_bf16_f32 v29, v30, v31
	v_lshl_add_u64 v[44:45], v[158:159], 0, v[146:147]
	v_cvt_pk_bf16_f32 v30, v24, v25
	v_cvt_pk_bf16_f32 v31, v26, v27
	global_store_dwordx4 v[108:109], v[92:95], off offset:256
	v_cvt_pk_bf16_f32 v76, v76, v77
	v_cvt_pk_bf16_f32 v77, v78, v79
	v_lshl_add_u64 v[92:93], v[158:159], 0, v[140:141]
	v_cvt_pk_bf16_f32 v78, v72, v73
	v_cvt_pk_bf16_f32 v79, v74, v75
	global_store_dwordx4 v[44:45], v[28:31], off offset:256
	v_cvt_pk_bf16_f32 v12, v12, v13
	v_cvt_pk_bf16_f32 v13, v14, v15
	v_lshl_add_u64 v[28:29], v[158:159], 0, v[148:149]
	v_cvt_pk_bf16_f32 v14, v8, v9
	v_cvt_pk_bf16_f32 v15, v10, v11
	v_cvt_pk_bf16_f32 v124, v124, v125
	v_cvt_pk_bf16_f32 v125, v126, v127
	v_cvt_pk_bf16_f32 v126, v120, v121
	v_cvt_pk_bf16_f32 v127, v122, v123
	v_cvt_pk_bf16_f32 v104, v116, v117
	v_cvt_pk_bf16_f32 v105, v118, v119
	v_cvt_pk_bf16_f32 v106, v112, v113
	v_cvt_pk_bf16_f32 v107, v114, v115
	v_cvt_pk_bf16_f32 v88, v100, v101
	v_cvt_pk_bf16_f32 v89, v102, v103
	v_cvt_pk_bf16_f32 v90, v96, v97
	v_cvt_pk_bf16_f32 v91, v98, v99
	global_store_dwordx4 v[92:93], v[76:79], off offset:256
	v_cvt_pk_bf16_f32 v72, v84, v85
	v_cvt_pk_bf16_f32 v73, v86, v87
	v_lshl_add_u64 v[76:77], v[158:159], 0, v[142:143]
	v_cvt_pk_bf16_f32 v74, v80, v81
	v_cvt_pk_bf16_f32 v75, v82, v83
	v_cvt_pk_bf16_f32 v71, v66, v67
	v_cvt_pk_bf16_f32 v60, v60, v61
	v_cvt_pk_bf16_f32 v61, v62, v63
	v_cvt_pk_bf16_f32 v62, v56, v57
	v_cvt_pk_bf16_f32 v63, v58, v59
	v_cvt_pk_bf16_f32 v40, v52, v53
	v_cvt_pk_bf16_f32 v41, v54, v55
	v_cvt_pk_bf16_f32 v42, v48, v49
	v_cvt_pk_bf16_f32 v43, v50, v51
	v_cvt_pk_bf16_f32 v24, v36, v37
	v_cvt_pk_bf16_f32 v25, v38, v39
	v_cvt_pk_bf16_f32 v26, v32, v33
	v_cvt_pk_bf16_f32 v27, v34, v35
	global_store_dwordx4 v[28:29], v[12:15], off offset:256
	v_cvt_pk_bf16_f32 v8, v20, v21
	v_cvt_pk_bf16_f32 v9, v22, v23
	v_lshl_add_u64 v[12:13], v[158:159], 0, v[150:151]
	v_cvt_pk_bf16_f32 v10, v16, v17
	v_cvt_pk_bf16_f32 v11, v18, v19
	v_cvt_pk_bf16_f32 v4, v4, v5
	v_cvt_pk_bf16_f32 v5, v6, v7
	v_cvt_pk_bf16_f32 v6, v0, v1
	v_cvt_pk_bf16_f32 v7, v2, v3
	s_andn2_b64 vcc, exec, s[42:43]
	s_mov_b64 s[42:43], -1
	global_store_dwordx4 v[160:161], v[124:127], off
	global_store_dwordx4 v[108:109], v[104:107], off
	global_store_dwordx4 v[92:93], v[88:91], off
	global_store_dwordx4 v[76:77], v[72:75], off
	global_store_dwordx4 v[76:77], v[68:71], off offset:256
	global_store_dwordx4 v[64:65], v[60:63], off
	global_store_dwordx4 v[44:45], v[40:43], off
	global_store_dwordx4 v[28:29], v[24:27], off
	global_store_dwordx4 v[12:13], v[8:11], off
	global_store_dwordx4 v[12:13], v[4:7], off offset:256
	s_cbranch_vccnz .LBB0_474
	s_andn2_b64 vcc, exec, s[0:1]
	s_cbranch_vccnz .LBB0_473
	s_barrier
	s_branch .LBB0_473

.LBB0_505:
	s_lshl_b32 s22, s86, 8
	s_and_b32 s22, s22, 0x100
	s_mul_i32 s22, s68, s22
	s_lshl_b32 s22, s22, 1
	s_add_u32 s70, s70, s22
	s_addc_u32 s71, s71, 0
	s_or_b32 s22, s37, s80
	s_lshl_b32 s37, s86, 5
	s_andn2_b32 s37, s37, 63
	s_lshl_b32 s22, s22, 1
	v_or_b32_e32 v141, s37, v137
	s_and_b32 s22, s22, 0xe80
	v_cvt_pk_bf16_f32 v124, v124, v125
	v_cvt_pk_bf16_f32 v125, v126, v127
	v_cvt_pk_bf16_f32 v126, v120, v121
	v_add_u32_e32 v120, s22, v141
	v_mad_i64_i32 v[154:155], s[72:73], s68, v134, 0
	v_ashrrev_i32_e32 v121, 31, v120
	v_lshl_add_u64 v[154:155], v[154:155], 1, s[70:71]
	v_lshlrev_b64 v[120:121], 1, v[120:121]
	v_cvt_pk_bf16_f32 v127, v122, v123
	v_lshl_add_u64 v[122:123], v[154:155], 0, v[120:121]
	v_cvt_pk_bf16_f32 v108, v108, v109
	v_cvt_pk_bf16_f32 v109, v110, v111
	v_cvt_pk_bf16_f32 v110, v104, v105
	v_cvt_pk_bf16_f32 v111, v106, v107
	v_mad_i64_i32 v[104:105], s[72:73], s68, v136, 0
	global_store_dwordx4 v[122:123], v[108:111], off offset:512
	v_cvt_pk_bf16_f32 v92, v92, v93
	v_cvt_pk_bf16_f32 v93, v94, v95
	v_lshl_add_u64 v[108:109], v[104:105], 1, s[70:71]
	v_lshl_add_u64 v[108:109], v[108:109], 0, v[120:121]
	v_cvt_pk_bf16_f32 v94, v88, v89
	v_cvt_pk_bf16_f32 v95, v90, v91
	v_mad_i64_i32 v[88:89], s[72:73], s68, v138, 0
	global_store_dwordx4 v[122:123], v[124:127], off
	global_store_dwordx4 v[108:109], v[92:95], off offset:512
	v_cvt_pk_bf16_f32 v104, v116, v117
	v_cvt_pk_bf16_f32 v105, v118, v119
	v_lshl_add_u64 v[92:93], v[88:89], 1, s[70:71]
	v_cvt_pk_bf16_f32 v106, v112, v113
	v_cvt_pk_bf16_f32 v107, v114, v115
	v_lshl_add_u64 v[92:93], v[92:93], 0, v[120:121]
	v_cvt_pk_bf16_f32 v76, v76, v77
	v_cvt_pk_bf16_f32 v77, v78, v79
	v_cvt_pk_bf16_f32 v78, v72, v73
	v_cvt_pk_bf16_f32 v79, v74, v75
	v_mad_i64_i32 v[72:73], s[72:73], s68, v140, 0
	v_cvt_pk_bf16_f32 v68, v68, v69
	v_cvt_pk_bf16_f32 v69, v70, v71
	v_cvt_pk_bf16_f32 v70, v64, v65
	v_mad_i64_i32 v[64:65], s[72:73], s68, v142, 0
	global_store_dwordx4 v[108:109], v[104:107], off
	global_store_dwordx4 v[92:93], v[76:79], off offset:512
	v_lshl_add_u64 v[64:65], v[64:65], 1, s[70:71]
	v_cvt_pk_bf16_f32 v88, v100, v101
	v_lshl_add_u64 v[76:77], v[72:73], 1, s[70:71]
	v_cvt_pk_bf16_f32 v89, v102, v103
	v_cvt_pk_bf16_f32 v90, v96, v97
	v_cvt_pk_bf16_f32 v91, v98, v99
	v_cvt_pk_bf16_f32 v72, v84, v85
	v_cvt_pk_bf16_f32 v73, v86, v87
	v_cvt_pk_bf16_f32 v74, v80, v81
	v_cvt_pk_bf16_f32 v75, v82, v83
	v_lshl_add_u64 v[76:77], v[76:77], 0, v[120:121]
	v_cvt_pk_bf16_f32 v71, v66, v67
	v_cvt_pk_bf16_f32 v60, v60, v61
	v_cvt_pk_bf16_f32 v61, v62, v63
	v_cvt_pk_bf16_f32 v62, v56, v57
	v_lshl_add_u64 v[56:57], v[64:65], 0, v[120:121]
	v_cvt_pk_bf16_f32 v44, v44, v45
	v_cvt_pk_bf16_f32 v45, v46, v47
	v_cvt_pk_bf16_f32 v46, v40, v41
	v_cvt_pk_bf16_f32 v47, v42, v43
	v_mad_i64_i32 v[40:41], s[72:73], s68, v144, 0
	global_store_dwordx4 v[92:93], v[88:91], off
	global_store_dwordx4 v[76:77], v[72:75], off
	global_store_dwordx4 v[76:77], v[68:71], off offset:512
	global_store_dwordx4 v[56:57], v[44:47], off offset:512
	v_cvt_pk_bf16_f32 v63, v58, v59
	v_cvt_pk_bf16_f32 v28, v28, v29
	v_lshl_add_u64 v[44:45], v[40:41], 1, s[70:71]
	v_lshl_add_u64 v[44:45], v[44:45], 0, v[120:121]
	v_cvt_pk_bf16_f32 v29, v30, v31
	v_cvt_pk_bf16_f32 v30, v24, v25
	v_cvt_pk_bf16_f32 v31, v26, v27
	v_mad_i64_i32 v[24:25], s[72:73], s68, v146, 0
	global_store_dwordx4 v[56:57], v[60:63], off
	global_store_dwordx4 v[44:45], v[28:31], off offset:512
	v_cvt_pk_bf16_f32 v40, v52, v53
	v_cvt_pk_bf16_f32 v41, v54, v55
	v_lshl_add_u64 v[28:29], v[24:25], 1, s[70:71]
	v_cvt_pk_bf16_f32 v42, v48, v49
	v_cvt_pk_bf16_f32 v43, v50, v51
	v_lshl_add_u64 v[28:29], v[28:29], 0, v[120:121]
	v_cvt_pk_bf16_f32 v12, v12, v13
	v_cvt_pk_bf16_f32 v13, v14, v15
	v_cvt_pk_bf16_f32 v14, v8, v9
	v_cvt_pk_bf16_f32 v15, v10, v11
	v_mad_i64_i32 v[8:9], s[68:69], s68, v148, 0
	global_store_dwordx4 v[44:45], v[40:43], off
	global_store_dwordx4 v[28:29], v[12:15], off offset:512
	v_cvt_pk_bf16_f32 v24, v36, v37
	v_cvt_pk_bf16_f32 v25, v38, v39
	v_lshl_add_u64 v[12:13], v[8:9], 1, s[70:71]
	v_cvt_pk_bf16_f32 v26, v32, v33
	v_cvt_pk_bf16_f32 v27, v34, v35
	v_cvt_pk_bf16_f32 v8, v20, v21
	v_cvt_pk_bf16_f32 v9, v22, v23
	v_cvt_pk_bf16_f32 v10, v16, v17
	v_cvt_pk_bf16_f32 v11, v18, v19
	v_lshl_add_u64 v[12:13], v[12:13], 0, v[120:121]
	v_cvt_pk_bf16_f32 v4, v4, v5
	v_cvt_pk_bf16_f32 v5, v6, v7
	v_cvt_pk_bf16_f32 v6, v0, v1
	v_cvt_pk_bf16_f32 v7, v2, v3
	s_andn2_b64 vcc, exec, s[42:43]
	s_mov_b64 s[42:43], -1
	global_store_dwordx4 v[28:29], v[24:27], off
	global_store_dwordx4 v[12:13], v[8:11], off
	global_store_dwordx4 v[12:13], v[4:7], off offset:512
	s_cbranch_vccnz .LBB0_494
	s_andn2_b64 vcc, exec, s[0:1]
	s_cbranch_vccnz .LBB0_493
	s_barrier
	s_branch .LBB0_493

.LBB0_509:
	v_readlane_b32 s0, v254, 11
	v_readlane_b32 s1, v254, 12
	s_andn2_b64 vcc, exec, s[0:1]
	s_cbranch_vccnz .LBB0_513
	v_mov_b32_e32 v10, v226
	v_readlane_b32 s0, v254, 13
	v_ashrrev_i32_e32 v0, 3, v10
	v_readlane_b32 s8, v254, 14
	v_add_u32_e32 v8, s0, v0
	s_mov_b64 s[0:1], s[94:95]
	v_and_b32_e32 v11, 7, v10
	v_readlane_b32 s9, v254, 15
	s_add_u32 s0, s0, s8
	s_addc_u32 s1, s1, s9
	v_lshlrev_b32_e32 v176, 8, v11
	v_lshl_add_u64 v[2:3], s[0:1], 0, v[176:177]
	s_mov_b64 s[0:1], 0x4b00000
	v_ashrrev_i32_e32 v9, 31, v8
	v_lshl_add_u64 v[0:1], v[2:3], 0, s[0:1]
	s_mov_b64 s[0:1], s[94:95]
	v_lshlrev_b64 v[4:5], 11, v[8:9]
	s_nop 0
	v_lshl_add_u64 v[4:5], s[0:1], 0, v[4:5]
	v_lshl_add_u64 v[6:7], v[4:5], 0, v[176:177]
	s_mov_b64 s[0:1], 0x2700000
	v_lshl_add_u64 v[4:5], v[6:7], 0, s[0:1]
	s_mov_b32 s0, 0x4b00000
	v_add_co_u32_e32 v2, vcc, s0, v2
	s_mov_b32 s0, 0x2700000
	s_nop 0
	v_addc_co_u32_e32 v3, vcc, 0, v3, vcc
	global_load_dwordx4 v[12:15], v[2:3], off
	v_add_co_u32_e32 v2, vcc, s0, v6
	s_waitcnt vmcnt(0) lgkmcnt(0)
	v_and_b32_e32 v6, 0xffff0000, v12
	v_addc_co_u32_e32 v3, vcc, 0, v7, vcc
	global_load_dwordx4 v[16:19], v[2:3], off
	v_lshlrev_b32_e32 v2, 16, v12
	v_cmp_eq_u32_e32 vcc, 0, v11
	s_waitcnt vmcnt(0) lgkmcnt(0)
	v_and_b32_e32 v7, 0xffff0000, v16
	v_lshlrev_b32_e32 v3, 16, v16
	v_mul_f32_e32 v6, v6, v7
	v_fmac_f32_e32 v6, v2, v3
	v_and_b32_e32 v7, 0xffff0000, v13
	v_and_b32_e32 v9, 0xffff0000, v17
	v_add_f32_e32 v2, 0, v6
	v_lshlrev_b32_e32 v3, 16, v13
	v_lshlrev_b32_e32 v6, 16, v17
	v_mul_f32_e32 v7, v7, v9
	v_fmac_f32_e32 v7, v3, v6
	v_add_f32_e32 v2, v2, v7
	v_and_b32_e32 v7, 0xffff0000, v14
	v_and_b32_e32 v9, 0xffff0000, v18
	v_lshlrev_b32_e32 v3, 16, v14
	v_lshlrev_b32_e32 v6, 16, v18
	v_mul_f32_e32 v7, v7, v9
	v_fmac_f32_e32 v7, v3, v6
	v_add_f32_e32 v2, v2, v7
	v_lshlrev_b32_e32 v3, 16, v15
	v_lshlrev_b32_e32 v6, 16, v19
	v_and_b32_e32 v7, 0xffff0000, v15
	v_and_b32_e32 v9, 0xffff0000, v19
	global_load_dwordx4 v[12:15], v[0:1], off offset:16
	global_load_dwordx4 v[16:19], v[4:5], off offset:16
	v_mul_f32_e32 v7, v7, v9
	v_fmac_f32_e32 v7, v3, v6
	v_add_f32_e32 v2, v2, v7
	s_waitcnt vmcnt(0) lgkmcnt(0)
	v_and_b32_e32 v7, 0xffff0000, v12
	v_and_b32_e32 v9, 0xffff0000, v16
	v_lshlrev_b32_e32 v3, 16, v12
	v_lshlrev_b32_e32 v6, 16, v16
	v_mul_f32_e32 v7, v7, v9
	v_fmac_f32_e32 v7, v3, v6
	v_add_f32_e32 v2, v2, v7
	v_and_b32_e32 v7, 0xffff0000, v13
	v_and_b32_e32 v9, 0xffff0000, v17
	v_lshlrev_b32_e32 v3, 16, v13
	v_lshlrev_b32_e32 v6, 16, v17
	v_mul_f32_e32 v7, v7, v9
	v_fmac_f32_e32 v7, v3, v6
	v_add_f32_e32 v2, v2, v7
	v_and_b32_e32 v7, 0xffff0000, v14
	v_and_b32_e32 v9, 0xffff0000, v18
	v_lshlrev_b32_e32 v3, 16, v14
	v_lshlrev_b32_e32 v6, 16, v18
	v_mul_f32_e32 v7, v7, v9
	v_fmac_f32_e32 v7, v3, v6
	v_add_f32_e32 v2, v2, v7
	v_lshlrev_b32_e32 v3, 16, v15
	v_lshlrev_b32_e32 v6, 16, v19
	v_and_b32_e32 v7, 0xffff0000, v15
	v_and_b32_e32 v9, 0xffff0000, v19
	global_load_dwordx4 v[12:15], v[0:1], off offset:32
	global_load_dwordx4 v[16:19], v[4:5], off offset:32
	v_mul_f32_e32 v7, v7, v9
	v_fmac_f32_e32 v7, v3, v6
	v_add_f32_e32 v2, v2, v7
	s_waitcnt vmcnt(0) lgkmcnt(0)
	v_and_b32_e32 v7, 0xffff0000, v12
	v_and_b32_e32 v9, 0xffff0000, v16
	v_lshlrev_b32_e32 v3, 16, v12
	v_lshlrev_b32_e32 v6, 16, v16
	v_mul_f32_e32 v7, v7, v9
	v_fmac_f32_e32 v7, v3, v6
	v_add_f32_e32 v2, v2, v7
	v_and_b32_e32 v7, 0xffff0000, v13
	v_and_b32_e32 v9, 0xffff0000, v17
	v_lshlrev_b32_e32 v3, 16, v13
	v_lshlrev_b32_e32 v6, 16, v17
	v_mul_f32_e32 v7, v7, v9
	v_fmac_f32_e32 v7, v3, v6
	v_add_f32_e32 v2, v2, v7
	v_and_b32_e32 v7, 0xffff0000, v14
	v_and_b32_e32 v9, 0xffff0000, v18
	v_lshlrev_b32_e32 v3, 16, v14
	v_lshlrev_b32_e32 v6, 16, v18
	v_mul_f32_e32 v7, v7, v9
	v_fmac_f32_e32 v7, v3, v6
	v_add_f32_e32 v2, v2, v7
	v_lshlrev_b32_e32 v3, 16, v15
	v_lshlrev_b32_e32 v6, 16, v19
	v_and_b32_e32 v7, 0xffff0000, v15
	v_and_b32_e32 v9, 0xffff0000, v19
	global_load_dwordx4 v[12:15], v[0:1], off offset:48
	global_load_dwordx4 v[16:19], v[4:5], off offset:48
	v_mul_f32_e32 v7, v7, v9
	v_fmac_f32_e32 v7, v3, v6
	v_add_f32_e32 v2, v2, v7
	s_waitcnt vmcnt(0) lgkmcnt(0)
	v_and_b32_e32 v7, 0xffff0000, v12
	v_and_b32_e32 v9, 0xffff0000, v16
	v_lshlrev_b32_e32 v3, 16, v12
	v_lshlrev_b32_e32 v6, 16, v16
	v_mul_f32_e32 v7, v7, v9
	v_fmac_f32_e32 v7, v3, v6
	v_add_f32_e32 v2, v2, v7
	v_and_b32_e32 v7, 0xffff0000, v13
	v_and_b32_e32 v9, 0xffff0000, v17
	v_lshlrev_b32_e32 v3, 16, v13
	v_lshlrev_b32_e32 v6, 16, v17
	v_mul_f32_e32 v7, v7, v9
	v_fmac_f32_e32 v7, v3, v6
	v_add_f32_e32 v2, v2, v7
	v_and_b32_e32 v7, 0xffff0000, v14
	v_and_b32_e32 v9, 0xffff0000, v18
	v_lshlrev_b32_e32 v3, 16, v14
	v_lshlrev_b32_e32 v6, 16, v18
	v_mul_f32_e32 v7, v7, v9
	v_fmac_f32_e32 v7, v3, v6
	v_add_f32_e32 v2, v2, v7
	v_lshlrev_b32_e32 v3, 16, v15
	v_lshlrev_b32_e32 v6, 16, v19
	v_and_b32_e32 v7, 0xffff0000, v15
	v_and_b32_e32 v9, 0xffff0000, v19
	global_load_dwordx4 v[12:15], v[0:1], off offset:64
	global_load_dwordx4 v[16:19], v[4:5], off offset:64
	v_mul_f32_e32 v7, v7, v9
	v_fmac_f32_e32 v7, v3, v6
	v_add_f32_e32 v2, v2, v7
	s_waitcnt vmcnt(0) lgkmcnt(0)
	v_and_b32_e32 v7, 0xffff0000, v12
	v_and_b32_e32 v9, 0xffff0000, v16
	v_lshlrev_b32_e32 v3, 16, v12
	v_lshlrev_b32_e32 v6, 16, v16
	v_mul_f32_e32 v7, v7, v9
	v_fmac_f32_e32 v7, v3, v6
	v_add_f32_e32 v2, v2, v7
	v_and_b32_e32 v7, 0xffff0000, v13
	v_and_b32_e32 v9, 0xffff0000, v17
	v_lshlrev_b32_e32 v3, 16, v13
	v_lshlrev_b32_e32 v6, 16, v17
	v_mul_f32_e32 v7, v7, v9
	v_fmac_f32_e32 v7, v3, v6
	v_add_f32_e32 v2, v2, v7
	v_and_b32_e32 v7, 0xffff0000, v14
	v_and_b32_e32 v9, 0xffff0000, v18
	v_lshlrev_b32_e32 v3, 16, v14
	v_lshlrev_b32_e32 v6, 16, v18
	v_mul_f32_e32 v7, v7, v9
	v_fmac_f32_e32 v7, v3, v6
	v_add_f32_e32 v2, v2, v7
	v_lshlrev_b32_e32 v3, 16, v15
	v_lshlrev_b32_e32 v6, 16, v19
	v_and_b32_e32 v7, 0xffff0000, v15
	v_and_b32_e32 v9, 0xffff0000, v19
	global_load_dwordx4 v[12:15], v[0:1], off offset:80
	global_load_dwordx4 v[16:19], v[4:5], off offset:80
	v_mul_f32_e32 v7, v7, v9
	v_fmac_f32_e32 v7, v3, v6
	v_add_f32_e32 v2, v2, v7
	s_waitcnt vmcnt(0) lgkmcnt(0)
	v_and_b32_e32 v7, 0xffff0000, v12
	v_and_b32_e32 v9, 0xffff0000, v16
	v_lshlrev_b32_e32 v3, 16, v12
	v_lshlrev_b32_e32 v6, 16, v16
	v_mul_f32_e32 v7, v7, v9
	v_fmac_f32_e32 v7, v3, v6
	v_add_f32_e32 v2, v2, v7
	v_and_b32_e32 v7, 0xffff0000, v13
	v_and_b32_e32 v9, 0xffff0000, v17
	v_lshlrev_b32_e32 v3, 16, v13
	v_lshlrev_b32_e32 v6, 16, v17
	v_mul_f32_e32 v7, v7, v9
	v_fmac_f32_e32 v7, v3, v6
	v_add_f32_e32 v2, v2, v7
	v_and_b32_e32 v7, 0xffff0000, v14
	v_and_b32_e32 v9, 0xffff0000, v18
	v_lshlrev_b32_e32 v3, 16, v14
	v_lshlrev_b32_e32 v6, 16, v18
	v_mul_f32_e32 v7, v7, v9
	v_fmac_f32_e32 v7, v3, v6
	v_add_f32_e32 v2, v2, v7
	v_lshlrev_b32_e32 v3, 16, v15
	v_lshlrev_b32_e32 v6, 16, v19
	v_and_b32_e32 v7, 0xffff0000, v15
	v_and_b32_e32 v9, 0xffff0000, v19
	global_load_dwordx4 v[12:15], v[0:1], off offset:96
	global_load_dwordx4 v[16:19], v[4:5], off offset:96
	v_mul_f32_e32 v7, v7, v9
	v_fmac_f32_e32 v7, v3, v6
	v_add_f32_e32 v2, v2, v7
	s_waitcnt vmcnt(0) lgkmcnt(0)
	v_and_b32_e32 v7, 0xffff0000, v12
	v_and_b32_e32 v9, 0xffff0000, v16
	v_lshlrev_b32_e32 v3, 16, v12
	v_lshlrev_b32_e32 v6, 16, v16
	v_mul_f32_e32 v7, v7, v9
	v_fmac_f32_e32 v7, v3, v6
	v_add_f32_e32 v2, v2, v7
	v_and_b32_e32 v7, 0xffff0000, v13
	v_and_b32_e32 v9, 0xffff0000, v17
	v_lshlrev_b32_e32 v3, 16, v13
	v_lshlrev_b32_e32 v6, 16, v17
	v_mul_f32_e32 v7, v7, v9
	v_fmac_f32_e32 v7, v3, v6
	v_add_f32_e32 v2, v2, v7
	v_and_b32_e32 v7, 0xffff0000, v14
	v_and_b32_e32 v9, 0xffff0000, v18
	v_lshlrev_b32_e32 v3, 16, v14
	v_lshlrev_b32_e32 v6, 16, v18
	v_mul_f32_e32 v7, v7, v9
	v_fmac_f32_e32 v7, v3, v6
	v_add_f32_e32 v2, v2, v7
	v_lshlrev_b32_e32 v3, 16, v15
	v_lshlrev_b32_e32 v6, 16, v19
	v_and_b32_e32 v7, 0xffff0000, v15
	v_and_b32_e32 v9, 0xffff0000, v19
	global_load_dwordx4 v[12:15], v[0:1], off offset:112
	global_load_dwordx4 v[16:19], v[4:5], off offset:112
	v_mul_f32_e32 v7, v7, v9
	v_fmac_f32_e32 v7, v3, v6
	v_add_f32_e32 v2, v2, v7
	s_waitcnt vmcnt(0) lgkmcnt(0)
	v_and_b32_e32 v7, 0xffff0000, v12
	v_and_b32_e32 v9, 0xffff0000, v16
	v_lshlrev_b32_e32 v3, 16, v12
	v_lshlrev_b32_e32 v6, 16, v16
	v_mul_f32_e32 v7, v7, v9
	v_fmac_f32_e32 v7, v3, v6
	v_add_f32_e32 v2, v2, v7
	v_and_b32_e32 v7, 0xffff0000, v13
	v_and_b32_e32 v9, 0xffff0000, v17
	v_lshlrev_b32_e32 v3, 16, v13
	v_lshlrev_b32_e32 v6, 16, v17
	v_mul_f32_e32 v7, v7, v9
	v_fmac_f32_e32 v7, v3, v6
	v_add_f32_e32 v2, v2, v7
	v_and_b32_e32 v7, 0xffff0000, v14
	v_and_b32_e32 v9, 0xffff0000, v18
	v_lshlrev_b32_e32 v3, 16, v14
	v_lshlrev_b32_e32 v6, 16, v18
	v_mul_f32_e32 v7, v7, v9
	v_fmac_f32_e32 v7, v3, v6
	v_add_f32_e32 v2, v2, v7
	v_lshlrev_b32_e32 v3, 16, v15
	v_lshlrev_b32_e32 v6, 16, v19
	v_and_b32_e32 v7, 0xffff0000, v15
	v_and_b32_e32 v9, 0xffff0000, v19
	global_load_dwordx4 v[12:15], v[0:1], off offset:128
	global_load_dwordx4 v[16:19], v[4:5], off offset:128
	v_mul_f32_e32 v7, v7, v9
	v_fmac_f32_e32 v7, v3, v6
	v_add_f32_e32 v2, v2, v7
	s_waitcnt vmcnt(0) lgkmcnt(0)
	v_and_b32_e32 v7, 0xffff0000, v12
	v_and_b32_e32 v9, 0xffff0000, v16
	v_lshlrev_b32_e32 v3, 16, v12
	v_lshlrev_b32_e32 v6, 16, v16
	v_mul_f32_e32 v7, v7, v9
	v_fmac_f32_e32 v7, v3, v6
	v_add_f32_e32 v2, v2, v7
	v_and_b32_e32 v7, 0xffff0000, v13
	v_and_b32_e32 v9, 0xffff0000, v17
	v_lshlrev_b32_e32 v3, 16, v13
	v_lshlrev_b32_e32 v6, 16, v17
	v_mul_f32_e32 v7, v7, v9
	v_fmac_f32_e32 v7, v3, v6
	v_add_f32_e32 v2, v2, v7
	v_and_b32_e32 v7, 0xffff0000, v14
	v_and_b32_e32 v9, 0xffff0000, v18
	v_lshlrev_b32_e32 v3, 16, v14
	v_lshlrev_b32_e32 v6, 16, v18
	v_mul_f32_e32 v7, v7, v9
	v_fmac_f32_e32 v7, v3, v6
	v_add_f32_e32 v2, v2, v7
	v_lshlrev_b32_e32 v3, 16, v15
	v_lshlrev_b32_e32 v6, 16, v19
	v_and_b32_e32 v7, 0xffff0000, v15
	v_and_b32_e32 v9, 0xffff0000, v19
	global_load_dwordx4 v[12:15], v[0:1], off offset:144
	global_load_dwordx4 v[16:19], v[4:5], off offset:144
	v_mul_f32_e32 v7, v7, v9
	v_fmac_f32_e32 v7, v3, v6
	v_add_f32_e32 v2, v2, v7
	s_waitcnt vmcnt(0) lgkmcnt(0)
	v_and_b32_e32 v7, 0xffff0000, v12
	v_and_b32_e32 v9, 0xffff0000, v16
	v_lshlrev_b32_e32 v3, 16, v12
	v_lshlrev_b32_e32 v6, 16, v16
	v_mul_f32_e32 v7, v7, v9
	v_fmac_f32_e32 v7, v3, v6
	v_add_f32_e32 v2, v2, v7
	v_and_b32_e32 v7, 0xffff0000, v13
	v_and_b32_e32 v9, 0xffff0000, v17
	v_lshlrev_b32_e32 v3, 16, v13
	v_lshlrev_b32_e32 v6, 16, v17
	v_mul_f32_e32 v7, v7, v9
	v_fmac_f32_e32 v7, v3, v6
	v_add_f32_e32 v2, v2, v7
	v_and_b32_e32 v7, 0xffff0000, v14
	v_and_b32_e32 v9, 0xffff0000, v18
	v_lshlrev_b32_e32 v3, 16, v14
	v_lshlrev_b32_e32 v6, 16, v18
	v_mul_f32_e32 v7, v7, v9
	v_fmac_f32_e32 v7, v3, v6
	v_add_f32_e32 v2, v2, v7
	v_lshlrev_b32_e32 v3, 16, v15
	v_lshlrev_b32_e32 v6, 16, v19
	v_and_b32_e32 v7, 0xffff0000, v15
	v_and_b32_e32 v9, 0xffff0000, v19
	global_load_dwordx4 v[12:15], v[0:1], off offset:160
	global_load_dwordx4 v[16:19], v[4:5], off offset:160
	v_mul_f32_e32 v7, v7, v9
	v_fmac_f32_e32 v7, v3, v6
	v_add_f32_e32 v2, v2, v7
	s_waitcnt vmcnt(0) lgkmcnt(0)
	v_and_b32_e32 v7, 0xffff0000, v12
	v_and_b32_e32 v9, 0xffff0000, v16
	v_lshlrev_b32_e32 v3, 16, v12
	v_lshlrev_b32_e32 v6, 16, v16
	v_mul_f32_e32 v7, v7, v9
	v_fmac_f32_e32 v7, v3, v6
	v_add_f32_e32 v2, v2, v7
	v_and_b32_e32 v7, 0xffff0000, v13
	v_and_b32_e32 v9, 0xffff0000, v17
	v_lshlrev_b32_e32 v3, 16, v13
	v_lshlrev_b32_e32 v6, 16, v17
	v_mul_f32_e32 v7, v7, v9
	v_fmac_f32_e32 v7, v3, v6
	v_add_f32_e32 v2, v2, v7
	v_and_b32_e32 v7, 0xffff0000, v14
	v_and_b32_e32 v9, 0xffff0000, v18
	v_lshlrev_b32_e32 v3, 16, v14
	v_lshlrev_b32_e32 v6, 16, v18
	v_mul_f32_e32 v7, v7, v9
	v_fmac_f32_e32 v7, v3, v6
	v_add_f32_e32 v2, v2, v7
	v_lshlrev_b32_e32 v3, 16, v15
	v_lshlrev_b32_e32 v6, 16, v19
	v_and_b32_e32 v7, 0xffff0000, v15
	v_and_b32_e32 v9, 0xffff0000, v19
	global_load_dwordx4 v[12:15], v[0:1], off offset:176
	global_load_dwordx4 v[16:19], v[4:5], off offset:176
	v_mul_f32_e32 v7, v7, v9
	v_fmac_f32_e32 v7, v3, v6
	v_add_f32_e32 v2, v2, v7
	s_waitcnt vmcnt(0) lgkmcnt(0)
	v_and_b32_e32 v7, 0xffff0000, v12
	v_and_b32_e32 v9, 0xffff0000, v16
	v_lshlrev_b32_e32 v3, 16, v12
	v_lshlrev_b32_e32 v6, 16, v16
	v_mul_f32_e32 v7, v7, v9
	v_fmac_f32_e32 v7, v3, v6
	v_add_f32_e32 v2, v2, v7
	v_and_b32_e32 v7, 0xffff0000, v13
	v_and_b32_e32 v9, 0xffff0000, v17
	v_lshlrev_b32_e32 v3, 16, v13
	v_lshlrev_b32_e32 v6, 16, v17
	v_mul_f32_e32 v7, v7, v9
	v_fmac_f32_e32 v7, v3, v6
	v_add_f32_e32 v2, v2, v7
	v_and_b32_e32 v7, 0xffff0000, v14
	v_and_b32_e32 v9, 0xffff0000, v18
	v_lshlrev_b32_e32 v3, 16, v14
	v_lshlrev_b32_e32 v6, 16, v18
	v_mul_f32_e32 v7, v7, v9
	v_fmac_f32_e32 v7, v3, v6
	v_add_f32_e32 v2, v2, v7
	v_lshlrev_b32_e32 v3, 16, v15
	v_lshlrev_b32_e32 v6, 16, v19
	v_and_b32_e32 v7, 0xffff0000, v15
	v_and_b32_e32 v9, 0xffff0000, v19
	global_load_dwordx4 v[12:15], v[0:1], off offset:192
	global_load_dwordx4 v[16:19], v[4:5], off offset:192
	v_mul_f32_e32 v7, v7, v9
	v_fmac_f32_e32 v7, v3, v6
	v_add_f32_e32 v2, v2, v7
	s_waitcnt vmcnt(0) lgkmcnt(0)
	v_and_b32_e32 v7, 0xffff0000, v12
	v_and_b32_e32 v9, 0xffff0000, v16
	v_lshlrev_b32_e32 v3, 16, v12
	v_lshlrev_b32_e32 v6, 16, v16
	v_mul_f32_e32 v7, v7, v9
	v_fmac_f32_e32 v7, v3, v6
	v_add_f32_e32 v2, v2, v7
	v_and_b32_e32 v7, 0xffff0000, v13
	v_and_b32_e32 v9, 0xffff0000, v17
	v_lshlrev_b32_e32 v3, 16, v13
	v_lshlrev_b32_e32 v6, 16, v17
	v_mul_f32_e32 v7, v7, v9
	v_fmac_f32_e32 v7, v3, v6
	v_add_f32_e32 v2, v2, v7
	v_and_b32_e32 v7, 0xffff0000, v14
	v_and_b32_e32 v9, 0xffff0000, v18
	v_lshlrev_b32_e32 v3, 16, v14
	v_lshlrev_b32_e32 v6, 16, v18
	v_mul_f32_e32 v7, v7, v9
	v_fmac_f32_e32 v7, v3, v6
	v_add_f32_e32 v2, v2, v7
	v_lshlrev_b32_e32 v3, 16, v15
	v_lshlrev_b32_e32 v6, 16, v19
	v_and_b32_e32 v7, 0xffff0000, v15
	v_and_b32_e32 v9, 0xffff0000, v19
	global_load_dwordx4 v[12:15], v[0:1], off offset:208
	global_load_dwordx4 v[16:19], v[4:5], off offset:208
	v_mul_f32_e32 v7, v7, v9
	v_fmac_f32_e32 v7, v3, v6
	v_add_f32_e32 v2, v2, v7
	s_waitcnt vmcnt(0) lgkmcnt(0)
	v_and_b32_e32 v7, 0xffff0000, v12
	v_and_b32_e32 v9, 0xffff0000, v16
	v_lshlrev_b32_e32 v3, 16, v12
	v_lshlrev_b32_e32 v6, 16, v16
	v_mul_f32_e32 v7, v7, v9
	v_fmac_f32_e32 v7, v3, v6
	v_add_f32_e32 v2, v2, v7
	v_and_b32_e32 v7, 0xffff0000, v13
	v_and_b32_e32 v9, 0xffff0000, v17
	v_lshlrev_b32_e32 v3, 16, v13
	v_lshlrev_b32_e32 v6, 16, v17
	v_mul_f32_e32 v7, v7, v9
	v_fmac_f32_e32 v7, v3, v6
	v_add_f32_e32 v2, v2, v7
	v_and_b32_e32 v7, 0xffff0000, v14
	v_and_b32_e32 v9, 0xffff0000, v18
	v_lshlrev_b32_e32 v3, 16, v14
	v_lshlrev_b32_e32 v6, 16, v18
	v_mul_f32_e32 v7, v7, v9
	v_fmac_f32_e32 v7, v3, v6
	v_add_f32_e32 v2, v2, v7
	v_lshlrev_b32_e32 v3, 16, v15
	v_lshlrev_b32_e32 v6, 16, v19
	v_and_b32_e32 v7, 0xffff0000, v15
	v_and_b32_e32 v9, 0xffff0000, v19
	global_load_dwordx4 v[12:15], v[0:1], off offset:224
	global_load_dwordx4 v[16:19], v[4:5], off offset:224
	v_mul_f32_e32 v7, v7, v9
	v_fmac_f32_e32 v7, v3, v6
	v_add_f32_e32 v2, v2, v7
	s_waitcnt vmcnt(0) lgkmcnt(0)
	v_and_b32_e32 v7, 0xffff0000, v12
	v_and_b32_e32 v9, 0xffff0000, v16
	v_lshlrev_b32_e32 v3, 16, v12
	v_lshlrev_b32_e32 v6, 16, v16
	v_mul_f32_e32 v7, v7, v9
	v_fmac_f32_e32 v7, v3, v6
	v_add_f32_e32 v2, v2, v7
	v_and_b32_e32 v7, 0xffff0000, v13
	v_and_b32_e32 v9, 0xffff0000, v17
	v_lshlrev_b32_e32 v3, 16, v13
	v_lshlrev_b32_e32 v6, 16, v17
	v_mul_f32_e32 v7, v7, v9
	v_fmac_f32_e32 v7, v3, v6
	v_add_f32_e32 v2, v2, v7
	v_and_b32_e32 v7, 0xffff0000, v14
	v_and_b32_e32 v9, 0xffff0000, v18
	v_lshlrev_b32_e32 v3, 16, v14
	v_lshlrev_b32_e32 v6, 16, v18
	v_mul_f32_e32 v7, v7, v9
	v_fmac_f32_e32 v7, v3, v6
	v_add_f32_e32 v2, v2, v7
	v_and_b32_e32 v7, 0xffff0000, v15
	v_and_b32_e32 v9, 0xffff0000, v19
	v_lshlrev_b32_e32 v3, 16, v15
	v_lshlrev_b32_e32 v6, 16, v19
	v_mul_f32_e32 v7, v7, v9
	v_fmac_f32_e32 v7, v3, v6
	v_add_f32_e32 v9, v2, v7
	global_load_dwordx4 v[0:3], v[0:1], off offset:240
	s_nop 0
	global_load_dwordx4 v[4:7], v[4:5], off offset:240
	s_waitcnt vmcnt(0) lgkmcnt(0)
	v_lshlrev_b32_e32 v12, 16, v0
	v_lshlrev_b32_e32 v13, 16, v4
	v_and_b32_e32 v0, 0xffff0000, v0
	v_and_b32_e32 v4, 0xffff0000, v4
	v_mul_f32_e32 v0, v0, v4
	v_fmac_f32_e32 v0, v12, v13
	v_add_f32_e32 v0, v9, v0
	v_lshlrev_b32_e32 v4, 16, v1
	v_lshlrev_b32_e32 v9, 16, v5
	v_and_b32_e32 v1, 0xffff0000, v1
	v_and_b32_e32 v5, 0xffff0000, v5
	v_mul_f32_e32 v1, v1, v5
	v_fmac_f32_e32 v1, v4, v9
	v_add_f32_e32 v0, v0, v1
	v_lshlrev_b32_e32 v1, 16, v2
	v_and_b32_e32 v2, 0xffff0000, v2
	v_and_b32_e32 v5, 0xffff0000, v6
	v_lshlrev_b32_e32 v4, 16, v6
	v_mul_f32_e32 v2, v2, v5
	v_fmac_f32_e32 v2, v1, v4
	v_lshlrev_b32_e32 v1, 16, v3
	v_and_b32_e32 v3, 0xffff0000, v3
	v_and_b32_e32 v4, 0xffff0000, v7
	v_add_f32_e32 v0, v0, v2
	v_lshlrev_b32_e32 v2, 16, v7
	v_mul_f32_e32 v3, v3, v4
	v_fmac_f32_e32 v3, v1, v2
	v_lshlrev_b32_e32 v1, 2, v10
	v_add_f32_e32 v0, v0, v3
	v_bitop3_b32 v2, v1, 4, v231 bitop3:0x6c
	ds_bpermute_b32 v2, v2, v0
	s_waitcnt lgkmcnt(0)
	v_add_f32_e32 v0, v0, v2
	v_bitop3_b32 v2, v1, 8, v231 bitop3:0x6c
	ds_bpermute_b32 v2, v2, v0
	v_bitop3_b32 v1, v1, 16, v231 bitop3:0x6c
	s_waitcnt lgkmcnt(0)
	v_add_f32_e32 v0, v0, v2
	ds_bpermute_b32 v1, v1, v0
	s_and_saveexec_b64 s[0:1], vcc
	s_cbranch_execz .LBB0_512
	v_readlane_b32 s3, v254, 16
	s_waitcnt lgkmcnt(0)
	v_add_f32_e32 v2, v0, v1
	s_mov_b64 s[34:35], s[94:95]
	v_add_u32_e32 v0, s3, v8
	v_ashrrev_i32_e32 v1, 31, v0
	s_nop 0
	v_lshl_add_u64 v[0:1], v[0:1], 2, s[34:35]
	v_add_co_u32_e32 v0, vcc, 0x30000, v0
	s_nop 1
	v_addc_co_u32_e32 v1, vcc, 0, v1, vcc
	global_store_dword v[0:1], v2, off

.LBB0_518:
	s_waitcnt lgkmcnt(0)
	v_mov_b64_e32 v[0:1], s[48:49]
	v_mov_b64_e32 v[2:3], s[60:61]
	global_load_dword v0, v[0:1], off sc1
	v_readlane_b32 s4, v252, 44
	global_load_dword v1, v[2:3], off sc1
	v_mov_b64_e32 v[2:3], s[62:63]
	global_load_dword v2, v[2:3], off sc1
	v_readlane_b32 s5, v252, 45
	s_or_b64 s[40:41], s[40:41], exec
	s_or_b64 s[38:39], s[38:39], exec
	s_waitcnt vmcnt(0) lgkmcnt(0)
	v_add_u32_e32 v4, v1, v0
	v_add_u32_e32 v6, v4, v2
	v_mov_b64_e32 v[4:5], s[76:77]
	global_load_dword v3, v[4:5], off sc1
	v_mov_b64_e32 v[4:5], s[18:19]
	global_load_dword v4, v[4:5], off sc1
	s_waitcnt vmcnt(0) lgkmcnt(0)
	v_add_u32_e32 v6, v6, v3
	v_add_u32_e32 v8, v6, v4
	v_mov_b64_e32 v[6:7], s[20:21]
	global_load_dword v5, v[6:7], off sc1
	v_mov_b64_e32 v[6:7], s[4:5]
	global_load_dword v6, v[6:7], off sc1
	v_readlane_b32 s4, v252, 46
	v_readlane_b32 s5, v252, 47
	s_waitcnt vmcnt(0) lgkmcnt(0)
	v_add_u32_e32 v8, v8, v5
	v_add_u32_e32 v10, v8, v6
	v_mov_b64_e32 v[8:9], s[4:5]
	v_readlane_b32 s4, v252, 48
	v_readlane_b32 s5, v252, 49
	global_load_dword v7, v[8:9], off sc1
	s_waitcnt vmcnt(0) lgkmcnt(0)
	v_add_u32_e32 v10, v10, v7
	v_mov_b64_e32 v[8:9], s[4:5]
	global_load_dword v8, v[8:9], off sc1
	v_readlane_b32 s4, v252, 50
	v_readlane_b32 s5, v252, 51
	s_waitcnt vmcnt(0) lgkmcnt(0)
	v_add_u32_e32 v12, v10, v8
	v_mov_b64_e32 v[10:11], s[4:5]
	v_readlane_b32 s4, v252, 52
	v_readlane_b32 s5, v252, 53
	global_load_dword v9, v[10:11], off sc1
	s_waitcnt vmcnt(0) lgkmcnt(0)
	v_add_u32_e32 v12, v12, v9
	v_mov_b64_e32 v[10:11], s[4:5]
	global_load_dword v10, v[10:11], off sc1
	v_readlane_b32 s4, v252, 54
	v_readlane_b32 s5, v252, 55
	s_waitcnt vmcnt(0) lgkmcnt(0)
	v_add_u32_e32 v14, v12, v10
	v_mov_b64_e32 v[12:13], s[54:55]
	global_load_dword v11, v[12:13], off sc1
	v_mov_b64_e32 v[12:13], s[64:65]
	global_load_dword v12, v[12:13], off sc1
	s_waitcnt vmcnt(0) lgkmcnt(0)
	v_add_u32_e32 v14, v14, v11
	v_add_u32_e32 v16, v14, v12
	v_mov_b64_e32 v[14:15], s[66:67]
	global_load_dword v13, v[14:15], off sc1
	v_mov_b64_e32 v[14:15], s[4:5]
	global_load_dword v14, v[14:15], off sc1
	v_readlane_b32 s4, v252, 56
	v_readlane_b32 s5, v252, 57
	s_waitcnt vmcnt(0) lgkmcnt(0)
	v_add_u32_e32 v16, v16, v13
	v_add_u32_e32 v18, v16, v14
	v_mov_b64_e32 v[16:17], s[4:5]
	global_load_dword v15, v[16:17], off sc1
	s_waitcnt vmcnt(0) lgkmcnt(0)
	v_add_u32_e32 v16, v18, v15
	v_cmp_ne_u32_e32 vcc, s6, v16
	s_and_saveexec_b64 s[42:43], vcc
	s_cbranch_execz .LBB0_517
	s_and_b32 s22, s3, 0xff
	s_mov_b64 s[46:47], -1
	s_cmp_eq_u32 s22, 0
	s_mov_b64 s[70:71], -1
	s_mov_b64 s[68:69], -1
	s_sleep 1
	s_cbranch_scc1 .LBB0_521
	s_and_saveexec_b64 s[72:73], s[70:71]
	s_cbranch_execz .LBB0_516
	s_branch .LBB0_524
.LBB0_521:
	v_readlane_b32 s4, v252, 42
	v_readlane_b32 s5, v252, 43
	s_mov_b64 s[70:71], 0
	s_nop 0
	v_mov_b64_e32 v[16:17], s[4:5]
	global_load_dword v16, v[16:17], off sc1
	s_waitcnt vmcnt(0) lgkmcnt(0)
	v_cmp_eq_u32_e32 vcc, 0, v16
	s_and_saveexec_b64 s[72:73], vcc
	s_cmp_lt_u32 s3, 0x400001
	s_cselect_b64 s[58:59], -1, 0
	s_xor_b64 s[68:69], exec, -1
	s_and_b64 s[70:71], s[58:59], exec
	s_or_b64 exec, exec, s[72:73]
	s_and_saveexec_b64 s[72:73], s[70:71]
	s_cbranch_execz .LBB0_516

.LBB0_525:
	s_or_b64 exec, exec, s[34:35]
	s_xor_b64 s[34:35], s[36:37], -1
	s_and_saveexec_b64 s[36:37], s[34:35]
	s_xor_b64 s[34:35], exec, s[36:37]
	s_cbranch_execz .LBB0_527
	v_readlane_b32 s4, v252, 42
	v_readlane_b32 s5, v252, 43
	s_nop 1
	v_mov_b64_e32 v[16:17], s[4:5]
	global_atomic_add v[16:17], v230, off

.LBB0_528:
	v_readlane_b32 s4, v253, 26
	v_readlane_b32 s5, v253, 27
	v_cvt_f32_u32_e32 v1, v2
	v_rcp_iflag_f32_e32 v1, v1
	v_mov_b64_e32 v[4:5], s[4:5]
	global_atomic_add v3, v[4:5], v230, off sc0
	v_sub_u32_e32 v4, 0, v2
	v_mul_f32_e32 v1, 0x4f7ffffe, v1
	v_cvt_u32_f32_e32 v1, v1
	v_mul_lo_u32 v4, v4, v1
	v_mul_hi_u32 v4, v1, v4
	v_add_u32_e32 v1, v1, v4
	s_waitcnt vmcnt(0) lgkmcnt(0)
	v_mul_hi_u32 v1, v3, v1
	v_mul_lo_u32 v4, v1, v2
	v_sub_u32_e32 v4, v3, v4
	v_cmp_ge_u32_e32 vcc, v4, v2
	v_add_u32_e32 v5, 1, v1
	s_nop 0
	v_cndmask_b32_e32 v1, v1, v5, vcc
	v_sub_u32_e32 v5, v4, v2
	v_cndmask_b32_e32 v4, v4, v5, vcc
	v_cmp_ge_u32_e32 vcc, v4, v2
	v_add_u32_e32 v4, 1, v1
	s_nop 0
	v_cndmask_b32_e32 v1, v1, v4, vcc
	v_add_u32_e32 v4, 1, v3
	v_mad_u64_u32 v[2:3], s[34:35], v2, v1, v[2:3]
	v_cmp_ne_u32_e32 vcc, v4, v2
	s_and_saveexec_b64 s[34:35], vcc
	s_xor_b64 s[34:35], exec, s[34:35]
	s_cbranch_execz .LBB0_541
	v_readlane_b32 s4, v253, 28
	v_readlane_b32 s5, v253, 29
	s_nop 1
	v_mov_b64_e32 v[2:3], s[4:5]
	global_load_dword v0, v[2:3], off sc1
	s_waitcnt vmcnt(0) lgkmcnt(0)
	v_cmp_eq_u32_e32 vcc, v0, v1
	s_and_saveexec_b64 s[36:37], vcc
	s_cbranch_execz .LBB0_540
	s_mov_b32 s3, 1
	s_mov_b64 s[38:39], 0
	s_branch .LBB0_532

.LBB0_532:
	s_and_b32 s22, s3, 0xff
	s_mov_b64 s[46:47], -1
	s_cmp_lg_u32 s22, 0
	s_mov_b64 s[68:69], -1
	s_sleep 1
	s_cbranch_scc1 .LBB0_536
	v_readlane_b32 s4, v252, 42
	v_readlane_b32 s5, v252, 43
	s_mov_b64 s[68:69], 0
	s_mov_b64 s[70:71], -1
	v_mov_b64_e32 v[2:3], s[4:5]
	global_load_dword v0, v[2:3], off sc1
	s_waitcnt vmcnt(0) lgkmcnt(0)
	v_cmp_eq_u32_e32 vcc, 0, v0
	s_and_saveexec_b64 s[72:73], vcc
	s_cmp_lt_u32 s3, 0x400001
	s_cselect_b64 s[58:59], -1, 0
	s_xor_b64 s[70:71], exec, -1
	s_and_b64 s[68:69], s[58:59], exec
	s_or_b64 exec, exec, s[72:73]
.LBB0_536:
	s_andn2_b64 s[42:43], s[42:43], exec
	s_and_b64 s[58:59], s[70:71], exec
	s_or_b64 s[42:43], s[42:43], s[58:59]
	s_and_saveexec_b64 s[70:71], s[68:69]
	s_cbranch_execz .LBB0_531
	v_readlane_b32 s4, v253, 28
	v_readlane_b32 s5, v253, 29
	s_add_i32 s3, s3, 1
	s_or_b64 s[42:43], s[42:43], exec
	v_mov_b64_e32 v[2:3], s[4:5]
	global_load_dword v0, v[2:3], off sc1
	s_waitcnt vmcnt(0) lgkmcnt(0)
	v_cmp_ne_u32_e32 vcc, v0, v1
	s_orn2_b64 s[46:47], vcc, exec
	s_branch .LBB0_531
.LBB0_538:
	s_or_b64 exec, exec, s[38:39]
	s_xor_b64 s[38:39], s[40:41], -1
	s_and_saveexec_b64 s[40:41], s[38:39]
	s_xor_b64 s[40:41], exec, s[40:41]
	s_cbranch_execz .LBB0_540
	v_readlane_b32 s4, v252, 42
	v_readlane_b32 s5, v252, 43
	s_nop 1
	v_mov_b64_e32 v[0:1], s[4:5]
	global_atomic_add v[0:1], v230, off

.LBB0_541:
	s_andn2_saveexec_b64 s[34:35], s[34:35]
	s_cbranch_execz .LBB0_557
	v_readlane_b32 s4, v253, 30
	v_readlane_b32 s5, v253, 31
	buffer_wbl2 sc1
	s_waitcnt vmcnt(0)
	s_mov_b64 s[36:37], -1
	v_mov_b64_e32 v[2:3], s[4:5]
	global_atomic_add v1, v[2:3], v230, off sc0
	v_cvt_f32_u32_e32 v2, v0
	v_sub_u32_e32 v3, 0, v0
	v_readlane_b32 s4, v253, 32
	v_readlane_b32 s5, v253, 33
	v_rcp_iflag_f32_e32 v2, v2
	s_nop 0
	v_mul_f32_e32 v2, 0x4f7ffffe, v2
	v_cvt_u32_f32_e32 v2, v2
	v_mul_lo_u32 v3, v3, v2
	v_mul_hi_u32 v3, v2, v3
	v_add_u32_e32 v2, v2, v3
	s_waitcnt vmcnt(0) lgkmcnt(0)
	v_mul_hi_u32 v2, v1, v2
	v_mul_lo_u32 v3, v2, v0
	v_sub_u32_e32 v3, v1, v3
	v_cmp_ge_u32_e32 vcc, v3, v0
	v_add_u32_e32 v4, 1, v2
	s_nop 0
	v_cndmask_b32_e32 v2, v2, v4, vcc
	v_sub_u32_e32 v4, v3, v0
	v_cndmask_b32_e32 v3, v3, v4, vcc
	v_cmp_ge_u32_e32 vcc, v3, v0
	v_add_u32_e32 v3, 1, v2
	s_nop 0
	v_cndmask_b32_e32 v2, v2, v3, vcc
	v_add_u32_e32 v3, 1, v1
	v_mad_u64_u32 v[0:1], s[34:35], v0, v2, v[0:1]
	v_cmp_ne_u32_e32 vcc, v3, v0
	v_mov_b64_e32 v[0:1], s[4:5]
	s_and_saveexec_b64 s[34:35], vcc
	s_cbranch_execz .LBB0_554
	v_readlane_b32 s4, v253, 32
	v_readlane_b32 s5, v253, 33
	s_mov_b64 s[38:39], 0
	s_nop 0
	v_mov_b64_e32 v[0:1], s[4:5]
	global_load_dword v0, v[0:1], off sc1
	s_waitcnt vmcnt(0) lgkmcnt(0)
	v_cmp_eq_u32_e32 vcc, v0, v2
	s_and_saveexec_b64 s[36:37], vcc
	s_cbranch_execz .LBB0_553
	s_mov_b32 s3, 1
	s_branch .LBB0_546

.LBB0_548:
	v_readlane_b32 s4, v252, 42
	v_readlane_b32 s5, v252, 43
	s_mov_b64 s[68:69], 0
	s_mov_b64 s[46:47], -1
	v_mov_b64_e32 v[0:1], s[4:5]
	global_load_dword v0, v[0:1], off sc1
	s_waitcnt vmcnt(0) lgkmcnt(0)
	v_cmp_eq_u32_e32 vcc, 0, v0
	s_and_saveexec_b64 s[70:71], vcc
	s_cmp_lt_u32 s3, 0x400001
	s_cselect_b64 s[58:59], -1, 0
	s_xor_b64 s[46:47], exec, -1
	s_and_b64 s[68:69], s[58:59], exec
	s_or_b64 exec, exec, s[70:71]
	s_and_saveexec_b64 s[70:71], s[68:69]
	s_cbranch_execz .LBB0_545
.LBB0_551:
	v_readlane_b32 s4, v253, 32
	v_readlane_b32 s5, v253, 33
	s_add_i32 s3, s3, 1
	s_or_b64 s[46:47], s[46:47], exec
	v_mov_b64_e32 v[0:1], s[4:5]
	global_load_dword v0, v[0:1], off sc1
	s_waitcnt vmcnt(0) lgkmcnt(0)
	v_cmp_ne_u32_e32 vcc, v0, v2
	s_orn2_b64 s[42:43], vcc, exec
	s_branch .LBB0_545

.LBB0_556:
	s_or_b64 exec, exec, s[34:35]
	v_readlane_b32 s4, v253, 28
	v_readlane_b32 s5, v253, 29
	s_waitcnt vmcnt(0) lgkmcnt(0)
	buffer_inv sc1
	v_mov_b64_e32 v[0:1], s[4:5]
	global_atomic_add v[0:1], v230, off
	s_waitcnt vmcnt(0)
.LBB0_557:
	s_or_b64 exec, exec, s[0:1]
	v_readlane_b32 s4, v255, 32
	s_mov_b64 s[0:1], s[94:95]
	s_lshl_b32 s52, s4, 1
	s_waitcnt lgkmcnt(0)
	s_barrier
	s_lshl_b64 s[34:35], s[52:53], 2
	s_add_u32 s0, s0, s34
	s_addc_u32 s1, s1, s35
	v_mov_b32_e32 v0, s0
	v_add_co_u32_e32 v0, vcc, 0x10000, v0
	v_mov_b32_e32 v1, s1
	s_nop 0
	v_addc_co_u32_e32 v1, vcc, 0, v1, vcc
	global_load_dword v0, v[0:1], off
	s_mov_b64 s[0:1], s[94:95]
	s_add_u32 s0, s0, s34
	s_addc_u32 s1, s1, s35
	v_mov_b32_e32 v1, s1
	v_readlane_b32 s5, v255, 33
	s_mul_i32 s76, s4, 0x2080
	s_lshl_b32 s52, s4, 7
	v_readlane_b32 s4, v252, 0
	v_readlane_b32 s5, v252, 1
	v_readlane_b32 s8, v252, 4
	v_readlane_b32 s6, v252, 2
	v_readlane_b32 s9, v252, 5
	v_readlane_b32 s10, v252, 6
	v_readlane_b32 s11, v252, 7
	v_readlane_b32 s4, v252, 8
	v_readlane_b32 s5, v252, 9
	v_readlane_b32 s6, v255, 24
	s_mov_b32 s10, 0x18000
	v_readlane_b32 s11, v255, 22
	s_movk_i32 s12, 0x110
	v_readlane_b32 s7, v252, 3
	s_waitcnt vmcnt(0) lgkmcnt(0)
	v_readfirstlane_b32 s74, v0
	v_mov_b32_e32 v0, s0
	v_add_co_u32_e32 v0, vcc, 0x10000, v0
	s_lshl_b64 s[0:1], s[52:53], 2
	s_nop 0
	v_addc_co_u32_e32 v1, vcc, 0, v1, vcc
	global_load_dword v0, v[0:1], off offset:4
	s_add_u32 s38, s8, s0
	s_addc_u32 s39, s9, s1
	s_movk_i32 s8, 0x60
	s_mov_b32 s9, 0x10000
	s_waitcnt vmcnt(0) lgkmcnt(0)
	v_readfirstlane_b32 s75, v0
	s_branch .LBB0_560

.LBB0_560:
	s_barrier
	s_and_saveexec_b64 s[0:1], s[4:5]
	s_cbranch_execz .LBB0_562
	s_mov_b64 s[34:35], s[94:95]
	s_lshl_b64 s[36:37], s[44:45], 2
	s_add_u32 s34, s34, s36
	s_addc_u32 s35, s35, s37
	v_mov_b64_e32 v[0:1], s[34:35]
	global_atomic_add v0, v[0:1], v230, off offset:256 sc0
	v_mov_b32_e32 v1, s11
	s_waitcnt vmcnt(0) lgkmcnt(0)
	ds_write_b32 v1, v0

.LBB0_572:
	s_lshl_b32 s34, s52, 11
	s_or_b32 s34, s34, s58
	s_mov_b32 s35, s53
	s_lshl_b64 s[34:35], s[34:35], 11
	s_add_u32 s34, s36, s34
	s_addc_u32 s35, s37, s35
	s_lshl_b32 s36, s3, 1
	s_add_u32 s34, s34, s36
	s_addc_u32 s35, s35, 0
	s_add_u32 s34, s34, 0x4b00400
	s_addc_u32 s35, s35, 0
	s_lshl_b32 s52, s52, 9
	s_lshl_b64 s[36:37], s[52:53], 2
	s_add_u32 s0, s0, s36
	s_addc_u32 s1, s1, s37
	s_lshl_b32 s3, s3, 2
	v_or_b32_e32 v160, s71, v129
	s_add_u32 s0, s0, s3
	s_addc_u32 s1, s1, 0
	v_lshlrev_b32_e32 v176, 2, v160
	v_lshl_add_u64 v[130:131], s[0:1], 0, v[176:177]
	s_mov_b64 s[0:1], 0x30000
	v_lshl_add_u64 v[132:133], v[130:131], 0, s[0:1]
	s_mov_b32 s0, 0x30000
	v_add_co_u32_e32 v130, vcc, s0, v130
	v_ashrrev_i32_e32 v129, 31, v128
	s_nop 0
	v_addc_co_u32_e32 v131, vcc, 0, v131, vcc
	global_load_dwordx4 v[134:137], v[130:131], off
	global_load_dwordx4 v[142:145], v[132:133], off offset:16
	global_load_dwordx4 v[152:155], v[132:133], off offset:512
	global_load_dwordx4 v[156:159], v[132:133], off offset:528
	v_and_b32_e32 v130, 1, v140
	v_cmp_eq_u32_e32 vcc, 0, v130
	v_or_b32_e32 v146, 48, v128
	v_or_b32_e32 v148, 32, v128
	v_or_b32_e32 v150, 16, v128
	v_lshlrev_b64 v[128:129], 11, v[128:129]
	v_lshl_add_u64 v[128:129], s[34:35], 0, v[128:129]
	v_lshlrev_b32_e32 v176, 1, v160
	v_lshl_add_u64 v[128:129], v[128:129], 0, v[176:177]
	v_ashrrev_i32_e32 v151, 31, v150
	v_ashrrev_i32_e32 v149, 31, v148
	v_ashrrev_i32_e32 v147, 31, v146
	s_mov_b64 s[0:1], 0x40000
	v_readlane_b32 s11, v255, 22
	s_movk_i32 s12, 0x110
	s_waitcnt vmcnt(0) lgkmcnt(0)
	v_xor_b32_e32 v140, 0x80000000, v142
	v_xor_b32_e32 v141, 0x80000000, v143
	v_xor_b32_e32 v138, 0x80000000, v144
	v_xor_b32_e32 v139, 0x80000000, v145
	v_cndmask_b32_e32 v139, v139, v145, vcc
	v_cndmask_b32_e32 v138, v138, v144, vcc
	v_cndmask_b32_e32 v141, v141, v143, vcc
	v_cndmask_b32_e32 v140, v140, v142, vcc
	v_xor_b32_e32 v144, 0x80000000, v134
	v_xor_b32_e32 v145, 0x80000000, v135
	v_xor_b32_e32 v142, 0x80000000, v136
	v_xor_b32_e32 v143, 0x80000000, v137
	v_cndmask_b32_e32 v143, v143, v137, vcc
	v_cndmask_b32_e32 v142, v142, v136, vcc
	v_cndmask_b32_e32 v145, v145, v135, vcc
	v_cndmask_b32_e32 v144, v144, v134, vcc
	v_xor_b32_e32 v132, 0x80000000, v152
	v_xor_b32_e32 v133, 0x80000000, v153
	v_xor_b32_e32 v130, 0x80000000, v154
	v_xor_b32_e32 v131, 0x80000000, v155
	v_xor_b32_e32 v136, 0x80000000, v156
	v_xor_b32_e32 v137, 0x80000000, v157
	v_xor_b32_e32 v134, 0x80000000, v158
	v_xor_b32_e32 v135, 0x80000000, v159
	v_pk_add_f32 v[124:125], v[124:125], v[144:145]
	v_pk_add_f32 v[126:127], v[126:127], v[142:143]
	v_pk_add_f32 v[120:121], v[120:121], v[140:141]
	v_pk_add_f32 v[122:123], v[122:123], v[138:139]
	v_cndmask_b32_e32 v131, v131, v155, vcc
	v_cndmask_b32_e32 v130, v130, v154, vcc
	v_cndmask_b32_e32 v133, v133, v153, vcc
	v_cndmask_b32_e32 v132, v132, v152, vcc
	v_cndmask_b32_e32 v135, v135, v159, vcc
	v_cndmask_b32_e32 v134, v134, v158, vcc
	v_cndmask_b32_e32 v137, v137, v157, vcc
	v_cndmask_b32_e32 v136, v136, v156, vcc
	v_pk_mul_f32 v[126:127], v[126:127], s[88:89] op_sel_hi:[1,0]
	v_pk_mul_f32 v[124:125], v[124:125], s[88:89] op_sel_hi:[1,0]
	v_pk_mul_f32 v[152:153], v[122:123], s[88:89] op_sel_hi:[1,0]
	v_pk_mul_f32 v[122:123], v[120:121], s[88:89] op_sel_hi:[1,0]
	v_cvt_pk_bf16_f32 v120, v124, v125
	v_cvt_pk_bf16_f32 v121, v126, v127
	v_cvt_pk_bf16_f32 v122, v122, v123
	v_cvt_pk_bf16_f32 v123, v152, v153
	v_pk_add_f32 v[116:117], v[116:117], v[132:133]
	v_pk_add_f32 v[118:119], v[118:119], v[130:131]
	v_pk_add_f32 v[112:113], v[112:113], v[136:137]
	v_pk_add_f32 v[114:115], v[114:115], v[134:135]
	global_store_dwordx4 v[128:129], v[120:123], off
	v_pk_mul_f32 v[118:119], v[118:119], s[88:89] op_sel_hi:[1,0]
	v_pk_mul_f32 v[116:117], v[116:117], s[88:89] op_sel_hi:[1,0]
	v_pk_mul_f32 v[120:121], v[114:115], s[88:89] op_sel_hi:[1,0]
	v_pk_mul_f32 v[114:115], v[112:113], s[88:89] op_sel_hi:[1,0]
	v_cvt_pk_bf16_f32 v112, v116, v117
	v_cvt_pk_bf16_f32 v113, v118, v119
	v_cvt_pk_bf16_f32 v114, v114, v115
	v_cvt_pk_bf16_f32 v115, v120, v121
	global_store_dwordx4 v[128:129], v[112:115], off offset:256
	v_pk_add_f32 v[108:109], v[108:109], v[144:145]
	v_pk_add_f32 v[110:111], v[110:111], v[142:143]
	v_lshlrev_b64 v[112:113], 11, v[150:151]
	v_pk_add_f32 v[104:105], v[104:105], v[140:141]
	v_pk_add_f32 v[106:107], v[106:107], v[138:139]
	v_lshl_add_u64 v[112:113], s[34:35], 0, v[112:113]
	v_pk_mul_f32 v[110:111], v[110:111], s[88:89] op_sel_hi:[1,0]
	v_pk_mul_f32 v[108:109], v[108:109], s[88:89] op_sel_hi:[1,0]
	v_pk_mul_f32 v[114:115], v[106:107], s[88:89] op_sel_hi:[1,0]
	v_pk_mul_f32 v[106:107], v[104:105], s[88:89] op_sel_hi:[1,0]
	v_lshl_add_u64 v[112:113], v[112:113], 0, v[176:177]
	v_cvt_pk_bf16_f32 v104, v108, v109
	v_cvt_pk_bf16_f32 v105, v110, v111
	v_cvt_pk_bf16_f32 v106, v106, v107
	v_cvt_pk_bf16_f32 v107, v114, v115
	v_pk_add_f32 v[96:97], v[96:97], v[132:133]
	v_pk_add_f32 v[98:99], v[98:99], v[130:131]
	v_pk_add_f32 v[88:89], v[88:89], v[136:137]
	v_pk_add_f32 v[90:91], v[90:91], v[134:135]
	global_store_dwordx4 v[112:113], v[104:107], off
	v_pk_mul_f32 v[98:99], v[98:99], s[88:89] op_sel_hi:[1,0]
	v_pk_mul_f32 v[96:97], v[96:97], s[88:89] op_sel_hi:[1,0]
	v_pk_mul_f32 v[104:105], v[90:91], s[88:89] op_sel_hi:[1,0]
	v_pk_mul_f32 v[90:91], v[88:89], s[88:89] op_sel_hi:[1,0]
	v_cvt_pk_bf16_f32 v88, v96, v97
	v_cvt_pk_bf16_f32 v89, v98, v99
	v_cvt_pk_bf16_f32 v90, v90, v91
	v_cvt_pk_bf16_f32 v91, v104, v105
	global_store_dwordx4 v[112:113], v[88:91], off offset:256
	v_pk_add_f32 v[92:93], v[92:93], v[140:141]
	v_pk_add_f32 v[94:95], v[94:95], v[138:139]
	v_lshlrev_b64 v[88:89], 11, v[148:149]
	v_lshl_add_u64 v[88:89], s[34:35], 0, v[88:89]
	v_lshl_add_u64 v[96:97], v[88:89], 0, v[176:177]
	v_pk_add_f32 v[88:89], v[100:101], v[144:145]
	v_pk_add_f32 v[90:91], v[102:103], v[142:143]
	v_pk_mul_f32 v[88:89], v[88:89], s[88:89] op_sel_hi:[1,0]
	v_pk_mul_f32 v[90:91], v[90:91], s[88:89] op_sel_hi:[1,0]
	v_pk_mul_f32 v[94:95], v[94:95], s[88:89] op_sel_hi:[1,0]
	v_pk_mul_f32 v[92:93], v[92:93], s[88:89] op_sel_hi:[1,0]
	v_cvt_pk_bf16_f32 v88, v88, v89
	v_cvt_pk_bf16_f32 v89, v90, v91
	v_cvt_pk_bf16_f32 v90, v92, v93
	v_cvt_pk_bf16_f32 v91, v94, v95
	v_pk_add_f32 v[80:81], v[80:81], v[132:133]
	v_pk_add_f32 v[82:83], v[82:83], v[130:131]
	v_pk_add_f32 v[72:73], v[72:73], v[136:137]
	v_pk_add_f32 v[74:75], v[74:75], v[134:135]
	global_store_dwordx4 v[96:97], v[88:91], off
	v_pk_mul_f32 v[82:83], v[82:83], s[88:89] op_sel_hi:[1,0]
	v_pk_mul_f32 v[80:81], v[80:81], s[88:89] op_sel_hi:[1,0]
	v_pk_mul_f32 v[88:89], v[74:75], s[88:89] op_sel_hi:[1,0]
	v_pk_mul_f32 v[74:75], v[72:73], s[88:89] op_sel_hi:[1,0]
	v_cvt_pk_bf16_f32 v72, v80, v81
	v_cvt_pk_bf16_f32 v73, v82, v83
	v_cvt_pk_bf16_f32 v74, v74, v75
	v_cvt_pk_bf16_f32 v75, v88, v89
	global_store_dwordx4 v[96:97], v[72:75], off offset:256
	v_pk_add_f32 v[76:77], v[76:77], v[140:141]
	v_pk_add_f32 v[78:79], v[78:79], v[138:139]
	v_lshlrev_b64 v[72:73], 11, v[146:147]
	v_lshl_add_u64 v[72:73], s[34:35], 0, v[72:73]
	v_lshl_add_u64 v[80:81], v[72:73], 0, v[176:177]
	v_pk_add_f32 v[72:73], v[84:85], v[144:145]
	v_pk_add_f32 v[74:75], v[86:87], v[142:143]
	v_pk_mul_f32 v[72:73], v[72:73], s[88:89] op_sel_hi:[1,0]
	v_pk_mul_f32 v[74:75], v[74:75], s[88:89] op_sel_hi:[1,0]
	v_pk_mul_f32 v[78:79], v[78:79], s[88:89] op_sel_hi:[1,0]
	v_pk_mul_f32 v[76:77], v[76:77], s[88:89] op_sel_hi:[1,0]
	v_cvt_pk_bf16_f32 v72, v72, v73
	v_cvt_pk_bf16_f32 v73, v74, v75
	v_cvt_pk_bf16_f32 v74, v76, v77
	v_cvt_pk_bf16_f32 v75, v78, v79
	v_pk_add_f32 v[68:69], v[68:69], v[132:133]
	v_pk_add_f32 v[70:71], v[70:71], v[130:131]
	v_pk_add_f32 v[64:65], v[64:65], v[136:137]
	v_pk_add_f32 v[66:67], v[66:67], v[134:135]
	global_store_dwordx4 v[80:81], v[72:75], off
	v_pk_mul_f32 v[70:71], v[70:71], s[88:89] op_sel_hi:[1,0]
	v_pk_mul_f32 v[68:69], v[68:69], s[88:89] op_sel_hi:[1,0]
	v_pk_mul_f32 v[72:73], v[66:67], s[88:89] op_sel_hi:[1,0]
	v_pk_mul_f32 v[66:67], v[64:65], s[88:89] op_sel_hi:[1,0]
	v_cvt_pk_bf16_f32 v64, v68, v69
	v_cvt_pk_bf16_f32 v65, v70, v71
	v_cvt_pk_bf16_f32 v66, v66, v67
	v_cvt_pk_bf16_f32 v67, v72, v73
	v_pk_add_f32 v[60:61], v[60:61], v[144:145]
	global_store_dwordx4 v[80:81], v[64:67], off offset:256
	v_pk_add_f32 v[62:63], v[62:63], v[142:143]
	v_pk_mul_f32 v[60:61], v[60:61], s[88:89] op_sel_hi:[1,0]
	v_lshl_add_u64 v[64:65], v[128:129], 0, s[0:1]
	v_pk_add_f32 v[56:57], v[56:57], v[140:141]
	v_pk_add_f32 v[58:59], v[58:59], v[138:139]
	s_mov_b32 s0, 0x40000
	v_pk_mul_f32 v[62:63], v[62:63], s[88:89] op_sel_hi:[1,0]
	v_pk_mul_f32 v[66:67], v[58:59], s[88:89] op_sel_hi:[1,0]
	v_pk_mul_f32 v[58:59], v[56:57], s[88:89] op_sel_hi:[1,0]
	v_cvt_pk_bf16_f32 v56, v60, v61
	v_add_co_u32_e32 v60, vcc, s0, v128
	v_cvt_pk_bf16_f32 v57, v62, v63
	v_cvt_pk_bf16_f32 v58, v58, v59
	v_cvt_pk_bf16_f32 v59, v66, v67
	v_addc_co_u32_e32 v61, vcc, 0, v129, vcc
	v_pk_add_f32 v[48:49], v[48:49], v[132:133]
	v_pk_add_f32 v[50:51], v[50:51], v[130:131]
	v_pk_add_f32 v[40:41], v[40:41], v[136:137]
	v_pk_add_f32 v[42:43], v[42:43], v[134:135]
	global_store_dwordx4 v[60:61], v[56:59], off
	v_pk_mul_f32 v[50:51], v[50:51], s[88:89] op_sel_hi:[1,0]
	v_pk_mul_f32 v[48:49], v[48:49], s[88:89] op_sel_hi:[1,0]
	v_pk_mul_f32 v[56:57], v[42:43], s[88:89] op_sel_hi:[1,0]
	v_pk_mul_f32 v[42:43], v[40:41], s[88:89] op_sel_hi:[1,0]
	v_cvt_pk_bf16_f32 v40, v48, v49
	v_cvt_pk_bf16_f32 v41, v50, v51
	v_cvt_pk_bf16_f32 v42, v42, v43
	v_cvt_pk_bf16_f32 v43, v56, v57
	global_store_dwordx4 v[64:65], v[40:43], off offset:256
	s_mov_b64 s[0:1], 0x48000
	v_pk_add_f32 v[44:45], v[44:45], v[140:141]
	v_pk_add_f32 v[40:41], v[52:53], v[144:145]
	v_pk_add_f32 v[42:43], v[54:55], v[142:143]
	v_lshl_add_u64 v[48:49], v[128:129], 0, s[0:1]
	v_pk_mul_f32 v[42:43], v[42:43], s[88:89] op_sel_hi:[1,0]
	v_pk_mul_f32 v[40:41], v[40:41], s[88:89] op_sel_hi:[1,0]
	v_pk_add_f32 v[46:47], v[46:47], v[138:139]
	v_pk_mul_f32 v[44:45], v[44:45], s[88:89] op_sel_hi:[1,0]
	s_mov_b32 s0, 0x48000
	v_pk_mul_f32 v[46:47], v[46:47], s[88:89] op_sel_hi:[1,0]
	v_cvt_pk_bf16_f32 v40, v40, v41
	v_cvt_pk_bf16_f32 v41, v42, v43
	v_cvt_pk_bf16_f32 v42, v44, v45
	v_add_co_u32_e32 v44, vcc, s0, v128
	v_cvt_pk_bf16_f32 v43, v46, v47
	s_nop 0
	v_addc_co_u32_e32 v45, vcc, 0, v129, vcc
	v_pk_add_f32 v[32:33], v[32:33], v[132:133]
	v_pk_add_f32 v[34:35], v[34:35], v[130:131]
	v_pk_add_f32 v[24:25], v[24:25], v[136:137]
	v_pk_add_f32 v[26:27], v[26:27], v[134:135]
	global_store_dwordx4 v[44:45], v[40:43], off
	v_pk_mul_f32 v[34:35], v[34:35], s[88:89] op_sel_hi:[1,0]
	v_pk_mul_f32 v[32:33], v[32:33], s[88:89] op_sel_hi:[1,0]
	v_pk_mul_f32 v[40:41], v[26:27], s[88:89] op_sel_hi:[1,0]
	v_pk_mul_f32 v[26:27], v[24:25], s[88:89] op_sel_hi:[1,0]
	v_cvt_pk_bf16_f32 v24, v32, v33
	v_cvt_pk_bf16_f32 v25, v34, v35
	v_cvt_pk_bf16_f32 v26, v26, v27
	v_cvt_pk_bf16_f32 v27, v40, v41
	global_store_dwordx4 v[48:49], v[24:27], off offset:256
	s_mov_b64 s[0:1], 0x50000
	v_pk_add_f32 v[28:29], v[28:29], v[140:141]
	v_pk_add_f32 v[24:25], v[36:37], v[144:145]
	v_pk_add_f32 v[26:27], v[38:39], v[142:143]
	v_lshl_add_u64 v[32:33], v[128:129], 0, s[0:1]
	v_pk_mul_f32 v[26:27], v[26:27], s[88:89] op_sel_hi:[1,0]
	v_pk_mul_f32 v[24:25], v[24:25], s[88:89] op_sel_hi:[1,0]
	v_pk_add_f32 v[30:31], v[30:31], v[138:139]
	v_pk_mul_f32 v[28:29], v[28:29], s[88:89] op_sel_hi:[1,0]
	s_mov_b32 s0, 0x50000
	v_pk_mul_f32 v[30:31], v[30:31], s[88:89] op_sel_hi:[1,0]
	v_cvt_pk_bf16_f32 v24, v24, v25
	v_cvt_pk_bf16_f32 v25, v26, v27
	v_cvt_pk_bf16_f32 v26, v28, v29
	v_add_co_u32_e32 v28, vcc, s0, v128
	v_cvt_pk_bf16_f32 v27, v30, v31
	s_nop 0
	v_addc_co_u32_e32 v29, vcc, 0, v129, vcc
	v_pk_add_f32 v[16:17], v[16:17], v[132:133]
	v_pk_add_f32 v[18:19], v[18:19], v[130:131]
	v_pk_add_f32 v[8:9], v[8:9], v[136:137]
	v_pk_add_f32 v[10:11], v[10:11], v[134:135]
	global_store_dwordx4 v[28:29], v[24:27], off
	v_pk_mul_f32 v[18:19], v[18:19], s[88:89] op_sel_hi:[1,0]
	v_pk_mul_f32 v[16:17], v[16:17], s[88:89] op_sel_hi:[1,0]
	v_pk_mul_f32 v[24:25], v[10:11], s[88:89] op_sel_hi:[1,0]
	v_pk_mul_f32 v[10:11], v[8:9], s[88:89] op_sel_hi:[1,0]
	v_cvt_pk_bf16_f32 v8, v16, v17
	v_cvt_pk_bf16_f32 v9, v18, v19
	v_cvt_pk_bf16_f32 v10, v10, v11
	v_cvt_pk_bf16_f32 v11, v24, v25
	global_store_dwordx4 v[32:33], v[8:11], off offset:256
	s_mov_b64 s[0:1], 0x58000
	v_pk_add_f32 v[12:13], v[12:13], v[140:141]
	v_pk_add_f32 v[8:9], v[20:21], v[144:145]
	v_pk_add_f32 v[10:11], v[22:23], v[142:143]
	v_lshl_add_u64 v[16:17], v[128:129], 0, s[0:1]
	v_pk_mul_f32 v[10:11], v[10:11], s[88:89] op_sel_hi:[1,0]
	v_pk_mul_f32 v[8:9], v[8:9], s[88:89] op_sel_hi:[1,0]
	v_pk_add_f32 v[14:15], v[14:15], v[138:139]
	v_pk_mul_f32 v[12:13], v[12:13], s[88:89] op_sel_hi:[1,0]
	s_mov_b32 s0, 0x58000
	v_pk_mul_f32 v[14:15], v[14:15], s[88:89] op_sel_hi:[1,0]
	v_cvt_pk_bf16_f32 v8, v8, v9
	v_cvt_pk_bf16_f32 v9, v10, v11
	v_cvt_pk_bf16_f32 v10, v12, v13
	v_add_co_u32_e32 v12, vcc, s0, v128
	v_cvt_pk_bf16_f32 v11, v14, v15
	s_nop 0
	v_addc_co_u32_e32 v13, vcc, 0, v129, vcc
	v_pk_add_f32 v[4:5], v[4:5], v[132:133]
	v_pk_add_f32 v[6:7], v[6:7], v[130:131]
	v_pk_add_f32 v[0:1], v[0:1], v[136:137]
	v_pk_add_f32 v[2:3], v[2:3], v[134:135]
	global_store_dwordx4 v[12:13], v[8:11], off
	v_pk_mul_f32 v[6:7], v[6:7], s[88:89] op_sel_hi:[1,0]
	v_pk_mul_f32 v[4:5], v[4:5], s[88:89] op_sel_hi:[1,0]
	v_pk_mul_f32 v[8:9], v[2:3], s[88:89] op_sel_hi:[1,0]
	v_pk_mul_f32 v[2:3], v[0:1], s[88:89] op_sel_hi:[1,0]
	v_cvt_pk_bf16_f32 v0, v4, v5
	v_cvt_pk_bf16_f32 v1, v6, v7
	v_cvt_pk_bf16_f32 v2, v2, v3
	v_cvt_pk_bf16_f32 v3, v8, v9
	global_store_dwordx4 v[16:17], v[0:3], off offset:256
	s_waitcnt vmcnt(0)
	s_barrier
	s_mov_b64 s[0:1], 0
.LBB0_573:
	s_and_b64 vcc, exec, s[0:1]
	s_cbranch_vccz .LBB0_602
	s_mov_b64 s[58:59], s[94:95]
	s_mov_b64 s[46:47], s[94:95]
	s_mov_b64 s[42:43], s[94:95]
	s_mov_b64 s[34:35], s[94:95]
	s_mov_b64 s[0:1], s[94:95]
	s_add_u32 s0, s0, s76
	s_addc_u32 s1, s1, 0
	s_add_u32 s0, s0, 0x20000
	s_addc_u32 s1, s1, 0
	s_lshl_b32 s22, s77, 5
	s_and_b32 s22, s22, 0xf800
	s_add_i32 s40, s22, 0xffffb000
	s_lshl_b32 s22, s77, 7
	s_and_b32 s73, s22, 0x780
	s_or_b32 s36, s40, s73
	s_mov_b32 s37, s53
	s_bfe_u32 s3, s77, 0x20004
	s_lshl_b64 s[60:61], s[36:37], 10
	s_add_u32 s22, s58, s60
	v_mov_b32_e32 v18, v226
	s_addc_u32 s37, s59, s61
	s_lshl_b32 s41, s3, 8
	s_add_u32 s58, s22, s41
	v_lshlrev_b32_e32 v0, 4, v18
	v_add_u32_e32 v30, 0x200, v18
	v_add_u32_e32 v10, 0x400, v18
	v_add_u32_e32 v12, 0x600, v18
	s_addc_u32 s59, s37, 0
	v_and_b32_e32 v20, 0xf0, v0
	v_mov_b32_e32 v21, v177
	v_ashrrev_i32_e32 v22, 4, v18
	v_ashrrev_i32_e32 v24, 4, v30
	v_ashrrev_i32_e32 v26, 4, v10
	v_ashrrev_i32_e32 v28, 4, v12
	s_mul_i32 s22, s3, 0x208
	v_lshl_add_u64 v[0:1], s[58:59], 0, v[20:21]
	s_mov_b64 s[14:15], 0x8b00000
	v_ashrrev_i32_e32 v23, 31, v22
	v_ashrrev_i32_e32 v25, 31, v24
	v_ashrrev_i32_e32 v27, 31, v26
	v_ashrrev_i32_e32 v29, 31, v28
	v_add_u32_e32 v32, s22, v18
	v_lshl_add_u64 v[8:9], v[0:1], 0, s[14:15]
	v_lshlrev_b64 v[16:17], 10, v[22:23]
	v_lshlrev_b64 v[2:3], 10, v[24:25]
	v_lshlrev_b64 v[10:11], 10, v[26:27]
	v_lshlrev_b64 v[12:13], 10, v[28:29]
	v_ashrrev_i32_e32 v33, 31, v32
	v_lshl_add_u64 v[0:1], v[8:9], 0, v[16:17]
	v_lshl_add_u64 v[2:3], v[8:9], 0, v[2:3]
	v_lshl_add_u64 v[10:11], v[8:9], 0, v[10:11]
	v_lshl_add_u64 v[8:9], v[8:9], 0, v[12:13]
	v_lshl_add_u64 v[32:33], v[32:33], 2, s[0:1]
	global_load_dwordx4 v[4:7], v[0:1], off
	s_nop 0
	global_load_dwordx4 v[0:3], v[2:3], off
	s_nop 0
	global_load_dwordx4 v[12:15], v[10:11], off
	s_nop 0
	global_load_dwordx4 v[8:11], v[8:9], off
	v_readfirstlane_b32 s58, v18
	global_load_dword v21, v[32:33], off
	v_cmp_gt_i32_e32 vcc, 8, v18
	v_mov_b32_e32 v19, 0
	v_mov_b32_e32 v25, 0
	s_and_saveexec_b64 s[68:69], vcc
	s_cbranch_execz .LBB0_576
	v_add_u32_e32 v30, s22, v30
	v_ashrrev_i32_e32 v31, 31, v30
	v_lshl_add_u64 v[30:31], v[30:31], 2, s[0:1]
	global_load_dword v25, v[30:31], off

.LBB0_578:
	s_or_b64 exec, exec, s[68:69]
	s_mov_b32 s41, s53
	s_lshl_b64 s[68:69], s[40:41], 10
	s_add_u32 s37, s46, s68
	s_addc_u32 s48, s47, s69
	s_lshl_b32 s3, s22, 1
	s_add_u32 s37, s37, s3
	s_addc_u32 s48, s48, 0
	s_add_u32 s60, s37, 0xab00000
	s_addc_u32 s61, s48, 0
	v_and_b32_e32 v27, 15, v18
	v_lshlrev_b64 v[32:33], 10, v[22:23]
	s_lshl_b32 s52, s22, 16
	v_lshlrev_b32_e32 v176, 4, v27
	v_lshl_add_u64 v[32:33], s[60:61], 0, v[32:33]
	s_add_u32 s37, s42, s52
	v_lshl_add_u64 v[36:37], v[32:33], 0, v[176:177]
	s_mov_b32 s7, 0x8000
	s_addc_u32 s48, s43, 0
	s_lshl_b64 s[70:71], s[40:41], 1
	v_ashrrev_i32_e32 v34, 3, v18
	v_lshl_add_u64 v[30:31], s[60:61], 0, v[16:17]
	v_add_co_u32_e64 v32, s[40:41], s7, v36
	s_add_u32 s62, s37, s70
	v_lshl_add_u64 v[30:31], v[30:31], 0, v[176:177]
	v_addc_co_u32_e64 v33, s[40:41], 0, v37, s[40:41]
	v_ashrrev_i32_e32 v35, 31, v34
	s_addc_u32 s63, s48, s71
	v_and_b32_e32 v29, 7, v18
	s_waitcnt vmcnt(0)
	global_load_dwordx4 v[96:99], v[30:31], off
	global_load_dwordx4 v[100:103], v[32:33], off
	v_lshlrev_b64 v[32:33], 16, v[34:35]
	v_lshl_add_u64 v[38:39], s[62:63], 0, v[32:33]
	v_lshlrev_b32_e32 v30, 4, v29
	v_mov_b32_e32 v31, v177
	v_lshl_add_u64 v[38:39], v[38:39], 0, v[30:31]
	s_mov_b32 s7, 0xcb00000
	s_mov_b64 s[14:15], 0xcb00000
	v_add_co_u32_e64 v42, s[40:41], s7, v38
	v_lshl_add_u64 v[40:41], v[38:39], 0, s[14:15]
	s_nop 0
	v_addc_co_u32_e64 v43, s[40:41], 0, v39, s[40:41]
	s_mov_b64 s[14:15], 0xcf00000
	s_mov_b32 s7, 0xcf00000
	v_lshl_add_u64 v[44:45], v[38:39], 0, s[14:15]
	v_add_co_u32_e64 v38, s[40:41], s7, v38
	v_readlane_b32 s7, v255, 23
	s_nop 0
	v_addc_co_u32_e64 v39, s[40:41], 0, v39, s[40:41]
	v_add_co_u32_e64 v46, s[40:41], s9, v36
	s_nop 1
	v_addc_co_u32_e64 v47, s[40:41], 0, v37, s[40:41]
	v_add_co_u32_e64 v36, s[40:41], s10, v36
	s_nop 1
	v_addc_co_u32_e64 v37, s[40:41], 0, v37, s[40:41]
	global_load_dwordx4 v[104:107], v[46:47], off
	global_load_dwordx4 v[108:111], v[36:37], off
	global_load_dwordx4 v[120:123], v[42:43], off
	global_load_dwordx4 v[112:115], v[40:41], off offset:128
	global_load_dwordx4 v[124:127], v[38:39], off
	global_load_dwordx4 v[116:119], v[44:45], off offset:128
	v_add_u32_e32 v36, s7, v20
	v_mul_lo_u32 v20, v22, s12
	v_add_u32_e32 v22, v36, v20
	s_waitcnt vmcnt(0) lgkmcnt(0)
	ds_write_b128 v22, v[4:7]
	v_mad_u64_u32 v[4:5], s[40:41], v24, s12, v[36:37]
	ds_write_b128 v4, v[0:3]
	v_mad_u64_u32 v[0:1], s[40:41], v26, s12, v[36:37]
	ds_write_b128 v0, v[12:15]
	v_mad_u64_u32 v[0:1], s[40:41], v28, s12, v[36:37]
	ds_write_b128 v0, v[8:11]
	v_lshl_add_u32 v0, v18, 2, 0
	v_add_u32_e32 v1, 0x11800, v0
	ds_write_b32 v1, v21
	s_and_saveexec_b64 s[40:41], vcc
	ds_write_b32 v1, v25 offset:2048
	s_or_b64 exec, exec, s[40:41]
	s_and_saveexec_b64 s[40:41], s[0:1]
	v_add_u32_e32 v0, 0x1a900, v0
	ds_write_b32 v0, v19
	s_or_b64 exec, exec, s[40:41]
	s_ashr_i32 s60, s58, 8
	s_lshl_b32 s0, s60, 7
	s_bfe_u32 s61, s58, 0x20006
	s_add_i32 s1, s0, 0
	v_and_b32_e32 v2, 31, v18
	s_lshl_b32 s37, s61, 5
	s_add_i32 s1, s1, 0x12100
	v_or_b32_e32 v1, s37, v2
	v_mov_b32_e32 v3, s1
	v_lshlrev_b32_e32 v0, 3, v18
	v_mad_u32_u24 v3, v1, s12, v3
	v_add_u32_e32 v1, 0, v20
	s_movk_i32 s1, 0x90
	v_and_b32_e32 v0, 8, v0
	v_add_u32_e32 v239, v1, v176
	v_mul_lo_u32 v1, v34, s1
	v_and_or_b32 v0, v30, s8, v0
	v_add_u32_e32 v1, 0, v1
	v_add_u32_e32 v240, v1, v0
	s_mul_i32 s1, s60, 0x410
	v_mad_u32_u24 v0, v2, s12, 0
	s_add_i32 s62, s1, 0
	s_or_b32 s72, s37, s73
	v_add_u32_e32 v4, s0, v0
	s_lshl_b32 s0, s77, 4
	s_lshr_b32 s59, s58, 6
	s_add_i32 s62, s62, 0x11800
	s_add_i32 s63, s72, 0x9f
	s_addk_i32 s72, 0x5f
	s_and_b32 s0, s0, 0x300
	v_bfe_u32 v236, v18, 5, 1
	v_lshlrev_b32_e32 v1, 7, v2
	s_add_u32 s0, s0, s68
	v_lshlrev_b32_e32 v237, 4, v236
	v_sub_u32_e32 v0, v0, v1
	s_addc_u32 s1, 0, s69
	v_add_u32_e32 v243, v0, v237
	v_lshl_add_u64 v[0:1], s[0:1], 0, v[16:17]
	v_lshl_add_u64 v[0:1], v[0:1], 0, v[176:177]
	v_lshl_add_u64 v[0:1], s[46:47], 0, v[0:1]
	s_mov_b64 s[0:1], 0xab38000
	v_lshl_add_u64 v[190:191], v[0:1], 0, s[0:1]
	v_lshl_add_u64 v[0:1], s[52:53], 0, v[32:33]
	v_mov_b32_e32 v31, v177
	s_add_u32 s0, s42, s70
	v_lshl_add_u64 v[0:1], v[0:1], 0, v[30:31]
	s_addc_u32 s1, s43, s71
	v_lshlrev_b32_e32 v235, 2, v236
	v_lshl_add_u64 v[0:1], s[0:1], 0, v[0:1]
	s_mov_b64 s[0:1], 0xcf00180
	v_lshl_add_u64 v[192:193], v[0:1], 0, s[0:1]
	v_sub_u32_e32 v0, v235, v2
	v_subrev_u32_e32 v0, s37, v0
	s_add_i32 s0, s37, s73
	v_mov_b32_e32 v248, 0
	v_lshlrev_b32_e32 v233, 3, v27
	v_and_b32_e32 v234, 63, v18
	v_add_u32_e32 v241, 0x8800, v240
	v_add_u32_e32 v242, 0xa800, v240
	v_mul_u32_u24_e32 v238, 0x110, v2
	v_add_u32_e32 v244, 0xd000, v243
	v_subrev_u32_e32 v245, s73, v0
	s_mov_b32 s22, 0
	s_sub_i32 s46, 0, s0
	v_add_u32_e32 v246, v4, v237
	v_add_u32_e32 v247, v3, v237
	s_mov_b32 s47, 0
	v_mov_b32_e32 v0, 0
	v_mov_b32_e32 v1, v248
	v_mov_b32_e32 v2, v248
	v_mov_b32_e32 v3, v248
	v_mov_b32_e32 v4, v248
	v_mov_b32_e32 v5, v248
	v_mov_b32_e32 v6, v248
	v_mov_b32_e32 v7, v248
	v_mov_b32_e32 v8, v248
	v_mov_b32_e32 v9, v248
	v_mov_b32_e32 v10, v248
	v_mov_b32_e32 v11, v248
	v_mov_b32_e32 v12, v248
	v_mov_b32_e32 v13, v248
	v_mov_b32_e32 v14, v248
	v_mov_b32_e32 v15, v248
	v_mov_b32_e32 v16, 0
	v_mov_b32_e32 v17, v248
	v_mov_b32_e32 v18, v248
	v_mov_b32_e32 v19, v248
	v_mov_b32_e32 v20, v248
	v_mov_b32_e32 v21, v248
	v_mov_b32_e32 v22, v248
	v_mov_b32_e32 v23, v248
	v_mov_b32_e32 v24, v248
	v_mov_b32_e32 v25, v248
	v_mov_b32_e32 v26, v248
	v_mov_b32_e32 v27, v248
	v_mov_b32_e32 v28, v248
	v_mov_b32_e32 v29, v248
	v_mov_b32_e32 v30, v248
	v_mov_b32_e32 v31, v248
	v_mov_b32_e32 v32, 0
	v_mov_b32_e32 v33, v248
	v_mov_b32_e32 v34, v248
	v_mov_b32_e32 v35, v248
	v_mov_b32_e32 v36, v248
	v_mov_b32_e32 v37, v248
	v_mov_b32_e32 v38, v248
	v_mov_b32_e32 v39, v248
	v_mov_b32_e32 v40, v248
	v_mov_b32_e32 v41, v248
	v_mov_b32_e32 v42, v248
	v_mov_b32_e32 v43, v248
	v_mov_b32_e32 v44, v248
	v_mov_b32_e32 v45, v248
	v_mov_b32_e32 v46, v248
	v_mov_b32_e32 v47, v248
	v_mov_b32_e32 v48, 0
	v_mov_b32_e32 v49, v248
	v_mov_b32_e32 v50, v248
	v_mov_b32_e32 v51, v248
	v_mov_b32_e32 v52, v248
	v_mov_b32_e32 v53, v248
	v_mov_b32_e32 v54, v248
	v_mov_b32_e32 v55, v248
	v_mov_b32_e32 v56, v248
	v_mov_b32_e32 v57, v248
	v_mov_b32_e32 v58, v248
	v_mov_b32_e32 v59, v248
	v_mov_b32_e32 v60, v248
	v_mov_b32_e32 v61, v248
	v_mov_b32_e32 v62, v248
	v_mov_b32_e32 v63, v248
	ds_write_b128 v239, v[96:99]
	ds_write_b128 v239, v[100:103] offset:8704
	ds_write2_b64 v241, v[120:121], v[122:123] offset1:2
	ds_write2_b64 v242, v[124:125], v[126:127] offset0:128 offset1:130
	s_waitcnt lgkmcnt(0)
	s_barrier
	s_branch .LBB0_584

.LBB0_600:
	s_cmpk_gt_u32 s58, 0xff
	s_waitcnt lgkmcnt(0)
	s_barrier
	s_cbranch_scc1 .LBB0_602
	v_div_scale_f32 v66, s[0:1], v65, v65, 1.0
	v_rcp_f32_e32 v68, v66
	v_div_scale_f32 v69, vcc, 1.0, v65, 1.0
	s_add_i32 s1, 0, 0x1a900
	v_fma_f32 v70, -v66, v68, 1.0
	v_fmac_f32_e32 v68, v70, v68
	v_mul_f32_e32 v70, v69, v68
	v_fma_f32 v71, -v66, v70, v69
	v_fmac_f32_e32 v70, v71, v68
	v_fma_f32 v66, -v66, v70, v69
	v_div_fmas_f32 v66, v66, v68, v70
	ds_read2st64_b32 v[74:75], v64 offset1:1
	ds_read2st64_b32 v[76:77], v64 offset0:2 offset1:3
	ds_read2st64_b32 v[78:79], v64 offset0:4 offset1:5
	ds_read2st64_b32 v[80:81], v64 offset0:6 offset1:7
	ds_read2st64_b32 v[82:83], v64 offset0:8 offset1:9
	ds_read2st64_b32 v[84:85], v64 offset0:10 offset1:11
	ds_read2st64_b32 v[86:87], v64 offset0:12 offset1:13
	ds_read2st64_b32 v[88:89], v64 offset0:14 offset1:15
	ds_read2st64_b32 v[90:91], v64 offset0:16 offset1:17
	ds_read2st64_b32 v[92:93], v64 offset0:18 offset1:19
	ds_read2st64_b32 v[94:95], v64 offset0:20 offset1:21
	s_waitcnt vmcnt(0)
	ds_read2st64_b32 v[96:97], v64 offset0:22 offset1:23
	ds_read2st64_b32 v[98:99], v64 offset0:24 offset1:25
	ds_read2st64_b32 v[100:101], v64 offset0:26 offset1:27
	ds_read2st64_b32 v[102:103], v64 offset0:28 offset1:29
	ds_read2st64_b32 v[104:105], v64 offset0:30 offset1:31
	ds_read2st64_b32 v[106:107], v64 offset0:32 offset1:33
	ds_read2st64_b32 v[108:109], v64 offset0:34 offset1:35
	ds_read2st64_b32 v[110:111], v64 offset0:36 offset1:37
	ds_read2st64_b32 v[112:113], v64 offset0:38 offset1:39
	ds_read2st64_b32 v[114:115], v64 offset0:40 offset1:41
	ds_read2st64_b32 v[116:117], v64 offset0:42 offset1:43
	ds_read2st64_b32 v[118:119], v64 offset0:44 offset1:45
	ds_read2st64_b32 v[120:121], v64 offset0:46 offset1:47
	ds_read2st64_b32 v[68:69], v64 offset0:58 offset1:59
	ds_read2st64_b32 v[122:123], v64 offset0:48 offset1:49
	ds_read2st64_b32 v[124:125], v64 offset0:50 offset1:51
	ds_read2st64_b32 v[126:127], v64 offset0:52 offset1:53
	ds_read2st64_b32 v[128:129], v64 offset0:54 offset1:55
	ds_read2st64_b32 v[70:71], v64 offset0:60 offset1:61
	ds_read2st64_b32 v[72:73], v64 offset0:62 offset1:63
	ds_read2st64_b32 v[130:131], v64 offset0:56 offset1:57
	v_div_fixup_f32 v66, v66, v65, 1.0
	s_waitcnt lgkmcnt(14)
	v_pk_fma_f32 v[74:75], v[48:49], v[66:67], v[74:75] op_sel_hi:[1,0,1] neg_lo:[0,0,1] neg_hi:[0,0,1]
	v_pk_fma_f32 v[50:51], v[50:51], v[66:67], v[76:77] op_sel_hi:[1,0,1] neg_lo:[0,0,1] neg_hi:[0,0,1]
	v_pk_mul_f32 v[134:135], v[74:75], v[74:75]
	s_waitcnt lgkmcnt(7)
	v_pk_fma_f32 v[64:65], v[10:11], v[66:67], v[68:69] op_sel_hi:[1,0,1] neg_lo:[0,0,1] neg_hi:[0,0,1]
	s_waitcnt lgkmcnt(2)
	v_pk_fma_f32 v[10:11], v[12:13], v[66:67], v[70:71] op_sel_hi:[1,0,1] neg_lo:[0,0,1] neg_hi:[0,0,1]
	s_waitcnt lgkmcnt(1)
	v_pk_fma_f32 v[12:13], v[14:15], v[66:67], v[72:73] op_sel_hi:[1,0,1] neg_lo:[0,0,1] neg_hi:[0,0,1]
	v_pk_mul_f32 v[132:133], v[50:51], v[50:51]
	v_pk_fma_f32 v[48:49], v[54:55], v[66:67], v[80:81] op_sel_hi:[1,0,1] neg_lo:[0,0,1] neg_hi:[0,0,1]
	v_pk_fma_f32 v[76:77], v[52:53], v[66:67], v[78:79] op_sel_hi:[1,0,1] neg_lo:[0,0,1] neg_hi:[0,0,1]
	v_pk_fma_f32 v[52:53], v[58:59], v[66:67], v[84:85] op_sel_hi:[1,0,1] neg_lo:[0,0,1] neg_hi:[0,0,1]
	v_pk_fma_f32 v[78:79], v[56:57], v[66:67], v[82:83] op_sel_hi:[1,0,1] neg_lo:[0,0,1] neg_hi:[0,0,1]
	v_pk_fma_f32 v[54:55], v[62:63], v[66:67], v[88:89] op_sel_hi:[1,0,1] neg_lo:[0,0,1] neg_hi:[0,0,1]
	v_pk_fma_f32 v[62:63], v[60:61], v[66:67], v[86:87] op_sel_hi:[1,0,1] neg_lo:[0,0,1] neg_hi:[0,0,1]
	v_pk_fma_f32 v[56:57], v[34:35], v[66:67], v[92:93] op_sel_hi:[1,0,1] neg_lo:[0,0,1] neg_hi:[0,0,1]
	v_pk_fma_f32 v[58:59], v[32:33], v[66:67], v[90:91] op_sel_hi:[1,0,1] neg_lo:[0,0,1] neg_hi:[0,0,1]
	v_pk_fma_f32 v[32:33], v[38:39], v[66:67], v[96:97] op_sel_hi:[1,0,1] neg_lo:[0,0,1] neg_hi:[0,0,1]
	v_pk_fma_f32 v[60:61], v[36:37], v[66:67], v[94:95] op_sel_hi:[1,0,1] neg_lo:[0,0,1] neg_hi:[0,0,1]
	v_pk_fma_f32 v[34:35], v[42:43], v[66:67], v[100:101] op_sel_hi:[1,0,1] neg_lo:[0,0,1] neg_hi:[0,0,1]
	v_pk_fma_f32 v[42:43], v[40:41], v[66:67], v[98:99] op_sel_hi:[1,0,1] neg_lo:[0,0,1] neg_hi:[0,0,1]
	v_pk_fma_f32 v[36:37], v[46:47], v[66:67], v[104:105] op_sel_hi:[1,0,1] neg_lo:[0,0,1] neg_hi:[0,0,1]
	v_pk_fma_f32 v[44:45], v[44:45], v[66:67], v[102:103] op_sel_hi:[1,0,1] neg_lo:[0,0,1] neg_hi:[0,0,1]
	v_pk_fma_f32 v[38:39], v[18:19], v[66:67], v[108:109] op_sel_hi:[1,0,1] neg_lo:[0,0,1] neg_hi:[0,0,1]
	v_pk_fma_f32 v[40:41], v[16:17], v[66:67], v[106:107] op_sel_hi:[1,0,1] neg_lo:[0,0,1] neg_hi:[0,0,1]
	v_pk_fma_f32 v[14:15], v[22:23], v[66:67], v[112:113] op_sel_hi:[1,0,1] neg_lo:[0,0,1] neg_hi:[0,0,1]
	v_pk_fma_f32 v[22:23], v[20:21], v[66:67], v[110:111] op_sel_hi:[1,0,1] neg_lo:[0,0,1] neg_hi:[0,0,1]
	v_pk_fma_f32 v[16:17], v[26:27], v[66:67], v[116:117] op_sel_hi:[1,0,1] neg_lo:[0,0,1] neg_hi:[0,0,1]
	v_pk_fma_f32 v[24:25], v[24:25], v[66:67], v[114:115] op_sel_hi:[1,0,1] neg_lo:[0,0,1] neg_hi:[0,0,1]
	v_pk_fma_f32 v[18:19], v[30:31], v[66:67], v[120:121] op_sel_hi:[1,0,1] neg_lo:[0,0,1] neg_hi:[0,0,1]
	v_pk_fma_f32 v[26:27], v[28:29], v[66:67], v[118:119] op_sel_hi:[1,0,1] neg_lo:[0,0,1] neg_hi:[0,0,1]
	v_pk_fma_f32 v[2:3], v[2:3], v[66:67], v[124:125] op_sel_hi:[1,0,1] neg_lo:[0,0,1] neg_hi:[0,0,1]
	v_pk_fma_f32 v[20:21], v[0:1], v[66:67], v[122:123] op_sel_hi:[1,0,1] neg_lo:[0,0,1] neg_hi:[0,0,1]
	v_pk_fma_f32 v[0:1], v[6:7], v[66:67], v[128:129] op_sel_hi:[1,0,1] neg_lo:[0,0,1] neg_hi:[0,0,1]
	v_pk_fma_f32 v[6:7], v[4:5], v[66:67], v[126:127] op_sel_hi:[1,0,1] neg_lo:[0,0,1] neg_hi:[0,0,1]
	s_waitcnt lgkmcnt(0)
	v_pk_fma_f32 v[4:5], v[8:9], v[66:67], v[130:131] op_sel_hi:[1,0,1] neg_lo:[0,0,1] neg_hi:[0,0,1]
	v_add_f32_e32 v66, v134, v135
	v_add_f32_e32 v66, v66, v132
	v_pk_mul_f32 v[136:137], v[76:77], v[76:77]
	v_add_f32_e32 v66, v66, v133
	v_add_f32_e32 v66, v66, v136
	v_pk_mul_f32 v[80:81], v[48:49], v[48:49]
	v_add_f32_e32 v66, v66, v137
	v_add_f32_e32 v66, v66, v80
	v_pk_mul_f32 v[82:83], v[78:79], v[78:79]
	v_add_f32_e32 v66, v66, v81
	v_add_f32_e32 v66, v66, v82
	v_pk_mul_f32 v[84:85], v[52:53], v[52:53]
	v_add_f32_e32 v66, v66, v83
	v_add_f32_e32 v66, v66, v84
	v_pk_mul_f32 v[86:87], v[62:63], v[62:63]
	v_add_f32_e32 v66, v66, v85
	v_add_f32_e32 v66, v66, v86
	v_pk_mul_f32 v[88:89], v[54:55], v[54:55]
	v_add_f32_e32 v66, v66, v87
	v_add_f32_e32 v66, v66, v88
	v_pk_mul_f32 v[90:91], v[58:59], v[58:59]
	v_add_f32_e32 v66, v66, v89
	v_add_f32_e32 v66, v66, v90
	v_pk_mul_f32 v[92:93], v[56:57], v[56:57]
	v_add_f32_e32 v66, v66, v91
	v_add_f32_e32 v66, v66, v92
	v_pk_mul_f32 v[94:95], v[60:61], v[60:61]
	v_add_f32_e32 v66, v66, v93
	v_add_f32_e32 v66, v66, v94
	v_pk_mul_f32 v[96:97], v[32:33], v[32:33]
	v_add_f32_e32 v66, v66, v95
	v_add_f32_e32 v66, v66, v96
	v_pk_mul_f32 v[98:99], v[42:43], v[42:43]
	v_add_f32_e32 v66, v66, v97
	v_add_f32_e32 v66, v66, v98
	v_pk_mul_f32 v[100:101], v[34:35], v[34:35]
	v_add_f32_e32 v66, v66, v99
	v_add_f32_e32 v66, v66, v100
	v_pk_mul_f32 v[102:103], v[44:45], v[44:45]
	v_add_f32_e32 v66, v66, v101
	v_add_f32_e32 v66, v66, v102
	v_pk_mul_f32 v[46:47], v[36:37], v[36:37]
	v_add_f32_e32 v66, v66, v103
	v_add_f32_e32 v46, v66, v46
	v_pk_mul_f32 v[106:107], v[40:41], v[40:41]
	v_add_f32_e32 v46, v46, v47
	v_add_f32_e32 v46, v46, v106
	v_pk_mul_f32 v[104:105], v[38:39], v[38:39]
	v_add_f32_e32 v46, v46, v107
	v_add_f32_e32 v46, v46, v104
	v_pk_mul_f32 v[110:111], v[22:23], v[22:23]
	v_add_f32_e32 v46, v46, v105
	v_add_f32_e32 v46, v46, v110
	v_pk_mul_f32 v[108:109], v[14:15], v[14:15]
	v_add_f32_e32 v46, v46, v111
	v_add_f32_e32 v46, v46, v108
	v_pk_mul_f32 v[114:115], v[24:25], v[24:25]
	v_add_f32_e32 v46, v46, v109
	v_add_f32_e32 v46, v46, v114
	v_pk_mul_f32 v[112:113], v[16:17], v[16:17]
	v_add_f32_e32 v46, v46, v115
	v_add_f32_e32 v46, v46, v112
	v_pk_mul_f32 v[28:29], v[26:27], v[26:27]
	v_add_f32_e32 v46, v46, v113
	v_add_f32_e32 v28, v46, v28
	v_pk_mul_f32 v[30:31], v[18:19], v[18:19]
	v_add_f32_e32 v28, v28, v29
	v_add_f32_e32 v28, v28, v30
	v_pk_mul_f32 v[118:119], v[20:21], v[20:21]
	v_add_f32_e32 v28, v28, v31
	v_add_f32_e32 v28, v28, v118
	v_pk_mul_f32 v[116:117], v[2:3], v[2:3]
	v_add_f32_e32 v28, v28, v119
	v_add_f32_e32 v28, v28, v116
	v_pk_mul_f32 v[122:123], v[6:7], v[6:7]
	v_add_f32_e32 v28, v28, v117
	v_add_f32_e32 v28, v28, v122
	v_pk_mul_f32 v[120:121], v[0:1], v[0:1]
	v_add_f32_e32 v28, v28, v123
	v_add_f32_e32 v28, v28, v120
	v_pk_mul_f32 v[8:9], v[4:5], v[4:5]
	v_add_f32_e32 v28, v28, v121
	v_add_f32_e32 v8, v28, v8
	v_pk_mul_f32 v[68:69], v[64:65], v[64:65]
	v_add_f32_e32 v8, v8, v9
	v_add_f32_e32 v8, v8, v68
	v_pk_mul_f32 v[70:71], v[10:11], v[10:11]
	v_add_f32_e32 v8, v8, v69
	v_add_f32_e32 v8, v8, v70
	v_pk_mul_f32 v[72:73], v[12:13], v[12:13]
	v_add_f32_e32 v8, v8, v71
	v_add_f32_e32 v8, v8, v72
	v_add_f32_e32 v8, v8, v73
	ds_bpermute_b32 v9, v67, v8
	s_waitcnt lgkmcnt(0)
	v_add_u32_e32 v28, s1, v237
	s_lshl_b32 s0, s59, 14
	ds_read_b128 v[28:31], v28
	s_waitcnt lgkmcnt(1)
	v_add_f32_e32 v8, v8, v9
	v_fmamk_f32 v8, v8, 0x3c000000, v228
	v_rsq_f32_e32 v8, v8
	s_add_i32 s0, s0, 0
	v_add_u32_e32 v66, s0, v238
	v_lshl_add_u32 v9, v236, 3, v66
	v_mul_f32_e32 v8, s75, v8
	v_pk_mul_f32 v[46:47], v[74:75], v[8:9] op_sel_hi:[1,0]
	v_or_b32_e32 v67, 8, v235
	s_waitcnt lgkmcnt(0)
	v_pk_mul_f32 v[28:29], v[28:29], v[46:47]
	v_pk_mul_f32 v[46:47], v[50:51], v[8:9] op_sel_hi:[1,0]
	v_cvt_pk_bf16_f32 v28, v28, v29
	v_pk_mul_f32 v[30:31], v[30:31], v[46:47]
	v_lshl_add_u32 v68, v67, 2, s1
	v_cvt_pk_bf16_f32 v29, v30, v31
	ds_write_b64 v9, v[28:29]
	ds_read_b128 v[28:31], v68
	v_lshl_add_u32 v9, v67, 1, v66
	v_pk_mul_f32 v[46:47], v[76:77], v[8:9] op_sel_hi:[1,0]
	v_or_b32_e32 v50, 16, v235
	v_lshl_add_u32 v51, v50, 2, s1
	s_waitcnt lgkmcnt(0)
	v_pk_mul_f32 v[28:29], v[28:29], v[46:47]
	v_pk_mul_f32 v[46:47], v[48:49], v[8:9] op_sel_hi:[1,0]
	v_cvt_pk_bf16_f32 v28, v28, v29
	v_pk_mul_f32 v[30:31], v[30:31], v[46:47]
	v_or_b32_e32 v48, 24, v235
	v_cvt_pk_bf16_f32 v29, v30, v31
	ds_write_b64 v9, v[28:29]
	ds_read_b128 v[28:31], v51
	v_lshl_add_u32 v9, v50, 1, v66
	v_pk_mul_f32 v[46:47], v[78:79], v[8:9] op_sel_hi:[1,0]
	v_lshl_add_u32 v49, v48, 2, s1
	s_or_b32 s52, s37, s36
	s_waitcnt lgkmcnt(0)
	v_pk_mul_f32 v[28:29], v[28:29], v[46:47]
	v_pk_mul_f32 v[46:47], v[52:53], v[8:9] op_sel_hi:[1,0]
	v_cvt_pk_bf16_f32 v28, v28, v29
	v_pk_mul_f32 v[30:31], v[30:31], v[46:47]
	s_lshl_b64 s[36:37], s[52:53], 11
	v_cvt_pk_bf16_f32 v29, v30, v31
	ds_write_b64 v9, v[28:29]
	ds_read_b128 v[28:31], v49
	v_lshl_add_u32 v9, v48, 1, v66
	v_pk_mul_f32 v[46:47], v[62:63], v[8:9] op_sel_hi:[1,0]
	v_or_b32_e32 v48, 32, v235
	v_lshl_add_u32 v49, v48, 2, s1
	s_waitcnt lgkmcnt(0)
	v_pk_mul_f32 v[28:29], v[46:47], v[28:29]
	v_pk_mul_f32 v[46:47], v[54:55], v[8:9] op_sel_hi:[1,0]
	v_cvt_pk_bf16_f32 v28, v28, v29
	v_pk_mul_f32 v[30:31], v[46:47], v[30:31]
	s_nop 0
	v_cvt_pk_bf16_f32 v29, v30, v31
	ds_write_b64 v9, v[28:29]
	ds_read_b128 v[28:31], v49
	v_lshl_add_u32 v9, v48, 1, v66
	v_pk_mul_f32 v[46:47], v[58:59], v[8:9] op_sel_hi:[1,0]
	v_or_b32_e32 v48, 40, v235
	v_lshl_add_u32 v49, v48, 2, s1
	s_waitcnt lgkmcnt(0)
	v_pk_mul_f32 v[28:29], v[46:47], v[28:29]
	v_pk_mul_f32 v[46:47], v[56:57], v[8:9] op_sel_hi:[1,0]
	v_cvt_pk_bf16_f32 v28, v28, v29
	v_pk_mul_f32 v[30:31], v[46:47], v[30:31]
	s_nop 0
	v_cvt_pk_bf16_f32 v29, v30, v31
	ds_write_b64 v9, v[28:29]
	ds_read_b128 v[28:31], v49
	v_lshl_add_u32 v9, v48, 1, v66
	v_pk_mul_f32 v[46:47], v[60:61], v[8:9] op_sel_hi:[1,0]
	v_pk_mul_f32 v[32:33], v[32:33], v[8:9] op_sel_hi:[1,0]
	v_or_b32_e32 v48, 48, v235
	s_waitcnt lgkmcnt(0)
	v_pk_mul_f32 v[28:29], v[46:47], v[28:29]
	v_pk_mul_f32 v[30:31], v[32:33], v[30:31]
	v_cvt_pk_bf16_f32 v28, v28, v29
	v_cvt_pk_bf16_f32 v29, v30, v31
	v_lshl_add_u32 v49, v48, 2, s1
	ds_write_b64 v9, v[28:29]
	ds_read_b128 v[28:31], v49
	v_lshl_add_u32 v9, v48, 1, v66
	v_pk_mul_f32 v[32:33], v[42:43], v[8:9] op_sel_hi:[1,0]
	v_or_b32_e32 v46, 56, v235
	v_lshl_add_u32 v47, v46, 2, s1
	s_waitcnt lgkmcnt(0)
	v_pk_mul_f32 v[28:29], v[32:33], v[28:29]
	v_pk_mul_f32 v[32:33], v[34:35], v[8:9] op_sel_hi:[1,0]
	v_cvt_pk_bf16_f32 v28, v28, v29
	v_pk_mul_f32 v[30:31], v[32:33], v[30:31]
	v_or_b32_e32 v34, 64, v235
	v_cvt_pk_bf16_f32 v29, v30, v31
	ds_write_b64 v9, v[28:29]
	ds_read_b128 v[28:31], v47
	v_lshl_add_u32 v9, v46, 1, v66
	v_pk_mul_f32 v[32:33], v[44:45], v[8:9] op_sel_hi:[1,0]
	v_lshl_add_u32 v35, v34, 2, s1
	s_waitcnt lgkmcnt(0)
	v_pk_mul_f32 v[28:29], v[32:33], v[28:29]
	v_pk_mul_f32 v[32:33], v[36:37], v[8:9] op_sel_hi:[1,0]
	v_cvt_pk_bf16_f32 v28, v28, v29
	v_pk_mul_f32 v[30:31], v[32:33], v[30:31]
	s_nop 0
	v_cvt_pk_bf16_f32 v29, v30, v31
	ds_write_b64 v9, v[28:29]
	ds_read_b128 v[28:31], v35
	v_lshl_add_u32 v9, v34, 1, v66
	v_pk_mul_f32 v[32:33], v[40:41], v[8:9] op_sel_hi:[1,0]
	v_or_b32_e32 v34, 0x48, v235
	v_lshl_add_u32 v35, v34, 2, s1
	s_waitcnt lgkmcnt(0)
	v_pk_mul_f32 v[28:29], v[32:33], v[28:29]
	v_pk_mul_f32 v[32:33], v[38:39], v[8:9] op_sel_hi:[1,0]
	v_cvt_pk_bf16_f32 v28, v28, v29
	v_pk_mul_f32 v[30:31], v[32:33], v[30:31]
	v_or_b32_e32 v32, 0x50, v235
	v_cvt_pk_bf16_f32 v29, v30, v31
	ds_write_b64 v9, v[28:29]
	ds_read_b128 v[28:31], v35
	v_lshl_add_u32 v9, v34, 1, v66
	v_pk_mul_f32 v[22:23], v[22:23], v[8:9] op_sel_hi:[1,0]
	v_pk_mul_f32 v[14:15], v[14:15], v[8:9] op_sel_hi:[1,0]
	v_lshl_add_u32 v33, v32, 2, s1
	s_waitcnt lgkmcnt(0)
	v_pk_mul_f32 v[22:23], v[22:23], v[28:29]
	v_pk_mul_f32 v[14:15], v[14:15], v[30:31]
	v_cvt_pk_bf16_f32 v22, v22, v23
	v_cvt_pk_bf16_f32 v23, v14, v15
	ds_write_b64 v9, v[22:23]
	ds_read_b128 v[28:31], v33
	v_lshl_add_u32 v9, v32, 1, v66
	v_pk_mul_f32 v[14:15], v[24:25], v[8:9] op_sel_hi:[1,0]
	v_pk_mul_f32 v[16:17], v[16:17], v[8:9] op_sel_hi:[1,0]
	v_or_b32_e32 v22, 0x58, v235
	s_waitcnt lgkmcnt(0)
	v_pk_mul_f32 v[14:15], v[14:15], v[28:29]
	v_pk_mul_f32 v[16:17], v[16:17], v[30:31]
	v_cvt_pk_bf16_f32 v14, v14, v15
	v_cvt_pk_bf16_f32 v15, v16, v17
	v_lshl_add_u32 v23, v22, 2, s1
	ds_write_b64 v9, v[14:15]
	ds_read_b128 v[14:17], v23
	v_lshl_add_u32 v9, v22, 1, v66
	v_pk_mul_f32 v[22:23], v[26:27], v[8:9] op_sel_hi:[1,0]
	v_pk_mul_f32 v[18:19], v[18:19], v[8:9] op_sel_hi:[1,0]
	v_or_b32_e32 v24, 0x60, v235
	s_waitcnt lgkmcnt(0)
	v_pk_mul_f32 v[14:15], v[22:23], v[14:15]
	v_pk_mul_f32 v[16:17], v[18:19], v[16:17]
	v_cvt_pk_bf16_f32 v14, v14, v15
	v_cvt_pk_bf16_f32 v15, v16, v17
	v_lshl_add_u32 v25, v24, 2, s1
	ds_write_b64 v9, v[14:15]
	ds_read_b128 v[14:17], v25
	v_lshl_add_u32 v9, v24, 1, v66
	v_pk_mul_f32 v[18:19], v[20:21], v[8:9] op_sel_hi:[1,0]
	v_pk_mul_f32 v[2:3], v[2:3], v[8:9] op_sel_hi:[1,0]
	v_or_b32_e32 v22, 0x68, v235
	s_waitcnt lgkmcnt(0)
	v_pk_mul_f32 v[14:15], v[18:19], v[14:15]
	v_pk_mul_f32 v[2:3], v[2:3], v[16:17]
	v_cvt_pk_bf16_f32 v14, v14, v15
	v_cvt_pk_bf16_f32 v15, v2, v3
	v_lshl_add_u32 v23, v22, 2, s1
	ds_write_b64 v9, v[14:15]
	ds_read_b128 v[14:17], v23
	v_lshl_add_u32 v9, v22, 1, v66
	v_pk_mul_f32 v[2:3], v[6:7], v[8:9] op_sel_hi:[1,0]
	v_pk_mul_f32 v[0:1], v[0:1], v[8:9] op_sel_hi:[1,0]
	v_or_b32_e32 v18, 0x70, v235
	s_waitcnt lgkmcnt(0)
	v_pk_mul_f32 v[2:3], v[2:3], v[14:15]
	v_pk_mul_f32 v[0:1], v[0:1], v[16:17]
	v_cvt_pk_bf16_f32 v2, v2, v3
	v_cvt_pk_bf16_f32 v3, v0, v1
	v_lshl_add_u32 v19, v18, 2, s1
	ds_write_b64 v9, v[2:3]
	ds_read_b128 v[0:3], v19
	v_pk_mul_f32 v[4:5], v[4:5], v[8:9] op_sel_hi:[1,0]
	v_or_b32_e32 v6, 0x78, v235
	s_waitcnt lgkmcnt(0)
	v_pk_mul_f32 v[0:1], v[4:5], v[0:1]
	v_pk_mul_f32 v[4:5], v[64:65], v[8:9] op_sel_hi:[1,0]
	v_cvt_pk_bf16_f32 v0, v0, v1
	v_pk_mul_f32 v[2:3], v[4:5], v[2:3]
	v_pk_mul_f32 v[4:5], v[10:11], v[8:9] op_sel_hi:[1,0]
	v_cvt_pk_bf16_f32 v1, v2, v3
	v_lshl_add_u32 v2, v18, 1, v66
	ds_write_b64 v2, v[0:1]
	v_lshl_add_u32 v0, v6, 2, s1
	ds_read_b128 v[0:3], v0
	s_add_u32 s1, s34, s36
	s_addc_u32 s22, s35, s37
	s_add_u32 s34, s1, s3
	s_addc_u32 s35, s22, 0
	s_waitcnt lgkmcnt(0)
	v_pk_mul_f32 v[0:1], v[4:5], v[0:1]
	v_pk_mul_f32 v[4:5], v[12:13], v[8:9] op_sel_hi:[1,0]
	v_cvt_pk_bf16_f32 v0, v0, v1
	v_pk_mul_f32 v[2:3], v[4:5], v[2:3]
	v_lshlrev_b32_e32 v4, 1, v233
	v_cvt_pk_bf16_f32 v1, v2, v3
	v_lshl_add_u32 v2, v6, 1, v66
	v_lshrrev_b32_e32 v6, 4, v234
	ds_write_b64 v2, v[0:1]
	v_mul_u32_u24_e32 v0, 0x110, v6
	s_waitcnt lgkmcnt(0)
	v_add3_u32 v8, s0, v176, v0
	ds_read_b128 v[0:3], v8
	v_mov_b32_e32 v5, v177
	v_lshl_add_u64 v[4:5], s[34:35], 0, v[4:5]
	s_mov_b64 s[0:1], 0x4b00000
	v_lshl_add_u64 v[4:5], v[4:5], 0, s[0:1]
	v_lshlrev_b32_e32 v176, 11, v6
	v_lshl_add_u64 v[6:7], v[4:5], 0, v[176:177]
	s_waitcnt lgkmcnt(0)
	global_store_dwordx4 v[6:7], v[0:3], off
	ds_read_b128 v[0:3], v8 offset:1088
	v_or_b32_e32 v6, 0x2000, v176
	v_mov_b32_e32 v7, v177
	v_lshl_add_u64 v[6:7], v[4:5], 0, v[6:7]
	s_mov_b64 s[0:1], 0
	s_waitcnt lgkmcnt(0)
	global_store_dwordx4 v[6:7], v[0:3], off
	ds_read_b128 v[0:3], v8 offset:2176
	v_or_b32_e32 v6, 0x4000, v176
	v_mov_b32_e32 v7, v177
	v_lshl_add_u64 v[6:7], v[4:5], 0, v[6:7]
	s_waitcnt lgkmcnt(0)
	global_store_dwordx4 v[6:7], v[0:3], off
	ds_read_b128 v[0:3], v8 offset:3264
	v_or_b32_e32 v6, 0x6000, v176
	v_mov_b32_e32 v7, v177
	v_lshl_add_u64 v[6:7], v[4:5], 0, v[6:7]
	s_waitcnt lgkmcnt(0)
	global_store_dwordx4 v[6:7], v[0:3], off
	ds_read_b128 v[0:3], v8 offset:4352
	v_or_b32_e32 v6, 0x8000, v176
	v_mov_b32_e32 v7, v177
	v_lshl_add_u64 v[6:7], v[4:5], 0, v[6:7]
	s_waitcnt lgkmcnt(0)
	global_store_dwordx4 v[6:7], v[0:3], off
	ds_read_b128 v[0:3], v8 offset:5440
	v_or_b32_e32 v6, 0xa000, v176
	v_mov_b32_e32 v7, v177
	v_lshl_add_u64 v[6:7], v[4:5], 0, v[6:7]
	s_waitcnt lgkmcnt(0)
	global_store_dwordx4 v[6:7], v[0:3], off
	ds_read_b128 v[0:3], v8 offset:6528
	v_or_b32_e32 v6, 0xc000, v176
	v_mov_b32_e32 v7, v177
	v_lshl_add_u64 v[6:7], v[4:5], 0, v[6:7]
	v_or_b32_e32 v176, 0xe000, v176
	s_waitcnt lgkmcnt(0)
	global_store_dwordx4 v[6:7], v[0:3], off
	ds_read_b128 v[0:3], v8 offset:7616
	v_lshl_add_u64 v[4:5], v[4:5], 0, v[176:177]
	s_waitcnt lgkmcnt(0)
	global_store_dwordx4 v[4:5], v[0:3], off
	s_branch .LBB0_603

.LBB0_610:
	s_lshl_b32 s34, s52, 12
	s_or_b32 s34, s34, s58
	s_addk_i32 s34, 0x4000
	s_mov_b32 s35, s53
	s_lshl_b64 s[34:35], s[34:35], 11
	s_add_u32 s34, s36, s34
	s_addc_u32 s35, s37, s35
	s_lshl_b32 s36, s3, 1
	s_add_u32 s34, s34, s36
	s_addc_u32 s35, s35, 0
	s_add_u32 s34, s34, 0x4b00400
	s_addc_u32 s35, s35, 0
	s_lshl_b32 s52, s52, 9
	s_lshl_b64 s[36:37], s[52:53], 2
	s_add_u32 s0, s0, s36
	s_addc_u32 s1, s1, s37
	s_lshl_b32 s3, s3, 2
	v_or_b32_e32 v160, s71, v129
	s_add_u32 s0, s0, s3
	s_addc_u32 s1, s1, 0
	v_lshlrev_b32_e32 v176, 2, v160
	v_lshl_add_u64 v[130:131], s[0:1], 0, v[176:177]
	s_mov_b64 s[0:1], 0x34000
	v_lshl_add_u64 v[132:133], v[130:131], 0, s[0:1]
	s_mov_b32 s0, 0x34000
	v_add_co_u32_e32 v130, vcc, s0, v130
	v_ashrrev_i32_e32 v129, 31, v128
	s_nop 0
	v_addc_co_u32_e32 v131, vcc, 0, v131, vcc
	global_load_dwordx4 v[134:137], v[130:131], off
	global_load_dwordx4 v[142:145], v[132:133], off offset:16
	global_load_dwordx4 v[152:155], v[132:133], off offset:512
	global_load_dwordx4 v[156:159], v[132:133], off offset:528
	v_and_b32_e32 v130, 1, v140
	v_cmp_eq_u32_e32 vcc, 0, v130
	v_or_b32_e32 v146, 48, v128
	v_or_b32_e32 v148, 32, v128
	v_or_b32_e32 v150, 16, v128
	v_lshlrev_b64 v[128:129], 11, v[128:129]
	v_lshl_add_u64 v[128:129], s[34:35], 0, v[128:129]
	v_lshlrev_b32_e32 v176, 1, v160
	v_lshl_add_u64 v[128:129], v[128:129], 0, v[176:177]
	v_ashrrev_i32_e32 v151, 31, v150
	v_ashrrev_i32_e32 v149, 31, v148
	v_ashrrev_i32_e32 v147, 31, v146
	s_mov_b64 s[0:1], 0x40000
	v_readlane_b32 s11, v255, 22
	s_movk_i32 s12, 0x110
	s_waitcnt vmcnt(0) lgkmcnt(0)
	v_xor_b32_e32 v140, 0x80000000, v142
	v_xor_b32_e32 v141, 0x80000000, v143
	v_xor_b32_e32 v138, 0x80000000, v144
	v_xor_b32_e32 v139, 0x80000000, v145
	v_cndmask_b32_e32 v139, v139, v145, vcc
	v_cndmask_b32_e32 v138, v138, v144, vcc
	v_cndmask_b32_e32 v141, v141, v143, vcc
	v_cndmask_b32_e32 v140, v140, v142, vcc
	v_xor_b32_e32 v144, 0x80000000, v134
	v_xor_b32_e32 v145, 0x80000000, v135
	v_xor_b32_e32 v142, 0x80000000, v136
	v_xor_b32_e32 v143, 0x80000000, v137
	v_cndmask_b32_e32 v143, v143, v137, vcc
	v_cndmask_b32_e32 v142, v142, v136, vcc
	v_cndmask_b32_e32 v145, v145, v135, vcc
	v_cndmask_b32_e32 v144, v144, v134, vcc
	v_xor_b32_e32 v132, 0x80000000, v152
	v_xor_b32_e32 v133, 0x80000000, v153
	v_xor_b32_e32 v130, 0x80000000, v154
	v_xor_b32_e32 v131, 0x80000000, v155
	v_xor_b32_e32 v136, 0x80000000, v156
	v_xor_b32_e32 v137, 0x80000000, v157
	v_xor_b32_e32 v134, 0x80000000, v158
	v_xor_b32_e32 v135, 0x80000000, v159
	v_pk_add_f32 v[124:125], v[124:125], v[144:145]
	v_pk_add_f32 v[126:127], v[126:127], v[142:143]
	v_pk_add_f32 v[120:121], v[120:121], v[140:141]
	v_pk_add_f32 v[122:123], v[122:123], v[138:139]
	v_cndmask_b32_e32 v131, v131, v155, vcc
	v_cndmask_b32_e32 v130, v130, v154, vcc
	v_cndmask_b32_e32 v133, v133, v153, vcc
	v_cndmask_b32_e32 v132, v132, v152, vcc
	v_cndmask_b32_e32 v135, v135, v159, vcc
	v_cndmask_b32_e32 v134, v134, v158, vcc
	v_cndmask_b32_e32 v137, v137, v157, vcc
	v_cndmask_b32_e32 v136, v136, v156, vcc
	v_pk_mul_f32 v[126:127], v[126:127], s[56:57] op_sel_hi:[1,0]
	v_pk_mul_f32 v[124:125], v[124:125], s[56:57] op_sel_hi:[1,0]
	v_pk_mul_f32 v[152:153], v[122:123], s[56:57] op_sel_hi:[1,0]
	v_pk_mul_f32 v[122:123], v[120:121], s[56:57] op_sel_hi:[1,0]
	v_cvt_pk_bf16_f32 v120, v124, v125
	v_cvt_pk_bf16_f32 v121, v126, v127
	v_cvt_pk_bf16_f32 v122, v122, v123
	v_cvt_pk_bf16_f32 v123, v152, v153
	v_pk_add_f32 v[116:117], v[116:117], v[132:133]
	v_pk_add_f32 v[118:119], v[118:119], v[130:131]
	v_pk_add_f32 v[112:113], v[112:113], v[136:137]
	v_pk_add_f32 v[114:115], v[114:115], v[134:135]
	global_store_dwordx4 v[128:129], v[120:123], off
	v_pk_mul_f32 v[118:119], v[118:119], s[56:57] op_sel_hi:[1,0]
	v_pk_mul_f32 v[116:117], v[116:117], s[56:57] op_sel_hi:[1,0]
	v_pk_mul_f32 v[120:121], v[114:115], s[56:57] op_sel_hi:[1,0]
	v_pk_mul_f32 v[114:115], v[112:113], s[56:57] op_sel_hi:[1,0]
	v_cvt_pk_bf16_f32 v112, v116, v117
	v_cvt_pk_bf16_f32 v113, v118, v119
	v_cvt_pk_bf16_f32 v114, v114, v115
	v_cvt_pk_bf16_f32 v115, v120, v121
	global_store_dwordx4 v[128:129], v[112:115], off offset:256
	v_pk_add_f32 v[108:109], v[108:109], v[144:145]
	v_pk_add_f32 v[110:111], v[110:111], v[142:143]
	v_lshlrev_b64 v[112:113], 11, v[150:151]
	v_pk_add_f32 v[104:105], v[104:105], v[140:141]
	v_pk_add_f32 v[106:107], v[106:107], v[138:139]
	v_lshl_add_u64 v[112:113], s[34:35], 0, v[112:113]
	v_pk_mul_f32 v[110:111], v[110:111], s[56:57] op_sel_hi:[1,0]
	v_pk_mul_f32 v[108:109], v[108:109], s[56:57] op_sel_hi:[1,0]
	v_pk_mul_f32 v[114:115], v[106:107], s[56:57] op_sel_hi:[1,0]
	v_pk_mul_f32 v[106:107], v[104:105], s[56:57] op_sel_hi:[1,0]
	v_lshl_add_u64 v[112:113], v[112:113], 0, v[176:177]
	v_cvt_pk_bf16_f32 v104, v108, v109
	v_cvt_pk_bf16_f32 v105, v110, v111
	v_cvt_pk_bf16_f32 v106, v106, v107
	v_cvt_pk_bf16_f32 v107, v114, v115
	v_pk_add_f32 v[96:97], v[96:97], v[132:133]
	v_pk_add_f32 v[98:99], v[98:99], v[130:131]
	v_pk_add_f32 v[88:89], v[88:89], v[136:137]
	v_pk_add_f32 v[90:91], v[90:91], v[134:135]
	global_store_dwordx4 v[112:113], v[104:107], off
	v_pk_mul_f32 v[98:99], v[98:99], s[56:57] op_sel_hi:[1,0]
	v_pk_mul_f32 v[96:97], v[96:97], s[56:57] op_sel_hi:[1,0]
	v_pk_mul_f32 v[104:105], v[90:91], s[56:57] op_sel_hi:[1,0]
	v_pk_mul_f32 v[90:91], v[88:89], s[56:57] op_sel_hi:[1,0]
	v_cvt_pk_bf16_f32 v88, v96, v97
	v_cvt_pk_bf16_f32 v89, v98, v99
	v_cvt_pk_bf16_f32 v90, v90, v91
	v_cvt_pk_bf16_f32 v91, v104, v105
	global_store_dwordx4 v[112:113], v[88:91], off offset:256
	v_pk_add_f32 v[92:93], v[92:93], v[140:141]
	v_pk_add_f32 v[94:95], v[94:95], v[138:139]
	v_lshlrev_b64 v[88:89], 11, v[148:149]
	v_lshl_add_u64 v[88:89], s[34:35], 0, v[88:89]
	v_lshl_add_u64 v[96:97], v[88:89], 0, v[176:177]
	v_pk_add_f32 v[88:89], v[100:101], v[144:145]
	v_pk_add_f32 v[90:91], v[102:103], v[142:143]
	v_pk_mul_f32 v[88:89], v[88:89], s[56:57] op_sel_hi:[1,0]
	v_pk_mul_f32 v[90:91], v[90:91], s[56:57] op_sel_hi:[1,0]
	v_pk_mul_f32 v[94:95], v[94:95], s[56:57] op_sel_hi:[1,0]
	v_pk_mul_f32 v[92:93], v[92:93], s[56:57] op_sel_hi:[1,0]
	v_cvt_pk_bf16_f32 v88, v88, v89
	v_cvt_pk_bf16_f32 v89, v90, v91
	v_cvt_pk_bf16_f32 v90, v92, v93
	v_cvt_pk_bf16_f32 v91, v94, v95
	v_pk_add_f32 v[80:81], v[80:81], v[132:133]
	v_pk_add_f32 v[82:83], v[82:83], v[130:131]
	v_pk_add_f32 v[72:73], v[72:73], v[136:137]
	v_pk_add_f32 v[74:75], v[74:75], v[134:135]
	global_store_dwordx4 v[96:97], v[88:91], off
	v_pk_mul_f32 v[82:83], v[82:83], s[56:57] op_sel_hi:[1,0]
	v_pk_mul_f32 v[80:81], v[80:81], s[56:57] op_sel_hi:[1,0]
	v_pk_mul_f32 v[88:89], v[74:75], s[56:57] op_sel_hi:[1,0]
	v_pk_mul_f32 v[74:75], v[72:73], s[56:57] op_sel_hi:[1,0]
	v_cvt_pk_bf16_f32 v72, v80, v81
	v_cvt_pk_bf16_f32 v73, v82, v83
	v_cvt_pk_bf16_f32 v74, v74, v75
	v_cvt_pk_bf16_f32 v75, v88, v89
	global_store_dwordx4 v[96:97], v[72:75], off offset:256
	v_pk_add_f32 v[76:77], v[76:77], v[140:141]
	v_pk_add_f32 v[78:79], v[78:79], v[138:139]
	v_lshlrev_b64 v[72:73], 11, v[146:147]
	v_lshl_add_u64 v[72:73], s[34:35], 0, v[72:73]
	v_lshl_add_u64 v[80:81], v[72:73], 0, v[176:177]
	v_pk_add_f32 v[72:73], v[84:85], v[144:145]
	v_pk_add_f32 v[74:75], v[86:87], v[142:143]
	v_pk_mul_f32 v[72:73], v[72:73], s[56:57] op_sel_hi:[1,0]
	v_pk_mul_f32 v[74:75], v[74:75], s[56:57] op_sel_hi:[1,0]
	v_pk_mul_f32 v[78:79], v[78:79], s[56:57] op_sel_hi:[1,0]
	v_pk_mul_f32 v[76:77], v[76:77], s[56:57] op_sel_hi:[1,0]
	v_cvt_pk_bf16_f32 v72, v72, v73
	v_cvt_pk_bf16_f32 v73, v74, v75
	v_cvt_pk_bf16_f32 v74, v76, v77
	v_cvt_pk_bf16_f32 v75, v78, v79
	v_pk_add_f32 v[68:69], v[68:69], v[132:133]
	v_pk_add_f32 v[70:71], v[70:71], v[130:131]
	v_pk_add_f32 v[64:65], v[64:65], v[136:137]
	v_pk_add_f32 v[66:67], v[66:67], v[134:135]
	global_store_dwordx4 v[80:81], v[72:75], off
	v_pk_mul_f32 v[70:71], v[70:71], s[56:57] op_sel_hi:[1,0]
	v_pk_mul_f32 v[68:69], v[68:69], s[56:57] op_sel_hi:[1,0]
	v_pk_mul_f32 v[72:73], v[66:67], s[56:57] op_sel_hi:[1,0]
	v_pk_mul_f32 v[66:67], v[64:65], s[56:57] op_sel_hi:[1,0]
	v_cvt_pk_bf16_f32 v64, v68, v69
	v_cvt_pk_bf16_f32 v65, v70, v71
	v_cvt_pk_bf16_f32 v66, v66, v67
	v_cvt_pk_bf16_f32 v67, v72, v73
	v_pk_add_f32 v[60:61], v[60:61], v[144:145]
	global_store_dwordx4 v[80:81], v[64:67], off offset:256
	v_pk_add_f32 v[62:63], v[62:63], v[142:143]
	v_pk_mul_f32 v[60:61], v[60:61], s[56:57] op_sel_hi:[1,0]
	v_lshl_add_u64 v[64:65], v[128:129], 0, s[0:1]
	v_pk_add_f32 v[56:57], v[56:57], v[140:141]
	v_pk_add_f32 v[58:59], v[58:59], v[138:139]
	s_mov_b32 s0, 0x40000
	v_pk_mul_f32 v[62:63], v[62:63], s[56:57] op_sel_hi:[1,0]
	v_pk_mul_f32 v[66:67], v[58:59], s[56:57] op_sel_hi:[1,0]
	v_pk_mul_f32 v[58:59], v[56:57], s[56:57] op_sel_hi:[1,0]
	v_cvt_pk_bf16_f32 v56, v60, v61
	v_add_co_u32_e32 v60, vcc, s0, v128
	v_cvt_pk_bf16_f32 v57, v62, v63
	v_cvt_pk_bf16_f32 v58, v58, v59
	v_cvt_pk_bf16_f32 v59, v66, v67
	v_addc_co_u32_e32 v61, vcc, 0, v129, vcc
	v_pk_add_f32 v[48:49], v[48:49], v[132:133]
	v_pk_add_f32 v[50:51], v[50:51], v[130:131]
	v_pk_add_f32 v[40:41], v[40:41], v[136:137]
	v_pk_add_f32 v[42:43], v[42:43], v[134:135]
	global_store_dwordx4 v[60:61], v[56:59], off
	v_pk_mul_f32 v[50:51], v[50:51], s[56:57] op_sel_hi:[1,0]
	v_pk_mul_f32 v[48:49], v[48:49], s[56:57] op_sel_hi:[1,0]
	v_pk_mul_f32 v[56:57], v[42:43], s[56:57] op_sel_hi:[1,0]
	v_pk_mul_f32 v[42:43], v[40:41], s[56:57] op_sel_hi:[1,0]
	v_cvt_pk_bf16_f32 v40, v48, v49
	v_cvt_pk_bf16_f32 v41, v50, v51
	v_cvt_pk_bf16_f32 v42, v42, v43
	v_cvt_pk_bf16_f32 v43, v56, v57
	global_store_dwordx4 v[64:65], v[40:43], off offset:256
	s_mov_b64 s[0:1], 0x48000
	v_pk_add_f32 v[44:45], v[44:45], v[140:141]
	v_pk_add_f32 v[40:41], v[52:53], v[144:145]
	v_pk_add_f32 v[42:43], v[54:55], v[142:143]
	v_lshl_add_u64 v[48:49], v[128:129], 0, s[0:1]
	v_pk_mul_f32 v[42:43], v[42:43], s[56:57] op_sel_hi:[1,0]
	v_pk_mul_f32 v[40:41], v[40:41], s[56:57] op_sel_hi:[1,0]
	v_pk_add_f32 v[46:47], v[46:47], v[138:139]
	v_pk_mul_f32 v[44:45], v[44:45], s[56:57] op_sel_hi:[1,0]
	s_mov_b32 s0, 0x48000
	v_pk_mul_f32 v[46:47], v[46:47], s[56:57] op_sel_hi:[1,0]
	v_cvt_pk_bf16_f32 v40, v40, v41
	v_cvt_pk_bf16_f32 v41, v42, v43
	v_cvt_pk_bf16_f32 v42, v44, v45
	v_add_co_u32_e32 v44, vcc, s0, v128
	v_cvt_pk_bf16_f32 v43, v46, v47
	s_nop 0
	v_addc_co_u32_e32 v45, vcc, 0, v129, vcc
	v_pk_add_f32 v[32:33], v[32:33], v[132:133]
	v_pk_add_f32 v[34:35], v[34:35], v[130:131]
	v_pk_add_f32 v[24:25], v[24:25], v[136:137]
	v_pk_add_f32 v[26:27], v[26:27], v[134:135]
	global_store_dwordx4 v[44:45], v[40:43], off
	v_pk_mul_f32 v[34:35], v[34:35], s[56:57] op_sel_hi:[1,0]
	v_pk_mul_f32 v[32:33], v[32:33], s[56:57] op_sel_hi:[1,0]
	v_pk_mul_f32 v[40:41], v[26:27], s[56:57] op_sel_hi:[1,0]
	v_pk_mul_f32 v[26:27], v[24:25], s[56:57] op_sel_hi:[1,0]
	v_cvt_pk_bf16_f32 v24, v32, v33
	v_cvt_pk_bf16_f32 v25, v34, v35
	v_cvt_pk_bf16_f32 v26, v26, v27
	v_cvt_pk_bf16_f32 v27, v40, v41
	global_store_dwordx4 v[48:49], v[24:27], off offset:256
	s_mov_b64 s[0:1], 0x50000
	v_pk_add_f32 v[28:29], v[28:29], v[140:141]
	v_pk_add_f32 v[24:25], v[36:37], v[144:145]
	v_pk_add_f32 v[26:27], v[38:39], v[142:143]
	v_lshl_add_u64 v[32:33], v[128:129], 0, s[0:1]
	v_pk_mul_f32 v[26:27], v[26:27], s[56:57] op_sel_hi:[1,0]
	v_pk_mul_f32 v[24:25], v[24:25], s[56:57] op_sel_hi:[1,0]
	v_pk_add_f32 v[30:31], v[30:31], v[138:139]
	v_pk_mul_f32 v[28:29], v[28:29], s[56:57] op_sel_hi:[1,0]
	s_mov_b32 s0, 0x50000
	v_pk_mul_f32 v[30:31], v[30:31], s[56:57] op_sel_hi:[1,0]
	v_cvt_pk_bf16_f32 v24, v24, v25
	v_cvt_pk_bf16_f32 v25, v26, v27
	v_cvt_pk_bf16_f32 v26, v28, v29
	v_add_co_u32_e32 v28, vcc, s0, v128
	v_cvt_pk_bf16_f32 v27, v30, v31
	s_nop 0
	v_addc_co_u32_e32 v29, vcc, 0, v129, vcc
	v_pk_add_f32 v[16:17], v[16:17], v[132:133]
	v_pk_add_f32 v[18:19], v[18:19], v[130:131]
	v_pk_add_f32 v[8:9], v[8:9], v[136:137]
	v_pk_add_f32 v[10:11], v[10:11], v[134:135]
	global_store_dwordx4 v[28:29], v[24:27], off
	v_pk_mul_f32 v[18:19], v[18:19], s[56:57] op_sel_hi:[1,0]
	v_pk_mul_f32 v[16:17], v[16:17], s[56:57] op_sel_hi:[1,0]
	v_pk_mul_f32 v[24:25], v[10:11], s[56:57] op_sel_hi:[1,0]
	v_pk_mul_f32 v[10:11], v[8:9], s[56:57] op_sel_hi:[1,0]
	v_cvt_pk_bf16_f32 v8, v16, v17
	v_cvt_pk_bf16_f32 v9, v18, v19
	v_cvt_pk_bf16_f32 v10, v10, v11
	v_cvt_pk_bf16_f32 v11, v24, v25
	global_store_dwordx4 v[32:33], v[8:11], off offset:256
	s_mov_b64 s[0:1], 0x58000
	v_pk_add_f32 v[12:13], v[12:13], v[140:141]
	v_pk_add_f32 v[8:9], v[20:21], v[144:145]
	v_pk_add_f32 v[10:11], v[22:23], v[142:143]
	v_lshl_add_u64 v[16:17], v[128:129], 0, s[0:1]
	v_pk_mul_f32 v[10:11], v[10:11], s[56:57] op_sel_hi:[1,0]
	v_pk_mul_f32 v[8:9], v[8:9], s[56:57] op_sel_hi:[1,0]
	v_pk_add_f32 v[14:15], v[14:15], v[138:139]
	v_pk_mul_f32 v[12:13], v[12:13], s[56:57] op_sel_hi:[1,0]
	s_mov_b32 s0, 0x58000
	v_pk_mul_f32 v[14:15], v[14:15], s[56:57] op_sel_hi:[1,0]
	v_cvt_pk_bf16_f32 v8, v8, v9
	v_cvt_pk_bf16_f32 v9, v10, v11
	v_cvt_pk_bf16_f32 v10, v12, v13
	v_add_co_u32_e32 v12, vcc, s0, v128
	v_cvt_pk_bf16_f32 v11, v14, v15
	s_nop 0
	v_addc_co_u32_e32 v13, vcc, 0, v129, vcc
	v_pk_add_f32 v[4:5], v[4:5], v[132:133]
	v_pk_add_f32 v[6:7], v[6:7], v[130:131]
	v_pk_add_f32 v[0:1], v[0:1], v[136:137]
	v_pk_add_f32 v[2:3], v[2:3], v[134:135]
	global_store_dwordx4 v[12:13], v[8:11], off
	v_pk_mul_f32 v[6:7], v[6:7], s[56:57] op_sel_hi:[1,0]
	v_pk_mul_f32 v[4:5], v[4:5], s[56:57] op_sel_hi:[1,0]
	v_pk_mul_f32 v[8:9], v[2:3], s[56:57] op_sel_hi:[1,0]
	v_pk_mul_f32 v[2:3], v[0:1], s[56:57] op_sel_hi:[1,0]
	v_cvt_pk_bf16_f32 v0, v4, v5
	v_cvt_pk_bf16_f32 v1, v6, v7
	v_cvt_pk_bf16_f32 v2, v2, v3
	v_cvt_pk_bf16_f32 v3, v8, v9
	global_store_dwordx4 v[16:17], v[0:3], off offset:256
	s_waitcnt vmcnt(0)
	s_barrier

.LBB0_612:
	s_andn2_b64 vcc, exec, s[0:1]
	s_cbranch_vccnz .LBB0_558
	s_mov_b64 s[58:59], s[94:95]
	s_mov_b64 s[42:43], s[94:95]
	s_mov_b64 s[46:47], s[94:95]
	s_mov_b64 s[34:35], s[94:95]
	s_mov_b64 s[0:1], s[94:95]
	s_add_u32 s0, s0, s76
	s_addc_u32 s1, s1, 0
	s_add_u32 s0, s0, 0x20000
	s_addc_u32 s1, s1, 0
	s_ashr_i32 s22, s77, 7
	s_add_i32 s36, s22, 8
	s_lshl_b32 s40, s36, 11
	s_lshl_b32 s36, s36, 12
	s_bfe_u32 s3, s77, 0x20005
	s_add_i32 s41, s36, 0xffffc000
	s_cmp_lt_i32 s22, 0
	s_cselect_b64 s[68:69], -1, 0
	s_and_b64 s[36:37], s[68:69], exec
	s_cselect_b32 s40, s40, s41
	s_lshl_b32 s22, s77, 7
	s_and_b32 s78, s22, 0xf80
	s_add_i32 s36, s40, s78
	s_ashr_i32 s37, s36, 31
	s_lshl_b64 s[60:61], s[36:37], 10
	s_add_u32 s22, s58, s60
	v_mov_b32_e32 v18, v226
	s_addc_u32 s37, s59, s61
	s_lshl_b32 s41, s3, 8
	s_add_u32 s58, s22, s41
	v_lshlrev_b32_e32 v0, 4, v18
	v_add_u32_e32 v30, 0x200, v18
	v_add_u32_e32 v10, 0x400, v18
	v_add_u32_e32 v12, 0x600, v18
	s_addc_u32 s59, s37, 0
	v_and_b32_e32 v20, 0xf0, v0
	v_mov_b32_e32 v21, v177
	v_ashrrev_i32_e32 v22, 4, v18
	v_ashrrev_i32_e32 v24, 4, v30
	v_ashrrev_i32_e32 v26, 4, v10
	v_ashrrev_i32_e32 v28, 4, v12
	s_mul_i32 s22, s3, 0x208
	v_lshl_add_u64 v[0:1], s[58:59], 0, v[20:21]
	s_mov_b64 s[14:15], 0x8b00000
	v_ashrrev_i32_e32 v23, 31, v22
	v_ashrrev_i32_e32 v25, 31, v24
	v_ashrrev_i32_e32 v27, 31, v26
	v_ashrrev_i32_e32 v29, 31, v28
	v_add_u32_e32 v32, s22, v18
	v_lshl_add_u64 v[8:9], v[0:1], 0, s[14:15]
	v_lshlrev_b64 v[16:17], 10, v[22:23]
	v_lshlrev_b64 v[2:3], 10, v[24:25]
	v_lshlrev_b64 v[10:11], 10, v[26:27]
	v_lshlrev_b64 v[12:13], 10, v[28:29]
	v_ashrrev_i32_e32 v33, 31, v32
	v_lshl_add_u64 v[0:1], v[8:9], 0, v[16:17]
	v_lshl_add_u64 v[2:3], v[8:9], 0, v[2:3]
	v_lshl_add_u64 v[10:11], v[8:9], 0, v[10:11]
	v_lshl_add_u64 v[8:9], v[8:9], 0, v[12:13]
	v_lshl_add_u64 v[32:33], v[32:33], 2, s[0:1]
	global_load_dwordx4 v[4:7], v[0:1], off
	s_nop 0
	global_load_dwordx4 v[0:3], v[2:3], off
	s_nop 0
	global_load_dwordx4 v[12:15], v[10:11], off
	s_nop 0
	global_load_dwordx4 v[8:11], v[8:9], off
	v_readfirstlane_b32 s58, v18
	global_load_dword v21, v[32:33], off
	v_cmp_gt_i32_e32 vcc, 8, v18
	v_mov_b32_e32 v19, 0
	v_mov_b32_e32 v25, 0
	s_and_saveexec_b64 s[70:71], vcc
	s_cbranch_execz .LBB0_615
	v_add_u32_e32 v30, s22, v30
	v_ashrrev_i32_e32 v31, 31, v30
	v_lshl_add_u64 v[30:31], v[30:31], 2, s[0:1]
	global_load_dword v25, v[30:31], off

.LBB0_639:
	s_cmpk_gt_u32 s58, 0xff
	s_waitcnt lgkmcnt(0)
	s_barrier
	s_cbranch_scc1 .LBB0_558
	v_div_scale_f32 v66, s[0:1], v65, v65, 1.0
	v_rcp_f32_e32 v68, v66
	v_div_scale_f32 v69, vcc, 1.0, v65, 1.0
	s_add_i32 s1, 0, 0x1a900
	v_fma_f32 v70, -v66, v68, 1.0
	v_fmac_f32_e32 v68, v70, v68
	v_mul_f32_e32 v70, v69, v68
	v_fma_f32 v71, -v66, v70, v69
	v_fmac_f32_e32 v70, v71, v68
	v_fma_f32 v66, -v66, v70, v69
	v_div_fmas_f32 v66, v66, v68, v70
	ds_read2st64_b32 v[74:75], v64 offset1:1
	ds_read2st64_b32 v[76:77], v64 offset0:2 offset1:3
	ds_read2st64_b32 v[78:79], v64 offset0:4 offset1:5
	ds_read2st64_b32 v[80:81], v64 offset0:6 offset1:7
	ds_read2st64_b32 v[82:83], v64 offset0:8 offset1:9
	ds_read2st64_b32 v[84:85], v64 offset0:10 offset1:11
	ds_read2st64_b32 v[86:87], v64 offset0:12 offset1:13
	ds_read2st64_b32 v[88:89], v64 offset0:14 offset1:15
	ds_read2st64_b32 v[90:91], v64 offset0:16 offset1:17
	ds_read2st64_b32 v[92:93], v64 offset0:18 offset1:19
	ds_read2st64_b32 v[94:95], v64 offset0:20 offset1:21
	s_waitcnt vmcnt(0)
	ds_read2st64_b32 v[96:97], v64 offset0:22 offset1:23
	ds_read2st64_b32 v[98:99], v64 offset0:24 offset1:25
	ds_read2st64_b32 v[100:101], v64 offset0:26 offset1:27
	ds_read2st64_b32 v[102:103], v64 offset0:28 offset1:29
	ds_read2st64_b32 v[104:105], v64 offset0:30 offset1:31
	ds_read2st64_b32 v[106:107], v64 offset0:32 offset1:33
	ds_read2st64_b32 v[108:109], v64 offset0:34 offset1:35
	ds_read2st64_b32 v[110:111], v64 offset0:36 offset1:37
	ds_read2st64_b32 v[112:113], v64 offset0:38 offset1:39
	ds_read2st64_b32 v[114:115], v64 offset0:40 offset1:41
	ds_read2st64_b32 v[116:117], v64 offset0:42 offset1:43
	ds_read2st64_b32 v[118:119], v64 offset0:44 offset1:45
	ds_read2st64_b32 v[120:121], v64 offset0:46 offset1:47
	ds_read2st64_b32 v[68:69], v64 offset0:58 offset1:59
	ds_read2st64_b32 v[122:123], v64 offset0:48 offset1:49
	ds_read2st64_b32 v[124:125], v64 offset0:50 offset1:51
	ds_read2st64_b32 v[126:127], v64 offset0:52 offset1:53
	ds_read2st64_b32 v[128:129], v64 offset0:54 offset1:55
	ds_read2st64_b32 v[70:71], v64 offset0:60 offset1:61
	ds_read2st64_b32 v[72:73], v64 offset0:62 offset1:63
	ds_read2st64_b32 v[130:131], v64 offset0:56 offset1:57
	v_div_fixup_f32 v66, v66, v65, 1.0
	s_waitcnt lgkmcnt(14)
	v_pk_fma_f32 v[74:75], v[48:49], v[66:67], v[74:75] op_sel_hi:[1,0,1] neg_lo:[0,0,1] neg_hi:[0,0,1]
	v_pk_fma_f32 v[50:51], v[50:51], v[66:67], v[76:77] op_sel_hi:[1,0,1] neg_lo:[0,0,1] neg_hi:[0,0,1]
	v_pk_mul_f32 v[134:135], v[74:75], v[74:75]
	s_waitcnt lgkmcnt(7)
	v_pk_fma_f32 v[64:65], v[10:11], v[66:67], v[68:69] op_sel_hi:[1,0,1] neg_lo:[0,0,1] neg_hi:[0,0,1]
	s_waitcnt lgkmcnt(2)
	v_pk_fma_f32 v[10:11], v[12:13], v[66:67], v[70:71] op_sel_hi:[1,0,1] neg_lo:[0,0,1] neg_hi:[0,0,1]
	s_waitcnt lgkmcnt(1)
	v_pk_fma_f32 v[12:13], v[14:15], v[66:67], v[72:73] op_sel_hi:[1,0,1] neg_lo:[0,0,1] neg_hi:[0,0,1]
	v_pk_mul_f32 v[132:133], v[50:51], v[50:51]
	v_pk_fma_f32 v[48:49], v[54:55], v[66:67], v[80:81] op_sel_hi:[1,0,1] neg_lo:[0,0,1] neg_hi:[0,0,1]
	v_pk_fma_f32 v[76:77], v[52:53], v[66:67], v[78:79] op_sel_hi:[1,0,1] neg_lo:[0,0,1] neg_hi:[0,0,1]
	v_pk_fma_f32 v[52:53], v[58:59], v[66:67], v[84:85] op_sel_hi:[1,0,1] neg_lo:[0,0,1] neg_hi:[0,0,1]
	v_pk_fma_f32 v[78:79], v[56:57], v[66:67], v[82:83] op_sel_hi:[1,0,1] neg_lo:[0,0,1] neg_hi:[0,0,1]
	v_pk_fma_f32 v[54:55], v[62:63], v[66:67], v[88:89] op_sel_hi:[1,0,1] neg_lo:[0,0,1] neg_hi:[0,0,1]
	v_pk_fma_f32 v[62:63], v[60:61], v[66:67], v[86:87] op_sel_hi:[1,0,1] neg_lo:[0,0,1] neg_hi:[0,0,1]
	v_pk_fma_f32 v[56:57], v[34:35], v[66:67], v[92:93] op_sel_hi:[1,0,1] neg_lo:[0,0,1] neg_hi:[0,0,1]
	v_pk_fma_f32 v[58:59], v[32:33], v[66:67], v[90:91] op_sel_hi:[1,0,1] neg_lo:[0,0,1] neg_hi:[0,0,1]
	v_pk_fma_f32 v[32:33], v[38:39], v[66:67], v[96:97] op_sel_hi:[1,0,1] neg_lo:[0,0,1] neg_hi:[0,0,1]
	v_pk_fma_f32 v[60:61], v[36:37], v[66:67], v[94:95] op_sel_hi:[1,0,1] neg_lo:[0,0,1] neg_hi:[0,0,1]
	v_pk_fma_f32 v[34:35], v[42:43], v[66:67], v[100:101] op_sel_hi:[1,0,1] neg_lo:[0,0,1] neg_hi:[0,0,1]
	v_pk_fma_f32 v[42:43], v[40:41], v[66:67], v[98:99] op_sel_hi:[1,0,1] neg_lo:[0,0,1] neg_hi:[0,0,1]
	v_pk_fma_f32 v[36:37], v[46:47], v[66:67], v[104:105] op_sel_hi:[1,0,1] neg_lo:[0,0,1] neg_hi:[0,0,1]
	v_pk_fma_f32 v[44:45], v[44:45], v[66:67], v[102:103] op_sel_hi:[1,0,1] neg_lo:[0,0,1] neg_hi:[0,0,1]
	v_pk_fma_f32 v[38:39], v[18:19], v[66:67], v[108:109] op_sel_hi:[1,0,1] neg_lo:[0,0,1] neg_hi:[0,0,1]
	v_pk_fma_f32 v[40:41], v[16:17], v[66:67], v[106:107] op_sel_hi:[1,0,1] neg_lo:[0,0,1] neg_hi:[0,0,1]
	v_pk_fma_f32 v[14:15], v[22:23], v[66:67], v[112:113] op_sel_hi:[1,0,1] neg_lo:[0,0,1] neg_hi:[0,0,1]
	v_pk_fma_f32 v[22:23], v[20:21], v[66:67], v[110:111] op_sel_hi:[1,0,1] neg_lo:[0,0,1] neg_hi:[0,0,1]
	v_pk_fma_f32 v[16:17], v[26:27], v[66:67], v[116:117] op_sel_hi:[1,0,1] neg_lo:[0,0,1] neg_hi:[0,0,1]
	v_pk_fma_f32 v[24:25], v[24:25], v[66:67], v[114:115] op_sel_hi:[1,0,1] neg_lo:[0,0,1] neg_hi:[0,0,1]
	v_pk_fma_f32 v[18:19], v[30:31], v[66:67], v[120:121] op_sel_hi:[1,0,1] neg_lo:[0,0,1] neg_hi:[0,0,1]
	v_pk_fma_f32 v[26:27], v[28:29], v[66:67], v[118:119] op_sel_hi:[1,0,1] neg_lo:[0,0,1] neg_hi:[0,0,1]
	v_pk_fma_f32 v[2:3], v[2:3], v[66:67], v[124:125] op_sel_hi:[1,0,1] neg_lo:[0,0,1] neg_hi:[0,0,1]
	v_pk_fma_f32 v[20:21], v[0:1], v[66:67], v[122:123] op_sel_hi:[1,0,1] neg_lo:[0,0,1] neg_hi:[0,0,1]
	v_pk_fma_f32 v[0:1], v[6:7], v[66:67], v[128:129] op_sel_hi:[1,0,1] neg_lo:[0,0,1] neg_hi:[0,0,1]
	v_pk_fma_f32 v[6:7], v[4:5], v[66:67], v[126:127] op_sel_hi:[1,0,1] neg_lo:[0,0,1] neg_hi:[0,0,1]
	s_waitcnt lgkmcnt(0)
	v_pk_fma_f32 v[4:5], v[8:9], v[66:67], v[130:131] op_sel_hi:[1,0,1] neg_lo:[0,0,1] neg_hi:[0,0,1]
	v_add_f32_e32 v66, v134, v135
	v_add_f32_e32 v66, v66, v132
	v_pk_mul_f32 v[136:137], v[76:77], v[76:77]
	v_add_f32_e32 v66, v66, v133
	v_add_f32_e32 v66, v66, v136
	v_pk_mul_f32 v[80:81], v[48:49], v[48:49]
	v_add_f32_e32 v66, v66, v137
	v_add_f32_e32 v66, v66, v80
	v_pk_mul_f32 v[82:83], v[78:79], v[78:79]
	v_add_f32_e32 v66, v66, v81
	v_add_f32_e32 v66, v66, v82
	v_pk_mul_f32 v[84:85], v[52:53], v[52:53]
	v_add_f32_e32 v66, v66, v83
	v_add_f32_e32 v66, v66, v84
	v_pk_mul_f32 v[86:87], v[62:63], v[62:63]
	v_add_f32_e32 v66, v66, v85
	v_add_f32_e32 v66, v66, v86
	v_pk_mul_f32 v[88:89], v[54:55], v[54:55]
	v_add_f32_e32 v66, v66, v87
	v_add_f32_e32 v66, v66, v88
	v_pk_mul_f32 v[90:91], v[58:59], v[58:59]
	v_add_f32_e32 v66, v66, v89
	v_add_f32_e32 v66, v66, v90
	v_pk_mul_f32 v[92:93], v[56:57], v[56:57]
	v_add_f32_e32 v66, v66, v91
	v_add_f32_e32 v66, v66, v92
	v_pk_mul_f32 v[94:95], v[60:61], v[60:61]
	v_add_f32_e32 v66, v66, v93
	v_add_f32_e32 v66, v66, v94
	v_pk_mul_f32 v[96:97], v[32:33], v[32:33]
	v_add_f32_e32 v66, v66, v95
	v_add_f32_e32 v66, v66, v96
	v_pk_mul_f32 v[98:99], v[42:43], v[42:43]
	v_add_f32_e32 v66, v66, v97
	v_add_f32_e32 v66, v66, v98
	v_pk_mul_f32 v[100:101], v[34:35], v[34:35]
	v_add_f32_e32 v66, v66, v99
	v_add_f32_e32 v66, v66, v100
	v_pk_mul_f32 v[102:103], v[44:45], v[44:45]
	v_add_f32_e32 v66, v66, v101
	v_add_f32_e32 v66, v66, v102
	v_pk_mul_f32 v[46:47], v[36:37], v[36:37]
	v_add_f32_e32 v66, v66, v103
	v_add_f32_e32 v46, v66, v46
	v_pk_mul_f32 v[106:107], v[40:41], v[40:41]
	v_add_f32_e32 v46, v46, v47
	v_add_f32_e32 v46, v46, v106
	v_pk_mul_f32 v[104:105], v[38:39], v[38:39]
	v_add_f32_e32 v46, v46, v107
	v_add_f32_e32 v46, v46, v104
	v_pk_mul_f32 v[110:111], v[22:23], v[22:23]
	v_add_f32_e32 v46, v46, v105
	v_add_f32_e32 v46, v46, v110
	v_pk_mul_f32 v[108:109], v[14:15], v[14:15]
	v_add_f32_e32 v46, v46, v111
	v_add_f32_e32 v46, v46, v108
	v_pk_mul_f32 v[114:115], v[24:25], v[24:25]
	v_add_f32_e32 v46, v46, v109
	v_add_f32_e32 v46, v46, v114
	v_pk_mul_f32 v[112:113], v[16:17], v[16:17]
	v_add_f32_e32 v46, v46, v115
	v_add_f32_e32 v46, v46, v112
	v_pk_mul_f32 v[28:29], v[26:27], v[26:27]
	v_add_f32_e32 v46, v46, v113
	v_add_f32_e32 v28, v46, v28
	v_pk_mul_f32 v[30:31], v[18:19], v[18:19]
	v_add_f32_e32 v28, v28, v29
	v_add_f32_e32 v28, v28, v30
	v_pk_mul_f32 v[118:119], v[20:21], v[20:21]
	v_add_f32_e32 v28, v28, v31
	v_add_f32_e32 v28, v28, v118
	v_pk_mul_f32 v[116:117], v[2:3], v[2:3]
	v_add_f32_e32 v28, v28, v119
	v_add_f32_e32 v28, v28, v116
	v_pk_mul_f32 v[122:123], v[6:7], v[6:7]
	v_add_f32_e32 v28, v28, v117
	v_add_f32_e32 v28, v28, v122
	v_pk_mul_f32 v[120:121], v[0:1], v[0:1]
	v_add_f32_e32 v28, v28, v123
	v_add_f32_e32 v28, v28, v120
	v_pk_mul_f32 v[8:9], v[4:5], v[4:5]
	v_add_f32_e32 v28, v28, v121
	v_add_f32_e32 v8, v28, v8
	v_pk_mul_f32 v[68:69], v[64:65], v[64:65]
	v_add_f32_e32 v8, v8, v9
	v_add_f32_e32 v8, v8, v68
	v_pk_mul_f32 v[70:71], v[10:11], v[10:11]
	v_add_f32_e32 v8, v8, v69
	v_add_f32_e32 v8, v8, v70
	v_pk_mul_f32 v[72:73], v[12:13], v[12:13]
	v_add_f32_e32 v8, v8, v71
	v_add_f32_e32 v8, v8, v72
	v_add_f32_e32 v8, v8, v73
	ds_bpermute_b32 v9, v67, v8
	s_waitcnt lgkmcnt(0)
	v_add_u32_e32 v28, s1, v237
	s_lshl_b32 s0, s59, 14
	ds_read_b128 v[28:31], v28
	s_waitcnt lgkmcnt(1)
	v_add_f32_e32 v8, v8, v9
	v_fmamk_f32 v8, v8, 0x3c000000, v228
	v_rsq_f32_e32 v8, v8
	s_add_i32 s0, s0, 0
	v_add_u32_e32 v66, s0, v238
	v_lshl_add_u32 v9, v236, 3, v66
	v_mul_f32_e32 v8, s75, v8
	v_pk_mul_f32 v[46:47], v[74:75], v[8:9] op_sel_hi:[1,0]
	v_or_b32_e32 v67, 8, v235
	s_waitcnt lgkmcnt(0)
	v_pk_mul_f32 v[28:29], v[28:29], v[46:47]
	v_pk_mul_f32 v[46:47], v[50:51], v[8:9] op_sel_hi:[1,0]
	v_cvt_pk_bf16_f32 v28, v28, v29
	v_pk_mul_f32 v[30:31], v[30:31], v[46:47]
	v_lshl_add_u32 v68, v67, 2, s1
	v_cvt_pk_bf16_f32 v29, v30, v31
	ds_write_b64 v9, v[28:29]
	ds_read_b128 v[28:31], v68
	v_lshl_add_u32 v9, v67, 1, v66
	v_pk_mul_f32 v[46:47], v[76:77], v[8:9] op_sel_hi:[1,0]
	v_or_b32_e32 v50, 16, v235
	v_lshl_add_u32 v51, v50, 2, s1
	s_waitcnt lgkmcnt(0)
	v_pk_mul_f32 v[28:29], v[28:29], v[46:47]
	v_pk_mul_f32 v[46:47], v[48:49], v[8:9] op_sel_hi:[1,0]
	v_cvt_pk_bf16_f32 v28, v28, v29
	v_pk_mul_f32 v[30:31], v[30:31], v[46:47]
	v_or_b32_e32 v48, 24, v235
	v_cvt_pk_bf16_f32 v29, v30, v31
	ds_write_b64 v9, v[28:29]
	ds_read_b128 v[28:31], v51
	v_lshl_add_u32 v9, v50, 1, v66
	v_pk_mul_f32 v[46:47], v[78:79], v[8:9] op_sel_hi:[1,0]
	v_lshl_add_u32 v49, v48, 2, s1
	s_or_b32 s36, s37, s36
	s_waitcnt lgkmcnt(0)
	v_pk_mul_f32 v[28:29], v[28:29], v[46:47]
	v_pk_mul_f32 v[46:47], v[52:53], v[8:9] op_sel_hi:[1,0]
	v_cvt_pk_bf16_f32 v28, v28, v29
	v_pk_mul_f32 v[30:31], v[30:31], v[46:47]
	s_ashr_i32 s37, s36, 31
	v_cvt_pk_bf16_f32 v29, v30, v31
	ds_write_b64 v9, v[28:29]
	ds_read_b128 v[28:31], v49
	v_lshl_add_u32 v9, v48, 1, v66
	v_pk_mul_f32 v[46:47], v[62:63], v[8:9] op_sel_hi:[1,0]
	v_or_b32_e32 v48, 32, v235
	v_lshl_add_u32 v49, v48, 2, s1
	s_waitcnt lgkmcnt(0)
	v_pk_mul_f32 v[28:29], v[46:47], v[28:29]
	v_pk_mul_f32 v[46:47], v[54:55], v[8:9] op_sel_hi:[1,0]
	v_cvt_pk_bf16_f32 v28, v28, v29
	v_pk_mul_f32 v[30:31], v[46:47], v[30:31]
	s_lshl_b64 s[36:37], s[36:37], 11
	v_cvt_pk_bf16_f32 v29, v30, v31
	ds_write_b64 v9, v[28:29]
	ds_read_b128 v[28:31], v49
	v_lshl_add_u32 v9, v48, 1, v66
	v_pk_mul_f32 v[46:47], v[58:59], v[8:9] op_sel_hi:[1,0]
	v_or_b32_e32 v48, 40, v235
	v_lshl_add_u32 v49, v48, 2, s1
	s_waitcnt lgkmcnt(0)
	v_pk_mul_f32 v[28:29], v[46:47], v[28:29]
	v_pk_mul_f32 v[46:47], v[56:57], v[8:9] op_sel_hi:[1,0]
	v_cvt_pk_bf16_f32 v28, v28, v29
	v_pk_mul_f32 v[30:31], v[46:47], v[30:31]
	s_nop 0
	v_cvt_pk_bf16_f32 v29, v30, v31
	ds_write_b64 v9, v[28:29]
	ds_read_b128 v[28:31], v49
	v_lshl_add_u32 v9, v48, 1, v66
	v_pk_mul_f32 v[46:47], v[60:61], v[8:9] op_sel_hi:[1,0]
	v_pk_mul_f32 v[32:33], v[32:33], v[8:9] op_sel_hi:[1,0]
	v_or_b32_e32 v48, 48, v235
	s_waitcnt lgkmcnt(0)
	v_pk_mul_f32 v[28:29], v[46:47], v[28:29]
	v_pk_mul_f32 v[30:31], v[32:33], v[30:31]
	v_cvt_pk_bf16_f32 v28, v28, v29
	v_cvt_pk_bf16_f32 v29, v30, v31
	v_lshl_add_u32 v49, v48, 2, s1
	ds_write_b64 v9, v[28:29]
	ds_read_b128 v[28:31], v49
	v_lshl_add_u32 v9, v48, 1, v66
	v_pk_mul_f32 v[32:33], v[42:43], v[8:9] op_sel_hi:[1,0]
	v_or_b32_e32 v46, 56, v235
	v_lshl_add_u32 v47, v46, 2, s1
	s_waitcnt lgkmcnt(0)
	v_pk_mul_f32 v[28:29], v[32:33], v[28:29]
	v_pk_mul_f32 v[32:33], v[34:35], v[8:9] op_sel_hi:[1,0]
	v_cvt_pk_bf16_f32 v28, v28, v29
	v_pk_mul_f32 v[30:31], v[32:33], v[30:31]
	v_or_b32_e32 v34, 64, v235
	v_cvt_pk_bf16_f32 v29, v30, v31
	ds_write_b64 v9, v[28:29]
	ds_read_b128 v[28:31], v47
	v_lshl_add_u32 v9, v46, 1, v66
	v_pk_mul_f32 v[32:33], v[44:45], v[8:9] op_sel_hi:[1,0]
	v_lshl_add_u32 v35, v34, 2, s1
	s_waitcnt lgkmcnt(0)
	v_pk_mul_f32 v[28:29], v[32:33], v[28:29]
	v_pk_mul_f32 v[32:33], v[36:37], v[8:9] op_sel_hi:[1,0]
	v_cvt_pk_bf16_f32 v28, v28, v29
	v_pk_mul_f32 v[30:31], v[32:33], v[30:31]
	s_nop 0
	v_cvt_pk_bf16_f32 v29, v30, v31
	ds_write_b64 v9, v[28:29]
	ds_read_b128 v[28:31], v35
	v_lshl_add_u32 v9, v34, 1, v66
	v_pk_mul_f32 v[32:33], v[40:41], v[8:9] op_sel_hi:[1,0]
	v_or_b32_e32 v34, 0x48, v235
	v_lshl_add_u32 v35, v34, 2, s1
	s_waitcnt lgkmcnt(0)
	v_pk_mul_f32 v[28:29], v[32:33], v[28:29]
	v_pk_mul_f32 v[32:33], v[38:39], v[8:9] op_sel_hi:[1,0]
	v_cvt_pk_bf16_f32 v28, v28, v29
	v_pk_mul_f32 v[30:31], v[32:33], v[30:31]
	v_or_b32_e32 v32, 0x50, v235
	v_cvt_pk_bf16_f32 v29, v30, v31
	ds_write_b64 v9, v[28:29]
	ds_read_b128 v[28:31], v35
	v_lshl_add_u32 v9, v34, 1, v66
	v_pk_mul_f32 v[22:23], v[22:23], v[8:9] op_sel_hi:[1,0]
	v_pk_mul_f32 v[14:15], v[14:15], v[8:9] op_sel_hi:[1,0]
	v_lshl_add_u32 v33, v32, 2, s1
	s_waitcnt lgkmcnt(0)
	v_pk_mul_f32 v[22:23], v[22:23], v[28:29]
	v_pk_mul_f32 v[14:15], v[14:15], v[30:31]
	v_cvt_pk_bf16_f32 v22, v22, v23
	v_cvt_pk_bf16_f32 v23, v14, v15
	ds_write_b64 v9, v[22:23]
	ds_read_b128 v[28:31], v33
	v_lshl_add_u32 v9, v32, 1, v66
	v_pk_mul_f32 v[14:15], v[24:25], v[8:9] op_sel_hi:[1,0]
	v_pk_mul_f32 v[16:17], v[16:17], v[8:9] op_sel_hi:[1,0]
	v_or_b32_e32 v22, 0x58, v235
	s_waitcnt lgkmcnt(0)
	v_pk_mul_f32 v[14:15], v[14:15], v[28:29]
	v_pk_mul_f32 v[16:17], v[16:17], v[30:31]
	v_cvt_pk_bf16_f32 v14, v14, v15
	v_cvt_pk_bf16_f32 v15, v16, v17
	v_lshl_add_u32 v23, v22, 2, s1
	ds_write_b64 v9, v[14:15]
	ds_read_b128 v[14:17], v23
	v_lshl_add_u32 v9, v22, 1, v66
	v_pk_mul_f32 v[22:23], v[26:27], v[8:9] op_sel_hi:[1,0]
	v_pk_mul_f32 v[18:19], v[18:19], v[8:9] op_sel_hi:[1,0]
	v_or_b32_e32 v24, 0x60, v235
	s_waitcnt lgkmcnt(0)
	v_pk_mul_f32 v[14:15], v[22:23], v[14:15]
	v_pk_mul_f32 v[16:17], v[18:19], v[16:17]
	v_cvt_pk_bf16_f32 v14, v14, v15
	v_cvt_pk_bf16_f32 v15, v16, v17
	v_lshl_add_u32 v25, v24, 2, s1
	ds_write_b64 v9, v[14:15]
	ds_read_b128 v[14:17], v25
	v_lshl_add_u32 v9, v24, 1, v66
	v_pk_mul_f32 v[18:19], v[20:21], v[8:9] op_sel_hi:[1,0]
	v_pk_mul_f32 v[2:3], v[2:3], v[8:9] op_sel_hi:[1,0]
	v_or_b32_e32 v22, 0x68, v235
	s_waitcnt lgkmcnt(0)
	v_pk_mul_f32 v[14:15], v[18:19], v[14:15]
	v_pk_mul_f32 v[2:3], v[2:3], v[16:17]
	v_cvt_pk_bf16_f32 v14, v14, v15
	v_cvt_pk_bf16_f32 v15, v2, v3
	v_lshl_add_u32 v23, v22, 2, s1
	ds_write_b64 v9, v[14:15]
	ds_read_b128 v[14:17], v23
	v_lshl_add_u32 v9, v22, 1, v66
	v_pk_mul_f32 v[2:3], v[6:7], v[8:9] op_sel_hi:[1,0]
	v_pk_mul_f32 v[0:1], v[0:1], v[8:9] op_sel_hi:[1,0]
	v_or_b32_e32 v18, 0x70, v235
	s_waitcnt lgkmcnt(0)
	v_pk_mul_f32 v[2:3], v[2:3], v[14:15]
	v_pk_mul_f32 v[0:1], v[0:1], v[16:17]
	v_cvt_pk_bf16_f32 v2, v2, v3
	v_cvt_pk_bf16_f32 v3, v0, v1
	v_lshl_add_u32 v19, v18, 2, s1
	ds_write_b64 v9, v[2:3]
	ds_read_b128 v[0:3], v19
	v_pk_mul_f32 v[4:5], v[4:5], v[8:9] op_sel_hi:[1,0]
	v_or_b32_e32 v6, 0x78, v235
	s_waitcnt lgkmcnt(0)
	v_pk_mul_f32 v[0:1], v[4:5], v[0:1]
	v_pk_mul_f32 v[4:5], v[64:65], v[8:9] op_sel_hi:[1,0]
	v_cvt_pk_bf16_f32 v0, v0, v1
	v_pk_mul_f32 v[2:3], v[4:5], v[2:3]
	v_pk_mul_f32 v[4:5], v[10:11], v[8:9] op_sel_hi:[1,0]
	v_cvt_pk_bf16_f32 v1, v2, v3
	v_lshl_add_u32 v2, v18, 1, v66
	ds_write_b64 v2, v[0:1]
	v_lshl_add_u32 v0, v6, 2, s1
	ds_read_b128 v[0:3], v0
	s_add_u32 s1, s34, s36
	s_addc_u32 s22, s35, s37
	s_add_u32 s34, s1, s3
	s_addc_u32 s35, s22, 0
	s_waitcnt lgkmcnt(0)
	v_pk_mul_f32 v[0:1], v[4:5], v[0:1]
	v_pk_mul_f32 v[4:5], v[12:13], v[8:9] op_sel_hi:[1,0]
	v_cvt_pk_bf16_f32 v0, v0, v1
	v_pk_mul_f32 v[2:3], v[4:5], v[2:3]
	v_lshlrev_b32_e32 v4, 1, v233
	v_cvt_pk_bf16_f32 v1, v2, v3
	v_lshl_add_u32 v2, v6, 1, v66
	v_lshrrev_b32_e32 v6, 4, v234
	ds_write_b64 v2, v[0:1]
	v_mul_u32_u24_e32 v0, 0x110, v6
	s_waitcnt lgkmcnt(0)
	v_add3_u32 v8, s0, v176, v0
	ds_read_b128 v[0:3], v8
	v_mov_b32_e32 v5, v177
	v_lshl_add_u64 v[4:5], s[34:35], 0, v[4:5]
	s_mov_b64 s[0:1], 0x4b00000
	v_lshl_add_u64 v[4:5], v[4:5], 0, s[0:1]
	v_lshlrev_b32_e32 v176, 11, v6
	v_lshl_add_u64 v[6:7], v[4:5], 0, v[176:177]
	s_waitcnt lgkmcnt(0)
	global_store_dwordx4 v[6:7], v[0:3], off
	ds_read_b128 v[0:3], v8 offset:1088
	v_or_b32_e32 v6, 0x2000, v176
	v_mov_b32_e32 v7, v177
	v_lshl_add_u64 v[6:7], v[4:5], 0, v[6:7]
	s_waitcnt lgkmcnt(0)
	global_store_dwordx4 v[6:7], v[0:3], off
	ds_read_b128 v[0:3], v8 offset:2176
	v_or_b32_e32 v6, 0x4000, v176
	v_mov_b32_e32 v7, v177
	v_lshl_add_u64 v[6:7], v[4:5], 0, v[6:7]
	s_waitcnt lgkmcnt(0)
	global_store_dwordx4 v[6:7], v[0:3], off
	ds_read_b128 v[0:3], v8 offset:3264
	v_or_b32_e32 v6, 0x6000, v176
	v_mov_b32_e32 v7, v177
	v_lshl_add_u64 v[6:7], v[4:5], 0, v[6:7]
	s_waitcnt lgkmcnt(0)
	global_store_dwordx4 v[6:7], v[0:3], off
	ds_read_b128 v[0:3], v8 offset:4352
	v_or_b32_e32 v6, 0x8000, v176
	v_mov_b32_e32 v7, v177
	v_lshl_add_u64 v[6:7], v[4:5], 0, v[6:7]
	s_waitcnt lgkmcnt(0)
	global_store_dwordx4 v[6:7], v[0:3], off
	ds_read_b128 v[0:3], v8 offset:5440
	v_or_b32_e32 v6, 0xa000, v176
	v_mov_b32_e32 v7, v177
	v_lshl_add_u64 v[6:7], v[4:5], 0, v[6:7]
	s_waitcnt lgkmcnt(0)
	global_store_dwordx4 v[6:7], v[0:3], off
	ds_read_b128 v[0:3], v8 offset:6528
	v_or_b32_e32 v6, 0xc000, v176
	v_mov_b32_e32 v7, v177
	v_lshl_add_u64 v[6:7], v[4:5], 0, v[6:7]
	v_or_b32_e32 v176, 0xe000, v176
	s_waitcnt lgkmcnt(0)
	global_store_dwordx4 v[6:7], v[0:3], off
	ds_read_b128 v[0:3], v8 offset:7616
	v_lshl_add_u64 v[4:5], v[4:5], 0, v[176:177]
	s_waitcnt lgkmcnt(0)
	global_store_dwordx4 v[4:5], v[0:3], off
	s_branch .LBB0_558

.LBB0_646:
	s_waitcnt lgkmcnt(0)
	v_mov_b64_e32 v[0:1], s[10:11]
	v_mov_b64_e32 v[2:3], s[12:13]
	global_load_dword v0, v[0:1], off sc1
	v_readlane_b32 s8, v252, 44
	global_load_dword v1, v[2:3], off sc1
	v_mov_b64_e32 v[2:3], s[14:15]
	global_load_dword v2, v[2:3], off sc1
	v_readlane_b32 s9, v252, 45
	s_or_b64 s[40:41], s[40:41], exec
	s_or_b64 s[38:39], s[38:39], exec
	s_waitcnt vmcnt(0) lgkmcnt(0)
	v_add_u32_e32 v4, v1, v0
	v_add_u32_e32 v6, v4, v2
	v_mov_b64_e32 v[4:5], s[16:17]
	global_load_dword v3, v[4:5], off sc1
	v_mov_b64_e32 v[4:5], s[18:19]
	global_load_dword v4, v[4:5], off sc1
	s_waitcnt vmcnt(0) lgkmcnt(0)
	v_add_u32_e32 v6, v6, v3
	v_add_u32_e32 v8, v6, v4
	v_mov_b64_e32 v[6:7], s[20:21]
	global_load_dword v5, v[6:7], off sc1
	v_mov_b64_e32 v[6:7], s[8:9]
	global_load_dword v6, v[6:7], off sc1
	v_readlane_b32 s8, v252, 46
	v_readlane_b32 s9, v252, 47
	s_waitcnt vmcnt(0) lgkmcnt(0)
	v_add_u32_e32 v8, v8, v5
	v_add_u32_e32 v10, v8, v6
	v_mov_b64_e32 v[8:9], s[8:9]
	v_readlane_b32 s8, v252, 48
	v_readlane_b32 s9, v252, 49
	global_load_dword v7, v[8:9], off sc1
	s_waitcnt vmcnt(0) lgkmcnt(0)
	v_add_u32_e32 v10, v10, v7
	v_mov_b64_e32 v[8:9], s[8:9]
	global_load_dword v8, v[8:9], off sc1
	v_readlane_b32 s8, v252, 50
	v_readlane_b32 s9, v252, 51
	s_waitcnt vmcnt(0) lgkmcnt(0)
	v_add_u32_e32 v12, v10, v8
	v_mov_b64_e32 v[10:11], s[8:9]
	v_readlane_b32 s8, v252, 52
	v_readlane_b32 s9, v252, 53
	global_load_dword v9, v[10:11], off sc1
	s_waitcnt vmcnt(0) lgkmcnt(0)
	v_add_u32_e32 v12, v12, v9
	v_mov_b64_e32 v[10:11], s[8:9]
	global_load_dword v10, v[10:11], off sc1
	v_readlane_b32 s8, v252, 54
	v_readlane_b32 s9, v252, 55
	s_waitcnt vmcnt(0) lgkmcnt(0)
	v_add_u32_e32 v14, v12, v10
	v_mov_b64_e32 v[12:13], s[54:55]
	global_load_dword v11, v[12:13], off sc1
	v_mov_b64_e32 v[12:13], s[64:65]
	global_load_dword v12, v[12:13], off sc1
	s_waitcnt vmcnt(0) lgkmcnt(0)
	v_add_u32_e32 v14, v14, v11
	v_add_u32_e32 v16, v14, v12
	v_mov_b64_e32 v[14:15], s[66:67]
	global_load_dword v13, v[14:15], off sc1
	v_mov_b64_e32 v[14:15], s[8:9]
	global_load_dword v14, v[14:15], off sc1
	v_readlane_b32 s8, v252, 56
	v_readlane_b32 s9, v252, 57
	s_waitcnt vmcnt(0) lgkmcnt(0)
	v_add_u32_e32 v16, v16, v13
	v_add_u32_e32 v18, v16, v14
	v_mov_b64_e32 v[16:17], s[8:9]
	global_load_dword v15, v[16:17], off sc1
	s_waitcnt vmcnt(0) lgkmcnt(0)
	v_add_u32_e32 v16, v18, v15
	v_cmp_ne_u32_e32 vcc, s6, v16
	s_and_saveexec_b64 s[42:43], vcc
	s_cbranch_execz .LBB0_645
	s_and_b32 s22, s3, 0xff
	s_mov_b64 s[44:45], -1
	s_cmp_eq_u32 s22, 0
	s_mov_b64 s[68:69], -1
	s_mov_b64 s[46:47], -1
	s_sleep 1
	s_cbranch_scc1 .LBB0_649
	s_and_saveexec_b64 s[70:71], s[68:69]
	s_cbranch_execz .LBB0_644
	s_branch .LBB0_652

.LBB0_705:
	s_mul_hi_i32 s39, s37, 0x9000
	s_mul_i32 s37, s37, 0x9000
	s_add_u32 s68, s73, s37
	s_addc_u32 s69, s74, s39
	s_lshl_b32 s37, s80, 8
	s_ashr_i32 s47, s46, 31
	s_or_b32 s37, s37, s76
	s_lshl_b64 s[46:47], s[46:47], 11
	v_lshl_add_u32 v146, v104, 3, s37
	s_add_u32 s46, s30, s46
	v_add_u32_e32 v190, s75, v144
	v_ashrrev_i32_e32 v147, 31, v146
	s_addc_u32 s47, s31, s47
	v_ashrrev_i32_e32 v191, 31, v190
	v_lshl_add_u64 v[104:105], v[146:147], 2, s[68:69]
	v_lshl_add_u64 v[174:175], v[146:147], 1, s[46:47]
	v_lshlrev_b64 v[144:145], 11, v[190:191]
	global_load_dwordx4 v[120:123], v[104:105], off
	global_load_dwordx4 v[116:119], v[104:105], off offset:16
	global_load_dwordx4 v[108:111], v[104:105], off offset:512
	s_nop 0
	global_load_dwordx4 v[104:107], v[104:105], off offset:528
	v_lshl_add_u64 v[186:187], v[174:175], 0, v[144:145]
	global_load_dwordx4 v[202:205], v[186:187], off
	global_load_dwordx4 v[206:209], v[186:187], off offset:256
	v_add_u32_e32 v144, 16, v190
	v_ashrrev_i32_e32 v145, 31, v144
	v_lshlrev_b64 v[144:145], 11, v[144:145]
	v_lshl_add_u64 v[196:197], v[174:175], 0, v[144:145]
	global_load_dwordx4 v[210:213], v[196:197], off
	global_load_dwordx4 v[160:163], v[196:197], off offset:256
	v_add_u32_e32 v144, 32, v190
	v_ashrrev_i32_e32 v145, 31, v144
	v_lshlrev_b64 v[144:145], 11, v[144:145]
	v_lshl_add_u64 v[194:195], v[174:175], 0, v[144:145]
	global_load_dwordx4 v[156:159], v[194:195], off
	global_load_dwordx4 v[152:155], v[194:195], off offset:256
	v_add_u32_e32 v144, 48, v190
	v_ashrrev_i32_e32 v145, 31, v144
	v_lshlrev_b64 v[144:145], 11, v[144:145]
	v_lshl_add_u64 v[192:193], v[174:175], 0, v[144:145]
	global_load_dwordx4 v[148:151], v[192:193], off
	global_load_dwordx4 v[144:147], v[192:193], off offset:256
	s_mov_b64 s[46:47], -1
	s_andn2_b64 vcc, exec, s[40:41]
	s_waitcnt vmcnt(0)
	v_cvt_f32_f16_e32 v214, v202
	v_cvt_f32_f16_sdwa v215, v202 dst_sel:DWORD dst_unused:UNUSED_PAD src0_sel:WORD_1
	v_cvt_f32_f16_e32 v202, v203
	v_cvt_f32_f16_sdwa v203, v203 dst_sel:DWORD dst_unused:UNUSED_PAD src0_sel:WORD_1
	s_waitcnt lgkmcnt(0)
	v_pk_fma_f32 v[140:141], v[140:141], v[120:121], v[214:215]
	v_pk_fma_f32 v[142:143], v[142:143], v[122:123], v[202:203]
	v_cvt_f32_f16_e32 v202, v204
	v_cvt_f32_f16_sdwa v203, v204 dst_sel:DWORD dst_unused:UNUSED_PAD src0_sel:WORD_1
	v_cvt_f32_f16_e32 v204, v205
	v_cvt_f32_f16_sdwa v205, v205 dst_sel:DWORD dst_unused:UNUSED_PAD src0_sel:WORD_1
	v_pk_fma_f32 v[204:205], v[138:139], v[118:119], v[204:205]
	v_pk_fma_f32 v[138:139], v[136:137], v[116:117], v[202:203]
	v_cvt_pk_f16_f32 v136, v140, v141
	v_cvt_pk_f16_f32 v137, v142, v143
	v_cvt_pk_f16_f32 v138, v138, v139
	v_cvt_pk_f16_f32 v139, v204, v205
	global_store_dwordx4 v[186:187], v[136:139], off
	s_nop 1
	v_cvt_f32_f16_e32 v136, v206
	v_cvt_f32_f16_sdwa v137, v206 dst_sel:DWORD dst_unused:UNUSED_PAD src0_sel:WORD_1
	v_cvt_f32_f16_e32 v138, v207
	v_cvt_f32_f16_sdwa v139, v207 dst_sel:DWORD dst_unused:UNUSED_PAD src0_sel:WORD_1
	v_pk_fma_f32 v[132:133], v[132:133], v[108:109], v[136:137]
	v_cvt_f32_f16_e32 v136, v208
	v_pk_fma_f32 v[134:135], v[134:135], v[110:111], v[138:139]
	v_cvt_f32_f16_sdwa v137, v208 dst_sel:DWORD dst_unused:UNUSED_PAD src0_sel:WORD_1
	v_cvt_f32_f16_e32 v138, v209
	v_cvt_f32_f16_sdwa v139, v209 dst_sel:DWORD dst_unused:UNUSED_PAD src0_sel:WORD_1
	v_pk_fma_f32 v[138:139], v[130:131], v[106:107], v[138:139]
	v_pk_fma_f32 v[130:131], v[128:129], v[104:105], v[136:137]
	v_cvt_pk_f16_f32 v128, v132, v133
	v_cvt_pk_f16_f32 v129, v134, v135
	v_cvt_pk_f16_f32 v130, v130, v131
	v_cvt_pk_f16_f32 v131, v138, v139
	global_store_dwordx4 v[186:187], v[128:131], off offset:256
	s_nop 1
	v_cvt_f32_f16_e32 v128, v210
	v_cvt_f32_f16_sdwa v129, v210 dst_sel:DWORD dst_unused:UNUSED_PAD src0_sel:WORD_1
	v_cvt_f32_f16_e32 v130, v211
	v_cvt_f32_f16_sdwa v131, v211 dst_sel:DWORD dst_unused:UNUSED_PAD src0_sel:WORD_1
	v_pk_fma_f32 v[124:125], v[124:125], v[120:121], v[128:129]
	v_cvt_f32_f16_e32 v128, v212
	v_pk_fma_f32 v[126:127], v[126:127], v[122:123], v[130:131]
	v_cvt_f32_f16_sdwa v129, v212 dst_sel:DWORD dst_unused:UNUSED_PAD src0_sel:WORD_1
	v_cvt_f32_f16_e32 v130, v213
	v_cvt_f32_f16_sdwa v131, v213 dst_sel:DWORD dst_unused:UNUSED_PAD src0_sel:WORD_1
	v_pk_fma_f32 v[130:131], v[114:115], v[118:119], v[130:131]
	v_pk_fma_f32 v[114:115], v[112:113], v[116:117], v[128:129]
	v_cvt_pk_f16_f32 v112, v124, v125
	v_cvt_pk_f16_f32 v113, v126, v127
	v_cvt_pk_f16_f32 v114, v114, v115
	v_cvt_pk_f16_f32 v115, v130, v131
	global_store_dwordx4 v[196:197], v[112:115], off
	s_nop 1
	v_cvt_f32_f16_e32 v112, v160
	v_cvt_f32_f16_sdwa v113, v160 dst_sel:DWORD dst_unused:UNUSED_PAD src0_sel:WORD_1
	v_cvt_f32_f16_e32 v114, v161
	v_cvt_f32_f16_sdwa v115, v161 dst_sel:DWORD dst_unused:UNUSED_PAD src0_sel:WORD_1
	v_pk_fma_f32 v[100:101], v[100:101], v[108:109], v[112:113]
	v_cvt_f32_f16_e32 v112, v162
	v_pk_fma_f32 v[102:103], v[102:103], v[110:111], v[114:115]
	v_cvt_f32_f16_sdwa v113, v162 dst_sel:DWORD dst_unused:UNUSED_PAD src0_sel:WORD_1
	v_cvt_f32_f16_e32 v114, v163
	v_cvt_f32_f16_sdwa v115, v163 dst_sel:DWORD dst_unused:UNUSED_PAD src0_sel:WORD_1
	v_pk_fma_f32 v[114:115], v[94:95], v[106:107], v[114:115]
	v_pk_fma_f32 v[94:95], v[92:93], v[104:105], v[112:113]
	v_cvt_pk_f16_f32 v92, v100, v101
	v_cvt_pk_f16_f32 v93, v102, v103
	v_cvt_pk_f16_f32 v94, v94, v95
	v_cvt_pk_f16_f32 v95, v114, v115
	global_store_dwordx4 v[196:197], v[92:95], off offset:256
	s_nop 1
	v_cvt_f32_f16_e32 v92, v156
	v_cvt_f32_f16_sdwa v93, v156 dst_sel:DWORD dst_unused:UNUSED_PAD src0_sel:WORD_1
	v_cvt_f32_f16_e32 v94, v157
	v_cvt_f32_f16_sdwa v95, v157 dst_sel:DWORD dst_unused:UNUSED_PAD src0_sel:WORD_1
	v_pk_fma_f32 v[92:93], v[96:97], v[120:121], v[92:93]
	v_cvt_f32_f16_e32 v96, v158
	v_pk_fma_f32 v[94:95], v[98:99], v[122:123], v[94:95]
	v_cvt_f32_f16_sdwa v97, v158 dst_sel:DWORD dst_unused:UNUSED_PAD src0_sel:WORD_1
	v_cvt_f32_f16_e32 v98, v159
	v_cvt_f32_f16_sdwa v99, v159 dst_sel:DWORD dst_unused:UNUSED_PAD src0_sel:WORD_1
	v_pk_fma_f32 v[98:99], v[90:91], v[118:119], v[98:99]
	v_pk_fma_f32 v[90:91], v[88:89], v[116:117], v[96:97]
	v_cvt_pk_f16_f32 v88, v92, v93
	v_cvt_pk_f16_f32 v89, v94, v95
	v_cvt_pk_f16_f32 v90, v90, v91
	v_cvt_pk_f16_f32 v91, v98, v99
	global_store_dwordx4 v[194:195], v[88:91], off
	s_nop 1
	v_cvt_f32_f16_e32 v88, v152
	v_cvt_f32_f16_sdwa v89, v152 dst_sel:DWORD dst_unused:UNUSED_PAD src0_sel:WORD_1
	v_cvt_f32_f16_e32 v90, v153
	v_cvt_f32_f16_sdwa v91, v153 dst_sel:DWORD dst_unused:UNUSED_PAD src0_sel:WORD_1
	v_pk_fma_f32 v[84:85], v[84:85], v[108:109], v[88:89]
	v_cvt_f32_f16_e32 v88, v154
	v_pk_fma_f32 v[86:87], v[86:87], v[110:111], v[90:91]
	v_cvt_f32_f16_sdwa v89, v154 dst_sel:DWORD dst_unused:UNUSED_PAD src0_sel:WORD_1
	v_cvt_f32_f16_e32 v90, v155
	v_cvt_f32_f16_sdwa v91, v155 dst_sel:DWORD dst_unused:UNUSED_PAD src0_sel:WORD_1
	v_pk_fma_f32 v[90:91], v[78:79], v[106:107], v[90:91]
	v_pk_fma_f32 v[78:79], v[76:77], v[104:105], v[88:89]
	v_cvt_pk_f16_f32 v76, v84, v85
	v_cvt_pk_f16_f32 v77, v86, v87
	v_cvt_pk_f16_f32 v78, v78, v79
	v_cvt_pk_f16_f32 v79, v90, v91
	global_store_dwordx4 v[194:195], v[76:79], off offset:256
	s_nop 1
	v_cvt_f32_f16_e32 v76, v148
	v_cvt_f32_f16_sdwa v77, v148 dst_sel:DWORD dst_unused:UNUSED_PAD src0_sel:WORD_1
	v_cvt_f32_f16_e32 v78, v149
	v_cvt_f32_f16_sdwa v79, v149 dst_sel:DWORD dst_unused:UNUSED_PAD src0_sel:WORD_1
	v_pk_fma_f32 v[76:77], v[80:81], v[120:121], v[76:77]
	v_cvt_f32_f16_e32 v80, v150
	v_pk_fma_f32 v[78:79], v[82:83], v[122:123], v[78:79]
	v_cvt_f32_f16_sdwa v81, v150 dst_sel:DWORD dst_unused:UNUSED_PAD src0_sel:WORD_1
	v_cvt_f32_f16_e32 v82, v151
	v_cvt_f32_f16_sdwa v83, v151 dst_sel:DWORD dst_unused:UNUSED_PAD src0_sel:WORD_1
	v_pk_fma_f32 v[82:83], v[74:75], v[118:119], v[82:83]
	v_pk_fma_f32 v[74:75], v[72:73], v[116:117], v[80:81]
	v_cvt_pk_f16_f32 v72, v76, v77
	v_cvt_pk_f16_f32 v73, v78, v79
	v_cvt_pk_f16_f32 v74, v74, v75
	v_cvt_pk_f16_f32 v75, v82, v83
	global_store_dwordx4 v[192:193], v[72:75], off
	s_nop 1
	v_cvt_f32_f16_e32 v72, v144
	v_cvt_f32_f16_sdwa v73, v144 dst_sel:DWORD dst_unused:UNUSED_PAD src0_sel:WORD_1
	v_cvt_f32_f16_e32 v74, v145
	v_cvt_f32_f16_sdwa v75, v145 dst_sel:DWORD dst_unused:UNUSED_PAD src0_sel:WORD_1
	v_pk_fma_f32 v[68:69], v[68:69], v[108:109], v[72:73]
	v_cvt_f32_f16_e32 v72, v146
	v_pk_fma_f32 v[70:71], v[70:71], v[110:111], v[74:75]
	v_cvt_f32_f16_sdwa v73, v146 dst_sel:DWORD dst_unused:UNUSED_PAD src0_sel:WORD_1
	v_cvt_f32_f16_e32 v74, v147
	v_cvt_f32_f16_sdwa v75, v147 dst_sel:DWORD dst_unused:UNUSED_PAD src0_sel:WORD_1
	v_pk_fma_f32 v[74:75], v[66:67], v[106:107], v[74:75]
	v_pk_fma_f32 v[66:67], v[64:65], v[104:105], v[72:73]
	v_cvt_pk_f16_f32 v64, v68, v69
	v_cvt_pk_f16_f32 v65, v70, v71
	v_cvt_pk_f16_f32 v66, v66, v67
	v_cvt_pk_f16_f32 v67, v74, v75
	global_store_dwordx4 v[192:193], v[64:67], off offset:256
	s_nop 1
	v_add_u32_e32 v64, 0x80, v190
	v_ashrrev_i32_e32 v65, 31, v64
	v_lshlrev_b64 v[64:65], 11, v[64:65]
	v_lshl_add_u64 v[100:101], v[174:175], 0, v[64:65]
	global_load_dwordx4 v[84:87], v[100:101], off
	global_load_dwordx4 v[88:91], v[100:101], off offset:256
	v_add_u32_e32 v64, 0x90, v190
	v_ashrrev_i32_e32 v65, 31, v64
	v_lshlrev_b64 v[64:65], 11, v[64:65]
	v_lshl_add_u64 v[102:103], v[174:175], 0, v[64:65]
	global_load_dwordx4 v[92:95], v[102:103], off
	global_load_dwordx4 v[96:99], v[102:103], off offset:256
	v_add_u32_e32 v64, 0xa0, v190
	v_ashrrev_i32_e32 v65, 31, v64
	v_lshlrev_b64 v[64:65], 11, v[64:65]
	v_lshl_add_u64 v[82:83], v[174:175], 0, v[64:65]
	global_load_dwordx4 v[76:79], v[82:83], off
	global_load_dwordx4 v[72:75], v[82:83], off offset:256
	v_add_u32_e32 v64, 0xb0, v190
	v_ashrrev_i32_e32 v65, 31, v64
	v_lshlrev_b64 v[64:65], 11, v[64:65]
	v_lshl_add_u64 v[80:81], v[174:175], 0, v[64:65]
	global_load_dwordx4 v[68:71], v[80:81], off
	global_load_dwordx4 v[64:67], v[80:81], off offset:256
	s_waitcnt vmcnt(7)
	v_cvt_f32_f16_e32 v112, v84
	v_cvt_f32_f16_sdwa v113, v84 dst_sel:DWORD dst_unused:UNUSED_PAD src0_sel:WORD_1
	v_cvt_f32_f16_e32 v84, v85
	v_cvt_f32_f16_sdwa v85, v85 dst_sel:DWORD dst_unused:UNUSED_PAD src0_sel:WORD_1
	v_pk_fma_f32 v[60:61], v[60:61], v[120:121], v[112:113]
	v_pk_fma_f32 v[62:63], v[62:63], v[122:123], v[84:85]
	v_cvt_f32_f16_e32 v84, v86
	v_cvt_f32_f16_sdwa v85, v86 dst_sel:DWORD dst_unused:UNUSED_PAD src0_sel:WORD_1
	v_cvt_f32_f16_e32 v86, v87
	v_cvt_f32_f16_sdwa v87, v87 dst_sel:DWORD dst_unused:UNUSED_PAD src0_sel:WORD_1
	v_pk_fma_f32 v[86:87], v[58:59], v[118:119], v[86:87]
	v_pk_fma_f32 v[58:59], v[56:57], v[116:117], v[84:85]
	v_cvt_pk_f16_f32 v56, v60, v61
	v_cvt_pk_f16_f32 v57, v62, v63
	v_cvt_pk_f16_f32 v58, v58, v59
	v_cvt_pk_f16_f32 v59, v86, v87
	global_store_dwordx4 v[100:101], v[56:59], off
	s_waitcnt vmcnt(7)
	s_nop 0
	v_cvt_f32_f16_e32 v56, v88
	v_cvt_f32_f16_sdwa v57, v88 dst_sel:DWORD dst_unused:UNUSED_PAD src0_sel:WORD_1
	v_cvt_f32_f16_e32 v58, v89
	v_cvt_f32_f16_sdwa v59, v89 dst_sel:DWORD dst_unused:UNUSED_PAD src0_sel:WORD_1
	v_pk_fma_f32 v[52:53], v[52:53], v[108:109], v[56:57]
	v_cvt_f32_f16_e32 v56, v90
	v_pk_fma_f32 v[54:55], v[54:55], v[110:111], v[58:59]
	v_cvt_f32_f16_sdwa v57, v90 dst_sel:DWORD dst_unused:UNUSED_PAD src0_sel:WORD_1
	v_cvt_f32_f16_e32 v58, v91
	v_cvt_f32_f16_sdwa v59, v91 dst_sel:DWORD dst_unused:UNUSED_PAD src0_sel:WORD_1
	v_pk_fma_f32 v[58:59], v[46:47], v[106:107], v[58:59]
	v_pk_fma_f32 v[46:47], v[44:45], v[104:105], v[56:57]
	v_cvt_pk_f16_f32 v44, v52, v53
	v_cvt_pk_f16_f32 v45, v54, v55
	v_cvt_pk_f16_f32 v46, v46, v47
	v_cvt_pk_f16_f32 v47, v58, v59
	global_store_dwordx4 v[100:101], v[44:47], off offset:256
	s_waitcnt vmcnt(7)
	s_nop 0
	v_cvt_f32_f16_e32 v44, v92
	v_cvt_f32_f16_sdwa v45, v92 dst_sel:DWORD dst_unused:UNUSED_PAD src0_sel:WORD_1
	v_cvt_f32_f16_e32 v46, v93
	v_cvt_f32_f16_sdwa v47, v93 dst_sel:DWORD dst_unused:UNUSED_PAD src0_sel:WORD_1
	v_pk_fma_f32 v[44:45], v[48:49], v[120:121], v[44:45]
	v_cvt_f32_f16_e32 v48, v94
	v_pk_fma_f32 v[46:47], v[50:51], v[122:123], v[46:47]
	v_cvt_f32_f16_sdwa v49, v94 dst_sel:DWORD dst_unused:UNUSED_PAD src0_sel:WORD_1
	v_cvt_f32_f16_e32 v50, v95
	v_cvt_f32_f16_sdwa v51, v95 dst_sel:DWORD dst_unused:UNUSED_PAD src0_sel:WORD_1
	v_pk_fma_f32 v[50:51], v[42:43], v[118:119], v[50:51]
	v_pk_fma_f32 v[42:43], v[40:41], v[116:117], v[48:49]
	v_cvt_pk_f16_f32 v40, v44, v45
	v_cvt_pk_f16_f32 v41, v46, v47
	v_cvt_pk_f16_f32 v42, v42, v43
	v_cvt_pk_f16_f32 v43, v50, v51
	global_store_dwordx4 v[102:103], v[40:43], off
	s_waitcnt vmcnt(7)
	s_nop 0
	v_cvt_f32_f16_e32 v40, v96
	v_cvt_f32_f16_sdwa v41, v96 dst_sel:DWORD dst_unused:UNUSED_PAD src0_sel:WORD_1
	v_cvt_f32_f16_e32 v42, v97
	v_cvt_f32_f16_sdwa v43, v97 dst_sel:DWORD dst_unused:UNUSED_PAD src0_sel:WORD_1
	v_pk_fma_f32 v[36:37], v[36:37], v[108:109], v[40:41]
	v_cvt_f32_f16_e32 v40, v98
	v_pk_fma_f32 v[38:39], v[38:39], v[110:111], v[42:43]
	v_cvt_f32_f16_sdwa v41, v98 dst_sel:DWORD dst_unused:UNUSED_PAD src0_sel:WORD_1
	v_cvt_f32_f16_e32 v42, v99
	v_cvt_f32_f16_sdwa v43, v99 dst_sel:DWORD dst_unused:UNUSED_PAD src0_sel:WORD_1
	v_pk_fma_f32 v[42:43], v[30:31], v[106:107], v[42:43]
	v_pk_fma_f32 v[30:31], v[28:29], v[104:105], v[40:41]
	v_cvt_pk_f16_f32 v28, v36, v37
	v_cvt_pk_f16_f32 v29, v38, v39
	v_cvt_pk_f16_f32 v30, v30, v31
	v_cvt_pk_f16_f32 v31, v42, v43
	global_store_dwordx4 v[102:103], v[28:31], off offset:256
	s_waitcnt vmcnt(7)
	s_nop 0
	v_cvt_f32_f16_e32 v28, v76
	v_cvt_f32_f16_sdwa v29, v76 dst_sel:DWORD dst_unused:UNUSED_PAD src0_sel:WORD_1
	v_cvt_f32_f16_e32 v30, v77
	v_cvt_f32_f16_sdwa v31, v77 dst_sel:DWORD dst_unused:UNUSED_PAD src0_sel:WORD_1
	v_pk_fma_f32 v[28:29], v[32:33], v[120:121], v[28:29]
	v_cvt_f32_f16_e32 v32, v78
	v_pk_fma_f32 v[30:31], v[34:35], v[122:123], v[30:31]
	v_cvt_f32_f16_sdwa v33, v78 dst_sel:DWORD dst_unused:UNUSED_PAD src0_sel:WORD_1
	v_cvt_f32_f16_e32 v34, v79
	v_cvt_f32_f16_sdwa v35, v79 dst_sel:DWORD dst_unused:UNUSED_PAD src0_sel:WORD_1
	v_pk_fma_f32 v[34:35], v[26:27], v[118:119], v[34:35]
	v_pk_fma_f32 v[26:27], v[24:25], v[116:117], v[32:33]
	v_cvt_pk_f16_f32 v24, v28, v29
	v_cvt_pk_f16_f32 v25, v30, v31
	v_cvt_pk_f16_f32 v26, v26, v27
	v_cvt_pk_f16_f32 v27, v34, v35
	global_store_dwordx4 v[82:83], v[24:27], off
	s_waitcnt vmcnt(7)
	s_nop 0
	v_cvt_f32_f16_e32 v24, v72
	v_cvt_f32_f16_sdwa v25, v72 dst_sel:DWORD dst_unused:UNUSED_PAD src0_sel:WORD_1
	v_cvt_f32_f16_e32 v26, v73
	v_cvt_f32_f16_sdwa v27, v73 dst_sel:DWORD dst_unused:UNUSED_PAD src0_sel:WORD_1
	v_pk_fma_f32 v[20:21], v[20:21], v[108:109], v[24:25]
	v_cvt_f32_f16_e32 v24, v74
	v_pk_fma_f32 v[22:23], v[22:23], v[110:111], v[26:27]
	v_cvt_f32_f16_sdwa v25, v74 dst_sel:DWORD dst_unused:UNUSED_PAD src0_sel:WORD_1
	v_cvt_f32_f16_e32 v26, v75
	v_cvt_f32_f16_sdwa v27, v75 dst_sel:DWORD dst_unused:UNUSED_PAD src0_sel:WORD_1
	v_pk_fma_f32 v[26:27], v[14:15], v[106:107], v[26:27]
	v_pk_fma_f32 v[14:15], v[12:13], v[104:105], v[24:25]
	v_cvt_pk_f16_f32 v12, v20, v21
	v_cvt_pk_f16_f32 v13, v22, v23
	v_cvt_pk_f16_f32 v14, v14, v15
	v_cvt_pk_f16_f32 v15, v26, v27
	global_store_dwordx4 v[82:83], v[12:15], off offset:256
	s_waitcnt vmcnt(7)
	s_nop 0
	v_cvt_f32_f16_e32 v12, v68
	v_cvt_f32_f16_sdwa v13, v68 dst_sel:DWORD dst_unused:UNUSED_PAD src0_sel:WORD_1
	v_cvt_f32_f16_e32 v14, v69
	v_cvt_f32_f16_sdwa v15, v69 dst_sel:DWORD dst_unused:UNUSED_PAD src0_sel:WORD_1
	v_pk_fma_f32 v[12:13], v[16:17], v[120:121], v[12:13]
	v_cvt_f32_f16_e32 v16, v70
	v_pk_fma_f32 v[14:15], v[18:19], v[122:123], v[14:15]
	v_cvt_f32_f16_sdwa v17, v70 dst_sel:DWORD dst_unused:UNUSED_PAD src0_sel:WORD_1
	v_cvt_f32_f16_e32 v18, v71
	v_cvt_f32_f16_sdwa v19, v71 dst_sel:DWORD dst_unused:UNUSED_PAD src0_sel:WORD_1
	v_pk_fma_f32 v[18:19], v[10:11], v[118:119], v[18:19]
	v_pk_fma_f32 v[10:11], v[8:9], v[116:117], v[16:17]
	v_cvt_pk_f16_f32 v8, v12, v13
	v_cvt_pk_f16_f32 v9, v14, v15
	v_cvt_pk_f16_f32 v10, v10, v11
	v_cvt_pk_f16_f32 v11, v18, v19
	global_store_dwordx4 v[80:81], v[8:11], off
	s_waitcnt vmcnt(7)
	s_nop 0
	v_cvt_f32_f16_e32 v8, v64
	v_cvt_f32_f16_sdwa v9, v64 dst_sel:DWORD dst_unused:UNUSED_PAD src0_sel:WORD_1
	v_cvt_f32_f16_e32 v10, v65
	v_cvt_f32_f16_sdwa v11, v65 dst_sel:DWORD dst_unused:UNUSED_PAD src0_sel:WORD_1
	v_pk_fma_f32 v[4:5], v[4:5], v[108:109], v[8:9]
	v_cvt_f32_f16_e32 v8, v66
	v_pk_fma_f32 v[6:7], v[6:7], v[110:111], v[10:11]
	v_cvt_f32_f16_sdwa v9, v66 dst_sel:DWORD dst_unused:UNUSED_PAD src0_sel:WORD_1
	v_cvt_f32_f16_e32 v10, v67
	v_cvt_f32_f16_sdwa v11, v67 dst_sel:DWORD dst_unused:UNUSED_PAD src0_sel:WORD_1
	v_pk_fma_f32 v[10:11], v[2:3], v[106:107], v[10:11]
	v_pk_fma_f32 v[2:3], v[0:1], v[104:105], v[8:9]
	v_cvt_pk_f16_f32 v0, v4, v5
	v_cvt_pk_f16_f32 v1, v6, v7
	v_cvt_pk_f16_f32 v2, v2, v3
	v_cvt_pk_f16_f32 v3, v10, v11
	global_store_dwordx4 v[80:81], v[0:3], off offset:256
	s_cbranch_vccnz .LBB0_690
	s_andn2_b64 vcc, exec, s[0:1]
	s_cbranch_vccnz .LBB0_689
	s_barrier
	s_branch .LBB0_689

.LBB0_760:
	v_readlane_b32 s8, v254, 54
	v_readlane_b32 s9, v254, 55
	s_add_u32 s43, s36, s8
	s_addc_u32 s48, s37, s9
	v_lshl_add_u64 v[0:1], v[12:13], 0, s[8:9]
	v_add_co_u32_e32 v0, vcc, s23, v0
	s_lshl_b64 s[40:41], s[52:53], 11
	s_nop 0
	v_addc_co_u32_e32 v1, vcc, 0, v1, vcc
	global_load_dwordx2 v[38:39], v[0:1], off
	s_add_u32 s22, s44, s40
	s_addc_u32 s40, s45, s41
	s_and_b64 s[0:1], s[0:1], exec
	s_cselect_b32 s1, s48, s40
	s_cselect_b32 s0, s43, s22
	v_lshlrev_b32_e32 v176, 3, v16
	v_lshl_add_u64 v[2:3], s[0:1], 0, v[176:177]
	s_mul_i32 s1, s42, 0x9000
	s_mul_hi_i32 s0, s42, 0x9000
	s_add_u32 s42, s3, s1
	s_addc_u32 s43, s46, s0
	s_add_u32 s40, s42, 0x1000
	s_addc_u32 s41, s43, 0
	v_lshlrev_b32_e32 v176, 4, v16
	v_mov_b32_e32 v23, v177
	v_lshl_add_u64 v[12:13], v[12:13], 0, s[62:63]
	s_waitcnt vmcnt(0)
	global_store_dwordx2 v[2:3], v[38:39], off
	global_load_dwordx2 v[40:41], v[0:1], off offset:512
	v_cvt_f32_f16_sdwa v43, v38 dst_sel:DWORD dst_unused:UNUSED_PAD src0_sel:WORD_1
	v_cvt_f32_f16_e32 v42, v38
	s_waitcnt vmcnt(0)
	global_store_dwordx2 v[2:3], v[40:41], off offset:512
	global_load_dwordx2 v[34:35], v[0:1], off offset:1024
	v_cvt_f32_f16_e32 v36, v40
	v_cvt_f32_f16_sdwa v37, v40 dst_sel:DWORD dst_unused:UNUSED_PAD src0_sel:WORD_1
	v_cvt_f32_f16_e32 v40, v39
	v_mov_b32_e32 v38, v37
	s_waitcnt vmcnt(0)
	global_store_dwordx2 v[2:3], v[34:35], off offset:1024
	global_load_dwordx2 v[0:1], v[0:1], off offset:1536
	v_cvt_f32_f16_e32 v28, v35
	v_cvt_f32_f16_sdwa v29, v35 dst_sel:DWORD dst_unused:UNUSED_PAD src0_sel:WORD_1
	v_cvt_f32_f16_e32 v30, v34
	v_cvt_f32_f16_sdwa v31, v34 dst_sel:DWORD dst_unused:UNUSED_PAD src0_sel:WORD_1
	v_cvt_f32_f16_e32 v34, v41
	v_cvt_f32_f16_sdwa v35, v41 dst_sel:DWORD dst_unused:UNUSED_PAD src0_sel:WORD_1
	v_cvt_f32_f16_sdwa v41, v39 dst_sel:DWORD dst_unused:UNUSED_PAD src0_sel:WORD_1
	v_mul_f32_e32 v32, v31, v31
	v_mov_b32_e32 v39, v35
	v_pk_mul_f32 v[38:39], v[38:39], v[38:39]
	s_waitcnt vmcnt(0)
	global_store_dwordx2 v[2:3], v[0:1], off offset:1536
	v_cvt_f32_f16_e32 v24, v1
	v_cvt_f32_f16_sdwa v25, v1 dst_sel:DWORD dst_unused:UNUSED_PAD src0_sel:WORD_1
	v_cvt_f32_f16_e32 v26, v0
	v_cvt_f32_f16_sdwa v27, v0 dst_sel:DWORD dst_unused:UNUSED_PAD src0_sel:WORD_1
	v_mov_b32_e32 v2, v43
	v_mov_b32_e32 v3, v41
	v_mov_b32_e32 v0, v42
	v_mov_b32_e32 v1, v40
	v_pk_mul_f32 v[2:3], v[2:3], v[2:3]
	v_pk_mul_f32 v[50:51], v[26:27], v[26:27]
	v_pk_fma_f32 v[0:1], v[0:1], v[0:1], v[2:3]
	v_mov_b32_e32 v2, v36
	v_mov_b32_e32 v3, v34
	v_pk_fma_f32 v[2:3], v[2:3], v[2:3], v[38:39]
	v_pk_fma_f32 v[38:39], v[30:31], v[30:31], v[32:33] op_sel_hi:[1,1,0]
	v_mul_f32_e32 v32, v29, v29
	v_pk_add_f32 v[0:1], v[0:1], v[0:1] op_sel:[0,1] op_sel_hi:[1,0]
	v_pk_add_f32 v[2:3], v[2:3], v[2:3] op_sel:[0,1] op_sel_hi:[1,0]
	v_pk_fma_f32 v[44:45], v[28:29], v[28:29], v[32:33] op_sel_hi:[1,1,0]
	v_pk_mul_f32 v[52:53], v[24:25], v[24:25]
	v_mov_b32_e32 v1, v50
	v_mov_b32_e32 v3, v51
	v_mov_b32_e32 v39, v52
	v_mov_b32_e32 v45, v53
	v_pk_add_f32 v[0:1], v[0:1], v[2:3]
	v_pk_add_f32 v[2:3], v[38:39], v[44:45]
	v_lshl_add_u64 v[38:39], s[40:41], 0, v[176:177]
	v_pk_add_f32 v[0:1], v[0:1], v[2:3]
	global_load_dwordx4 v[50:53], v[38:39], off
	v_add_f32_e32 v0, v0, v1
	ds_bpermute_b32 v1, v17, v0
	v_lshl_add_u64 v[38:39], s[42:43], 0, v[176:177]
	global_load_dwordx4 v[54:57], v[38:39], off
	v_lshl_add_u64 v[44:45], v[14:15], 0, s[8:9]
	v_lshl_add_u64 v[14:15], v[14:15], 0, s[62:63]
	s_waitcnt lgkmcnt(0)
	v_add_f32_e32 v0, v0, v1
	ds_bpermute_b32 v1, v33, v0
	s_waitcnt lgkmcnt(0)
	v_add_f32_e32 v0, v0, v1
	ds_bpermute_b32 v1, v46, v0
	s_waitcnt lgkmcnt(0)
	v_add_f32_e32 v0, v0, v1
	ds_bpermute_b32 v1, v47, v0
	s_waitcnt lgkmcnt(0)
	v_add_f32_e32 v0, v0, v1
	ds_bpermute_b32 v1, v48, v0
	s_waitcnt lgkmcnt(0)
	v_add_f32_e32 v0, v0, v1
	ds_bpermute_b32 v1, v49, v0
	s_waitcnt lgkmcnt(0)
	v_add_f32_e32 v0, v0, v1
	v_fmamk_f32 v0, v0, 0x3a800000, v228
	v_cmp_gt_f32_e32 vcc, s89, v0
	v_mul_f32_e32 v1, 0x4f800000, v0
	s_nop 0
	v_cndmask_b32_e32 v0, v0, v1, vcc
	v_sqrt_f32_e32 v1, v0
	s_nop 0
	v_add_u32_e32 v2, -1, v1
	v_fma_f32 v3, -v2, v1, v0
	v_cmp_ge_f32_e64 s[0:1], 0, v3
	v_add_u32_e32 v3, 1, v1
	s_nop 0
	v_cndmask_b32_e64 v2, v1, v2, s[0:1]
	v_fma_f32 v1, -v3, v1, v0
	v_cmp_lt_f32_e64 s[0:1], 0, v1
	s_nop 1
	v_cndmask_b32_e64 v1, v2, v3, s[0:1]
	v_mul_f32_e32 v2, 0x37800000, v1
	v_cndmask_b32_e32 v1, v1, v2, vcc
	v_cmp_class_f32_e32 vcc, v0, v229
	s_nop 1
	v_cndmask_b32_e32 v0, v1, v0, vcc
	v_div_scale_f32 v1, s[0:1], v0, v0, 1.0
	v_rcp_f32_e32 v2, v1
	v_readlane_b32 s0, v255, 1
	s_add_i32 s47, s47, s0
	s_add_u32 s36, s36, s62
	v_fma_f32 v3, -v1, v2, 1.0
	v_fmac_f32_e32 v2, v3, v2
	v_div_scale_f32 v3, vcc, 1.0, v0, 1.0
	v_mul_f32_e32 v19, v3, v2
	v_fma_f32 v21, -v1, v19, v3
	v_fmac_f32_e32 v19, v21, v2
	v_fma_f32 v1, -v1, v19, v3
	v_div_fmas_f32 v1, v1, v2, v19
	v_div_fixup_f32 v32, v1, v0, 1.0
	global_load_dwordx4 v[0:3], v[4:5], off
	v_pk_mul_f32 v[40:41], v[40:41], v[32:33] op_sel_hi:[1,0]
	v_pk_mul_f32 v[42:43], v[42:43], v[32:33] op_sel_hi:[1,0]
	v_mov_b32_e32 v19, v177
	v_pk_mul_f32 v[34:35], v[34:35], v[32:33] op_sel_hi:[1,0]
	v_pk_mul_f32 v[36:37], v[36:37], v[32:33] op_sel_hi:[1,0]
	v_mov_b32_e32 v21, v177
	v_pk_mul_f32 v[28:29], v[28:29], v[32:33] op_sel_hi:[1,0]
	v_pk_mul_f32 v[30:31], v[30:31], v[32:33] op_sel_hi:[1,0]
	v_pk_mul_f32 v[24:25], v[24:25], v[32:33] op_sel_hi:[1,0]
	v_pk_mul_f32 v[26:27], v[26:27], v[32:33] op_sel_hi:[1,0]
	s_addc_u32 s37, s37, s63
	s_cmpk_gt_i32 s47, 0x7fff
	v_readlane_b32 s1, v255, 2
	s_waitcnt vmcnt(0)
	v_pk_mul_f32 v[0:1], v[0:1], v[42:43]
	v_pk_mul_f32 v[2:3], v[2:3], v[40:41]
	v_pk_add_f32 v[40:41], v[52:53], 1.0 op_sel_hi:[1,0]
	v_pk_add_f32 v[42:43], v[50:51], 1.0 op_sel_hi:[1,0]
	v_pk_fma_f32 v[2:3], v[40:41], v[2:3], v[56:57]
	v_pk_fma_f32 v[0:1], v[42:43], v[0:1], v[54:55]
	v_add_co_u32_e32 v40, vcc, s49, v44
	v_cvt_pk_bf16_f32 v0, v0, v1
	v_cvt_pk_bf16_f32 v1, v2, v3
	v_addc_co_u32_e32 v41, vcc, 0, v45, vcc
	global_store_dwordx2 v[40:41], v[0:1], off
	global_load_dwordx4 v[0:3], v[6:7], off
	v_lshl_add_u64 v[42:43], s[40:41], 0, v[18:19]
	global_load_dwordx4 v[42:45], v[42:43], off
	s_nop 0
	global_load_dwordx4 v[50:53], v[38:39], off offset:1024
	s_waitcnt vmcnt(0)
	v_pk_mul_f32 v[0:1], v[0:1], v[36:37]
	v_pk_mul_f32 v[2:3], v[2:3], v[34:35]
	s_waitcnt lgkmcnt(0)
	v_pk_add_f32 v[34:35], v[44:45], 1.0 op_sel_hi:[1,0]
	v_pk_add_f32 v[36:37], v[42:43], 1.0 op_sel_hi:[1,0]
	v_pk_fma_f32 v[2:3], v[34:35], v[2:3], v[52:53]
	v_pk_fma_f32 v[0:1], v[36:37], v[0:1], v[50:51]
	v_lshl_add_u64 v[34:35], s[40:41], 0, v[20:21]
	v_cvt_pk_bf16_f32 v0, v0, v1
	v_cvt_pk_bf16_f32 v1, v2, v3
	global_store_dwordx2 v[40:41], v[0:1], off offset:512
	global_load_dwordx4 v[0:3], v[8:9], off
	s_nop 0
	global_load_dwordx4 v[34:37], v[34:35], off
	s_nop 0
	global_load_dwordx4 v[42:45], v[38:39], off offset:2048
	s_waitcnt vmcnt(0)
	v_pk_mul_f32 v[0:1], v[0:1], v[30:31]
	v_pk_mul_f32 v[2:3], v[2:3], v[28:29]
	s_waitcnt lgkmcnt(0)
	v_pk_add_f32 v[28:29], v[36:37], 1.0 op_sel_hi:[1,0]
	v_pk_add_f32 v[30:31], v[34:35], 1.0 op_sel_hi:[1,0]
	v_pk_fma_f32 v[2:3], v[28:29], v[2:3], v[44:45]
	v_pk_fma_f32 v[0:1], v[30:31], v[0:1], v[42:43]
	v_lshl_add_u64 v[28:29], s[40:41], 0, v[22:23]
	v_cvt_pk_bf16_f32 v0, v0, v1
	v_cvt_pk_bf16_f32 v1, v2, v3
	global_store_dwordx2 v[40:41], v[0:1], off offset:1024
	global_load_dwordx4 v[0:3], v[10:11], off
	s_nop 0
	global_load_dwordx4 v[28:31], v[28:29], off
	s_nop 0
	global_load_dwordx4 v[34:37], v[38:39], off offset:3072
	s_waitcnt vmcnt(0)
	v_pk_mul_f32 v[0:1], v[0:1], v[26:27]
	v_pk_mul_f32 v[2:3], v[2:3], v[24:25]
	s_waitcnt lgkmcnt(0)
	v_pk_add_f32 v[24:25], v[30:31], 1.0 op_sel_hi:[1,0]
	v_pk_add_f32 v[26:27], v[28:29], 1.0 op_sel_hi:[1,0]
	v_pk_fma_f32 v[2:3], v[2:3], v[24:25], v[36:37]
	v_pk_fma_f32 v[0:1], v[0:1], v[26:27], v[34:35]
	s_nop 0
	v_cvt_pk_bf16_f32 v0, v0, v1
	v_cvt_pk_bf16_f32 v1, v2, v3
	global_store_dwordx2 v[40:41], v[0:1], off offset:1536
	s_cbranch_scc1 .LBB0_765

.LBB0_768:
	v_readlane_b32 s8, v254, 38
	v_readlane_b32 s9, v254, 39
	s_andn2_b64 vcc, exec, s[8:9]
	s_mov_b64 s[42:43], 0x2000
	s_cbranch_vccnz .LBB0_771
	s_mul_hi_i32 s1, s0, 0x9000
	s_mul_i32 s0, s0, 0x9000
	v_readlane_b32 s3, v255, 34
	s_add_u32 s3, s3, s0
	v_readlane_b32 s0, v255, 35
	s_addc_u32 s22, s0, s1
	s_add_u32 s0, s3, 0x6000
	s_addc_u32 s1, s22, 0
	s_add_u32 s36, s3, 0x7000
	s_addc_u32 s37, s22, 0
	v_lshlrev_b32_e32 v176, 4, v16
	v_readlane_b32 s8, v254, 17
	v_lshl_add_u64 v[0:1], s[36:37], 0, v[176:177]
	v_readlane_b32 s9, v254, 18
	global_load_dwordx4 v[8:11], v[0:1], off
	v_lshl_add_u64 v[0:1], s[0:1], 0, v[176:177]
	global_load_dwordx4 v[0:3], v[0:1], off
	v_lshlrev_b32_e32 v17, 2, v16
	v_xor_b32_e32 v68, 4, v17
	global_load_dwordx4 v[4:7], v176, s[8:9]
	v_xor_b32_e32 v69, 8, v17
	v_xor_b32_e32 v70, 16, v17
	v_xor_b32_e32 v71, 32, v17
	v_xor_b32_e32 v72, 64, v17
	v_xor_b32_e32 v73, 0x80, v17
	s_mov_b32 s3, 0
	s_waitcnt vmcnt(0) lgkmcnt(0)
	v_pk_add_f32 v[8:9], v[8:9], 1.0 op_sel_hi:[1,0]
	v_pk_add_f32 v[10:11], v[10:11], 1.0 op_sel_hi:[1,0]
	v_pk_mul_f32 v[20:21], v[4:5], v[8:9]
	v_or_b32_e32 v4, 0x400, v176
	v_mov_b32_e32 v5, v177
	v_pk_mul_f32 v[18:19], v[6:7], v[10:11]
	v_lshl_add_u64 v[6:7], s[36:37], 0, v[4:5]
	global_load_dwordx4 v[12:15], v[6:7], off
	global_load_dwordx4 v[8:11], v4, s[8:9]
	v_lshl_add_u64 v[4:5], s[0:1], 0, v[4:5]
	global_load_dwordx4 v[4:7], v[4:5], off
	s_waitcnt vmcnt(0) lgkmcnt(0)
	v_pk_add_f32 v[12:13], v[12:13], 1.0 op_sel_hi:[1,0]
	v_pk_add_f32 v[14:15], v[14:15], 1.0 op_sel_hi:[1,0]
	v_pk_mul_f32 v[24:25], v[8:9], v[12:13]
	v_or_b32_e32 v8, 0x800, v176
	v_mov_b32_e32 v9, v177
	v_pk_mul_f32 v[22:23], v[10:11], v[14:15]
	v_lshl_add_u64 v[10:11], s[36:37], 0, v[8:9]
	global_load_dwordx4 v[26:29], v[10:11], off
	global_load_dwordx4 v[12:15], v8, s[8:9]
	v_or_b32_e32 v176, 0xc00, v176
	global_load_dwordx4 v[32:35], v176, s[8:9]
	v_lshl_add_u64 v[8:9], s[0:1], 0, v[8:9]
	global_load_dwordx4 v[8:11], v[8:9], off
	s_waitcnt vmcnt(0) lgkmcnt(0)
	v_pk_add_f32 v[28:29], v[28:29], 1.0 op_sel_hi:[1,0]
	v_pk_add_f32 v[30:31], v[26:27], 1.0 op_sel_hi:[1,0]
	v_pk_mul_f32 v[26:27], v[14:15], v[28:29]
	v_pk_mul_f32 v[28:29], v[12:13], v[30:31]
	v_lshl_add_u64 v[12:13], s[36:37], 0, v[176:177]
	global_load_dwordx4 v[36:39], v[12:13], off
	v_lshl_add_u64 v[12:13], s[0:1], 0, v[176:177]
	global_load_dwordx4 v[12:15], v[12:13], off
	v_lshlrev_b32_e32 v176, 3, v16
	s_mov_b64 s[0:1], 0x4b00000
	v_lshl_add_u64 v[40:41], s[92:93], 0, v[176:177]
	s_waitcnt vmcnt(0) lgkmcnt(0)
	v_pk_add_f32 v[36:37], v[36:37], 1.0 op_sel_hi:[1,0]
	v_pk_add_f32 v[30:31], v[38:39], 1.0 op_sel_hi:[1,0]
	v_pk_mul_f32 v[32:33], v[32:33], v[36:37]
	v_lshl_add_u64 v[36:37], s[34:35], 0, v[176:177]
	v_pk_mul_f32 v[30:31], v[34:35], v[30:31]
	v_lshl_add_u64 v[34:35], s[30:31], 0, v[176:177]
	v_lshl_add_u64 v[38:39], v[36:37], 0, s[0:1]
	v_lshlrev_b32_e32 v176, 3, v16
	s_mov_b64 s[34:35], s[38:39]
.LBB0_770:
	v_lshl_add_u64 v[16:17], v[40:41], 0, s[72:73]
	v_add_co_u32_e32 v56, vcc, s23, v16
	s_add_i32 s0, s60, s3
	s_nop 0
	v_addc_co_u32_e32 v57, vcc, 0, v17, vcc
	global_load_dwordx2 v[58:59], v[56:57], off
	s_add_u32 s1, s34, s72
	s_addc_u32 s40, s35, s73
	s_add_i32 s52, s0, 0xffffc000
	s_lshl_b64 s[36:37], s[52:53], 11
	s_add_u32 s22, s44, s36
	s_addc_u32 s36, s45, s37
	s_cmpk_lt_i32 s0, 0x4000
	s_cselect_b32 s37, s40, s36
	s_cselect_b32 s36, s1, s22
	v_lshl_add_u64 v[60:61], s[36:37], 0, v[176:177]
	s_add_i32 s40, s0, 1
	s_ashr_i32 s41, s40, 31
	s_lshl_b64 s[36:37], s[40:41], 11
	v_lshl_add_u64 v[66:67], v[34:35], 0, s[36:37]
	s_add_u32 s1, s38, s36
	s_addc_u32 s40, s39, s37
	s_add_i32 s52, s0, 0xffffc001
	v_lshl_add_u64 v[44:45], v[38:39], 0, s[36:37]
	s_lshl_b64 s[36:37], s[52:53], 11
	s_add_u32 s22, s44, s36
	s_addc_u32 s36, s45, s37
	s_cmpk_lt_i32 s0, 0x3fff
	s_cselect_b32 s37, s40, s36
	s_cselect_b32 s36, s1, s22
	v_lshl_add_u64 v[64:65], s[36:37], 0, v[176:177]
	s_add_i32 s40, s0, 2
	s_ashr_i32 s41, s40, 31
	s_lshl_b64 s[36:37], s[40:41], 11
	s_add_u32 s1, s38, s36
	s_addc_u32 s40, s39, s37
	s_add_i32 s52, s0, 0xffffc002
	v_lshl_add_u64 v[54:55], v[34:35], 0, s[36:37]
	v_lshl_add_u64 v[46:47], v[38:39], 0, s[36:37]
	s_lshl_b64 s[36:37], s[52:53], 11
	s_add_u32 s22, s44, s36
	s_addc_u32 s36, s45, s37
	v_lshl_add_u64 v[42:43], v[36:37], 0, s[72:73]
	s_cmpk_lt_i32 s0, 0x3ffe
	v_add_co_u32_e32 v42, vcc, s49, v42
	s_cselect_b32 s37, s40, s36
	s_cselect_b32 s36, s1, s22
	s_add_i32 s40, s0, 3
	v_addc_co_u32_e32 v43, vcc, 0, v43, vcc
	s_ashr_i32 s41, s40, 31
	v_lshl_add_u64 v[52:53], s[36:37], 0, v[176:177]
	s_lshl_b64 s[36:37], s[40:41], 11
	s_add_u32 s40, s38, s36
	s_addc_u32 s1, s39, s37
	s_add_i32 s52, s0, 0xffffc003
	v_lshl_add_u64 v[50:51], v[34:35], 0, s[36:37]
	v_lshl_add_u64 v[16:17], v[38:39], 0, s[36:37]
	s_lshl_b64 s[36:37], s[52:53], 11
	s_add_u32 s22, s44, s36
	s_addc_u32 s36, s45, s37
	s_cmpk_lt_i32 s0, 0x3ffd
	s_cselect_b32 s1, s1, s36
	s_cselect_b32 s0, s40, s22
	v_lshl_add_u64 v[48:49], s[0:1], 0, v[176:177]
	s_add_i32 s3, s3, 4
	s_add_u32 s34, s34, 0x2000
	s_addc_u32 s35, s35, 0
	v_lshl_add_u64 v[36:37], v[36:37], 0, s[42:43]
	v_lshl_add_u64 v[40:41], v[40:41], 0, s[42:43]
	s_cmp_ge_i32 s3, s7
	s_waitcnt vmcnt(0)
	global_store_dwordx2 v[60:61], v[58:59], off
	global_load_dwordx2 v[62:63], v[56:57], off offset:512
	v_cvt_f32_f16_sdwa v75, v58 dst_sel:DWORD dst_unused:UNUSED_PAD src0_sel:WORD_1
	v_cvt_f32_f16_sdwa v77, v59 dst_sel:DWORD dst_unused:UNUSED_PAD src0_sel:WORD_1
	v_cvt_f32_f16_e32 v74, v58
	v_cvt_f32_f16_e32 v76, v59
	v_mov_b32_e32 v80, v75
	v_mov_b32_e32 v81, v77
	v_mov_b32_e32 v58, v74
	v_mov_b32_e32 v59, v76
	v_pk_mul_f32 v[80:81], v[80:81], v[80:81]
	s_waitcnt vmcnt(0)
	global_store_dwordx2 v[60:61], v[62:63], off offset:512
	global_load_dwordx2 v[78:79], v[56:57], off offset:1024
	v_pk_fma_f32 v[58:59], v[58:59], v[58:59], v[80:81]
	v_cvt_f32_f16_e32 v80, v62
	v_cvt_f32_f16_sdwa v81, v62 dst_sel:DWORD dst_unused:UNUSED_PAD src0_sel:WORD_1
	v_cvt_f32_f16_e32 v62, v63
	v_cvt_f32_f16_sdwa v63, v63 dst_sel:DWORD dst_unused:UNUSED_PAD src0_sel:WORD_1
	v_mov_b32_e32 v82, v80
	v_mov_b32_e32 v84, v81
	v_mov_b32_e32 v83, v62
	v_mov_b32_e32 v85, v63
	v_pk_mul_f32 v[84:85], v[84:85], v[84:85]
	v_pk_add_f32 v[58:59], v[58:59], v[58:59] op_sel:[0,1] op_sel_hi:[1,0]
	v_pk_fma_f32 v[82:83], v[82:83], v[82:83], v[84:85]
	s_waitcnt vmcnt(0)
	global_store_dwordx2 v[60:61], v[78:79], off offset:1024
	global_load_dwordx2 v[56:57], v[56:57], off offset:1536
	v_cvt_f32_f16_sdwa v85, v78 dst_sel:DWORD dst_unused:UNUSED_PAD src0_sel:WORD_1
	v_cvt_f32_f16_sdwa v87, v79 dst_sel:DWORD dst_unused:UNUSED_PAD src0_sel:WORD_1
	v_cvt_f32_f16_e32 v84, v78
	v_cvt_f32_f16_e32 v86, v79
	v_mul_f32_e32 v78, v85, v85
	v_mul_f32_e32 v88, v87, v87
	v_pk_add_f32 v[82:83], v[82:83], v[82:83] op_sel:[0,1] op_sel_hi:[1,0]
	v_pk_fma_f32 v[78:79], v[84:85], v[84:85], v[78:79] op_sel_hi:[1,1,0]
	v_pk_fma_f32 v[88:89], v[86:87], v[86:87], v[88:89] op_sel_hi:[1,1,0]
	s_waitcnt vmcnt(0)
	global_store_dwordx2 v[60:61], v[56:57], off offset:1536
	global_load_dwordx2 v[94:95], v[66:67], off
	v_cvt_f32_f16_e32 v90, v56
	v_cvt_f32_f16_sdwa v91, v56 dst_sel:DWORD dst_unused:UNUSED_PAD src0_sel:WORD_1
	v_cvt_f32_f16_e32 v92, v57
	v_cvt_f32_f16_sdwa v93, v57 dst_sel:DWORD dst_unused:UNUSED_PAD src0_sel:WORD_1
	v_pk_mul_f32 v[56:57], v[90:91], v[90:91]
	s_nop 0
	v_mov_b32_e32 v59, v56
	v_pk_mul_f32 v[60:61], v[92:93], v[92:93]
	v_mov_b32_e32 v83, v57
	v_mov_b32_e32 v79, v60
	v_mov_b32_e32 v89, v61
	v_pk_add_f32 v[56:57], v[58:59], v[82:83]
	v_pk_add_f32 v[58:59], v[78:79], v[88:89]
	s_waitcnt vmcnt(0)
	global_store_dwordx2 v[64:65], v[94:95], off
	global_load_dwordx2 v[78:79], v[66:67], off offset:512
	v_pk_add_f32 v[56:57], v[56:57], v[58:59]
	s_waitcnt vmcnt(0)
	global_store_dwordx2 v[64:65], v[78:79], off offset:512
	v_add_f32_e32 v56, v56, v57
	ds_bpermute_b32 v57, v68, v56
	s_waitcnt lgkmcnt(0)
	v_add_f32_e32 v56, v56, v57
	ds_bpermute_b32 v57, v69, v56
	s_waitcnt lgkmcnt(0)
	v_add_f32_e32 v56, v56, v57
	ds_bpermute_b32 v57, v70, v56
	s_waitcnt lgkmcnt(0)
	v_add_f32_e32 v56, v56, v57
	ds_bpermute_b32 v57, v71, v56
	s_waitcnt lgkmcnt(0)
	v_add_f32_e32 v56, v56, v57
	ds_bpermute_b32 v57, v72, v56
	s_waitcnt lgkmcnt(0)
	v_add_f32_e32 v56, v56, v57
	ds_bpermute_b32 v57, v73, v56
	s_waitcnt lgkmcnt(0)
	v_add_f32_e32 v56, v56, v57
	v_fmamk_f32 v56, v56, 0x3a800000, v228
	v_mul_f32_e32 v57, 0x4f800000, v56
	v_cmp_gt_f32_e32 vcc, s89, v56
	s_nop 1
	v_cndmask_b32_e32 v56, v56, v57, vcc
	v_sqrt_f32_e32 v57, v56
	s_nop 0
	v_add_u32_e32 v58, -1, v57
	v_add_u32_e32 v59, 1, v57
	v_fma_f32 v60, -v58, v57, v56
	v_fma_f32 v61, -v59, v57, v56
	v_cmp_ge_f32_e64 s[0:1], 0, v60
	s_nop 1
	v_cndmask_b32_e64 v57, v57, v58, s[0:1]
	v_cmp_lt_f32_e64 s[0:1], 0, v61
	s_nop 1
	v_cndmask_b32_e64 v57, v57, v59, s[0:1]
	v_mul_f32_e32 v58, 0x37800000, v57
	v_cndmask_b32_e32 v57, v57, v58, vcc
	v_cmp_class_f32_e32 vcc, v56, v229
	s_nop 1
	v_cndmask_b32_e32 v56, v57, v56, vcc
	v_div_scale_f32 v57, s[0:1], v56, v56, 1.0
	v_rcp_f32_e32 v59, v57
	v_div_scale_f32 v58, vcc, 1.0, v56, 1.0
	v_fma_f32 v60, -v57, v59, 1.0
	v_fmac_f32_e32 v59, v60, v59
	v_mul_f32_e32 v60, v58, v59
	v_fma_f32 v61, -v57, v60, v58
	v_fmac_f32_e32 v60, v61, v59
	v_fma_f32 v57, -v57, v60, v58
	v_div_fmas_f32 v57, v57, v59, v60
	v_div_fixup_f32 v56, v57, v56, 1.0
	v_pk_mul_f32 v[58:59], v[74:75], v[56:57] op_sel_hi:[1,0]
	v_pk_mul_f32 v[74:75], v[80:81], v[56:57] op_sel_hi:[1,0]
	v_pk_mul_f32 v[80:81], v[86:87], v[56:57] op_sel_hi:[1,0]
	global_load_dwordx2 v[86:87], v[66:67], off offset:1024
	v_pk_mul_f32 v[60:61], v[76:77], v[56:57] op_sel_hi:[1,0]
	v_pk_mul_f32 v[76:77], v[84:85], v[56:57] op_sel_hi:[1,0]
	v_pk_mul_f32 v[62:63], v[62:63], v[56:57] op_sel_hi:[1,0]
	v_pk_mul_f32 v[82:83], v[90:91], v[56:57] op_sel_hi:[1,0]
	v_pk_mul_f32 v[56:57], v[92:93], v[56:57] op_sel_hi:[1,0]
	v_pk_fma_f32 v[60:61], v[18:19], v[60:61], v[2:3]
	v_pk_fma_f32 v[58:59], v[20:21], v[58:59], v[0:1]
	v_pk_fma_f32 v[74:75], v[24:25], v[74:75], v[4:5]
	v_pk_fma_f32 v[76:77], v[28:29], v[76:77], v[8:9]
	v_pk_fma_f32 v[84:85], v[30:31], v[56:57], v[14:15]
	v_cvt_pk_bf16_f32 v56, v58, v59
	v_cvt_pk_bf16_f32 v57, v60, v61
	v_cvt_pk_bf16_f32 v58, v74, v75
	v_cvt_pk_bf16_f32 v60, v76, v77
	v_cvt_f32_f16_sdwa v75, v94 dst_sel:DWORD dst_unused:UNUSED_PAD src0_sel:WORD_1
	v_cvt_f32_f16_sdwa v77, v95 dst_sel:DWORD dst_unused:UNUSED_PAD src0_sel:WORD_1
	v_cvt_f32_f16_e32 v74, v94
	v_cvt_f32_f16_e32 v76, v95
	v_pk_fma_f32 v[62:63], v[22:23], v[62:63], v[6:7]
	v_pk_fma_f32 v[82:83], v[32:33], v[82:83], v[12:13]
	v_pk_fma_f32 v[80:81], v[26:27], v[80:81], v[10:11]
	v_cvt_pk_bf16_f32 v59, v62, v63
	v_cvt_pk_bf16_f32 v62, v82, v83
	v_mov_b32_e32 v82, v75
	v_mov_b32_e32 v83, v77
	v_cvt_pk_bf16_f32 v61, v80, v81
	v_mov_b32_e32 v80, v74
	v_mov_b32_e32 v81, v76
	v_pk_mul_f32 v[82:83], v[82:83], v[82:83]
	v_cvt_pk_bf16_f32 v63, v84, v85
	v_pk_fma_f32 v[80:81], v[80:81], v[80:81], v[82:83]
	v_cvt_f32_f16_sdwa v83, v78 dst_sel:DWORD dst_unused:UNUSED_PAD src0_sel:WORD_1
	v_cvt_f32_f16_sdwa v85, v79 dst_sel:DWORD dst_unused:UNUSED_PAD src0_sel:WORD_1
	v_cvt_f32_f16_e32 v82, v78
	v_cvt_f32_f16_e32 v84, v79
	v_mov_b32_e32 v88, v83
	v_mov_b32_e32 v89, v85
	v_mov_b32_e32 v78, v82
	v_mov_b32_e32 v79, v84
	v_pk_mul_f32 v[88:89], v[88:89], v[88:89]
	v_pk_add_f32 v[80:81], v[80:81], v[80:81] op_sel:[0,1] op_sel_hi:[1,0]
	v_pk_fma_f32 v[78:79], v[78:79], v[78:79], v[88:89]
	s_waitcnt vmcnt(0)
	global_store_dwordx2 v[64:65], v[86:87], off offset:1024
	global_load_dwordx2 v[66:67], v[66:67], off offset:1536
	v_cvt_f32_f16_sdwa v89, v86 dst_sel:DWORD dst_unused:UNUSED_PAD src0_sel:WORD_1
	v_cvt_f32_f16_sdwa v91, v87 dst_sel:DWORD dst_unused:UNUSED_PAD src0_sel:WORD_1
	v_cvt_f32_f16_e32 v88, v86
	v_cvt_f32_f16_e32 v90, v87
	v_mul_f32_e32 v86, v89, v89
	v_mul_f32_e32 v92, v91, v91
	v_pk_add_f32 v[78:79], v[78:79], v[78:79] op_sel:[0,1] op_sel_hi:[1,0]
	v_pk_fma_f32 v[86:87], v[88:89], v[88:89], v[86:87] op_sel_hi:[1,1,0]
	v_pk_fma_f32 v[92:93], v[90:91], v[90:91], v[92:93] op_sel_hi:[1,1,0]
	s_waitcnt vmcnt(0)
	global_store_dwordx2 v[64:65], v[66:67], off offset:1536
	global_load_dwordx2 v[64:65], v[54:55], off
	v_cvt_f32_f16_e32 v94, v66
	v_cvt_f32_f16_sdwa v95, v66 dst_sel:DWORD dst_unused:UNUSED_PAD src0_sel:WORD_1
	v_cvt_f32_f16_e32 v96, v67
	v_cvt_f32_f16_sdwa v97, v67 dst_sel:DWORD dst_unused:UNUSED_PAD src0_sel:WORD_1
	v_pk_mul_f32 v[66:67], v[94:95], v[94:95]
	s_nop 0
	v_mov_b32_e32 v81, v66
	v_pk_mul_f32 v[98:99], v[96:97], v[96:97]
	v_mov_b32_e32 v79, v67
	v_mov_b32_e32 v87, v98
	v_mov_b32_e32 v93, v99
	v_pk_add_f32 v[66:67], v[80:81], v[78:79]
	v_pk_add_f32 v[78:79], v[86:87], v[92:93]
	s_waitcnt vmcnt(0)
	global_store_dwordx2 v[52:53], v[64:65], off
	v_pk_add_f32 v[66:67], v[66:67], v[78:79]
	s_nop 0
	v_add_f32_e32 v66, v66, v67
	ds_bpermute_b32 v67, v68, v66
	s_waitcnt lgkmcnt(0)
	v_add_f32_e32 v66, v66, v67
	ds_bpermute_b32 v67, v69, v66
	s_waitcnt lgkmcnt(0)
	v_add_f32_e32 v66, v66, v67
	ds_bpermute_b32 v67, v70, v66
	s_waitcnt lgkmcnt(0)
	v_add_f32_e32 v66, v66, v67
	ds_bpermute_b32 v67, v71, v66
	s_waitcnt lgkmcnt(0)
	v_add_f32_e32 v66, v66, v67
	ds_bpermute_b32 v67, v72, v66
	s_waitcnt lgkmcnt(0)
	v_add_f32_e32 v66, v66, v67
	ds_bpermute_b32 v67, v73, v66
	s_waitcnt lgkmcnt(0)
	v_add_f32_e32 v66, v66, v67
	v_fmamk_f32 v66, v66, 0x3a800000, v228
	v_mul_f32_e32 v67, 0x4f800000, v66
	v_cmp_gt_f32_e32 vcc, s89, v66
	s_nop 1
	v_cndmask_b32_e32 v66, v66, v67, vcc
	v_sqrt_f32_e32 v67, v66
	s_nop 0
	v_add_u32_e32 v78, -1, v67
	v_add_u32_e32 v79, 1, v67
	v_fma_f32 v80, -v78, v67, v66
	v_fma_f32 v81, -v79, v67, v66
	v_cmp_ge_f32_e64 s[0:1], 0, v80
	s_nop 1
	v_cndmask_b32_e64 v67, v67, v78, s[0:1]
	v_cmp_lt_f32_e64 s[0:1], 0, v81
	s_nop 1
	v_cndmask_b32_e64 v67, v67, v79, s[0:1]
	v_mul_f32_e32 v78, 0x37800000, v67
	v_cndmask_b32_e32 v67, v67, v78, vcc
	v_cmp_class_f32_e32 vcc, v66, v229
	s_nop 1
	v_cndmask_b32_e32 v78, v67, v66, vcc
	global_load_dwordx2 v[66:67], v[54:55], off offset:512
	v_div_scale_f32 v79, s[0:1], v78, v78, 1.0
	v_rcp_f32_e32 v81, v79
	v_div_scale_f32 v80, vcc, 1.0, v78, 1.0
	v_fma_f32 v86, -v79, v81, 1.0
	v_fmac_f32_e32 v81, v86, v81
	v_mul_f32_e32 v86, v80, v81
	v_fma_f32 v87, -v79, v86, v80
	v_fmac_f32_e32 v86, v87, v81
	v_fma_f32 v79, -v79, v86, v80
	v_div_fmas_f32 v79, v79, v81, v86
	v_div_fixup_f32 v78, v79, v78, 1.0
	v_pk_mul_f32 v[86:87], v[90:91], v[78:79] op_sel_hi:[1,0]
	v_pk_mul_f32 v[74:75], v[74:75], v[78:79] op_sel_hi:[1,0]
	v_pk_mul_f32 v[76:77], v[76:77], v[78:79] op_sel_hi:[1,0]
	v_pk_mul_f32 v[80:81], v[82:83], v[78:79] op_sel_hi:[1,0]
	v_pk_mul_f32 v[82:83], v[84:85], v[78:79] op_sel_hi:[1,0]
	v_pk_mul_f32 v[84:85], v[88:89], v[78:79] op_sel_hi:[1,0]
	v_pk_mul_f32 v[88:89], v[94:95], v[78:79] op_sel_hi:[1,0]
	v_pk_mul_f32 v[78:79], v[96:97], v[78:79] op_sel_hi:[1,0]
	v_pk_fma_f32 v[76:77], v[18:19], v[76:77], v[2:3]
	v_pk_fma_f32 v[74:75], v[20:21], v[74:75], v[0:1]
	v_pk_fma_f32 v[82:83], v[22:23], v[82:83], v[6:7]
	v_pk_fma_f32 v[80:81], v[24:25], v[80:81], v[4:5]
	v_pk_fma_f32 v[84:85], v[28:29], v[84:85], v[8:9]
	v_pk_fma_f32 v[78:79], v[30:31], v[78:79], v[14:15]
	v_cvt_pk_bf16_f32 v74, v74, v75
	v_cvt_pk_bf16_f32 v75, v76, v77
	v_cvt_pk_bf16_f32 v76, v80, v81
	v_cvt_pk_bf16_f32 v77, v82, v83
	v_cvt_pk_bf16_f32 v80, v84, v85
	v_cvt_pk_bf16_f32 v83, v78, v79
	v_cvt_f32_f16_sdwa v79, v64 dst_sel:DWORD dst_unused:UNUSED_PAD src0_sel:WORD_1
	v_cvt_f32_f16_sdwa v85, v65 dst_sel:DWORD dst_unused:UNUSED_PAD src0_sel:WORD_1
	v_cvt_f32_f16_e32 v78, v64
	v_cvt_f32_f16_e32 v84, v65
	v_pk_fma_f32 v[86:87], v[26:27], v[86:87], v[10:11]
	v_pk_fma_f32 v[88:89], v[32:33], v[88:89], v[12:13]
	v_cvt_pk_bf16_f32 v81, v86, v87
	v_mov_b32_e32 v86, v79
	v_mov_b32_e32 v87, v85
	v_mov_b32_e32 v64, v78
	v_mov_b32_e32 v65, v84
	v_pk_mul_f32 v[86:87], v[86:87], v[86:87]
	v_cvt_pk_bf16_f32 v82, v88, v89
	v_pk_fma_f32 v[64:65], v[64:65], v[64:65], v[86:87]
	s_waitcnt vmcnt(0)
	global_store_dwordx2 v[52:53], v[66:67], off offset:512
	global_load_dwordx2 v[90:91], v[54:55], off offset:1024
	v_cvt_f32_f16_sdwa v87, v66 dst_sel:DWORD dst_unused:UNUSED_PAD src0_sel:WORD_1
	v_cvt_f32_f16_sdwa v89, v67 dst_sel:DWORD dst_unused:UNUSED_PAD src0_sel:WORD_1
	v_cvt_f32_f16_e32 v86, v66
	v_cvt_f32_f16_e32 v88, v67
	v_mov_b32_e32 v92, v87
	v_mov_b32_e32 v93, v89
	v_mov_b32_e32 v66, v86
	v_mov_b32_e32 v67, v88
	v_pk_mul_f32 v[92:93], v[92:93], v[92:93]
	v_pk_add_f32 v[64:65], v[64:65], v[64:65] op_sel:[0,1] op_sel_hi:[1,0]
	v_pk_fma_f32 v[66:67], v[66:67], v[66:67], v[92:93]
	s_waitcnt vmcnt(0)
	global_store_dwordx2 v[52:53], v[90:91], off offset:1024
	global_load_dwordx2 v[54:55], v[54:55], off offset:1536
	v_cvt_f32_f16_sdwa v93, v90 dst_sel:DWORD dst_unused:UNUSED_PAD src0_sel:WORD_1
	v_cvt_f32_f16_sdwa v95, v91 dst_sel:DWORD dst_unused:UNUSED_PAD src0_sel:WORD_1
	v_cvt_f32_f16_e32 v92, v90
	v_cvt_f32_f16_e32 v94, v91
	v_mul_f32_e32 v90, v93, v93
	v_mul_f32_e32 v96, v95, v95
	v_pk_add_f32 v[66:67], v[66:67], v[66:67] op_sel:[0,1] op_sel_hi:[1,0]
	v_pk_fma_f32 v[90:91], v[92:93], v[92:93], v[90:91] op_sel_hi:[1,1,0]
	v_pk_fma_f32 v[96:97], v[94:95], v[94:95], v[96:97] op_sel_hi:[1,1,0]
	s_waitcnt vmcnt(0)
	global_store_dwordx2 v[52:53], v[54:55], off offset:1536
	global_load_dwordx2 v[52:53], v[50:51], off
	v_cvt_f32_f16_e32 v98, v54
	v_cvt_f32_f16_sdwa v99, v54 dst_sel:DWORD dst_unused:UNUSED_PAD src0_sel:WORD_1
	v_cvt_f32_f16_e32 v100, v55
	v_cvt_f32_f16_sdwa v101, v55 dst_sel:DWORD dst_unused:UNUSED_PAD src0_sel:WORD_1
	v_pk_mul_f32 v[54:55], v[98:99], v[98:99]
	s_nop 0
	v_mov_b32_e32 v65, v54
	v_pk_mul_f32 v[102:103], v[100:101], v[100:101]
	v_mov_b32_e32 v67, v55
	v_mov_b32_e32 v91, v102
	v_mov_b32_e32 v97, v103
	v_pk_add_f32 v[54:55], v[64:65], v[66:67]
	v_pk_add_f32 v[64:65], v[90:91], v[96:97]
	s_waitcnt vmcnt(0)
	global_store_dwordx2 v[48:49], v[52:53], off
	v_pk_add_f32 v[54:55], v[54:55], v[64:65]
	s_nop 0
	v_add_f32_e32 v54, v54, v55
	ds_bpermute_b32 v55, v68, v54
	s_waitcnt lgkmcnt(0)
	v_add_f32_e32 v54, v54, v55
	ds_bpermute_b32 v55, v69, v54
	s_waitcnt lgkmcnt(0)
	v_add_f32_e32 v54, v54, v55
	ds_bpermute_b32 v55, v70, v54
	s_waitcnt lgkmcnt(0)
	v_add_f32_e32 v54, v54, v55
	ds_bpermute_b32 v55, v71, v54
	s_waitcnt lgkmcnt(0)
	v_add_f32_e32 v54, v54, v55
	ds_bpermute_b32 v55, v72, v54
	s_waitcnt lgkmcnt(0)
	v_add_f32_e32 v54, v54, v55
	ds_bpermute_b32 v55, v73, v54
	s_waitcnt lgkmcnt(0)
	v_add_f32_e32 v54, v54, v55
	v_fmamk_f32 v54, v54, 0x3a800000, v228
	v_mul_f32_e32 v55, 0x4f800000, v54
	v_cmp_gt_f32_e32 vcc, s89, v54
	s_nop 1
	v_cndmask_b32_e32 v64, v54, v55, vcc
	global_load_dwordx2 v[54:55], v[50:51], off offset:512
	v_sqrt_f32_e32 v65, v64
	s_waitcnt vmcnt(0)
	global_store_dwordx2 v[48:49], v[54:55], off offset:512
	v_add_u32_e32 v66, -1, v65
	v_add_u32_e32 v67, 1, v65
	v_fma_f32 v90, -v66, v65, v64
	v_fma_f32 v91, -v67, v65, v64
	v_cmp_ge_f32_e64 s[0:1], 0, v90
	s_nop 1
	v_cndmask_b32_e64 v65, v65, v66, s[0:1]
	v_cmp_lt_f32_e64 s[0:1], 0, v91
	s_nop 1
	v_cndmask_b32_e64 v65, v65, v67, s[0:1]
	v_mul_f32_e32 v66, 0x37800000, v65
	v_cndmask_b32_e32 v65, v65, v66, vcc
	v_cmp_class_f32_e32 vcc, v64, v229
	s_nop 1
	v_cndmask_b32_e32 v64, v65, v64, vcc
	v_div_scale_f32 v65, s[0:1], v64, v64, 1.0
	v_rcp_f32_e32 v67, v65
	v_div_scale_f32 v66, vcc, 1.0, v64, 1.0
	v_fma_f32 v90, -v65, v67, 1.0
	v_fmac_f32_e32 v67, v90, v67
	v_mul_f32_e32 v90, v66, v67
	v_fma_f32 v91, -v65, v90, v66
	v_fmac_f32_e32 v90, v91, v67
	v_fma_f32 v65, -v65, v90, v66
	v_div_fmas_f32 v65, v65, v67, v90
	global_load_dwordx2 v[66:67], v[50:51], off offset:1024
	v_div_fixup_f32 v64, v65, v64, 1.0
	v_pk_mul_f32 v[78:79], v[78:79], v[64:65] op_sel_hi:[1,0]
	v_pk_mul_f32 v[84:85], v[84:85], v[64:65] op_sel_hi:[1,0]
	v_pk_mul_f32 v[86:87], v[86:87], v[64:65] op_sel_hi:[1,0]
	v_pk_mul_f32 v[88:89], v[88:89], v[64:65] op_sel_hi:[1,0]
	v_pk_mul_f32 v[90:91], v[92:93], v[64:65] op_sel_hi:[1,0]
	v_pk_mul_f32 v[92:93], v[94:95], v[64:65] op_sel_hi:[1,0]
	v_pk_mul_f32 v[94:95], v[98:99], v[64:65] op_sel_hi:[1,0]
	v_pk_mul_f32 v[64:65], v[100:101], v[64:65] op_sel_hi:[1,0]
	v_pk_fma_f32 v[84:85], v[18:19], v[84:85], v[2:3]
	v_pk_fma_f32 v[78:79], v[20:21], v[78:79], v[0:1]
	v_pk_fma_f32 v[88:89], v[22:23], v[88:89], v[6:7]
	v_pk_fma_f32 v[64:65], v[30:31], v[64:65], v[14:15]
	v_cvt_pk_bf16_f32 v78, v78, v79
	v_cvt_pk_bf16_f32 v79, v84, v85
	v_cvt_pk_bf16_f32 v85, v88, v89
	v_cvt_pk_bf16_f32 v89, v64, v65
	v_cvt_f32_f16_e32 v64, v52
	v_cvt_f32_f16_sdwa v65, v52 dst_sel:DWORD dst_unused:UNUSED_PAD src0_sel:WORD_1
	v_cvt_f32_f16_e32 v52, v53
	v_cvt_f32_f16_sdwa v53, v53 dst_sel:DWORD dst_unused:UNUSED_PAD src0_sel:WORD_1
	v_pk_fma_f32 v[86:87], v[24:25], v[86:87], v[4:5]
	v_pk_fma_f32 v[92:93], v[26:27], v[92:93], v[10:11]
	v_pk_fma_f32 v[90:91], v[28:29], v[90:91], v[8:9]
	v_cvt_pk_bf16_f32 v84, v86, v87
	v_cvt_pk_bf16_f32 v87, v92, v93
	v_mov_b32_e32 v92, v65
	v_mov_b32_e32 v93, v53
	v_pk_fma_f32 v[94:95], v[32:33], v[94:95], v[12:13]
	v_cvt_pk_bf16_f32 v86, v90, v91
	v_mov_b32_e32 v90, v64
	v_mov_b32_e32 v91, v52
	v_pk_mul_f32 v[92:93], v[92:93], v[92:93]
	v_cvt_pk_bf16_f32 v88, v94, v95
	v_pk_fma_f32 v[90:91], v[90:91], v[90:91], v[92:93]
	v_cvt_f32_f16_sdwa v93, v54 dst_sel:DWORD dst_unused:UNUSED_PAD src0_sel:WORD_1
	v_cvt_f32_f16_sdwa v95, v55 dst_sel:DWORD dst_unused:UNUSED_PAD src0_sel:WORD_1
	v_cvt_f32_f16_e32 v92, v54
	v_cvt_f32_f16_e32 v94, v55
	v_mov_b32_e32 v96, v93
	v_mov_b32_e32 v97, v95
	v_mov_b32_e32 v54, v92
	v_mov_b32_e32 v55, v94
	v_pk_mul_f32 v[96:97], v[96:97], v[96:97]
	v_pk_add_f32 v[90:91], v[90:91], v[90:91] op_sel:[0,1] op_sel_hi:[1,0]
	v_pk_fma_f32 v[54:55], v[54:55], v[54:55], v[96:97]
	s_waitcnt vmcnt(0)
	global_store_dwordx2 v[48:49], v[66:67], off offset:1024
	global_load_dwordx2 v[50:51], v[50:51], off offset:1536
	v_cvt_f32_f16_sdwa v97, v66 dst_sel:DWORD dst_unused:UNUSED_PAD src0_sel:WORD_1
	v_cvt_f32_f16_sdwa v99, v67 dst_sel:DWORD dst_unused:UNUSED_PAD src0_sel:WORD_1
	v_cvt_f32_f16_e32 v96, v66
	v_cvt_f32_f16_e32 v98, v67
	v_mul_f32_e32 v66, v97, v97
	v_mul_f32_e32 v100, v99, v99
	v_pk_add_f32 v[54:55], v[54:55], v[54:55] op_sel:[0,1] op_sel_hi:[1,0]
	v_pk_fma_f32 v[66:67], v[96:97], v[96:97], v[66:67] op_sel_hi:[1,1,0]
	v_pk_fma_f32 v[100:101], v[98:99], v[98:99], v[100:101] op_sel_hi:[1,1,0]
	s_waitcnt vmcnt(0)
	global_store_dwordx2 v[48:49], v[50:51], off offset:1536
	global_store_dwordx2 v[42:43], v[56:57], off
	global_store_dwordx2 v[42:43], v[58:59], off offset:512
	global_store_dwordx2 v[42:43], v[60:61], off offset:1024
	global_store_dwordx2 v[42:43], v[62:63], off offset:1536
	global_store_dwordx2 v[44:45], v[74:75], off
	global_store_dwordx2 v[44:45], v[76:77], off offset:512
	global_store_dwordx2 v[44:45], v[80:81], off offset:1024
	global_store_dwordx2 v[44:45], v[82:83], off offset:1536
	global_store_dwordx2 v[46:47], v[78:79], off
	global_store_dwordx2 v[46:47], v[84:85], off offset:512
	global_store_dwordx2 v[46:47], v[86:87], off offset:1024
	global_store_dwordx2 v[46:47], v[88:89], off offset:1536
	v_cvt_f32_f16_e32 v102, v50
	v_cvt_f32_f16_sdwa v103, v50 dst_sel:DWORD dst_unused:UNUSED_PAD src0_sel:WORD_1
	v_cvt_f32_f16_e32 v104, v51
	v_cvt_f32_f16_sdwa v105, v51 dst_sel:DWORD dst_unused:UNUSED_PAD src0_sel:WORD_1
	v_pk_mul_f32 v[42:43], v[102:103], v[102:103]
	s_nop 0
	v_mov_b32_e32 v91, v42
	v_pk_mul_f32 v[44:45], v[104:105], v[104:105]
	v_mov_b32_e32 v55, v43
	v_mov_b32_e32 v67, v44
	v_mov_b32_e32 v101, v45
	v_pk_add_f32 v[42:43], v[90:91], v[54:55]
	v_pk_add_f32 v[44:45], v[66:67], v[100:101]
	s_nop 0
	v_pk_add_f32 v[42:43], v[42:43], v[44:45]
	s_nop 0
	v_add_f32_e32 v42, v42, v43
	ds_bpermute_b32 v43, v68, v42
	s_waitcnt lgkmcnt(0)
	v_add_f32_e32 v42, v42, v43
	ds_bpermute_b32 v43, v69, v42
	s_waitcnt lgkmcnt(0)
	v_add_f32_e32 v42, v42, v43
	ds_bpermute_b32 v43, v70, v42
	s_waitcnt lgkmcnt(0)
	v_add_f32_e32 v42, v42, v43
	ds_bpermute_b32 v43, v71, v42
	s_waitcnt lgkmcnt(0)
	v_add_f32_e32 v42, v42, v43
	ds_bpermute_b32 v43, v72, v42
	s_waitcnt lgkmcnt(0)
	v_add_f32_e32 v42, v42, v43
	ds_bpermute_b32 v43, v73, v42
	s_waitcnt lgkmcnt(0)
	v_add_f32_e32 v42, v42, v43
	v_fmamk_f32 v42, v42, 0x3a800000, v228
	v_mul_f32_e32 v43, 0x4f800000, v42
	v_cmp_gt_f32_e32 vcc, s89, v42
	s_nop 1
	v_cndmask_b32_e32 v42, v42, v43, vcc
	v_sqrt_f32_e32 v43, v42
	s_nop 0
	v_add_u32_e32 v44, -1, v43
	v_add_u32_e32 v45, 1, v43
	v_fma_f32 v46, -v44, v43, v42
	v_fma_f32 v47, -v45, v43, v42
	v_cmp_ge_f32_e64 s[0:1], 0, v46
	s_nop 1
	v_cndmask_b32_e64 v43, v43, v44, s[0:1]
	v_cmp_lt_f32_e64 s[0:1], 0, v47
	s_nop 1
	v_cndmask_b32_e64 v43, v43, v45, s[0:1]
	v_mul_f32_e32 v44, 0x37800000, v43
	v_cndmask_b32_e32 v43, v43, v44, vcc
	v_cmp_class_f32_e32 vcc, v42, v229
	s_nop 1
	v_cndmask_b32_e32 v42, v43, v42, vcc
	v_div_scale_f32 v43, s[0:1], v42, v42, 1.0
	v_rcp_f32_e32 v45, v43
	v_div_scale_f32 v44, vcc, 1.0, v42, 1.0
	v_fma_f32 v46, -v43, v45, 1.0
	v_fmac_f32_e32 v45, v46, v45
	v_mul_f32_e32 v46, v44, v45
	v_fma_f32 v47, -v43, v46, v44
	v_fmac_f32_e32 v46, v47, v45
	v_fma_f32 v43, -v43, v46, v44
	v_div_fmas_f32 v43, v43, v45, v46
	v_div_fixup_f32 v42, v43, v42, 1.0
	v_pk_mul_f32 v[44:45], v[64:65], v[42:43] op_sel_hi:[1,0]
	v_pk_mul_f32 v[46:47], v[52:53], v[42:43] op_sel_hi:[1,0]
	v_pk_mul_f32 v[48:49], v[92:93], v[42:43] op_sel_hi:[1,0]
	v_pk_mul_f32 v[50:51], v[94:95], v[42:43] op_sel_hi:[1,0]
	v_pk_mul_f32 v[52:53], v[96:97], v[42:43] op_sel_hi:[1,0]
	v_pk_mul_f32 v[54:55], v[98:99], v[42:43] op_sel_hi:[1,0]
	v_pk_mul_f32 v[56:57], v[102:103], v[42:43] op_sel_hi:[1,0]
	v_pk_mul_f32 v[42:43], v[104:105], v[42:43] op_sel_hi:[1,0]
	v_pk_fma_f32 v[46:47], v[18:19], v[46:47], v[2:3]
	v_pk_fma_f32 v[44:45], v[20:21], v[44:45], v[0:1]
	v_pk_fma_f32 v[50:51], v[22:23], v[50:51], v[6:7]
	v_pk_fma_f32 v[48:49], v[24:25], v[48:49], v[4:5]
	v_pk_fma_f32 v[54:55], v[26:27], v[54:55], v[10:11]
	v_pk_fma_f32 v[52:53], v[28:29], v[52:53], v[8:9]
	v_pk_fma_f32 v[42:43], v[30:31], v[42:43], v[14:15]
	v_pk_fma_f32 v[56:57], v[32:33], v[56:57], v[12:13]
	v_cvt_pk_bf16_f32 v44, v44, v45
	v_cvt_pk_bf16_f32 v45, v46, v47
	v_cvt_pk_bf16_f32 v46, v48, v49
	v_cvt_pk_bf16_f32 v47, v50, v51
	v_cvt_pk_bf16_f32 v48, v52, v53
	v_cvt_pk_bf16_f32 v49, v54, v55
	v_cvt_pk_bf16_f32 v50, v56, v57
	v_cvt_pk_bf16_f32 v51, v42, v43
	global_store_dwordx2 v[16:17], v[44:45], off
	global_store_dwordx2 v[16:17], v[46:47], off offset:512
	global_store_dwordx2 v[16:17], v[48:49], off offset:1024
	global_store_dwordx2 v[16:17], v[50:51], off offset:1536
	s_cbranch_scc0 .LBB0_770

.LBB0_779:
	v_lshl_add_u64 v[0:1], s[38:39], 0, v[6:7]
	v_add_co_u32_e32 v0, vcc, 0x4000000, v0
	s_mul_i32 s1, s40, 0x9000
	s_nop 0
	v_addc_co_u32_e32 v1, vcc, 0, v1, vcc
	global_load_dwordx2 v[28:29], v[0:1], off
	global_load_dwordx2 v[2:3], v[0:1], off offset:512
	global_load_dwordx2 v[24:25], v[0:1], off offset:1024
	s_nop 0
	global_load_dwordx2 v[0:1], v[0:1], off offset:1536
	s_mul_hi_i32 s0, s40, 0x9000
	s_add_u32 s42, s3, s1
	s_addc_u32 s43, s22, s0
	s_add_u32 s40, s42, 0x1000
	s_addc_u32 s41, s43, 0
	s_waitcnt vmcnt(0)
	v_cvt_f32_f16_e32 v26, v2
	v_cvt_f32_f16_e32 v18, v25
	v_cvt_f32_f16_e32 v14, v1
	v_cvt_f32_f16_sdwa v15, v1 dst_sel:DWORD dst_unused:UNUSED_PAD src0_sel:WORD_1
	v_cvt_f32_f16_sdwa v19, v25 dst_sel:DWORD dst_unused:UNUSED_PAD src0_sel:WORD_1
	v_cvt_f32_f16_e32 v20, v24
	v_cvt_f32_f16_sdwa v21, v24 dst_sel:DWORD dst_unused:UNUSED_PAD src0_sel:WORD_1
	v_cvt_f32_f16_e32 v24, v3
	v_cvt_f32_f16_sdwa v25, v3 dst_sel:DWORD dst_unused:UNUSED_PAD src0_sel:WORD_1
	v_cvt_f32_f16_sdwa v1, v29 dst_sel:DWORD dst_unused:UNUSED_PAD src0_sel:WORD_1
	v_cvt_f32_f16_sdwa v3, v28 dst_sel:DWORD dst_unused:UNUSED_PAD src0_sel:WORD_1
	v_cvt_f32_f16_e32 v16, v0
	v_cvt_f32_f16_sdwa v17, v0 dst_sel:DWORD dst_unused:UNUSED_PAD src0_sel:WORD_1
	v_cvt_f32_f16_sdwa v27, v2 dst_sel:DWORD dst_unused:UNUSED_PAD src0_sel:WORD_1
	v_cvt_f32_f16_e32 v0, v29
	v_cvt_f32_f16_e32 v2, v28
	v_mov_b32_e32 v30, v3
	v_mov_b32_e32 v31, v1
	v_mov_b32_e32 v29, v0
	v_mov_b32_e32 v28, v2
	v_pk_mul_f32 v[30:31], v[30:31], v[30:31]
	v_mov_b32_e32 v38, v27
	v_mov_b32_e32 v39, v25
	v_pk_fma_f32 v[28:29], v[28:29], v[28:29], v[30:31]
	v_mov_b32_e32 v30, v26
	v_mov_b32_e32 v31, v24
	v_pk_mul_f32 v[38:39], v[38:39], v[38:39]
	v_mul_f32_e32 v22, v21, v21
	v_pk_fma_f32 v[30:31], v[30:31], v[30:31], v[38:39]
	v_pk_fma_f32 v[38:39], v[20:21], v[20:21], v[22:23] op_sel_hi:[1,1,0]
	v_mul_f32_e32 v22, v19, v19
	v_pk_add_f32 v[28:29], v[28:29], v[28:29] op_sel:[0,1] op_sel_hi:[1,0]
	v_pk_add_f32 v[30:31], v[30:31], v[30:31] op_sel:[0,1] op_sel_hi:[1,0]
	v_pk_fma_f32 v[40:41], v[18:19], v[18:19], v[22:23] op_sel_hi:[1,1,0]
	v_pk_mul_f32 v[42:43], v[16:17], v[16:17]
	v_pk_mul_f32 v[44:45], v[14:15], v[14:15]
	v_mov_b32_e32 v29, v42
	v_mov_b32_e32 v31, v43
	v_mov_b32_e32 v39, v44
	v_mov_b32_e32 v41, v45
	v_pk_add_f32 v[28:29], v[28:29], v[30:31]
	v_pk_add_f32 v[30:31], v[38:39], v[40:41]
	global_load_dwordx4 v[38:41], v[4:5], off
	v_pk_add_f32 v[28:29], v[28:29], v[30:31]
	v_lshl_add_u64 v[30:31], s[36:37], 0, v[6:7]
	v_add_f32_e32 v9, v28, v29
	ds_bpermute_b32 v11, v23, v9
	s_waitcnt lgkmcnt(0)
	v_add_f32_e32 v9, v9, v11
	ds_bpermute_b32 v11, v32, v9
	s_waitcnt lgkmcnt(0)
	v_add_f32_e32 v9, v9, v11
	ds_bpermute_b32 v11, v33, v9
	s_waitcnt lgkmcnt(0)
	v_add_f32_e32 v9, v9, v11
	ds_bpermute_b32 v11, v35, v9
	s_waitcnt lgkmcnt(0)
	v_add_f32_e32 v9, v9, v11
	ds_bpermute_b32 v11, v36, v9
	s_waitcnt lgkmcnt(0)
	v_add_f32_e32 v9, v9, v11
	ds_bpermute_b32 v11, v37, v9
	s_waitcnt lgkmcnt(0)
	v_add_f32_e32 v9, v9, v11
	v_fmamk_f32 v9, v9, 0x3a800000, v228
	v_cmp_gt_f32_e32 vcc, s89, v9
	v_mul_f32_e32 v11, 0x4f800000, v9
	s_nop 0
	v_cndmask_b32_e32 v9, v9, v11, vcc
	v_sqrt_f32_e32 v11, v9
	s_nop 0
	v_add_u32_e32 v13, -1, v11
	v_fma_f32 v22, -v13, v11, v9
	v_cmp_ge_f32_e64 s[0:1], 0, v22
	v_add_u32_e32 v22, 1, v11
	s_nop 0
	v_cndmask_b32_e64 v13, v11, v13, s[0:1]
	v_fma_f32 v11, -v22, v11, v9
	v_cmp_lt_f32_e64 s[0:1], 0, v11
	s_nop 1
	v_cndmask_b32_e64 v11, v13, v22, s[0:1]
	v_mul_f32_e32 v13, 0x37800000, v11
	v_cndmask_b32_e32 v11, v11, v13, vcc
	v_cmp_class_f32_e32 vcc, v9, v229
	s_nop 1
	v_cndmask_b32_e32 v9, v11, v9, vcc
	v_div_scale_f32 v11, s[0:1], v9, v9, 1.0
	v_rcp_f32_e32 v13, v11
	v_readlane_b32 s0, v255, 1
	s_add_i32 s44, s44, s0
	s_add_u32 s38, s38, s8
	v_fma_f32 v22, -v11, v13, 1.0
	v_fmac_f32_e32 v13, v22, v13
	v_div_scale_f32 v22, vcc, 1.0, v9, 1.0
	v_mul_f32_e32 v28, v22, v13
	v_fma_f32 v29, -v11, v28, v22
	v_fmac_f32_e32 v28, v29, v13
	v_fma_f32 v11, -v11, v28, v22
	v_div_fmas_f32 v11, v11, v13, v28
	v_lshl_add_u64 v[28:29], s[40:41], 0, v[176:177]
	global_load_dwordx4 v[42:45], v[28:29], off
	v_lshl_add_u64 v[28:29], s[42:43], 0, v[176:177]
	global_load_dwordx4 v[46:49], v[28:29], off
	v_div_fixup_f32 v22, v11, v9, 1.0
	v_pk_mul_f32 v[0:1], v[0:1], v[22:23] op_sel_hi:[1,0]
	v_pk_mul_f32 v[2:3], v[2:3], v[22:23] op_sel_hi:[1,0]
	s_waitcnt vmcnt(0)
	v_pk_mul_f32 v[0:1], v[40:41], v[0:1]
	v_pk_mul_f32 v[2:3], v[38:39], v[2:3]
	v_add_co_u32_e32 v30, vcc, s49, v30
	v_mov_b32_e32 v9, v177
	s_nop 0
	v_addc_co_u32_e32 v31, vcc, 0, v31, vcc
	v_pk_mul_f32 v[24:25], v[24:25], v[22:23] op_sel_hi:[1,0]
	v_pk_mul_f32 v[26:27], v[26:27], v[22:23] op_sel_hi:[1,0]
	v_mov_b32_e32 v11, v177
	v_pk_mul_f32 v[18:19], v[18:19], v[22:23] op_sel_hi:[1,0]
	v_pk_mul_f32 v[20:21], v[20:21], v[22:23] op_sel_hi:[1,0]
	v_mov_b32_e32 v13, v177
	v_pk_mul_f32 v[14:15], v[14:15], v[22:23] op_sel_hi:[1,0]
	v_pk_mul_f32 v[16:17], v[16:17], v[22:23] op_sel_hi:[1,0]
	s_addc_u32 s39, s39, s9
	s_add_u32 s36, s36, s8
	s_addc_u32 s37, s37, s9
	s_cmpk_gt_i32 s44, 0x7fff
	v_readlane_b32 s1, v255, 2
	s_waitcnt lgkmcnt(0)
	v_pk_add_f32 v[38:39], v[44:45], 1.0 op_sel_hi:[1,0]
	v_pk_add_f32 v[40:41], v[42:43], 1.0 op_sel_hi:[1,0]
	v_pk_fma_f32 v[0:1], v[38:39], v[0:1], v[48:49]
	v_pk_fma_f32 v[2:3], v[40:41], v[2:3], v[46:47]
	v_lshl_add_u64 v[38:39], s[40:41], 0, v[8:9]
	v_cvt_pk_bf16_f32 v2, v2, v3
	v_cvt_pk_bf16_f32 v3, v0, v1
	global_store_dwordx2 v[30:31], v[2:3], off
	global_load_dwordx4 v[0:3], v[4:5], off offset:1024
	s_nop 0
	global_load_dwordx4 v[38:41], v[38:39], off
	s_nop 0
	global_load_dwordx4 v[42:45], v[28:29], off offset:1024
	s_waitcnt vmcnt(0)
	v_pk_mul_f32 v[0:1], v[0:1], v[26:27]
	v_pk_mul_f32 v[2:3], v[2:3], v[24:25]
	s_waitcnt lgkmcnt(0)
	v_pk_add_f32 v[24:25], v[40:41], 1.0 op_sel_hi:[1,0]
	v_pk_add_f32 v[26:27], v[38:39], 1.0 op_sel_hi:[1,0]
	v_pk_fma_f32 v[2:3], v[24:25], v[2:3], v[44:45]
	v_pk_fma_f32 v[0:1], v[26:27], v[0:1], v[42:43]
	v_lshl_add_u64 v[24:25], s[40:41], 0, v[10:11]
	v_cvt_pk_bf16_f32 v0, v0, v1
	v_cvt_pk_bf16_f32 v1, v2, v3
	global_store_dwordx2 v[30:31], v[0:1], off offset:512
	global_load_dwordx4 v[0:3], v[4:5], off offset:2048
	s_nop 0
	global_load_dwordx4 v[24:27], v[24:25], off
	s_nop 0
	global_load_dwordx4 v[38:41], v[28:29], off offset:2048
	s_waitcnt vmcnt(0)
	v_pk_mul_f32 v[0:1], v[0:1], v[20:21]
	v_pk_mul_f32 v[2:3], v[2:3], v[18:19]
	s_waitcnt lgkmcnt(0)
	v_pk_add_f32 v[18:19], v[26:27], 1.0 op_sel_hi:[1,0]
	v_pk_add_f32 v[20:21], v[24:25], 1.0 op_sel_hi:[1,0]
	v_pk_fma_f32 v[2:3], v[18:19], v[2:3], v[40:41]
	v_pk_fma_f32 v[0:1], v[20:21], v[0:1], v[38:39]
	v_lshl_add_u64 v[18:19], s[40:41], 0, v[12:13]
	v_cvt_pk_bf16_f32 v0, v0, v1
	v_cvt_pk_bf16_f32 v1, v2, v3
	global_store_dwordx2 v[30:31], v[0:1], off offset:1024
	global_load_dwordx4 v[0:3], v[4:5], off offset:3072
	s_nop 0
	global_load_dwordx4 v[18:21], v[18:19], off
	s_nop 0
	global_load_dwordx4 v[24:27], v[28:29], off offset:3072
	s_waitcnt vmcnt(0)
	v_pk_mul_f32 v[0:1], v[0:1], v[16:17]
	v_pk_mul_f32 v[2:3], v[2:3], v[14:15]
	s_waitcnt lgkmcnt(0)
	v_pk_add_f32 v[14:15], v[20:21], 1.0 op_sel_hi:[1,0]
	v_pk_add_f32 v[16:17], v[18:19], 1.0 op_sel_hi:[1,0]
	v_pk_fma_f32 v[2:3], v[14:15], v[2:3], v[26:27]
	v_pk_fma_f32 v[0:1], v[16:17], v[0:1], v[24:25]
	s_nop 0
	v_cvt_pk_bf16_f32 v0, v0, v1
	v_cvt_pk_bf16_f32 v1, v2, v3
	global_store_dwordx2 v[30:31], v[0:1], off offset:1536
	s_cbranch_scc1 .LBB0_784

.LBB0_787:
	v_readlane_b32 s8, v254, 38
	v_readlane_b32 s9, v254, 39
	s_andn2_b64 vcc, exec, s[8:9]
	s_cbranch_vccnz .LBB0_791
	s_mul_hi_i32 s1, s0, 0x9000
	s_mul_i32 s0, s0, 0x9000
	v_readlane_b32 s3, v255, 34
	s_add_u32 s3, s3, s0
	v_readlane_b32 s0, v255, 35
	s_addc_u32 s22, s0, s1
	s_add_u32 s0, s3, 0x6000
	s_addc_u32 s1, s22, 0
	s_add_u32 s36, s3, 0x7000
	s_addc_u32 s37, s22, 0
	v_lshlrev_b32_e32 v176, 4, v34
	v_readlane_b32 s68, v252, 26
	v_lshl_add_u64 v[0:1], s[36:37], 0, v[176:177]
	v_readlane_b32 s69, v252, 27
	global_load_dwordx4 v[8:11], v[0:1], off
	v_lshl_add_u64 v[0:1], s[0:1], 0, v[176:177]
	global_load_dwordx4 v[0:3], v[0:1], off
	v_readlane_b32 s10, v255, 6
	v_readlane_b32 s11, v255, 7
	global_load_dwordx4 v[4:7], v176, s[68:69]
	global_load_dwordx4 v[30:33], v176, s[68:69] offset:3072
	s_add_u32 s38, s34, s10
	v_readlane_b32 s40, v254, 58
	v_readlane_b32 s8, v255, 26
	v_readlane_b32 s7, v255, 25
	s_addc_u32 s39, s35, s11
	s_mov_b32 s22, 0
	v_readlane_b32 s41, v254, 59
	v_readlane_b32 s70, v252, 28
	v_readlane_b32 s71, v252, 29
	v_readlane_b32 s72, v252, 30
	v_readlane_b32 s73, v252, 31
	v_readlane_b32 s74, v252, 32
	v_readlane_b32 s75, v252, 33
	v_readlane_b32 s76, v252, 34
	v_readlane_b32 s77, v252, 35
	v_readlane_b32 s78, v252, 36
	v_readlane_b32 s79, v252, 37
	v_readlane_b32 s80, v252, 38
	v_readlane_b32 s81, v252, 39
	v_readlane_b32 s82, v252, 40
	v_readlane_b32 s83, v252, 41
	v_readlane_b32 s9, v255, 27
	s_waitcnt vmcnt(0) lgkmcnt(0)
	v_pk_add_f32 v[8:9], v[8:9], 1.0 op_sel_hi:[1,0]
	v_pk_add_f32 v[10:11], v[10:11], 1.0 op_sel_hi:[1,0]
	v_pk_mul_f32 v[18:19], v[4:5], v[8:9]
	v_or_b32_e32 v4, 0x400, v176
	v_mov_b32_e32 v5, v177
	v_pk_mul_f32 v[16:17], v[6:7], v[10:11]
	v_lshl_add_u64 v[6:7], s[36:37], 0, v[4:5]
	global_load_dwordx4 v[12:15], v[6:7], off
	global_load_dwordx4 v[8:11], v176, s[68:69] offset:1024
	v_lshl_add_u64 v[4:5], s[0:1], 0, v[4:5]
	global_load_dwordx4 v[4:7], v[4:5], off
	s_waitcnt vmcnt(0) lgkmcnt(0)
	v_pk_add_f32 v[12:13], v[12:13], 1.0 op_sel_hi:[1,0]
	v_pk_add_f32 v[14:15], v[14:15], 1.0 op_sel_hi:[1,0]
	v_pk_mul_f32 v[22:23], v[8:9], v[12:13]
	v_or_b32_e32 v8, 0x800, v176
	v_mov_b32_e32 v9, v177
	v_pk_mul_f32 v[20:21], v[10:11], v[14:15]
	v_lshl_add_u64 v[10:11], s[36:37], 0, v[8:9]
	global_load_dwordx4 v[24:27], v[10:11], off
	global_load_dwordx4 v[12:15], v176, s[68:69] offset:2048
	v_or_b32_e32 v176, 0xc00, v176
	v_lshl_add_u64 v[8:9], s[0:1], 0, v[8:9]
	global_load_dwordx4 v[8:11], v[8:9], off
	s_waitcnt vmcnt(0) lgkmcnt(0)
	v_pk_add_f32 v[26:27], v[26:27], 1.0 op_sel_hi:[1,0]
	v_pk_add_f32 v[28:29], v[24:25], 1.0 op_sel_hi:[1,0]
	v_pk_mul_f32 v[24:25], v[14:15], v[26:27]
	v_pk_mul_f32 v[26:27], v[12:13], v[28:29]
	v_lshl_add_u64 v[12:13], s[36:37], 0, v[176:177]
	global_load_dwordx4 v[36:39], v[12:13], off
	v_lshl_add_u64 v[12:13], s[0:1], 0, v[176:177]
	global_load_dwordx4 v[12:15], v[12:13], off
	v_lshlrev_b32_e32 v176, 3, v34
	v_lshlrev_b32_e32 v34, 2, v34
	v_xor_b32_e32 v101, 4, v34
	v_xor_b32_e32 v102, 8, v34
	v_xor_b32_e32 v103, 16, v34
	v_xor_b32_e32 v104, 32, v34
	v_xor_b32_e32 v105, 64, v34
	v_xor_b32_e32 v106, 0x80, v34
	v_lshl_add_u64 v[34:35], s[34:35], 0, v[176:177]
	s_mov_b64 s[0:1], 0x4b00000
	v_lshl_add_u64 v[34:35], v[34:35], 0, s[0:1]
	s_waitcnt vmcnt(0) lgkmcnt(0)
	v_pk_add_f32 v[28:29], v[38:39], 1.0 op_sel_hi:[1,0]
	v_pk_add_f32 v[36:37], v[36:37], 1.0 op_sel_hi:[1,0]
	v_pk_mul_f32 v[28:29], v[32:33], v[28:29]
	v_pk_mul_f32 v[30:31], v[30:31], v[36:37]
	v_lshl_add_u64 v[32:33], s[30:31], 0, v[176:177]
.LBB0_789:
	v_lshl_add_u64 v[36:37], s[40:41], 0, v[176:177]
	v_add_co_u32_e32 v36, vcc, 0x4000000, v36
	s_add_i32 s3, s8, s22
	s_nop 0
	v_addc_co_u32_e32 v37, vcc, 0, v37, vcc
	global_load_dwordx2 v[38:39], v[36:37], off
	s_add_i32 s0, s3, 1
	s_ashr_i32 s1, s0, 31
	s_lshl_b64 s[42:43], s[0:1], 11
	s_add_i32 s0, s3, 2
	s_ashr_i32 s1, s0, 31
	s_lshl_b64 s[36:37], s[0:1], 11
	s_add_i32 s0, s3, 3
	s_ashr_i32 s1, s0, 31
	s_lshl_b64 s[34:35], s[0:1], 11
	s_add_i32 s22, s22, 4
	s_add_u32 s40, s40, 0x2000
	s_addc_u32 s41, s41, 0
	s_waitcnt vmcnt(0)
	v_cvt_f32_f16_e32 v80, v38
	v_cvt_f32_f16_sdwa v81, v38 dst_sel:DWORD dst_unused:UNUSED_PAD src0_sel:WORD_1
	v_cvt_f32_f16_e32 v82, v39
	v_cvt_f32_f16_sdwa v83, v39 dst_sel:DWORD dst_unused:UNUSED_PAD src0_sel:WORD_1
	global_load_dwordx2 v[38:39], v[36:37], off offset:512
	v_mov_b32_e32 v110, v81
	v_mov_b32_e32 v108, v80
	v_mov_b32_e32 v111, v83
	v_mov_b32_e32 v109, v82
	v_pk_mul_f32 v[110:111], v[110:111], v[110:111]
	s_waitcnt vmcnt(0)
	v_cvt_f32_f16_e32 v76, v38
	v_cvt_f32_f16_sdwa v77, v38 dst_sel:DWORD dst_unused:UNUSED_PAD src0_sel:WORD_1
	v_cvt_f32_f16_e32 v78, v39
	v_cvt_f32_f16_sdwa v79, v39 dst_sel:DWORD dst_unused:UNUSED_PAD src0_sel:WORD_1
	global_load_dwordx2 v[38:39], v[36:37], off offset:1024
	v_mov_b32_e32 v112, v77
	global_load_dwordx2 v[36:37], v[36:37], off offset:1536
	v_mov_b32_e32 v113, v79
	v_pk_fma_f32 v[108:109], v[108:109], v[108:109], v[110:111]
	v_mov_b32_e32 v110, v76
	v_mov_b32_e32 v111, v78
	v_pk_mul_f32 v[112:113], v[112:113], v[112:113]
	v_pk_add_f32 v[108:109], v[108:109], v[108:109] op_sel:[0,1] op_sel_hi:[1,0]
	v_pk_fma_f32 v[110:111], v[110:111], v[110:111], v[112:113]
	s_waitcnt vmcnt(0)
	v_cvt_f32_f16_e32 v72, v38
	v_cvt_f32_f16_sdwa v73, v38 dst_sel:DWORD dst_unused:UNUSED_PAD src0_sel:WORD_1
	s_waitcnt vmcnt(0)
	v_cvt_f32_f16_e32 v68, v36
	v_cvt_f32_f16_sdwa v69, v36 dst_sel:DWORD dst_unused:UNUSED_PAD src0_sel:WORD_1
	v_cvt_f32_f16_e32 v70, v37
	v_cvt_f32_f16_sdwa v71, v37 dst_sel:DWORD dst_unused:UNUSED_PAD src0_sel:WORD_1
	v_lshl_add_u64 v[36:37], v[32:33], 0, s[42:43]
	v_cvt_f32_f16_e32 v74, v39
	v_cvt_f32_f16_sdwa v75, v39 dst_sel:DWORD dst_unused:UNUSED_PAD src0_sel:WORD_1
	global_load_dwordx2 v[38:39], v[36:37], off
	v_mul_f32_e32 v100, v73, v73
	v_pk_fma_f32 v[112:113], v[72:73], v[72:73], v[100:101] op_sel_hi:[1,1,0]
	v_mul_f32_e32 v100, v75, v75
	v_pk_add_f32 v[110:111], v[110:111], v[110:111] op_sel:[0,1] op_sel_hi:[1,0]
	v_pk_fma_f32 v[114:115], v[74:75], v[74:75], v[100:101] op_sel_hi:[1,1,0]
	v_pk_mul_f32 v[116:117], v[68:69], v[68:69]
	v_pk_mul_f32 v[118:119], v[70:71], v[70:71]
	v_mov_b32_e32 v109, v116
	v_mov_b32_e32 v111, v117
	v_mov_b32_e32 v113, v118
	v_mov_b32_e32 v115, v119
	v_pk_add_f32 v[108:109], v[108:109], v[110:111]
	v_pk_add_f32 v[110:111], v[112:113], v[114:115]
	s_waitcnt vmcnt(0)
	v_cvt_f32_f16_e32 v96, v38
	v_cvt_f32_f16_sdwa v97, v38 dst_sel:DWORD dst_unused:UNUSED_PAD src0_sel:WORD_1
	v_cvt_f32_f16_e32 v98, v39
	v_cvt_f32_f16_sdwa v99, v39 dst_sel:DWORD dst_unused:UNUSED_PAD src0_sel:WORD_1
	global_load_dwordx2 v[38:39], v[36:37], off offset:512
	v_pk_add_f32 v[108:109], v[108:109], v[110:111]
	s_waitcnt vmcnt(0)
	v_cvt_f32_f16_e32 v92, v38
	v_cvt_f32_f16_sdwa v93, v38 dst_sel:DWORD dst_unused:UNUSED_PAD src0_sel:WORD_1
	v_cvt_f32_f16_e32 v94, v39
	v_cvt_f32_f16_sdwa v95, v39 dst_sel:DWORD dst_unused:UNUSED_PAD src0_sel:WORD_1
	global_load_dwordx2 v[38:39], v[36:37], off offset:1024
	v_add_f32_e32 v100, v108, v109
	global_load_dwordx2 v[36:37], v[36:37], off offset:1536
	ds_bpermute_b32 v107, v101, v100
	s_waitcnt lgkmcnt(0)
	v_add_f32_e32 v100, v100, v107
	ds_bpermute_b32 v107, v102, v100
	s_waitcnt lgkmcnt(0)
	v_add_f32_e32 v100, v100, v107
	ds_bpermute_b32 v107, v103, v100
	s_waitcnt lgkmcnt(0)
	v_add_f32_e32 v100, v100, v107
	ds_bpermute_b32 v107, v104, v100
	s_waitcnt lgkmcnt(0)
	v_add_f32_e32 v100, v100, v107
	ds_bpermute_b32 v107, v105, v100
	s_waitcnt lgkmcnt(0)
	v_add_f32_e32 v100, v100, v107
	ds_bpermute_b32 v107, v106, v100
	s_waitcnt lgkmcnt(0)
	v_add_f32_e32 v100, v100, v107
	v_fmamk_f32 v100, v100, 0x3a800000, v228
	v_cmp_gt_f32_e32 vcc, s89, v100
	v_mul_f32_e32 v107, 0x4f800000, v100
	s_waitcnt vmcnt(1)
	v_cvt_f32_f16_e32 v88, v38
	v_cvt_f32_f16_sdwa v89, v38 dst_sel:DWORD dst_unused:UNUSED_PAD src0_sel:WORD_1
	s_waitcnt vmcnt(0)
	v_cvt_f32_f16_e32 v84, v36
	v_cvt_f32_f16_sdwa v85, v36 dst_sel:DWORD dst_unused:UNUSED_PAD src0_sel:WORD_1
	v_cvt_f32_f16_e32 v86, v37
	v_cvt_f32_f16_sdwa v87, v37 dst_sel:DWORD dst_unused:UNUSED_PAD src0_sel:WORD_1
	v_lshl_add_u64 v[36:37], v[32:33], 0, s[36:37]
	v_cvt_f32_f16_e32 v90, v39
	v_cvt_f32_f16_sdwa v91, v39 dst_sel:DWORD dst_unused:UNUSED_PAD src0_sel:WORD_1
	global_load_dwordx2 v[38:39], v[36:37], off
	v_cndmask_b32_e32 v100, v100, v107, vcc
	v_sqrt_f32_e32 v107, v100
	s_waitcnt vmcnt(0)
	v_cvt_f32_f16_e32 v64, v38
	v_cvt_f32_f16_sdwa v65, v38 dst_sel:DWORD dst_unused:UNUSED_PAD src0_sel:WORD_1
	v_cvt_f32_f16_e32 v66, v39
	v_cvt_f32_f16_sdwa v67, v39 dst_sel:DWORD dst_unused:UNUSED_PAD src0_sel:WORD_1
	global_load_dwordx2 v[38:39], v[36:37], off offset:512
	v_add_u32_e32 v108, -1, v107
	v_fma_f32 v109, -v108, v107, v100
	v_cmp_ge_f32_e64 s[0:1], 0, v109
	v_add_u32_e32 v109, 1, v107
	s_waitcnt vmcnt(0)
	v_cvt_f32_f16_e32 v60, v38
	v_cvt_f32_f16_sdwa v61, v38 dst_sel:DWORD dst_unused:UNUSED_PAD src0_sel:WORD_1
	v_cvt_f32_f16_e32 v62, v39
	v_cvt_f32_f16_sdwa v63, v39 dst_sel:DWORD dst_unused:UNUSED_PAD src0_sel:WORD_1
	global_load_dwordx2 v[38:39], v[36:37], off offset:1024
	v_cndmask_b32_e64 v108, v107, v108, s[0:1]
	global_load_dwordx2 v[36:37], v[36:37], off offset:1536
	v_fma_f32 v107, -v109, v107, v100
	v_cmp_lt_f32_e64 s[0:1], 0, v107
	s_waitcnt vmcnt(1)
	v_cvt_f32_f16_e32 v56, v38
	v_cvt_f32_f16_sdwa v57, v38 dst_sel:DWORD dst_unused:UNUSED_PAD src0_sel:WORD_1
	s_waitcnt vmcnt(0)
	v_cvt_f32_f16_e32 v52, v36
	v_cvt_f32_f16_sdwa v53, v36 dst_sel:DWORD dst_unused:UNUSED_PAD src0_sel:WORD_1
	v_cvt_f32_f16_e32 v54, v37
	v_cvt_f32_f16_sdwa v55, v37 dst_sel:DWORD dst_unused:UNUSED_PAD src0_sel:WORD_1
	v_lshl_add_u64 v[36:37], v[32:33], 0, s[34:35]
	v_cvt_f32_f16_e32 v58, v39
	v_cvt_f32_f16_sdwa v59, v39 dst_sel:DWORD dst_unused:UNUSED_PAD src0_sel:WORD_1
	global_load_dwordx2 v[38:39], v[36:37], off
	v_cndmask_b32_e64 v107, v108, v109, s[0:1]
	v_mul_f32_e32 v108, 0x37800000, v107
	v_cndmask_b32_e32 v107, v107, v108, vcc
	v_cmp_class_f32_e32 vcc, v100, v229
	s_waitcnt vmcnt(0)
	v_cvt_f32_f16_e32 v48, v38
	v_cvt_f32_f16_sdwa v49, v38 dst_sel:DWORD dst_unused:UNUSED_PAD src0_sel:WORD_1
	v_cvt_f32_f16_e32 v50, v39
	v_cvt_f32_f16_sdwa v51, v39 dst_sel:DWORD dst_unused:UNUSED_PAD src0_sel:WORD_1
	global_load_dwordx2 v[38:39], v[36:37], off offset:512
	v_cndmask_b32_e32 v100, v107, v100, vcc
	v_div_scale_f32 v107, s[0:1], v100, v100, 1.0
	v_rcp_f32_e32 v108, v107
	s_waitcnt vmcnt(0)
	v_cvt_f32_f16_e32 v44, v38
	v_cvt_f32_f16_sdwa v45, v38 dst_sel:DWORD dst_unused:UNUSED_PAD src0_sel:WORD_1
	v_cvt_f32_f16_e32 v46, v39
	v_cvt_f32_f16_sdwa v47, v39 dst_sel:DWORD dst_unused:UNUSED_PAD src0_sel:WORD_1
	global_load_dwordx2 v[38:39], v[36:37], off offset:1024
	v_fma_f32 v109, -v107, v108, 1.0
	v_fmac_f32_e32 v108, v109, v108
	v_div_scale_f32 v109, vcc, 1.0, v100, 1.0
	v_mul_f32_e32 v110, v109, v108
	v_fma_f32 v111, -v107, v110, v109
	v_fmac_f32_e32 v110, v111, v108
	v_fma_f32 v107, -v107, v110, v109
	v_div_fmas_f32 v107, v107, v108, v110
	v_div_fixup_f32 v100, v107, v100, 1.0
	v_pk_mul_f32 v[80:81], v[80:81], v[100:101] op_sel_hi:[1,0]
	v_pk_mul_f32 v[82:83], v[82:83], v[100:101] op_sel_hi:[1,0]
	v_lshl_add_u64 v[108:109], s[38:39], 0, v[176:177]
	v_pk_fma_f32 v[82:83], v[16:17], v[82:83], v[2:3]
	v_pk_fma_f32 v[80:81], v[18:19], v[80:81], v[0:1]
	v_pk_mul_f32 v[72:73], v[72:73], v[100:101] op_sel_hi:[1,0]
	v_pk_mul_f32 v[74:75], v[74:75], v[100:101] op_sel_hi:[1,0]
	v_pk_mul_f32 v[68:69], v[68:69], v[100:101] op_sel_hi:[1,0]
	v_pk_mul_f32 v[70:71], v[70:71], v[100:101] op_sel_hi:[1,0]
	v_cvt_pk_bf16_f32 v80, v80, v81
	v_cvt_pk_bf16_f32 v81, v82, v83
	v_add_co_u32_e32 v82, vcc, s49, v108
	v_pk_fma_f32 v[74:75], v[24:25], v[74:75], v[10:11]
	v_pk_fma_f32 v[72:73], v[26:27], v[72:73], v[8:9]
	v_pk_fma_f32 v[70:71], v[28:29], v[70:71], v[14:15]
	v_pk_fma_f32 v[68:69], v[30:31], v[68:69], v[12:13]
	v_addc_co_u32_e32 v83, vcc, 0, v109, vcc
	v_cvt_pk_bf16_f32 v72, v72, v73
	v_cvt_pk_bf16_f32 v73, v74, v75
	v_cvt_pk_bf16_f32 v68, v68, v69
	v_cvt_pk_bf16_f32 v69, v70, v71
	v_mov_b32_e32 v70, v97
	v_mov_b32_e32 v71, v99
	v_pk_mul_f32 v[76:77], v[76:77], v[100:101] op_sel_hi:[1,0]
	v_pk_mul_f32 v[78:79], v[78:79], v[100:101] op_sel_hi:[1,0]
	v_pk_mul_f32 v[70:71], v[70:71], v[70:71]
	v_pk_fma_f32 v[78:79], v[20:21], v[78:79], v[6:7]
	v_pk_fma_f32 v[76:77], v[22:23], v[76:77], v[4:5]
	v_mul_f32_e32 v74, v91, v91
	v_cvt_pk_bf16_f32 v76, v76, v77
	v_cvt_pk_bf16_f32 v77, v78, v79
	v_pk_fma_f32 v[74:75], v[90:91], v[90:91], v[74:75] op_sel_hi:[1,1,0]
	v_pk_mul_f32 v[78:79], v[86:87], v[86:87]
	s_add_u32 s38, s38, 0x2000
	v_mov_b32_e32 v75, v79
	s_addc_u32 s39, s39, 0
	s_cmp_ge_i32 s22, s7
	s_waitcnt vmcnt(0)
	v_cvt_f32_f16_e32 v40, v38
	v_cvt_f32_f16_sdwa v41, v38 dst_sel:DWORD dst_unused:UNUSED_PAD src0_sel:WORD_1
	v_cvt_f32_f16_e32 v42, v39
	v_cvt_f32_f16_sdwa v43, v39 dst_sel:DWORD dst_unused:UNUSED_PAD src0_sel:WORD_1
	global_load_dwordx2 v[38:39], v[36:37], off offset:1536
	s_waitcnt vmcnt(0)
	v_cvt_f32_f16_e32 v36, v38
	global_store_dwordx2 v[82:83], v[72:73], off offset:1024
	global_store_dwordx2 v[82:83], v[68:69], off offset:1536
	v_mov_b32_e32 v68, v96
	v_mov_b32_e32 v69, v98
	v_mov_b32_e32 v72, v93
	v_mov_b32_e32 v73, v95
	v_pk_fma_f32 v[68:69], v[68:69], v[68:69], v[70:71]
	v_mov_b32_e32 v70, v92
	v_mov_b32_e32 v71, v94
	v_pk_mul_f32 v[72:73], v[72:73], v[72:73]
	global_store_dwordx2 v[82:83], v[76:77], off offset:512
	v_pk_fma_f32 v[70:71], v[70:71], v[70:71], v[72:73]
	v_mul_f32_e32 v72, v89, v89
	v_pk_add_f32 v[68:69], v[68:69], v[68:69] op_sel:[0,1] op_sel_hi:[1,0]
	v_pk_add_f32 v[70:71], v[70:71], v[70:71] op_sel:[0,1] op_sel_hi:[1,0]
	v_pk_fma_f32 v[72:73], v[88:89], v[88:89], v[72:73] op_sel_hi:[1,1,0]
	v_pk_mul_f32 v[76:77], v[84:85], v[84:85]
	v_mov_b32_e32 v73, v78
	v_mov_b32_e32 v69, v76
	v_mov_b32_e32 v71, v77
	v_pk_add_f32 v[68:69], v[68:69], v[70:71]
	v_pk_add_f32 v[70:71], v[72:73], v[74:75]
	global_store_dwordx2 v[82:83], v[80:81], off
	v_pk_add_f32 v[68:69], v[68:69], v[70:71]
	v_pk_mul_f32 v[76:77], v[52:53], v[52:53]
	v_add_f32_e32 v68, v68, v69
	ds_bpermute_b32 v69, v101, v68
	v_pk_mul_f32 v[78:79], v[54:55], v[54:55]
	v_cvt_f32_f16_sdwa v37, v38 dst_sel:DWORD dst_unused:UNUSED_PAD src0_sel:WORD_1
	v_cvt_f32_f16_e32 v38, v39
	v_cvt_f32_f16_sdwa v39, v39 dst_sel:DWORD dst_unused:UNUSED_PAD src0_sel:WORD_1
	s_waitcnt lgkmcnt(0)
	v_add_f32_e32 v68, v68, v69
	ds_bpermute_b32 v69, v102, v68
	s_waitcnt lgkmcnt(0)
	v_add_f32_e32 v68, v68, v69
	ds_bpermute_b32 v69, v103, v68
	s_waitcnt lgkmcnt(0)
	v_add_f32_e32 v68, v68, v69
	ds_bpermute_b32 v69, v104, v68
	s_waitcnt lgkmcnt(0)
	v_add_f32_e32 v68, v68, v69
	ds_bpermute_b32 v69, v105, v68
	s_waitcnt lgkmcnt(0)
	v_add_f32_e32 v68, v68, v69
	ds_bpermute_b32 v69, v106, v68
	s_waitcnt lgkmcnt(0)
	v_add_f32_e32 v68, v68, v69
	v_fmamk_f32 v68, v68, 0x3a800000, v228
	v_cmp_gt_f32_e32 vcc, s89, v68
	v_mul_f32_e32 v69, 0x4f800000, v68
	s_nop 0
	v_cndmask_b32_e32 v68, v68, v69, vcc
	v_sqrt_f32_e32 v69, v68
	s_nop 0
	v_add_u32_e32 v70, -1, v69
	v_fma_f32 v71, -v70, v69, v68
	v_cmp_ge_f32_e64 s[0:1], 0, v71
	v_add_u32_e32 v71, 1, v69
	s_nop 0
	v_cndmask_b32_e64 v70, v69, v70, s[0:1]
	v_fma_f32 v69, -v71, v69, v68
	v_cmp_lt_f32_e64 s[0:1], 0, v69
	s_nop 1
	v_cndmask_b32_e64 v69, v70, v71, s[0:1]
	v_mul_f32_e32 v70, 0x37800000, v69
	v_cndmask_b32_e32 v69, v69, v70, vcc
	v_cmp_class_f32_e32 vcc, v68, v229
	s_nop 1
	v_cndmask_b32_e32 v68, v69, v68, vcc
	v_div_scale_f32 v69, s[0:1], v68, v68, 1.0
	v_rcp_f32_e32 v70, v69
	s_nop 0
	v_fma_f32 v71, -v69, v70, 1.0
	v_fmac_f32_e32 v70, v71, v70
	v_div_scale_f32 v71, vcc, 1.0, v68, 1.0
	v_mul_f32_e32 v72, v71, v70
	v_fma_f32 v73, -v69, v72, v71
	v_fmac_f32_e32 v72, v73, v70
	v_fma_f32 v69, -v69, v72, v71
	v_div_fmas_f32 v69, v69, v70, v72
	v_div_fixup_f32 v68, v69, v68, 1.0
	v_pk_mul_f32 v[72:73], v[96:97], v[68:69] op_sel_hi:[1,0]
	v_pk_mul_f32 v[74:75], v[98:99], v[68:69] op_sel_hi:[1,0]
	v_pk_fma_f32 v[72:73], v[18:19], v[72:73], v[0:1]
	v_pk_fma_f32 v[74:75], v[16:17], v[74:75], v[2:3]
	v_lshl_add_u64 v[70:71], v[34:35], 0, s[42:43]
	v_cvt_pk_bf16_f32 v72, v72, v73
	v_cvt_pk_bf16_f32 v73, v74, v75
	global_store_dwordx2 v[70:71], v[72:73], off
	v_pk_mul_f32 v[72:73], v[92:93], v[68:69] op_sel_hi:[1,0]
	v_pk_mul_f32 v[74:75], v[94:95], v[68:69] op_sel_hi:[1,0]
	v_pk_fma_f32 v[72:73], v[22:23], v[72:73], v[4:5]
	v_pk_fma_f32 v[74:75], v[20:21], v[74:75], v[6:7]
	v_cvt_pk_bf16_f32 v72, v72, v73
	v_cvt_pk_bf16_f32 v73, v74, v75
	global_store_dwordx2 v[70:71], v[72:73], off offset:512
	v_pk_mul_f32 v[72:73], v[88:89], v[68:69] op_sel_hi:[1,0]
	v_pk_mul_f32 v[74:75], v[90:91], v[68:69] op_sel_hi:[1,0]
	v_pk_fma_f32 v[72:73], v[26:27], v[72:73], v[8:9]
	v_pk_fma_f32 v[74:75], v[24:25], v[74:75], v[10:11]
	v_cvt_pk_bf16_f32 v72, v72, v73
	v_cvt_pk_bf16_f32 v73, v74, v75
	global_store_dwordx2 v[70:71], v[72:73], off offset:1024
	v_pk_mul_f32 v[72:73], v[84:85], v[68:69] op_sel_hi:[1,0]
	v_pk_mul_f32 v[68:69], v[86:87], v[68:69] op_sel_hi:[1,0]
	v_pk_fma_f32 v[72:73], v[30:31], v[72:73], v[12:13]
	v_pk_fma_f32 v[68:69], v[28:29], v[68:69], v[14:15]
	v_cvt_pk_bf16_f32 v72, v72, v73
	v_cvt_pk_bf16_f32 v73, v68, v69
	global_store_dwordx2 v[70:71], v[72:73], off offset:1536
	v_mov_b32_e32 v70, v65
	v_mov_b32_e32 v71, v67
	v_mov_b32_e32 v68, v64
	v_mov_b32_e32 v69, v66
	v_pk_mul_f32 v[70:71], v[70:71], v[70:71]
	v_mov_b32_e32 v72, v61
	v_mov_b32_e32 v73, v63
	v_pk_fma_f32 v[68:69], v[68:69], v[68:69], v[70:71]
	v_mov_b32_e32 v70, v60
	v_mov_b32_e32 v71, v62
	v_pk_mul_f32 v[72:73], v[72:73], v[72:73]
	v_mul_f32_e32 v74, v59, v59
	v_pk_fma_f32 v[70:71], v[70:71], v[70:71], v[72:73]
	v_mul_f32_e32 v72, v57, v57
	v_pk_add_f32 v[68:69], v[68:69], v[68:69] op_sel:[0,1] op_sel_hi:[1,0]
	v_pk_add_f32 v[70:71], v[70:71], v[70:71] op_sel:[0,1] op_sel_hi:[1,0]
	v_pk_fma_f32 v[72:73], v[56:57], v[56:57], v[72:73] op_sel_hi:[1,1,0]
	v_pk_fma_f32 v[74:75], v[58:59], v[58:59], v[74:75] op_sel_hi:[1,1,0]
	v_mov_b32_e32 v69, v76
	v_mov_b32_e32 v71, v77
	v_mov_b32_e32 v73, v78
	v_mov_b32_e32 v75, v79
	v_pk_add_f32 v[68:69], v[68:69], v[70:71]
	v_pk_add_f32 v[70:71], v[72:73], v[74:75]
	s_nop 0
	v_pk_add_f32 v[68:69], v[68:69], v[70:71]
	s_nop 0
	v_add_f32_e32 v68, v68, v69
	ds_bpermute_b32 v69, v101, v68
	s_waitcnt lgkmcnt(0)
	v_add_f32_e32 v68, v68, v69
	ds_bpermute_b32 v69, v102, v68
	s_waitcnt lgkmcnt(0)
	v_add_f32_e32 v68, v68, v69
	ds_bpermute_b32 v69, v103, v68
	s_waitcnt lgkmcnt(0)
	v_add_f32_e32 v68, v68, v69
	ds_bpermute_b32 v69, v104, v68
	s_waitcnt lgkmcnt(0)
	v_add_f32_e32 v68, v68, v69
	ds_bpermute_b32 v69, v105, v68
	s_waitcnt lgkmcnt(0)
	v_add_f32_e32 v68, v68, v69
	ds_bpermute_b32 v69, v106, v68
	s_waitcnt lgkmcnt(0)
	v_add_f32_e32 v68, v68, v69
	v_fmamk_f32 v68, v68, 0x3a800000, v228
	v_cmp_gt_f32_e32 vcc, s89, v68
	v_mul_f32_e32 v69, 0x4f800000, v68
	s_nop 0
	v_cndmask_b32_e32 v68, v68, v69, vcc
	v_sqrt_f32_e32 v69, v68
	s_nop 0
	v_add_u32_e32 v70, -1, v69
	v_fma_f32 v71, -v70, v69, v68
	v_cmp_ge_f32_e64 s[0:1], 0, v71
	v_add_u32_e32 v71, 1, v69
	s_nop 0
	v_cndmask_b32_e64 v70, v69, v70, s[0:1]
	v_fma_f32 v69, -v71, v69, v68
	v_cmp_lt_f32_e64 s[0:1], 0, v69
	s_nop 1
	v_cndmask_b32_e64 v69, v70, v71, s[0:1]
	v_mul_f32_e32 v70, 0x37800000, v69
	v_cndmask_b32_e32 v69, v69, v70, vcc
	v_cmp_class_f32_e32 vcc, v68, v229
	s_nop 1
	v_cndmask_b32_e32 v68, v69, v68, vcc
	v_div_scale_f32 v69, s[0:1], v68, v68, 1.0
	v_rcp_f32_e32 v70, v69
	s_nop 0
	v_fma_f32 v71, -v69, v70, 1.0
	v_fmac_f32_e32 v70, v71, v70
	v_div_scale_f32 v71, vcc, 1.0, v68, 1.0
	v_mul_f32_e32 v72, v71, v70
	v_fma_f32 v73, -v69, v72, v71
	v_fmac_f32_e32 v72, v73, v70
	v_fma_f32 v69, -v69, v72, v71
	v_div_fmas_f32 v69, v69, v70, v72
	v_div_fixup_f32 v68, v69, v68, 1.0
	v_pk_mul_f32 v[56:57], v[56:57], v[68:69] op_sel_hi:[1,0]
	v_pk_mul_f32 v[58:59], v[58:59], v[68:69] op_sel_hi:[1,0]
	v_pk_mul_f32 v[52:53], v[52:53], v[68:69] op_sel_hi:[1,0]
	v_pk_mul_f32 v[54:55], v[54:55], v[68:69] op_sel_hi:[1,0]
	v_pk_fma_f32 v[58:59], v[24:25], v[58:59], v[10:11]
	v_pk_fma_f32 v[56:57], v[26:27], v[56:57], v[8:9]
	v_pk_fma_f32 v[54:55], v[28:29], v[54:55], v[14:15]
	v_pk_fma_f32 v[52:53], v[30:31], v[52:53], v[12:13]
	v_lshl_add_u64 v[70:71], v[34:35], 0, s[36:37]
	v_cvt_pk_bf16_f32 v56, v56, v57
	v_cvt_pk_bf16_f32 v57, v58, v59
	v_cvt_pk_bf16_f32 v52, v52, v53
	v_cvt_pk_bf16_f32 v53, v54, v55
	v_mov_b32_e32 v54, v49
	v_mov_b32_e32 v55, v51
	v_pk_mul_f32 v[60:61], v[60:61], v[68:69] op_sel_hi:[1,0]
	v_pk_mul_f32 v[62:63], v[62:63], v[68:69] op_sel_hi:[1,0]
	global_store_dwordx2 v[70:71], v[56:57], off offset:1024
	global_store_dwordx2 v[70:71], v[52:53], off offset:1536
	v_mov_b32_e32 v52, v48
	v_mov_b32_e32 v53, v50
	v_pk_mul_f32 v[54:55], v[54:55], v[54:55]
	v_mov_b32_e32 v56, v45
	v_mov_b32_e32 v57, v47
	v_pk_fma_f32 v[62:63], v[20:21], v[62:63], v[6:7]
	v_pk_fma_f32 v[60:61], v[22:23], v[60:61], v[4:5]
	v_pk_fma_f32 v[52:53], v[52:53], v[52:53], v[54:55]
	v_mov_b32_e32 v54, v44
	v_mov_b32_e32 v55, v46
	v_pk_mul_f32 v[56:57], v[56:57], v[56:57]
	v_cvt_pk_bf16_f32 v60, v60, v61
	v_cvt_pk_bf16_f32 v61, v62, v63
	v_pk_fma_f32 v[54:55], v[54:55], v[54:55], v[56:57]
	v_mul_f32_e32 v56, v41, v41
	v_mul_f32_e32 v58, v43, v43
	global_store_dwordx2 v[70:71], v[60:61], off offset:512
	v_pk_add_f32 v[52:53], v[52:53], v[52:53] op_sel:[0,1] op_sel_hi:[1,0]
	v_pk_add_f32 v[54:55], v[54:55], v[54:55] op_sel:[0,1] op_sel_hi:[1,0]
	v_pk_fma_f32 v[56:57], v[40:41], v[40:41], v[56:57] op_sel_hi:[1,1,0]
	v_pk_fma_f32 v[58:59], v[42:43], v[42:43], v[58:59] op_sel_hi:[1,1,0]
	v_pk_mul_f32 v[60:61], v[36:37], v[36:37]
	v_pk_mul_f32 v[62:63], v[38:39], v[38:39]
	v_mov_b32_e32 v53, v60
	v_mov_b32_e32 v55, v61
	v_mov_b32_e32 v57, v62
	v_mov_b32_e32 v59, v63
	v_pk_add_f32 v[52:53], v[52:53], v[54:55]
	v_pk_add_f32 v[54:55], v[56:57], v[58:59]
	v_pk_mul_f32 v[64:65], v[64:65], v[68:69] op_sel_hi:[1,0]
	v_pk_add_f32 v[52:53], v[52:53], v[54:55]
	v_pk_mul_f32 v[66:67], v[66:67], v[68:69] op_sel_hi:[1,0]
	v_add_f32_e32 v52, v52, v53
	ds_bpermute_b32 v53, v101, v52
	v_pk_fma_f32 v[66:67], v[16:17], v[66:67], v[2:3]
	v_pk_fma_f32 v[64:65], v[18:19], v[64:65], v[0:1]
	s_waitcnt lgkmcnt(0)
	v_add_f32_e32 v52, v52, v53
	ds_bpermute_b32 v53, v102, v52
	v_cvt_pk_bf16_f32 v64, v64, v65
	v_cvt_pk_bf16_f32 v65, v66, v67
	global_store_dwordx2 v[70:71], v[64:65], off
	s_waitcnt lgkmcnt(0)
	v_add_f32_e32 v52, v52, v53
	ds_bpermute_b32 v53, v103, v52
	s_waitcnt lgkmcnt(0)
	v_add_f32_e32 v52, v52, v53
	ds_bpermute_b32 v53, v104, v52
	s_waitcnt lgkmcnt(0)
	v_add_f32_e32 v52, v52, v53
	ds_bpermute_b32 v53, v105, v52
	s_waitcnt lgkmcnt(0)
	v_add_f32_e32 v52, v52, v53
	ds_bpermute_b32 v53, v106, v52
	s_waitcnt lgkmcnt(0)
	v_add_f32_e32 v52, v52, v53
	v_fmamk_f32 v52, v52, 0x3a800000, v228
	v_cmp_gt_f32_e32 vcc, s89, v52
	v_mul_f32_e32 v53, 0x4f800000, v52
	s_nop 0
	v_cndmask_b32_e32 v52, v52, v53, vcc
	v_sqrt_f32_e32 v53, v52
	s_nop 0
	v_add_u32_e32 v54, -1, v53
	v_fma_f32 v55, -v54, v53, v52
	v_cmp_ge_f32_e64 s[0:1], 0, v55
	v_add_u32_e32 v55, 1, v53
	s_nop 0
	v_cndmask_b32_e64 v54, v53, v54, s[0:1]
	v_fma_f32 v53, -v55, v53, v52
	v_cmp_lt_f32_e64 s[0:1], 0, v53
	s_nop 1
	v_cndmask_b32_e64 v53, v54, v55, s[0:1]
	v_mul_f32_e32 v54, 0x37800000, v53
	v_cndmask_b32_e32 v53, v53, v54, vcc
	v_cmp_class_f32_e32 vcc, v52, v229
	s_nop 1
	v_cndmask_b32_e32 v52, v53, v52, vcc
	v_div_scale_f32 v53, s[0:1], v52, v52, 1.0
	v_rcp_f32_e32 v54, v53
	s_nop 0
	v_fma_f32 v55, -v53, v54, 1.0
	v_fmac_f32_e32 v54, v55, v54
	v_div_scale_f32 v55, vcc, 1.0, v52, 1.0
	v_mul_f32_e32 v56, v55, v54
	v_fma_f32 v57, -v53, v56, v55
	v_fmac_f32_e32 v56, v57, v54
	v_fma_f32 v53, -v53, v56, v55
	v_div_fmas_f32 v53, v53, v54, v56
	v_div_fixup_f32 v52, v53, v52, 1.0
	v_pk_mul_f32 v[48:49], v[48:49], v[52:53] op_sel_hi:[1,0]
	v_pk_mul_f32 v[50:51], v[50:51], v[52:53] op_sel_hi:[1,0]
	v_pk_mul_f32 v[44:45], v[44:45], v[52:53] op_sel_hi:[1,0]
	v_pk_mul_f32 v[46:47], v[46:47], v[52:53] op_sel_hi:[1,0]
	v_pk_mul_f32 v[40:41], v[40:41], v[52:53] op_sel_hi:[1,0]
	v_pk_mul_f32 v[42:43], v[42:43], v[52:53] op_sel_hi:[1,0]
	v_pk_mul_f32 v[36:37], v[36:37], v[52:53] op_sel_hi:[1,0]
	v_pk_mul_f32 v[38:39], v[38:39], v[52:53] op_sel_hi:[1,0]
	v_pk_fma_f32 v[50:51], v[16:17], v[50:51], v[2:3]
	v_pk_fma_f32 v[48:49], v[18:19], v[48:49], v[0:1]
	v_pk_fma_f32 v[46:47], v[20:21], v[46:47], v[6:7]
	v_pk_fma_f32 v[44:45], v[22:23], v[44:45], v[4:5]
	v_pk_fma_f32 v[42:43], v[24:25], v[42:43], v[10:11]
	v_pk_fma_f32 v[40:41], v[26:27], v[40:41], v[8:9]
	v_pk_fma_f32 v[38:39], v[28:29], v[38:39], v[14:15]
	v_pk_fma_f32 v[36:37], v[30:31], v[36:37], v[12:13]
	v_lshl_add_u64 v[54:55], v[34:35], 0, s[34:35]
	v_cvt_pk_bf16_f32 v48, v48, v49
	v_cvt_pk_bf16_f32 v49, v50, v51
	v_cvt_pk_bf16_f32 v44, v44, v45
	v_cvt_pk_bf16_f32 v45, v46, v47
	v_cvt_pk_bf16_f32 v40, v40, v41
	v_cvt_pk_bf16_f32 v41, v42, v43
	v_cvt_pk_bf16_f32 v36, v36, v37
	v_cvt_pk_bf16_f32 v37, v38, v39
	global_store_dwordx2 v[54:55], v[48:49], off
	global_store_dwordx2 v[54:55], v[44:45], off offset:512
	global_store_dwordx2 v[54:55], v[40:41], off offset:1024
	global_store_dwordx2 v[54:55], v[36:37], off offset:1536
	s_cbranch_scc0 .LBB0_789
	v_readlane_b32 s10, v253, 44
	v_readlane_b32 s12, v253, 42
	v_readlane_b32 s14, v253, 40
	v_readlane_b32 s16, v253, 38
	v_readlane_b32 s11, v253, 45
	v_readlane_b32 s13, v253, 43
	v_readlane_b32 s15, v253, 41
	v_readlane_b32 s17, v253, 39

.LBB0_847:
	v_mul_f32_e32 v138, 0xbfb8aa3b, v124
	v_exp_f32_e32 v138, v138
	v_mul_f32_e32 v139, 0xbfb8aa3b, v125
	v_exp_f32_e32 v139, v139
	v_mul_f32_e32 v145, 0xbfb8aa3b, v126
	v_add_f32_e32 v138, 1.0, v138
	v_rcp_f32_e32 v148, v138
	v_add_f32_e32 v138, 1.0, v139
	v_rcp_f32_e32 v149, v138
	v_exp_f32_e32 v145, v145
	v_lshl_or_b32 v146, s78, 7, v142
	v_lshl_add_u32 v144, s79, 8, v140
	v_pk_mul_f32 v[124:125], v[124:125], v[148:149]
	v_mul_f32_e32 v148, 0xbfb8aa3b, v127
	v_exp_f32_e32 v148, v148
	v_pk_mul_f32 v[116:117], v[124:125], v[116:117]
	v_add_f32_e32 v124, 1.0, v145
	v_mul_f32_e32 v145, 0xbfb8aa3b, v120
	v_add_f32_e32 v125, 1.0, v148
	v_rcp_f32_e32 v124, v124
	v_rcp_f32_e32 v125, v125
	v_exp_f32_e32 v145, v145
	v_mul_f32_e32 v148, 0xbfb8aa3b, v121
	v_exp_f32_e32 v148, v148
	v_pk_mul_f32 v[124:125], v[126:127], v[124:125]
	v_add_f32_e32 v126, 1.0, v145
	v_mul_f32_e32 v145, 0xbfb8aa3b, v122
	v_add_f32_e32 v127, 1.0, v148
	v_exp_f32_e32 v145, v145
	v_mul_f32_e32 v148, 0xbfb8aa3b, v123
	v_exp_f32_e32 v149, v148
	v_rcp_f32_e32 v126, v126
	v_add_f32_e32 v145, 1.0, v145
	v_rcp_f32_e32 v127, v127
	v_rcp_f32_e32 v148, v145
	v_add_f32_e32 v145, 1.0, v149
	v_rcp_f32_e32 v149, v145
	v_pk_mul_f32 v[120:121], v[120:121], v[126:127]
	v_pk_mul_f32 v[118:119], v[124:125], v[118:119]
	v_pk_mul_f32 v[120:121], v[120:121], v[112:113]
	v_pk_mul_f32 v[112:113], v[122:123], v[148:149]
	v_ashrrev_i32_e32 v147, 31, v146
	v_pk_mul_f32 v[122:123], v[112:113], v[114:115]
	v_cvt_pk_bf16_f32 v115, v118, v119
	v_mul_f32_e32 v118, 0xbfb8aa3b, v108
	v_mul_f32_e32 v119, 0xbfb8aa3b, v109
	v_exp_f32_e32 v118, v118
	v_exp_f32_e32 v119, v119
	v_mov_b64_e32 v[138:139], s[34:35]
	v_mad_i64_i32 v[150:151], s[68:69], v144, s29, v[138:139]
	v_lshlrev_b64 v[112:113], 1, v[146:147]
	v_lshl_add_u64 v[124:125], v[150:151], 0, v[112:113]
	v_cvt_pk_bf16_f32 v114, v116, v117
	v_cvt_pk_bf16_f32 v116, v120, v121
	v_cvt_pk_bf16_f32 v117, v122, v123
	global_store_dwordx4 v[124:125], v[114:117], off
	s_andn2_b64 vcc, exec, s[38:39]
	s_mov_b64 s[38:39], -1
	v_add_f32_e32 v114, 1.0, v118
	v_add_f32_e32 v115, 1.0, v119
	v_rcp_f32_e32 v114, v114
	v_rcp_f32_e32 v115, v115
	v_or_b32_e32 v116, 16, v144
	v_mad_i64_i32 v[116:117], s[68:69], v116, s29, v[138:139]
	v_pk_mul_f32 v[108:109], v[108:109], v[114:115]
	v_mul_f32_e32 v114, 0xbfb8aa3b, v110
	v_mul_f32_e32 v115, 0xbfb8aa3b, v111
	v_exp_f32_e32 v114, v114
	v_exp_f32_e32 v115, v115
	v_pk_mul_f32 v[100:101], v[108:109], v[100:101]
	v_add_f32_e32 v108, 1.0, v114
	v_add_f32_e32 v109, 1.0, v115
	v_mul_f32_e32 v114, 0xbfb8aa3b, v104
	v_mul_f32_e32 v115, 0xbfb8aa3b, v105
	v_rcp_f32_e32 v108, v108
	v_rcp_f32_e32 v109, v109
	v_exp_f32_e32 v114, v114
	v_exp_f32_e32 v115, v115
	v_pk_mul_f32 v[108:109], v[110:111], v[108:109]
	v_add_f32_e32 v110, 1.0, v114
	v_add_f32_e32 v111, 1.0, v115
	v_mul_f32_e32 v114, 0xbfb8aa3b, v106
	v_mul_f32_e32 v115, 0xbfb8aa3b, v107
	v_exp_f32_e32 v114, v114
	v_exp_f32_e32 v115, v115
	v_rcp_f32_e32 v110, v110
	v_rcp_f32_e32 v111, v111
	v_add_f32_e32 v114, 1.0, v114
	v_add_f32_e32 v115, 1.0, v115
	v_rcp_f32_e32 v114, v114
	v_rcp_f32_e32 v115, v115
	v_pk_mul_f32 v[104:105], v[104:105], v[110:111]
	v_pk_mul_f32 v[102:103], v[108:109], v[102:103]
	v_pk_mul_f32 v[104:105], v[104:105], v[96:97]
	v_pk_mul_f32 v[96:97], v[106:107], v[114:115]
	v_lshl_add_u64 v[108:109], v[116:117], 0, v[112:113]
	v_pk_mul_f32 v[106:107], v[96:97], v[98:99]
	v_cvt_pk_bf16_f32 v96, v100, v101
	v_mul_f32_e32 v100, 0xbfb8aa3b, v92
	v_mul_f32_e32 v101, 0xbfb8aa3b, v93
	v_exp_f32_e32 v100, v100
	v_exp_f32_e32 v101, v101
	v_cvt_pk_bf16_f32 v97, v102, v103
	v_cvt_pk_bf16_f32 v98, v104, v105
	v_cvt_pk_bf16_f32 v99, v106, v107
	global_store_dwordx4 v[108:109], v[96:99], off
	s_nop 1
	v_add_f32_e32 v96, 1.0, v100
	v_add_f32_e32 v97, 1.0, v101
	v_rcp_f32_e32 v96, v96
	v_rcp_f32_e32 v97, v97
	v_or_b32_e32 v98, 32, v144
	v_mad_i64_i32 v[98:99], s[68:69], v98, s29, v[138:139]
	v_pk_mul_f32 v[92:93], v[92:93], v[96:97]
	v_mul_f32_e32 v96, 0xbfb8aa3b, v94
	v_mul_f32_e32 v97, 0xbfb8aa3b, v95
	v_exp_f32_e32 v96, v96
	v_exp_f32_e32 v97, v97
	v_pk_mul_f32 v[84:85], v[92:93], v[84:85]
	v_add_f32_e32 v92, 1.0, v96
	v_add_f32_e32 v93, 1.0, v97
	v_mul_f32_e32 v96, 0xbfb8aa3b, v88
	v_mul_f32_e32 v97, 0xbfb8aa3b, v89
	v_rcp_f32_e32 v92, v92
	v_rcp_f32_e32 v93, v93
	v_exp_f32_e32 v96, v96
	v_exp_f32_e32 v97, v97
	v_pk_mul_f32 v[92:93], v[94:95], v[92:93]
	v_add_f32_e32 v94, 1.0, v96
	v_add_f32_e32 v95, 1.0, v97
	v_mul_f32_e32 v96, 0xbfb8aa3b, v90
	v_mul_f32_e32 v97, 0xbfb8aa3b, v91
	v_exp_f32_e32 v96, v96
	v_exp_f32_e32 v97, v97
	v_rcp_f32_e32 v94, v94
	v_rcp_f32_e32 v95, v95
	v_add_f32_e32 v96, 1.0, v96
	v_add_f32_e32 v97, 1.0, v97
	v_rcp_f32_e32 v96, v96
	v_rcp_f32_e32 v97, v97
	v_pk_mul_f32 v[88:89], v[88:89], v[94:95]
	v_pk_mul_f32 v[86:87], v[92:93], v[86:87]
	v_pk_mul_f32 v[88:89], v[88:89], v[80:81]
	v_pk_mul_f32 v[80:81], v[90:91], v[96:97]
	v_lshl_add_u64 v[92:93], v[98:99], 0, v[112:113]
	v_pk_mul_f32 v[90:91], v[80:81], v[82:83]
	v_cvt_pk_bf16_f32 v80, v84, v85
	v_mul_f32_e32 v84, 0xbfb8aa3b, v76
	v_mul_f32_e32 v85, 0xbfb8aa3b, v77
	v_exp_f32_e32 v84, v84
	v_exp_f32_e32 v85, v85
	v_cvt_pk_bf16_f32 v81, v86, v87
	v_cvt_pk_bf16_f32 v82, v88, v89
	v_cvt_pk_bf16_f32 v83, v90, v91
	global_store_dwordx4 v[92:93], v[80:83], off
	s_nop 1
	v_add_f32_e32 v80, 1.0, v84
	v_add_f32_e32 v81, 1.0, v85
	v_rcp_f32_e32 v80, v80
	v_rcp_f32_e32 v81, v81
	v_or_b32_e32 v82, 48, v144
	v_mad_i64_i32 v[82:83], s[68:69], v82, s29, v[138:139]
	v_pk_mul_f32 v[76:77], v[76:77], v[80:81]
	v_mul_f32_e32 v80, 0xbfb8aa3b, v78
	v_mul_f32_e32 v81, 0xbfb8aa3b, v79
	v_exp_f32_e32 v80, v80
	v_exp_f32_e32 v81, v81
	v_pk_mul_f32 v[68:69], v[76:77], v[68:69]
	v_add_f32_e32 v76, 1.0, v80
	v_add_f32_e32 v77, 1.0, v81
	v_mul_f32_e32 v80, 0xbfb8aa3b, v72
	v_mul_f32_e32 v81, 0xbfb8aa3b, v73
	v_rcp_f32_e32 v76, v76
	v_rcp_f32_e32 v77, v77
	v_exp_f32_e32 v80, v80
	v_exp_f32_e32 v81, v81
	v_pk_mul_f32 v[76:77], v[78:79], v[76:77]
	v_add_f32_e32 v78, 1.0, v80
	v_add_f32_e32 v79, 1.0, v81
	v_mul_f32_e32 v80, 0xbfb8aa3b, v74
	v_mul_f32_e32 v81, 0xbfb8aa3b, v75
	v_exp_f32_e32 v80, v80
	v_exp_f32_e32 v81, v81
	v_rcp_f32_e32 v78, v78
	v_rcp_f32_e32 v79, v79
	v_add_f32_e32 v80, 1.0, v80
	v_add_f32_e32 v81, 1.0, v81
	v_rcp_f32_e32 v80, v80
	v_rcp_f32_e32 v81, v81
	v_pk_mul_f32 v[72:73], v[72:73], v[78:79]
	v_pk_mul_f32 v[70:71], v[76:77], v[70:71]
	v_pk_mul_f32 v[72:73], v[72:73], v[64:65]
	v_pk_mul_f32 v[64:65], v[74:75], v[80:81]
	v_lshl_add_u64 v[76:77], v[82:83], 0, v[112:113]
	v_pk_mul_f32 v[74:75], v[64:65], v[66:67]
	v_cvt_pk_bf16_f32 v64, v68, v69
	v_mul_f32_e32 v68, 0xbfb8aa3b, v60
	v_mul_f32_e32 v69, 0xbfb8aa3b, v61
	v_exp_f32_e32 v68, v68
	v_exp_f32_e32 v69, v69
	v_cvt_pk_bf16_f32 v65, v70, v71
	v_cvt_pk_bf16_f32 v66, v72, v73
	v_cvt_pk_bf16_f32 v67, v74, v75
	global_store_dwordx4 v[76:77], v[64:67], off
	s_nop 1
	v_add_f32_e32 v64, 1.0, v68
	v_add_f32_e32 v65, 1.0, v69
	v_rcp_f32_e32 v64, v64
	v_rcp_f32_e32 v65, v65
	v_add_u32_e32 v66, 0x80, v144
	v_mad_i64_i32 v[66:67], s[68:69], v66, s29, v[138:139]
	v_pk_mul_f32 v[60:61], v[60:61], v[64:65]
	v_mul_f32_e32 v64, 0xbfb8aa3b, v62
	v_mul_f32_e32 v65, 0xbfb8aa3b, v63
	v_exp_f32_e32 v64, v64
	v_exp_f32_e32 v65, v65
	v_pk_mul_f32 v[52:53], v[60:61], v[52:53]
	v_add_f32_e32 v60, 1.0, v64
	v_add_f32_e32 v61, 1.0, v65
	v_mul_f32_e32 v64, 0xbfb8aa3b, v56
	v_mul_f32_e32 v65, 0xbfb8aa3b, v57
	v_rcp_f32_e32 v60, v60
	v_rcp_f32_e32 v61, v61
	v_exp_f32_e32 v64, v64
	v_exp_f32_e32 v65, v65
	v_pk_mul_f32 v[60:61], v[62:63], v[60:61]
	v_add_f32_e32 v62, 1.0, v64
	v_add_f32_e32 v63, 1.0, v65
	v_mul_f32_e32 v64, 0xbfb8aa3b, v58
	v_mul_f32_e32 v65, 0xbfb8aa3b, v59
	v_exp_f32_e32 v64, v64
	v_exp_f32_e32 v65, v65
	v_rcp_f32_e32 v62, v62
	v_rcp_f32_e32 v63, v63
	v_add_f32_e32 v64, 1.0, v64
	v_add_f32_e32 v65, 1.0, v65
	v_rcp_f32_e32 v64, v64
	v_rcp_f32_e32 v65, v65
	v_pk_mul_f32 v[56:57], v[56:57], v[62:63]
	v_pk_mul_f32 v[54:55], v[60:61], v[54:55]
	v_pk_mul_f32 v[56:57], v[56:57], v[48:49]
	v_pk_mul_f32 v[48:49], v[58:59], v[64:65]
	v_lshl_add_u64 v[60:61], v[66:67], 0, v[112:113]
	v_pk_mul_f32 v[58:59], v[48:49], v[50:51]
	v_cvt_pk_bf16_f32 v48, v52, v53
	v_mul_f32_e32 v52, 0xbfb8aa3b, v44
	v_mul_f32_e32 v53, 0xbfb8aa3b, v45
	v_exp_f32_e32 v52, v52
	v_exp_f32_e32 v53, v53
	v_cvt_pk_bf16_f32 v49, v54, v55
	v_cvt_pk_bf16_f32 v50, v56, v57
	v_cvt_pk_bf16_f32 v51, v58, v59
	global_store_dwordx4 v[60:61], v[48:51], off
	s_nop 1
	v_add_f32_e32 v48, 1.0, v52
	v_add_f32_e32 v49, 1.0, v53
	v_rcp_f32_e32 v48, v48
	v_rcp_f32_e32 v49, v49
	v_add_u32_e32 v50, 0x90, v144
	v_mad_i64_i32 v[50:51], s[68:69], v50, s29, v[138:139]
	v_pk_mul_f32 v[44:45], v[44:45], v[48:49]
	v_mul_f32_e32 v48, 0xbfb8aa3b, v46
	v_mul_f32_e32 v49, 0xbfb8aa3b, v47
	v_exp_f32_e32 v48, v48
	v_exp_f32_e32 v49, v49
	v_pk_mul_f32 v[36:37], v[44:45], v[36:37]
	v_add_f32_e32 v44, 1.0, v48
	v_add_f32_e32 v45, 1.0, v49
	v_mul_f32_e32 v48, 0xbfb8aa3b, v40
	v_mul_f32_e32 v49, 0xbfb8aa3b, v41
	v_rcp_f32_e32 v44, v44
	v_rcp_f32_e32 v45, v45
	v_exp_f32_e32 v48, v48
	v_exp_f32_e32 v49, v49
	v_pk_mul_f32 v[44:45], v[46:47], v[44:45]
	v_add_f32_e32 v46, 1.0, v48
	v_add_f32_e32 v47, 1.0, v49
	v_mul_f32_e32 v48, 0xbfb8aa3b, v42
	v_mul_f32_e32 v49, 0xbfb8aa3b, v43
	v_exp_f32_e32 v48, v48
	v_exp_f32_e32 v49, v49
	v_rcp_f32_e32 v46, v46
	v_rcp_f32_e32 v47, v47
	v_add_f32_e32 v48, 1.0, v48
	v_add_f32_e32 v49, 1.0, v49
	v_rcp_f32_e32 v48, v48
	v_rcp_f32_e32 v49, v49
	v_pk_mul_f32 v[40:41], v[40:41], v[46:47]
	v_pk_mul_f32 v[38:39], v[44:45], v[38:39]
	v_pk_mul_f32 v[40:41], v[40:41], v[32:33]
	v_pk_mul_f32 v[32:33], v[42:43], v[48:49]
	v_lshl_add_u64 v[44:45], v[50:51], 0, v[112:113]
	v_pk_mul_f32 v[42:43], v[32:33], v[34:35]
	v_cvt_pk_bf16_f32 v32, v36, v37
	v_mul_f32_e32 v36, 0xbfb8aa3b, v28
	v_mul_f32_e32 v37, 0xbfb8aa3b, v29
	v_exp_f32_e32 v36, v36
	v_exp_f32_e32 v37, v37
	v_cvt_pk_bf16_f32 v33, v38, v39
	v_cvt_pk_bf16_f32 v34, v40, v41
	v_cvt_pk_bf16_f32 v35, v42, v43
	global_store_dwordx4 v[44:45], v[32:35], off
	s_nop 1
	v_add_f32_e32 v32, 1.0, v36
	v_add_f32_e32 v33, 1.0, v37
	v_rcp_f32_e32 v32, v32
	v_rcp_f32_e32 v33, v33
	v_add_u32_e32 v34, 0xa0, v144
	v_mad_i64_i32 v[34:35], s[68:69], v34, s29, v[138:139]
	v_pk_mul_f32 v[28:29], v[28:29], v[32:33]
	v_mul_f32_e32 v32, 0xbfb8aa3b, v30
	v_mul_f32_e32 v33, 0xbfb8aa3b, v31
	v_exp_f32_e32 v32, v32
	v_exp_f32_e32 v33, v33
	v_pk_mul_f32 v[20:21], v[28:29], v[20:21]
	v_add_f32_e32 v28, 1.0, v32
	v_add_f32_e32 v29, 1.0, v33
	v_mul_f32_e32 v32, 0xbfb8aa3b, v24
	v_mul_f32_e32 v33, 0xbfb8aa3b, v25
	v_rcp_f32_e32 v28, v28
	v_rcp_f32_e32 v29, v29
	v_exp_f32_e32 v32, v32
	v_exp_f32_e32 v33, v33
	v_pk_mul_f32 v[28:29], v[30:31], v[28:29]
	v_add_f32_e32 v30, 1.0, v32
	v_add_f32_e32 v31, 1.0, v33
	v_mul_f32_e32 v32, 0xbfb8aa3b, v26
	v_mul_f32_e32 v33, 0xbfb8aa3b, v27
	v_exp_f32_e32 v32, v32
	v_exp_f32_e32 v33, v33
	v_rcp_f32_e32 v30, v30
	v_rcp_f32_e32 v31, v31
	v_add_f32_e32 v32, 1.0, v32
	v_add_f32_e32 v33, 1.0, v33
	v_rcp_f32_e32 v32, v32
	v_rcp_f32_e32 v33, v33
	v_pk_mul_f32 v[24:25], v[24:25], v[30:31]
	v_pk_mul_f32 v[22:23], v[28:29], v[22:23]
	v_pk_mul_f32 v[24:25], v[24:25], v[16:17]
	v_pk_mul_f32 v[16:17], v[26:27], v[32:33]
	v_lshl_add_u64 v[28:29], v[34:35], 0, v[112:113]
	v_pk_mul_f32 v[26:27], v[16:17], v[18:19]
	v_cvt_pk_bf16_f32 v16, v20, v21
	v_mul_f32_e32 v20, 0xbfb8aa3b, v12
	v_mul_f32_e32 v21, 0xbfb8aa3b, v13
	v_exp_f32_e32 v20, v20
	v_exp_f32_e32 v21, v21
	v_cvt_pk_bf16_f32 v17, v22, v23
	v_cvt_pk_bf16_f32 v18, v24, v25
	v_cvt_pk_bf16_f32 v19, v26, v27
	global_store_dwordx4 v[28:29], v[16:19], off
	s_nop 1
	v_add_f32_e32 v16, 1.0, v20
	v_add_f32_e32 v17, 1.0, v21
	v_rcp_f32_e32 v16, v16
	v_rcp_f32_e32 v17, v17
	v_add_u32_e32 v18, 0xb0, v144
	v_mad_i64_i32 v[18:19], s[68:69], v18, s29, v[138:139]
	v_pk_mul_f32 v[12:13], v[12:13], v[16:17]
	v_mul_f32_e32 v16, 0xbfb8aa3b, v14
	v_mul_f32_e32 v17, 0xbfb8aa3b, v15
	v_exp_f32_e32 v16, v16
	v_exp_f32_e32 v17, v17
	v_pk_mul_f32 v[4:5], v[12:13], v[4:5]
	v_add_f32_e32 v12, 1.0, v16
	v_add_f32_e32 v13, 1.0, v17
	v_mul_f32_e32 v16, 0xbfb8aa3b, v8
	v_mul_f32_e32 v17, 0xbfb8aa3b, v9
	v_rcp_f32_e32 v12, v12
	v_rcp_f32_e32 v13, v13
	v_exp_f32_e32 v16, v16
	v_exp_f32_e32 v17, v17
	v_pk_mul_f32 v[12:13], v[14:15], v[12:13]
	v_add_f32_e32 v14, 1.0, v16
	v_add_f32_e32 v15, 1.0, v17
	v_mul_f32_e32 v16, 0xbfb8aa3b, v10
	v_mul_f32_e32 v17, 0xbfb8aa3b, v11
	v_exp_f32_e32 v16, v16
	v_exp_f32_e32 v17, v17
	v_rcp_f32_e32 v14, v14
	v_rcp_f32_e32 v15, v15
	v_add_f32_e32 v16, 1.0, v16
	v_add_f32_e32 v17, 1.0, v17
	v_rcp_f32_e32 v16, v16
	v_rcp_f32_e32 v17, v17
	v_pk_mul_f32 v[8:9], v[8:9], v[14:15]
	v_pk_mul_f32 v[6:7], v[12:13], v[6:7]
	v_pk_mul_f32 v[8:9], v[8:9], v[0:1]
	v_pk_mul_f32 v[0:1], v[10:11], v[16:17]
	v_lshl_add_u64 v[12:13], v[18:19], 0, v[112:113]
	v_pk_mul_f32 v[10:11], v[0:1], v[2:3]
	v_cvt_pk_bf16_f32 v0, v4, v5
	v_cvt_pk_bf16_f32 v1, v6, v7
	v_cvt_pk_bf16_f32 v2, v8, v9
	v_cvt_pk_bf16_f32 v3, v10, v11
	global_store_dwordx4 v[12:13], v[0:3], off
	s_cbranch_vccnz .LBB0_840
	s_andn2_b64 vcc, exec, s[0:1]
	s_cbranch_vccnz .LBB0_839
	s_barrier
	s_branch .LBB0_839

.LBB0_920:
	s_ashr_i32 s48, s73, 31
	s_and_b64 s[46:47], s[46:47], exec
	s_cselect_b32 s47, s48, 0
	s_cselect_b32 s46, s73, s90
	s_lshl_b64 s[90:91], s[46:47], 11
	s_add_u32 s70, s70, s90
	s_addc_u32 s71, s71, s91
	s_lshl_b64 s[46:47], s[46:47], 12
	s_add_u32 s46, s68, s46
	s_addc_u32 s47, s69, s47
	s_lshl_b32 s48, s62, 8
	s_or_b32 s48, s48, s80
	v_lshl_add_u32 v146, v129, 3, s48
	s_mul_i32 s49, s72, 0x9000
	s_mul_hi_i32 s48, s72, 0x9000
	s_add_u32 s68, s77, s49
	v_ashrrev_i32_e32 v147, 31, v146
	s_addc_u32 s69, s78, s48
	v_lshlrev_b64 v[148:149], 2, v[146:147]
	v_lshl_add_u64 v[142:143], s[68:69], 0, v[148:149]
	global_load_dwordx4 v[130:133], v[142:143], off
	global_load_dwordx4 v[134:137], v[142:143], off offset:16
	global_load_dwordx4 v[138:141], v[142:143], off offset:512
	s_nop 0
	global_load_dwordx4 v[142:145], v[142:143], off offset:528
	v_add_u32_e32 v196, s79, v128
	v_ashrrev_i32_e32 v197, 31, v196
	v_lshl_add_u64 v[194:195], v[146:147], 1, s[70:71]
	v_lshlrev_b64 v[128:129], 11, v[196:197]
	v_lshl_add_u64 v[128:129], v[194:195], 0, v[128:129]
	global_load_dwordx4 v[206:209], v[128:129], off
	global_load_dwordx4 v[210:213], v[128:129], off offset:256
	v_add_u32_e32 v186, 16, v196
	v_ashrrev_i32_e32 v187, 31, v186
	v_lshlrev_b64 v[128:129], 11, v[186:187]
	v_lshl_add_u64 v[128:129], v[194:195], 0, v[128:129]
	v_lshl_add_u64 v[192:193], s[46:47], 0, v[148:149]
	v_add_u32_e32 v200, 32, v196
	v_ashrrev_i32_e32 v201, 31, v200
	v_add_u32_e32 v198, 48, v196
	v_ashrrev_i32_e32 v199, 31, v198
	v_lshlrev_b64 v[214:215], 12, v[196:197]
	v_lshl_add_u64 v[214:215], v[192:193], 0, v[214:215]
	s_mov_b64 s[46:47], -1
	s_and_b64 vcc, exec, s[38:39]
	s_waitcnt vmcnt(0) lgkmcnt(0)
	v_pk_mul_f32 v[174:175], v[132:133], 0.5 op_sel_hi:[1,0]
	v_pk_mul_f32 v[170:171], v[136:137], 0.5 op_sel_hi:[1,0]
	v_pk_mul_f32 v[166:167], v[140:141], 0.5 op_sel_hi:[1,0]
	v_pk_mul_f32 v[162:163], v[144:145], 0.5 op_sel_hi:[1,0]
	global_load_dwordx4 v[148:151], v[128:129], off
	global_load_dwordx4 v[144:147], v[128:129], off offset:256
	v_lshlrev_b64 v[128:129], 11, v[200:201]
	v_lshl_add_u64 v[128:129], v[194:195], 0, v[128:129]
	v_pk_mul_f32 v[168:169], v[138:139], 0.5 op_sel_hi:[1,0]
	v_pk_mul_f32 v[164:165], v[142:143], 0.5 op_sel_hi:[1,0]
	global_load_dwordx4 v[140:143], v[128:129], off
	global_load_dwordx4 v[136:139], v[128:129], off offset:256
	v_lshlrev_b64 v[128:129], 11, v[198:199]
	v_lshl_add_u64 v[128:129], v[194:195], 0, v[128:129]
	v_pk_mul_f32 v[190:191], v[130:131], 0.5 op_sel_hi:[1,0]
	v_pk_mul_f32 v[172:173], v[134:135], 0.5 op_sel_hi:[1,0]
	global_load_dwordx4 v[132:135], v[128:129], off
	s_nop 0
	global_load_dwordx4 v[128:131], v[128:129], off offset:256
	v_cvt_f32_f16_e32 v216, v206
	v_cvt_f32_f16_sdwa v217, v206 dst_sel:DWORD dst_unused:UNUSED_PAD src0_sel:WORD_1
	v_cvt_f32_f16_e32 v206, v207
	v_cvt_f32_f16_sdwa v207, v207 dst_sel:DWORD dst_unused:UNUSED_PAD src0_sel:WORD_1
	v_pk_fma_f32 v[124:125], v[124:125], v[190:191], v[216:217]
	v_pk_fma_f32 v[126:127], v[126:127], v[174:175], v[206:207]
	v_cvt_f32_f16_e32 v206, v208
	v_cvt_f32_f16_sdwa v207, v208 dst_sel:DWORD dst_unused:UNUSED_PAD src0_sel:WORD_1
	v_cvt_f32_f16_e32 v208, v209
	v_cvt_f32_f16_sdwa v209, v209 dst_sel:DWORD dst_unused:UNUSED_PAD src0_sel:WORD_1
	v_pk_fma_f32 v[120:121], v[120:121], v[172:173], v[206:207]
	v_pk_fma_f32 v[122:123], v[122:123], v[170:171], v[208:209]
	global_store_dwordx4 v[214:215], v[124:127], off
	global_store_dwordx4 v[214:215], v[120:123], off offset:16
	s_nop 1
	v_cvt_f32_f16_e32 v122, v211
	v_cvt_f32_f16_sdwa v123, v211 dst_sel:DWORD dst_unused:UNUSED_PAD src0_sel:WORD_1
	v_cvt_f32_f16_e32 v120, v210
	v_cvt_f32_f16_sdwa v121, v210 dst_sel:DWORD dst_unused:UNUSED_PAD src0_sel:WORD_1
	v_pk_fma_f32 v[118:119], v[118:119], v[166:167], v[122:123]
	v_cvt_f32_f16_e32 v122, v213
	v_cvt_f32_f16_sdwa v123, v213 dst_sel:DWORD dst_unused:UNUSED_PAD src0_sel:WORD_1
	v_pk_fma_f32 v[116:117], v[116:117], v[168:169], v[120:121]
	v_cvt_f32_f16_e32 v120, v212
	v_cvt_f32_f16_sdwa v121, v212 dst_sel:DWORD dst_unused:UNUSED_PAD src0_sel:WORD_1
	v_pk_fma_f32 v[114:115], v[114:115], v[162:163], v[122:123]
	v_pk_fma_f32 v[112:113], v[112:113], v[164:165], v[120:121]
	global_store_dwordx4 v[214:215], v[116:119], off offset:512
	global_store_dwordx4 v[214:215], v[112:115], off offset:528
	s_waitcnt vmcnt(0) lgkmcnt(0)
	v_cvt_f32_f16_e32 v116, v149
	v_cvt_f32_f16_e32 v114, v148
	v_cvt_f32_f16_sdwa v115, v148 dst_sel:DWORD dst_unused:UNUSED_PAD src0_sel:WORD_1
	v_cvt_f32_f16_sdwa v117, v149 dst_sel:DWORD dst_unused:UNUSED_PAD src0_sel:WORD_1
	v_lshlrev_b64 v[112:113], 12, v[186:187]
	v_lshl_add_u64 v[112:113], v[192:193], 0, v[112:113]
	v_pk_fma_f32 v[108:109], v[108:109], v[190:191], v[114:115]
	v_cvt_f32_f16_e32 v114, v150
	v_cvt_f32_f16_sdwa v115, v150 dst_sel:DWORD dst_unused:UNUSED_PAD src0_sel:WORD_1
	v_pk_fma_f32 v[110:111], v[110:111], v[174:175], v[116:117]
	v_cvt_f32_f16_e32 v116, v151
	v_cvt_f32_f16_sdwa v117, v151 dst_sel:DWORD dst_unused:UNUSED_PAD src0_sel:WORD_1
	v_pk_fma_f32 v[104:105], v[104:105], v[172:173], v[114:115]
	v_pk_fma_f32 v[106:107], v[106:107], v[170:171], v[116:117]
	global_store_dwordx4 v[112:113], v[108:111], off
	global_store_dwordx4 v[112:113], v[104:107], off offset:16
	s_nop 1
	v_cvt_f32_f16_e32 v104, v144
	v_cvt_f32_f16_sdwa v105, v144 dst_sel:DWORD dst_unused:UNUSED_PAD src0_sel:WORD_1
	v_cvt_f32_f16_e32 v106, v145
	v_cvt_f32_f16_sdwa v107, v145 dst_sel:DWORD dst_unused:UNUSED_PAD src0_sel:WORD_1
	v_pk_fma_f32 v[100:101], v[100:101], v[168:169], v[104:105]
	v_cvt_f32_f16_e32 v104, v146
	v_cvt_f32_f16_sdwa v105, v146 dst_sel:DWORD dst_unused:UNUSED_PAD src0_sel:WORD_1
	v_pk_fma_f32 v[102:103], v[102:103], v[166:167], v[106:107]
	v_cvt_f32_f16_e32 v106, v147
	v_cvt_f32_f16_sdwa v107, v147 dst_sel:DWORD dst_unused:UNUSED_PAD src0_sel:WORD_1
	v_pk_fma_f32 v[92:93], v[92:93], v[164:165], v[104:105]
	v_pk_fma_f32 v[94:95], v[94:95], v[162:163], v[106:107]
	global_store_dwordx4 v[112:113], v[100:103], off offset:512
	global_store_dwordx4 v[112:113], v[92:95], off offset:528
	s_nop 0
	v_add_u32_e32 v102, 0x90, v196
	v_lshlrev_b64 v[92:93], 12, v[200:201]
	v_lshl_add_u64 v[100:101], v[192:193], 0, v[92:93]
	v_cvt_f32_f16_e32 v92, v140
	v_cvt_f32_f16_sdwa v93, v140 dst_sel:DWORD dst_unused:UNUSED_PAD src0_sel:WORD_1
	v_cvt_f32_f16_e32 v94, v141
	v_cvt_f32_f16_sdwa v95, v141 dst_sel:DWORD dst_unused:UNUSED_PAD src0_sel:WORD_1
	v_ashrrev_i32_e32 v103, 31, v102
	v_pk_fma_f32 v[92:93], v[96:97], v[190:191], v[92:93]
	v_cvt_f32_f16_e32 v96, v142
	v_cvt_f32_f16_sdwa v97, v142 dst_sel:DWORD dst_unused:UNUSED_PAD src0_sel:WORD_1
	v_pk_fma_f32 v[94:95], v[98:99], v[174:175], v[94:95]
	v_cvt_f32_f16_e32 v98, v143
	v_cvt_f32_f16_sdwa v99, v143 dst_sel:DWORD dst_unused:UNUSED_PAD src0_sel:WORD_1
	v_pk_fma_f32 v[88:89], v[88:89], v[172:173], v[96:97]
	v_pk_fma_f32 v[90:91], v[90:91], v[170:171], v[98:99]
	global_store_dwordx4 v[100:101], v[92:95], off
	global_store_dwordx4 v[100:101], v[88:91], off offset:16
	s_nop 1
	v_cvt_f32_f16_e32 v88, v136
	v_cvt_f32_f16_sdwa v89, v136 dst_sel:DWORD dst_unused:UNUSED_PAD src0_sel:WORD_1
	v_cvt_f32_f16_e32 v90, v137
	v_cvt_f32_f16_sdwa v91, v137 dst_sel:DWORD dst_unused:UNUSED_PAD src0_sel:WORD_1
	v_pk_fma_f32 v[84:85], v[84:85], v[168:169], v[88:89]
	v_cvt_f32_f16_e32 v88, v138
	v_cvt_f32_f16_sdwa v89, v138 dst_sel:DWORD dst_unused:UNUSED_PAD src0_sel:WORD_1
	v_pk_fma_f32 v[86:87], v[86:87], v[166:167], v[90:91]
	v_cvt_f32_f16_e32 v90, v139
	v_cvt_f32_f16_sdwa v91, v139 dst_sel:DWORD dst_unused:UNUSED_PAD src0_sel:WORD_1
	v_pk_fma_f32 v[76:77], v[76:77], v[164:165], v[88:89]
	v_pk_fma_f32 v[78:79], v[78:79], v[162:163], v[90:91]
	global_store_dwordx4 v[100:101], v[84:87], off offset:512
	global_store_dwordx4 v[100:101], v[76:79], off offset:528
	v_add_u32_e32 v100, 0x80, v196
	v_ashrrev_i32_e32 v101, 31, v100
	v_lshlrev_b64 v[76:77], 12, v[198:199]
	v_lshl_add_u64 v[84:85], v[192:193], 0, v[76:77]
	v_cvt_f32_f16_e32 v76, v132
	v_cvt_f32_f16_sdwa v77, v132 dst_sel:DWORD dst_unused:UNUSED_PAD src0_sel:WORD_1
	v_cvt_f32_f16_e32 v78, v133
	v_cvt_f32_f16_sdwa v79, v133 dst_sel:DWORD dst_unused:UNUSED_PAD src0_sel:WORD_1
	v_pk_fma_f32 v[76:77], v[80:81], v[190:191], v[76:77]
	v_cvt_f32_f16_e32 v80, v134
	v_cvt_f32_f16_sdwa v81, v134 dst_sel:DWORD dst_unused:UNUSED_PAD src0_sel:WORD_1
	v_pk_fma_f32 v[78:79], v[82:83], v[174:175], v[78:79]
	v_cvt_f32_f16_e32 v82, v135
	v_cvt_f32_f16_sdwa v83, v135 dst_sel:DWORD dst_unused:UNUSED_PAD src0_sel:WORD_1
	v_pk_fma_f32 v[72:73], v[72:73], v[172:173], v[80:81]
	v_add_u32_e32 v80, 0xb0, v196
	v_ashrrev_i32_e32 v81, 31, v80
	v_pk_fma_f32 v[74:75], v[74:75], v[170:171], v[82:83]
	global_store_dwordx4 v[84:85], v[76:79], off
	global_store_dwordx4 v[84:85], v[72:75], off offset:16
	v_add_u32_e32 v82, 0xa0, v196
	v_ashrrev_i32_e32 v83, 31, v82
	v_cvt_f32_f16_e32 v72, v128
	v_cvt_f32_f16_sdwa v73, v128 dst_sel:DWORD dst_unused:UNUSED_PAD src0_sel:WORD_1
	v_cvt_f32_f16_e32 v74, v129
	v_cvt_f32_f16_sdwa v75, v129 dst_sel:DWORD dst_unused:UNUSED_PAD src0_sel:WORD_1
	v_pk_fma_f32 v[68:69], v[68:69], v[168:169], v[72:73]
	v_cvt_f32_f16_e32 v72, v130
	v_cvt_f32_f16_sdwa v73, v130 dst_sel:DWORD dst_unused:UNUSED_PAD src0_sel:WORD_1
	v_pk_fma_f32 v[70:71], v[70:71], v[166:167], v[74:75]
	v_cvt_f32_f16_e32 v74, v131
	v_cvt_f32_f16_sdwa v75, v131 dst_sel:DWORD dst_unused:UNUSED_PAD src0_sel:WORD_1
	v_pk_fma_f32 v[64:65], v[64:65], v[164:165], v[72:73]
	v_pk_fma_f32 v[66:67], v[66:67], v[162:163], v[74:75]
	global_store_dwordx4 v[84:85], v[68:71], off offset:512
	global_store_dwordx4 v[84:85], v[64:67], off offset:528
	s_nop 1
	v_lshlrev_b64 v[64:65], 11, v[100:101]
	v_lshl_add_u64 v[64:65], v[194:195], 0, v[64:65]
	global_load_dwordx4 v[84:87], v[64:65], off
	global_load_dwordx4 v[88:91], v[64:65], off offset:256
	v_lshlrev_b64 v[64:65], 11, v[102:103]
	v_lshl_add_u64 v[64:65], v[194:195], 0, v[64:65]
	global_load_dwordx4 v[92:95], v[64:65], off
	global_load_dwordx4 v[96:99], v[64:65], off offset:256
	v_lshlrev_b64 v[64:65], 11, v[82:83]
	v_lshl_add_u64 v[64:65], v[194:195], 0, v[64:65]
	global_load_dwordx4 v[76:79], v[64:65], off
	global_load_dwordx4 v[72:75], v[64:65], off offset:256
	v_lshlrev_b64 v[64:65], 11, v[80:81]
	v_lshl_add_u64 v[64:65], v[194:195], 0, v[64:65]
	global_load_dwordx4 v[68:71], v[64:65], off
	s_nop 0
	global_load_dwordx4 v[64:67], v[64:65], off offset:256
	v_lshlrev_b64 v[100:101], 12, v[100:101]
	v_lshl_add_u64 v[100:101], v[192:193], 0, v[100:101]
	s_waitcnt vmcnt(0) lgkmcnt(0)
	v_cvt_f32_f16_e32 v104, v84
	v_cvt_f32_f16_sdwa v105, v84 dst_sel:DWORD dst_unused:UNUSED_PAD src0_sel:WORD_1
	v_cvt_f32_f16_e32 v84, v85
	v_cvt_f32_f16_sdwa v85, v85 dst_sel:DWORD dst_unused:UNUSED_PAD src0_sel:WORD_1
	v_pk_fma_f32 v[60:61], v[60:61], v[190:191], v[104:105]
	v_pk_fma_f32 v[62:63], v[62:63], v[174:175], v[84:85]
	v_cvt_f32_f16_e32 v84, v86
	v_cvt_f32_f16_sdwa v85, v86 dst_sel:DWORD dst_unused:UNUSED_PAD src0_sel:WORD_1
	v_cvt_f32_f16_e32 v86, v87
	v_cvt_f32_f16_sdwa v87, v87 dst_sel:DWORD dst_unused:UNUSED_PAD src0_sel:WORD_1
	v_pk_fma_f32 v[56:57], v[56:57], v[172:173], v[84:85]
	v_pk_fma_f32 v[58:59], v[58:59], v[170:171], v[86:87]
	global_store_dwordx4 v[100:101], v[60:63], off
	global_store_dwordx4 v[100:101], v[56:59], off offset:16
	s_nop 1
	v_cvt_f32_f16_e32 v56, v88
	v_cvt_f32_f16_sdwa v57, v88 dst_sel:DWORD dst_unused:UNUSED_PAD src0_sel:WORD_1
	v_cvt_f32_f16_e32 v58, v89
	v_cvt_f32_f16_sdwa v59, v89 dst_sel:DWORD dst_unused:UNUSED_PAD src0_sel:WORD_1
	v_pk_fma_f32 v[52:53], v[52:53], v[168:169], v[56:57]
	v_cvt_f32_f16_e32 v56, v90
	v_cvt_f32_f16_sdwa v57, v90 dst_sel:DWORD dst_unused:UNUSED_PAD src0_sel:WORD_1
	v_pk_fma_f32 v[54:55], v[54:55], v[166:167], v[58:59]
	v_cvt_f32_f16_e32 v58, v91
	v_cvt_f32_f16_sdwa v59, v91 dst_sel:DWORD dst_unused:UNUSED_PAD src0_sel:WORD_1
	v_pk_fma_f32 v[44:45], v[44:45], v[164:165], v[56:57]
	v_pk_fma_f32 v[46:47], v[46:47], v[162:163], v[58:59]
	global_store_dwordx4 v[100:101], v[52:55], off offset:512
	global_store_dwordx4 v[100:101], v[44:47], off offset:528
	s_nop 1
	v_lshlrev_b64 v[44:45], 12, v[102:103]
	v_lshl_add_u64 v[52:53], v[192:193], 0, v[44:45]
	v_cvt_f32_f16_e32 v44, v92
	v_cvt_f32_f16_sdwa v45, v92 dst_sel:DWORD dst_unused:UNUSED_PAD src0_sel:WORD_1
	v_cvt_f32_f16_e32 v46, v93
	v_cvt_f32_f16_sdwa v47, v93 dst_sel:DWORD dst_unused:UNUSED_PAD src0_sel:WORD_1
	v_pk_fma_f32 v[44:45], v[48:49], v[190:191], v[44:45]
	v_cvt_f32_f16_e32 v48, v94
	v_cvt_f32_f16_sdwa v49, v94 dst_sel:DWORD dst_unused:UNUSED_PAD src0_sel:WORD_1
	v_pk_fma_f32 v[46:47], v[50:51], v[174:175], v[46:47]
	v_cvt_f32_f16_e32 v50, v95
	v_cvt_f32_f16_sdwa v51, v95 dst_sel:DWORD dst_unused:UNUSED_PAD src0_sel:WORD_1
	v_pk_fma_f32 v[40:41], v[40:41], v[172:173], v[48:49]
	v_pk_fma_f32 v[42:43], v[42:43], v[170:171], v[50:51]
	global_store_dwordx4 v[52:53], v[44:47], off
	global_store_dwordx4 v[52:53], v[40:43], off offset:16
	s_nop 1
	v_cvt_f32_f16_e32 v40, v96
	v_cvt_f32_f16_sdwa v41, v96 dst_sel:DWORD dst_unused:UNUSED_PAD src0_sel:WORD_1
	v_cvt_f32_f16_e32 v42, v97
	v_cvt_f32_f16_sdwa v43, v97 dst_sel:DWORD dst_unused:UNUSED_PAD src0_sel:WORD_1
	v_pk_fma_f32 v[36:37], v[36:37], v[168:169], v[40:41]
	v_cvt_f32_f16_e32 v40, v98
	v_cvt_f32_f16_sdwa v41, v98 dst_sel:DWORD dst_unused:UNUSED_PAD src0_sel:WORD_1
	v_pk_fma_f32 v[38:39], v[38:39], v[166:167], v[42:43]
	v_cvt_f32_f16_e32 v42, v99
	v_cvt_f32_f16_sdwa v43, v99 dst_sel:DWORD dst_unused:UNUSED_PAD src0_sel:WORD_1
	v_pk_fma_f32 v[28:29], v[28:29], v[164:165], v[40:41]
	v_pk_fma_f32 v[30:31], v[30:31], v[162:163], v[42:43]
	global_store_dwordx4 v[52:53], v[36:39], off offset:512
	global_store_dwordx4 v[52:53], v[28:31], off offset:528
	s_nop 1
	v_lshlrev_b64 v[28:29], 12, v[82:83]
	v_lshl_add_u64 v[36:37], v[192:193], 0, v[28:29]
	v_cvt_f32_f16_e32 v28, v76
	v_cvt_f32_f16_sdwa v29, v76 dst_sel:DWORD dst_unused:UNUSED_PAD src0_sel:WORD_1
	v_cvt_f32_f16_e32 v30, v77
	v_cvt_f32_f16_sdwa v31, v77 dst_sel:DWORD dst_unused:UNUSED_PAD src0_sel:WORD_1
	v_pk_fma_f32 v[28:29], v[32:33], v[190:191], v[28:29]
	v_cvt_f32_f16_e32 v32, v78
	v_cvt_f32_f16_sdwa v33, v78 dst_sel:DWORD dst_unused:UNUSED_PAD src0_sel:WORD_1
	v_pk_fma_f32 v[30:31], v[34:35], v[174:175], v[30:31]
	v_cvt_f32_f16_e32 v34, v79
	v_cvt_f32_f16_sdwa v35, v79 dst_sel:DWORD dst_unused:UNUSED_PAD src0_sel:WORD_1
	v_pk_fma_f32 v[24:25], v[24:25], v[172:173], v[32:33]
	v_pk_fma_f32 v[26:27], v[26:27], v[170:171], v[34:35]
	global_store_dwordx4 v[36:37], v[28:31], off
	global_store_dwordx4 v[36:37], v[24:27], off offset:16
	s_nop 1
	v_cvt_f32_f16_e32 v24, v72
	v_cvt_f32_f16_sdwa v25, v72 dst_sel:DWORD dst_unused:UNUSED_PAD src0_sel:WORD_1
	v_cvt_f32_f16_e32 v26, v73
	v_cvt_f32_f16_sdwa v27, v73 dst_sel:DWORD dst_unused:UNUSED_PAD src0_sel:WORD_1
	v_pk_fma_f32 v[20:21], v[20:21], v[168:169], v[24:25]
	v_cvt_f32_f16_e32 v24, v74
	v_cvt_f32_f16_sdwa v25, v74 dst_sel:DWORD dst_unused:UNUSED_PAD src0_sel:WORD_1
	v_pk_fma_f32 v[22:23], v[22:23], v[166:167], v[26:27]
	v_cvt_f32_f16_e32 v26, v75
	v_cvt_f32_f16_sdwa v27, v75 dst_sel:DWORD dst_unused:UNUSED_PAD src0_sel:WORD_1
	v_pk_fma_f32 v[12:13], v[12:13], v[164:165], v[24:25]
	v_pk_fma_f32 v[14:15], v[14:15], v[162:163], v[26:27]
	global_store_dwordx4 v[36:37], v[20:23], off offset:512
	global_store_dwordx4 v[36:37], v[12:15], off offset:528
	s_nop 1
	v_lshlrev_b64 v[12:13], 12, v[80:81]
	v_lshl_add_u64 v[20:21], v[192:193], 0, v[12:13]
	v_cvt_f32_f16_e32 v12, v68
	v_cvt_f32_f16_sdwa v13, v68 dst_sel:DWORD dst_unused:UNUSED_PAD src0_sel:WORD_1
	v_cvt_f32_f16_e32 v14, v69
	v_cvt_f32_f16_sdwa v15, v69 dst_sel:DWORD dst_unused:UNUSED_PAD src0_sel:WORD_1
	v_pk_fma_f32 v[12:13], v[16:17], v[190:191], v[12:13]
	v_cvt_f32_f16_e32 v16, v70
	v_pk_fma_f32 v[14:15], v[18:19], v[174:175], v[14:15]
	v_cvt_f32_f16_sdwa v17, v70 dst_sel:DWORD dst_unused:UNUSED_PAD src0_sel:WORD_1
	v_cvt_f32_f16_e32 v18, v71
	v_cvt_f32_f16_sdwa v19, v71 dst_sel:DWORD dst_unused:UNUSED_PAD src0_sel:WORD_1
	v_pk_fma_f32 v[8:9], v[8:9], v[172:173], v[16:17]
	v_pk_fma_f32 v[10:11], v[10:11], v[170:171], v[18:19]
	global_store_dwordx4 v[20:21], v[12:15], off
	global_store_dwordx4 v[20:21], v[8:11], off offset:16
	s_nop 1
	v_cvt_f32_f16_e32 v8, v64
	v_cvt_f32_f16_sdwa v9, v64 dst_sel:DWORD dst_unused:UNUSED_PAD src0_sel:WORD_1
	v_cvt_f32_f16_e32 v10, v65
	v_cvt_f32_f16_sdwa v11, v65 dst_sel:DWORD dst_unused:UNUSED_PAD src0_sel:WORD_1
	v_pk_fma_f32 v[4:5], v[4:5], v[168:169], v[8:9]
	v_cvt_f32_f16_e32 v8, v66
	v_pk_fma_f32 v[6:7], v[6:7], v[166:167], v[10:11]
	v_cvt_f32_f16_sdwa v9, v66 dst_sel:DWORD dst_unused:UNUSED_PAD src0_sel:WORD_1
	v_cvt_f32_f16_e32 v10, v67
	v_cvt_f32_f16_sdwa v11, v67 dst_sel:DWORD dst_unused:UNUSED_PAD src0_sel:WORD_1
	v_pk_fma_f32 v[0:1], v[0:1], v[164:165], v[8:9]
	v_pk_fma_f32 v[2:3], v[2:3], v[162:163], v[10:11]
	global_store_dwordx4 v[20:21], v[4:7], off offset:512
	global_store_dwordx4 v[20:21], v[0:3], off offset:528
	s_cbranch_vccnz .LBB0_901
	s_andn2_b64 vcc, exec, s[34:35]
	s_cbranch_vccnz .LBB0_900
	s_barrier
	s_branch .LBB0_900

.LBB0_950:
	s_mul_hi_i32 s45, s43, 0x9000
	s_mul_i32 s43, s43, 0x9000
	s_add_u32 s44, s77, s43
	s_addc_u32 s45, s78, s45
	s_lshl_b32 s43, s80, 8
	s_or_b32 s43, s43, s71
	v_lshl_add_u32 v146, v129, 3, s43
	v_ashrrev_i32_e32 v147, 31, v146
	v_lshl_add_u64 v[142:143], v[146:147], 2, s[44:45]
	global_load_dwordx4 v[130:133], v[142:143], off
	global_load_dwordx4 v[134:137], v[142:143], off offset:16
	global_load_dwordx4 v[138:141], v[142:143], off offset:512
	s_nop 0
	global_load_dwordx4 v[142:145], v[142:143], off offset:528
	s_ashr_i32 s43, s42, 31
	s_lshl_b64 s[42:43], s[42:43], 11
	s_add_u32 s42, s30, s42
	v_add_u32_e32 v194, s70, v128
	s_addc_u32 s43, s31, s43
	v_ashrrev_i32_e32 v195, 31, v194
	v_lshl_add_u64 v[192:193], v[146:147], 1, s[42:43]
	v_lshlrev_b64 v[128:129], 11, v[194:195]
	v_lshl_add_u64 v[186:187], v[192:193], 0, v[128:129]
	global_load_dwordx4 v[206:209], v[186:187], off
	global_load_dwordx4 v[210:213], v[186:187], off offset:256
	v_add_u32_e32 v128, 16, v194
	v_ashrrev_i32_e32 v129, 31, v128
	v_lshlrev_b64 v[128:129], 11, v[128:129]
	v_lshl_add_u64 v[200:201], v[192:193], 0, v[128:129]
	v_add_u32_e32 v128, 32, v194
	v_ashrrev_i32_e32 v129, 31, v128
	v_lshlrev_b64 v[128:129], 11, v[128:129]
	v_lshl_add_u64 v[198:199], v[192:193], 0, v[128:129]
	v_add_u32_e32 v128, 48, v194
	v_ashrrev_i32_e32 v129, 31, v128
	v_lshlrev_b64 v[128:129], 11, v[128:129]
	v_lshl_add_u64 v[196:197], v[192:193], 0, v[128:129]
	s_mov_b64 s[42:43], -1
	s_and_b64 vcc, exec, s[36:37]
	s_waitcnt vmcnt(0) lgkmcnt(0)
	v_pk_mul_f32 v[174:175], v[132:133], 0.5 op_sel_hi:[1,0]
	v_pk_mul_f32 v[170:171], v[136:137], 0.5 op_sel_hi:[1,0]
	v_pk_mul_f32 v[166:167], v[140:141], 0.5 op_sel_hi:[1,0]
	v_pk_mul_f32 v[162:163], v[144:145], 0.5 op_sel_hi:[1,0]
	global_load_dwordx4 v[148:151], v[200:201], off
	global_load_dwordx4 v[144:147], v[200:201], off offset:256
	v_pk_mul_f32 v[168:169], v[138:139], 0.5 op_sel_hi:[1,0]
	v_pk_mul_f32 v[164:165], v[142:143], 0.5 op_sel_hi:[1,0]
	global_load_dwordx4 v[140:143], v[198:199], off
	global_load_dwordx4 v[136:139], v[198:199], off offset:256
	v_pk_mul_f32 v[190:191], v[130:131], 0.5 op_sel_hi:[1,0]
	v_pk_mul_f32 v[172:173], v[134:135], 0.5 op_sel_hi:[1,0]
	global_load_dwordx4 v[132:135], v[196:197], off
	global_load_dwordx4 v[128:131], v[196:197], off offset:256
	v_cvt_f32_f16_e32 v214, v206
	v_cvt_f32_f16_sdwa v215, v206 dst_sel:DWORD dst_unused:UNUSED_PAD src0_sel:WORD_1
	v_cvt_f32_f16_e32 v206, v207
	v_cvt_f32_f16_sdwa v207, v207 dst_sel:DWORD dst_unused:UNUSED_PAD src0_sel:WORD_1
	v_pk_fma_f32 v[124:125], v[124:125], v[190:191], v[214:215]
	v_pk_fma_f32 v[126:127], v[126:127], v[174:175], v[206:207]
	v_cvt_f32_f16_e32 v206, v208
	v_cvt_f32_f16_sdwa v207, v208 dst_sel:DWORD dst_unused:UNUSED_PAD src0_sel:WORD_1
	v_cvt_f32_f16_e32 v208, v209
	v_cvt_f32_f16_sdwa v209, v209 dst_sel:DWORD dst_unused:UNUSED_PAD src0_sel:WORD_1
	v_pk_fma_f32 v[208:209], v[122:123], v[170:171], v[208:209]
	v_pk_fma_f32 v[122:123], v[120:121], v[172:173], v[206:207]
	v_cvt_pk_f16_f32 v120, v124, v125
	v_cvt_pk_f16_f32 v121, v126, v127
	v_cvt_pk_f16_f32 v122, v122, v123
	v_cvt_pk_f16_f32 v123, v208, v209
	global_store_dwordx4 v[186:187], v[120:123], off
	s_nop 1
	v_cvt_f32_f16_e32 v120, v210
	v_cvt_f32_f16_sdwa v121, v210 dst_sel:DWORD dst_unused:UNUSED_PAD src0_sel:WORD_1
	v_cvt_f32_f16_e32 v122, v211
	v_cvt_f32_f16_sdwa v123, v211 dst_sel:DWORD dst_unused:UNUSED_PAD src0_sel:WORD_1
	v_pk_fma_f32 v[116:117], v[116:117], v[168:169], v[120:121]
	v_cvt_f32_f16_e32 v120, v212
	v_pk_fma_f32 v[118:119], v[118:119], v[166:167], v[122:123]
	v_cvt_f32_f16_sdwa v121, v212 dst_sel:DWORD dst_unused:UNUSED_PAD src0_sel:WORD_1
	v_cvt_f32_f16_e32 v122, v213
	v_cvt_f32_f16_sdwa v123, v213 dst_sel:DWORD dst_unused:UNUSED_PAD src0_sel:WORD_1
	v_pk_fma_f32 v[122:123], v[114:115], v[162:163], v[122:123]
	v_pk_fma_f32 v[114:115], v[112:113], v[164:165], v[120:121]
	v_cvt_pk_f16_f32 v112, v116, v117
	v_cvt_pk_f16_f32 v113, v118, v119
	v_cvt_pk_f16_f32 v114, v114, v115
	v_cvt_pk_f16_f32 v115, v122, v123
	global_store_dwordx4 v[186:187], v[112:115], off offset:256
	s_waitcnt vmcnt(7)
	s_nop 0
	v_cvt_f32_f16_e32 v112, v148
	v_cvt_f32_f16_sdwa v113, v148 dst_sel:DWORD dst_unused:UNUSED_PAD src0_sel:WORD_1
	v_cvt_f32_f16_e32 v114, v149
	v_cvt_f32_f16_sdwa v115, v149 dst_sel:DWORD dst_unused:UNUSED_PAD src0_sel:WORD_1
	v_pk_fma_f32 v[108:109], v[108:109], v[190:191], v[112:113]
	v_cvt_f32_f16_e32 v112, v150
	v_pk_fma_f32 v[110:111], v[110:111], v[174:175], v[114:115]
	v_cvt_f32_f16_sdwa v113, v150 dst_sel:DWORD dst_unused:UNUSED_PAD src0_sel:WORD_1
	v_cvt_f32_f16_e32 v114, v151
	v_cvt_f32_f16_sdwa v115, v151 dst_sel:DWORD dst_unused:UNUSED_PAD src0_sel:WORD_1
	v_pk_fma_f32 v[114:115], v[106:107], v[170:171], v[114:115]
	v_pk_fma_f32 v[106:107], v[104:105], v[172:173], v[112:113]
	v_cvt_pk_f16_f32 v104, v108, v109
	v_cvt_pk_f16_f32 v105, v110, v111
	v_cvt_pk_f16_f32 v106, v106, v107
	v_cvt_pk_f16_f32 v107, v114, v115
	global_store_dwordx4 v[200:201], v[104:107], off
	s_waitcnt vmcnt(7)
	s_nop 0
	v_cvt_f32_f16_e32 v104, v144
	v_cvt_f32_f16_sdwa v105, v144 dst_sel:DWORD dst_unused:UNUSED_PAD src0_sel:WORD_1
	v_cvt_f32_f16_e32 v106, v145
	v_cvt_f32_f16_sdwa v107, v145 dst_sel:DWORD dst_unused:UNUSED_PAD src0_sel:WORD_1
	v_pk_fma_f32 v[100:101], v[100:101], v[168:169], v[104:105]
	v_cvt_f32_f16_e32 v104, v146
	v_pk_fma_f32 v[102:103], v[102:103], v[166:167], v[106:107]
	v_cvt_f32_f16_sdwa v105, v146 dst_sel:DWORD dst_unused:UNUSED_PAD src0_sel:WORD_1
	v_cvt_f32_f16_e32 v106, v147
	v_cvt_f32_f16_sdwa v107, v147 dst_sel:DWORD dst_unused:UNUSED_PAD src0_sel:WORD_1
	v_pk_fma_f32 v[106:107], v[94:95], v[162:163], v[106:107]
	v_pk_fma_f32 v[94:95], v[92:93], v[164:165], v[104:105]
	v_cvt_pk_f16_f32 v92, v100, v101
	v_cvt_pk_f16_f32 v93, v102, v103
	v_cvt_pk_f16_f32 v94, v94, v95
	v_cvt_pk_f16_f32 v95, v106, v107
	global_store_dwordx4 v[200:201], v[92:95], off offset:256
	s_waitcnt vmcnt(7)
	s_nop 0
	v_cvt_f32_f16_e32 v92, v140
	v_cvt_f32_f16_sdwa v93, v140 dst_sel:DWORD dst_unused:UNUSED_PAD src0_sel:WORD_1
	v_cvt_f32_f16_e32 v94, v141
	v_cvt_f32_f16_sdwa v95, v141 dst_sel:DWORD dst_unused:UNUSED_PAD src0_sel:WORD_1
	v_pk_fma_f32 v[92:93], v[96:97], v[190:191], v[92:93]
	v_cvt_f32_f16_e32 v96, v142
	v_pk_fma_f32 v[94:95], v[98:99], v[174:175], v[94:95]
	v_cvt_f32_f16_sdwa v97, v142 dst_sel:DWORD dst_unused:UNUSED_PAD src0_sel:WORD_1
	v_cvt_f32_f16_e32 v98, v143
	v_cvt_f32_f16_sdwa v99, v143 dst_sel:DWORD dst_unused:UNUSED_PAD src0_sel:WORD_1
	v_pk_fma_f32 v[98:99], v[90:91], v[170:171], v[98:99]
	v_pk_fma_f32 v[90:91], v[88:89], v[172:173], v[96:97]
	v_cvt_pk_f16_f32 v88, v92, v93
	v_cvt_pk_f16_f32 v89, v94, v95
	v_cvt_pk_f16_f32 v90, v90, v91
	v_cvt_pk_f16_f32 v91, v98, v99
	global_store_dwordx4 v[198:199], v[88:91], off
	s_waitcnt vmcnt(7)
	s_nop 0
	v_cvt_f32_f16_e32 v88, v136
	v_cvt_f32_f16_sdwa v89, v136 dst_sel:DWORD dst_unused:UNUSED_PAD src0_sel:WORD_1
	v_cvt_f32_f16_e32 v90, v137
	v_cvt_f32_f16_sdwa v91, v137 dst_sel:DWORD dst_unused:UNUSED_PAD src0_sel:WORD_1
	v_pk_fma_f32 v[84:85], v[84:85], v[168:169], v[88:89]
	v_cvt_f32_f16_e32 v88, v138
	v_pk_fma_f32 v[86:87], v[86:87], v[166:167], v[90:91]
	v_cvt_f32_f16_sdwa v89, v138 dst_sel:DWORD dst_unused:UNUSED_PAD src0_sel:WORD_1
	v_cvt_f32_f16_e32 v90, v139
	v_cvt_f32_f16_sdwa v91, v139 dst_sel:DWORD dst_unused:UNUSED_PAD src0_sel:WORD_1
	v_pk_fma_f32 v[90:91], v[78:79], v[162:163], v[90:91]
	v_pk_fma_f32 v[78:79], v[76:77], v[164:165], v[88:89]
	v_cvt_pk_f16_f32 v76, v84, v85
	v_cvt_pk_f16_f32 v77, v86, v87
	v_cvt_pk_f16_f32 v78, v78, v79
	v_cvt_pk_f16_f32 v79, v90, v91
	global_store_dwordx4 v[198:199], v[76:79], off offset:256
	s_waitcnt vmcnt(7)
	s_nop 0
	v_cvt_f32_f16_e32 v76, v132
	v_cvt_f32_f16_sdwa v77, v132 dst_sel:DWORD dst_unused:UNUSED_PAD src0_sel:WORD_1
	v_cvt_f32_f16_e32 v78, v133
	v_cvt_f32_f16_sdwa v79, v133 dst_sel:DWORD dst_unused:UNUSED_PAD src0_sel:WORD_1
	v_pk_fma_f32 v[76:77], v[80:81], v[190:191], v[76:77]
	v_cvt_f32_f16_e32 v80, v134
	v_pk_fma_f32 v[78:79], v[82:83], v[174:175], v[78:79]
	v_cvt_f32_f16_sdwa v81, v134 dst_sel:DWORD dst_unused:UNUSED_PAD src0_sel:WORD_1
	v_cvt_f32_f16_e32 v82, v135
	v_cvt_f32_f16_sdwa v83, v135 dst_sel:DWORD dst_unused:UNUSED_PAD src0_sel:WORD_1
	v_pk_fma_f32 v[82:83], v[74:75], v[170:171], v[82:83]
	v_pk_fma_f32 v[74:75], v[72:73], v[172:173], v[80:81]
	v_cvt_pk_f16_f32 v72, v76, v77
	v_cvt_pk_f16_f32 v73, v78, v79
	v_cvt_pk_f16_f32 v74, v74, v75
	v_cvt_pk_f16_f32 v75, v82, v83
	global_store_dwordx4 v[196:197], v[72:75], off
	s_waitcnt vmcnt(7)
	s_nop 0
	v_cvt_f32_f16_e32 v72, v128
	v_cvt_f32_f16_sdwa v73, v128 dst_sel:DWORD dst_unused:UNUSED_PAD src0_sel:WORD_1
	v_cvt_f32_f16_e32 v74, v129
	v_cvt_f32_f16_sdwa v75, v129 dst_sel:DWORD dst_unused:UNUSED_PAD src0_sel:WORD_1
	v_pk_fma_f32 v[68:69], v[68:69], v[168:169], v[72:73]
	v_cvt_f32_f16_e32 v72, v130
	v_pk_fma_f32 v[70:71], v[70:71], v[166:167], v[74:75]
	v_cvt_f32_f16_sdwa v73, v130 dst_sel:DWORD dst_unused:UNUSED_PAD src0_sel:WORD_1
	v_cvt_f32_f16_e32 v74, v131
	v_cvt_f32_f16_sdwa v75, v131 dst_sel:DWORD dst_unused:UNUSED_PAD src0_sel:WORD_1
	v_pk_fma_f32 v[74:75], v[66:67], v[162:163], v[74:75]
	v_pk_fma_f32 v[66:67], v[64:65], v[164:165], v[72:73]
	v_cvt_pk_f16_f32 v64, v68, v69
	v_cvt_pk_f16_f32 v65, v70, v71
	v_cvt_pk_f16_f32 v66, v66, v67
	v_cvt_pk_f16_f32 v67, v74, v75
	global_store_dwordx4 v[196:197], v[64:67], off offset:256
	s_nop 1
	v_add_u32_e32 v64, 0x80, v194
	v_ashrrev_i32_e32 v65, 31, v64
	v_lshlrev_b64 v[64:65], 11, v[64:65]
	v_lshl_add_u64 v[100:101], v[192:193], 0, v[64:65]
	global_load_dwordx4 v[84:87], v[100:101], off
	global_load_dwordx4 v[88:91], v[100:101], off offset:256
	v_add_u32_e32 v64, 0x90, v194
	v_ashrrev_i32_e32 v65, 31, v64
	v_lshlrev_b64 v[64:65], 11, v[64:65]
	v_lshl_add_u64 v[102:103], v[192:193], 0, v[64:65]
	global_load_dwordx4 v[92:95], v[102:103], off
	global_load_dwordx4 v[96:99], v[102:103], off offset:256
	v_add_u32_e32 v64, 0xa0, v194
	v_ashrrev_i32_e32 v65, 31, v64
	v_lshlrev_b64 v[64:65], 11, v[64:65]
	v_lshl_add_u64 v[82:83], v[192:193], 0, v[64:65]
	global_load_dwordx4 v[76:79], v[82:83], off
	global_load_dwordx4 v[72:75], v[82:83], off offset:256
	v_add_u32_e32 v64, 0xb0, v194
	v_ashrrev_i32_e32 v65, 31, v64
	v_lshlrev_b64 v[64:65], 11, v[64:65]
	v_lshl_add_u64 v[80:81], v[192:193], 0, v[64:65]
	global_load_dwordx4 v[68:71], v[80:81], off
	global_load_dwordx4 v[64:67], v[80:81], off offset:256
	s_waitcnt vmcnt(7)
	v_cvt_f32_f16_e32 v104, v84
	v_cvt_f32_f16_sdwa v105, v84 dst_sel:DWORD dst_unused:UNUSED_PAD src0_sel:WORD_1
	v_cvt_f32_f16_e32 v84, v85
	v_cvt_f32_f16_sdwa v85, v85 dst_sel:DWORD dst_unused:UNUSED_PAD src0_sel:WORD_1
	v_pk_fma_f32 v[60:61], v[60:61], v[190:191], v[104:105]
	v_pk_fma_f32 v[62:63], v[62:63], v[174:175], v[84:85]
	v_cvt_f32_f16_e32 v84, v86
	v_cvt_f32_f16_sdwa v85, v86 dst_sel:DWORD dst_unused:UNUSED_PAD src0_sel:WORD_1
	v_cvt_f32_f16_e32 v86, v87
	v_cvt_f32_f16_sdwa v87, v87 dst_sel:DWORD dst_unused:UNUSED_PAD src0_sel:WORD_1
	v_pk_fma_f32 v[86:87], v[58:59], v[170:171], v[86:87]
	v_pk_fma_f32 v[58:59], v[56:57], v[172:173], v[84:85]
	v_cvt_pk_f16_f32 v56, v60, v61
	v_cvt_pk_f16_f32 v57, v62, v63
	v_cvt_pk_f16_f32 v58, v58, v59
	v_cvt_pk_f16_f32 v59, v86, v87
	global_store_dwordx4 v[100:101], v[56:59], off
	s_waitcnt vmcnt(7)
	s_nop 0
	v_cvt_f32_f16_e32 v56, v88
	v_cvt_f32_f16_sdwa v57, v88 dst_sel:DWORD dst_unused:UNUSED_PAD src0_sel:WORD_1
	v_cvt_f32_f16_e32 v58, v89
	v_cvt_f32_f16_sdwa v59, v89 dst_sel:DWORD dst_unused:UNUSED_PAD src0_sel:WORD_1
	v_pk_fma_f32 v[52:53], v[52:53], v[168:169], v[56:57]
	v_cvt_f32_f16_e32 v56, v90
	v_pk_fma_f32 v[54:55], v[54:55], v[166:167], v[58:59]
	v_cvt_f32_f16_sdwa v57, v90 dst_sel:DWORD dst_unused:UNUSED_PAD src0_sel:WORD_1
	v_cvt_f32_f16_e32 v58, v91
	v_cvt_f32_f16_sdwa v59, v91 dst_sel:DWORD dst_unused:UNUSED_PAD src0_sel:WORD_1
	v_pk_fma_f32 v[58:59], v[46:47], v[162:163], v[58:59]
	v_pk_fma_f32 v[46:47], v[44:45], v[164:165], v[56:57]
	v_cvt_pk_f16_f32 v44, v52, v53
	v_cvt_pk_f16_f32 v45, v54, v55
	v_cvt_pk_f16_f32 v46, v46, v47
	v_cvt_pk_f16_f32 v47, v58, v59
	global_store_dwordx4 v[100:101], v[44:47], off offset:256
	s_waitcnt vmcnt(7)
	s_nop 0
	v_cvt_f32_f16_e32 v44, v92
	v_cvt_f32_f16_sdwa v45, v92 dst_sel:DWORD dst_unused:UNUSED_PAD src0_sel:WORD_1
	v_cvt_f32_f16_e32 v46, v93
	v_cvt_f32_f16_sdwa v47, v93 dst_sel:DWORD dst_unused:UNUSED_PAD src0_sel:WORD_1
	v_pk_fma_f32 v[44:45], v[48:49], v[190:191], v[44:45]
	v_cvt_f32_f16_e32 v48, v94
	v_pk_fma_f32 v[46:47], v[50:51], v[174:175], v[46:47]
	v_cvt_f32_f16_sdwa v49, v94 dst_sel:DWORD dst_unused:UNUSED_PAD src0_sel:WORD_1
	v_cvt_f32_f16_e32 v50, v95
	v_cvt_f32_f16_sdwa v51, v95 dst_sel:DWORD dst_unused:UNUSED_PAD src0_sel:WORD_1
	v_pk_fma_f32 v[50:51], v[42:43], v[170:171], v[50:51]
	v_pk_fma_f32 v[42:43], v[40:41], v[172:173], v[48:49]
	v_cvt_pk_f16_f32 v40, v44, v45
	v_cvt_pk_f16_f32 v41, v46, v47
	v_cvt_pk_f16_f32 v42, v42, v43
	v_cvt_pk_f16_f32 v43, v50, v51
	global_store_dwordx4 v[102:103], v[40:43], off
	s_waitcnt vmcnt(7)
	s_nop 0
	v_cvt_f32_f16_e32 v40, v96
	v_cvt_f32_f16_sdwa v41, v96 dst_sel:DWORD dst_unused:UNUSED_PAD src0_sel:WORD_1
	v_cvt_f32_f16_e32 v42, v97
	v_cvt_f32_f16_sdwa v43, v97 dst_sel:DWORD dst_unused:UNUSED_PAD src0_sel:WORD_1
	v_pk_fma_f32 v[36:37], v[36:37], v[168:169], v[40:41]
	v_cvt_f32_f16_e32 v40, v98
	v_pk_fma_f32 v[38:39], v[38:39], v[166:167], v[42:43]
	v_cvt_f32_f16_sdwa v41, v98 dst_sel:DWORD dst_unused:UNUSED_PAD src0_sel:WORD_1
	v_cvt_f32_f16_e32 v42, v99
	v_cvt_f32_f16_sdwa v43, v99 dst_sel:DWORD dst_unused:UNUSED_PAD src0_sel:WORD_1
	v_pk_fma_f32 v[42:43], v[30:31], v[162:163], v[42:43]
	v_pk_fma_f32 v[30:31], v[28:29], v[164:165], v[40:41]
	v_cvt_pk_f16_f32 v28, v36, v37
	v_cvt_pk_f16_f32 v29, v38, v39
	v_cvt_pk_f16_f32 v30, v30, v31
	v_cvt_pk_f16_f32 v31, v42, v43
	global_store_dwordx4 v[102:103], v[28:31], off offset:256
	s_waitcnt vmcnt(7)
	s_nop 0
	v_cvt_f32_f16_e32 v28, v76
	v_cvt_f32_f16_sdwa v29, v76 dst_sel:DWORD dst_unused:UNUSED_PAD src0_sel:WORD_1
	v_cvt_f32_f16_e32 v30, v77
	v_cvt_f32_f16_sdwa v31, v77 dst_sel:DWORD dst_unused:UNUSED_PAD src0_sel:WORD_1
	v_pk_fma_f32 v[28:29], v[32:33], v[190:191], v[28:29]
	v_cvt_f32_f16_e32 v32, v78
	v_pk_fma_f32 v[30:31], v[34:35], v[174:175], v[30:31]
	v_cvt_f32_f16_sdwa v33, v78 dst_sel:DWORD dst_unused:UNUSED_PAD src0_sel:WORD_1
	v_cvt_f32_f16_e32 v34, v79
	v_cvt_f32_f16_sdwa v35, v79 dst_sel:DWORD dst_unused:UNUSED_PAD src0_sel:WORD_1
	v_pk_fma_f32 v[34:35], v[26:27], v[170:171], v[34:35]
	v_pk_fma_f32 v[26:27], v[24:25], v[172:173], v[32:33]
	v_cvt_pk_f16_f32 v24, v28, v29
	v_cvt_pk_f16_f32 v25, v30, v31
	v_cvt_pk_f16_f32 v26, v26, v27
	v_cvt_pk_f16_f32 v27, v34, v35
	global_store_dwordx4 v[82:83], v[24:27], off
	s_waitcnt vmcnt(7)
	s_nop 0
	v_cvt_f32_f16_e32 v24, v72
	v_cvt_f32_f16_sdwa v25, v72 dst_sel:DWORD dst_unused:UNUSED_PAD src0_sel:WORD_1
	v_cvt_f32_f16_e32 v26, v73
	v_cvt_f32_f16_sdwa v27, v73 dst_sel:DWORD dst_unused:UNUSED_PAD src0_sel:WORD_1
	v_pk_fma_f32 v[20:21], v[20:21], v[168:169], v[24:25]
	v_cvt_f32_f16_e32 v24, v74
	v_pk_fma_f32 v[22:23], v[22:23], v[166:167], v[26:27]
	v_cvt_f32_f16_sdwa v25, v74 dst_sel:DWORD dst_unused:UNUSED_PAD src0_sel:WORD_1
	v_cvt_f32_f16_e32 v26, v75
	v_cvt_f32_f16_sdwa v27, v75 dst_sel:DWORD dst_unused:UNUSED_PAD src0_sel:WORD_1
	v_pk_fma_f32 v[26:27], v[14:15], v[162:163], v[26:27]
	v_pk_fma_f32 v[14:15], v[12:13], v[164:165], v[24:25]
	v_cvt_pk_f16_f32 v12, v20, v21
	v_cvt_pk_f16_f32 v13, v22, v23
	v_cvt_pk_f16_f32 v14, v14, v15
	v_cvt_pk_f16_f32 v15, v26, v27
	global_store_dwordx4 v[82:83], v[12:15], off offset:256
	s_waitcnt vmcnt(7)
	s_nop 0
	v_cvt_f32_f16_e32 v12, v68
	v_cvt_f32_f16_sdwa v13, v68 dst_sel:DWORD dst_unused:UNUSED_PAD src0_sel:WORD_1
	v_cvt_f32_f16_e32 v14, v69
	v_cvt_f32_f16_sdwa v15, v69 dst_sel:DWORD dst_unused:UNUSED_PAD src0_sel:WORD_1
	v_pk_fma_f32 v[12:13], v[16:17], v[190:191], v[12:13]
	v_cvt_f32_f16_e32 v16, v70
	v_pk_fma_f32 v[14:15], v[18:19], v[174:175], v[14:15]
	v_cvt_f32_f16_sdwa v17, v70 dst_sel:DWORD dst_unused:UNUSED_PAD src0_sel:WORD_1
	v_cvt_f32_f16_e32 v18, v71
	v_cvt_f32_f16_sdwa v19, v71 dst_sel:DWORD dst_unused:UNUSED_PAD src0_sel:WORD_1
	v_pk_fma_f32 v[18:19], v[10:11], v[170:171], v[18:19]
	v_pk_fma_f32 v[10:11], v[8:9], v[172:173], v[16:17]
	v_cvt_pk_f16_f32 v8, v12, v13
	v_cvt_pk_f16_f32 v9, v14, v15
	v_cvt_pk_f16_f32 v10, v10, v11
	v_cvt_pk_f16_f32 v11, v18, v19
	global_store_dwordx4 v[80:81], v[8:11], off
	s_waitcnt vmcnt(7)
	s_nop 0
	v_cvt_f32_f16_e32 v8, v64
	v_cvt_f32_f16_sdwa v9, v64 dst_sel:DWORD dst_unused:UNUSED_PAD src0_sel:WORD_1
	v_cvt_f32_f16_e32 v10, v65
	v_cvt_f32_f16_sdwa v11, v65 dst_sel:DWORD dst_unused:UNUSED_PAD src0_sel:WORD_1
	v_pk_fma_f32 v[4:5], v[4:5], v[168:169], v[8:9]
	v_cvt_f32_f16_e32 v8, v66
	v_pk_fma_f32 v[6:7], v[6:7], v[166:167], v[10:11]
	v_cvt_f32_f16_sdwa v9, v66 dst_sel:DWORD dst_unused:UNUSED_PAD src0_sel:WORD_1
	v_cvt_f32_f16_e32 v10, v67
	v_cvt_f32_f16_sdwa v11, v67 dst_sel:DWORD dst_unused:UNUSED_PAD src0_sel:WORD_1
	v_pk_fma_f32 v[10:11], v[2:3], v[162:163], v[10:11]
	v_pk_fma_f32 v[2:3], v[0:1], v[164:165], v[8:9]
	v_cvt_pk_f16_f32 v0, v4, v5
	v_cvt_pk_f16_f32 v1, v6, v7
	v_cvt_pk_f16_f32 v2, v2, v3
	v_cvt_pk_f16_f32 v3, v10, v11
	global_store_dwordx4 v[80:81], v[0:3], off offset:256
	s_cbranch_vccnz .LBB0_931
	s_andn2_b64 vcc, exec, s[34:35]
	s_cbranch_vccnz .LBB0_930
	s_barrier
	s_branch .LBB0_930

.LBB0_984:
	v_readlane_b32 s8, v253, 30
	v_readlane_b32 s9, v253, 31
	buffer_wbl2 sc1
	s_waitcnt vmcnt(0)
	s_mov_b64 s[36:37], -1
	v_mov_b64_e32 v[2:3], s[8:9]
	global_atomic_add v1, v[2:3], v230, off sc0
	v_cvt_f32_u32_e32 v2, v0
	v_sub_u32_e32 v3, 0, v0
	v_readlane_b32 s8, v253, 32
	v_readlane_b32 s9, v253, 33
	v_rcp_iflag_f32_e32 v2, v2
	s_nop 0
	v_mul_f32_e32 v2, 0x4f7ffffe, v2
	v_cvt_u32_f32_e32 v2, v2
	v_mul_lo_u32 v3, v3, v2
	v_mul_hi_u32 v3, v2, v3
	v_add_u32_e32 v2, v2, v3
	s_waitcnt vmcnt(0) lgkmcnt(0)
	v_mul_hi_u32 v2, v1, v2
	v_mul_lo_u32 v3, v2, v0
	v_sub_u32_e32 v3, v1, v3
	v_cmp_ge_u32_e32 vcc, v3, v0
	v_add_u32_e32 v4, 1, v2
	s_nop 0
	v_cndmask_b32_e32 v2, v2, v4, vcc
	v_sub_u32_e32 v4, v3, v0
	v_cndmask_b32_e32 v3, v3, v4, vcc
	v_cmp_ge_u32_e32 vcc, v3, v0
	v_add_u32_e32 v3, 1, v2
	s_nop 0
	v_cndmask_b32_e32 v2, v2, v3, vcc
	v_add_u32_e32 v3, 1, v1
	v_mad_u64_u32 v[0:1], s[34:35], v0, v2, v[0:1]
	v_cmp_ne_u32_e32 vcc, v3, v0
	v_mov_b64_e32 v[0:1], s[8:9]
	s_and_saveexec_b64 s[34:35], vcc
	s_cbranch_execz .LBB0_996
	v_readlane_b32 s8, v253, 32
	v_readlane_b32 s9, v253, 33
	s_mov_b64 s[38:39], 0
	s_nop 0
	v_mov_b64_e32 v[0:1], s[8:9]
	global_load_dword v0, v[0:1], off sc1
	s_waitcnt vmcnt(0) lgkmcnt(0)
	v_cmp_eq_u32_e32 vcc, v0, v2
	s_and_saveexec_b64 s[36:37], vcc
	s_cbranch_execz .LBB0_995
	s_mov_b32 s3, 1
	s_branch .LBB0_988

.LBB0_997:
	global_atomic_add v[0:1], v230, off
	s_getpc_b64 s[98:99]
